# removed the no-op s_setprio 0 / s_setprio 1 pairs between the two 16-MFMA halves of every GEMM super-phase (56 sites)
# speedup vs baseline: 1.0074x; 1.0074x over previous
; #define PG8_STAGE(bufoff, gbase, voff) do { _Pragma("unroll") for (int _i = 0; _i < 2; ++_i) \
;         __builtin_amdgcn_global_load_lds((const unsigned*)((const char*)(gbase) + (voff)[_i]), (PG8_LAS unsigned*)(lds + (bufoff) + ldsw + _i * 8192), 16, 0, 0); } while (0)
; #define PG8_LDA(dst, b, h) do { _Pragma("unroll") for (int m = 0; m < 4; ++m) _Pragma("unroll") for (int k = 0; k < 2; ++k) dst[m][k] = *(const PG8_LAS bf16x8*)(lds + PG8_SA(b, h) + aoff + m * 2048 + k * 1024); } while (0)
; template <class Epi, class Sched, bool ALIGN_EPI = false, bool SP2 = false>
; __device__ __forceinline__ void gemm_phase(PG8_LAS unsigned char* lds, const Gemm g, const Sched& S, const Epi& E) {
;     ...
;         const bool has_next = S.next(ui + 1, nxt);
;         const char* nA = has_next ? (const char*)g.A + (size_t)nxt.pm * tstep : cA; const char* nB = has_next ? (const char*)g.Bt + (size_t)nxt.pn * tstep : cB;
;         for (int t = 0; t < nt; t += 2) {
;             const bool last = (t == nt - 2);
;             const char* a1 = cA + (size_t)(t + 1) * kstep;
;             const char* a2 = last ? nA : cA + (size_t)(t + 2) * kstep; const char* b2 = last ? nB : cB + (size_t)(t + 2) * kstep;
;             const char* a3 = a2 + kstep; const char* b3 = b2 + kstep;
;             if (last && has_next) S.a_ready(nxt);
;             if constexpr (SP2) {
;             PG8_LDB(B0, 0, 0); PG8_LDB(B1, 0, 1); PG8_SCHED; PG8_LDA(At, 0, 0); PG8_STAGE(PG8_SA(1, 1), a1 + hstep, voffA);
;             PG8_WAIT_V(8); PG8_WAIT_L(0); PG8_BAR; PG8_MMA(0, 0, At, B0); PG8_MMA(0, 1, At, B1); PG8_BAR; PG8_SCHED;
;             PG8_LDA(At, 0, 1); PG8_STAGE(PG8_SB(0, 0), b2, voffB); PG8_STAGE(PG8_SB(0, 1), b2 + hstep, voffB); PG8_STAGE(PG8_SA(0, 0), a2, voffA);
;             PG8_WAIT_V(8); PG8_WAIT_L(0); PG8_BAR; PG8_MMA(1, 0, At, B0); PG8_MMA(1, 1, At, B1); PG8_BAR; PG8_SCHED;
;             PG8_LDB(B0, 1, 0); PG8_LDB(B1, 1, 1); PG8_SCHED; PG8_LDA(At, 1, 0); PG8_STAGE(PG8_SA(0, 1), a2 + hstep, voffA);
;             PG8_WAIT_V(8); PG8_WAIT_L(0); PG8_BAR; PG8_MMA(0, 0, At, B0); PG8_MMA(0, 1, At, B1); PG8_BAR; PG8_SCHED;
;             PG8_LDA(At, 1, 1); PG8_STAGE(PG8_SB(1, 0), b3, voffB); PG8_STAGE(PG8_SB(1, 1), b3 + hstep, voffB); PG8_STAGE(PG8_SA(1, 0), a3, voffA);
;             PG8_WAIT_V(8); PG8_WAIT_L(0); PG8_BAR; PG8_MMA(1, 0, At, B0); PG8_MMA(1, 1, At, B1); PG8_BAR; PG8_SCHED;
.LBB0_300:
	s_ashr_i32 s13, s12, 31
	s_lshl_b64 s[16:17], s[12:13], 19
	s_add_u32 s16, s0, s16
	s_addc_u32 s17, s1, s17
	s_and_b64 s[18:19], s[4:5], exec
	s_cselect_b32 s13, s17, s25
	s_cselect_b32 s21, s16, s24
	s_ashr_i32 s11, s10, 31
	s_lshl_b64 s[18:19], s[10:11], 19
	s_add_u32 s18, s33, s18
	s_addc_u32 s19, s34, s19
	s_and_b64 s[28:29], s[4:5], exec
	s_cselect_b32 s11, s19, s27
	s_cselect_b32 s44, s18, s26
	s_add_u32 s24, s24, 0x40080
	s_addc_u32 s25, s25, 0
	s_add_u32 s45, s26, 0x100
	s_addc_u32 s46, s27, 0
	s_mov_b32 s47, -2
	s_add_u32 s26, s24, 0xfffc0080
	s_addc_u32 s27, s25, -1
	s_add_i32 s48, 0, 0x10000
	s_cmp_eq_u32 s47, 12
	s_cselect_b32 s29, s13, s27
	s_cselect_b32 s28, s21, s26
	v_add_u32_e32 v154, s48, v156
	s_cselect_b32 s27, s11, s46
	s_cselect_b32 s26, s44, s45
	s_add_i32 s50, 0, 0x14000
	ds_read_b128 v[94:97], v154
	ds_read_b128 v[134:137], v154 offset:1024
	ds_read_b128 v[158:161], v154 offset:2048
	ds_read_b128 v[162:165], v154 offset:3072
	v_add_u32_e32 v154, s50, v156
	ds_read_b128 v[166:169], v154
	ds_read_b128 v[170:173], v154 offset:1024
	ds_read_b128 v[174:177], v154 offset:2048
	ds_read_b128 v[186:189], v154 offset:3072
	v_lshl_add_u64 v[154:155], s[24:25], 0, v[150:151]
	s_add_i32 m0, s23, 0xc000
	ds_read_b128 v[190:193], v157
	ds_read_b128 v[194:197], v157 offset:1024
	ds_read_b128 v[198:201], v157 offset:2048
	ds_read_b128 v[202:205], v157 offset:3072
	ds_read_b128 v[206:209], v157 offset:4096
	ds_read_b128 v[210:213], v157 offset:5120
	ds_read_b128 v[214:217], v157 offset:6144
	ds_read_b128 v[218:221], v157 offset:7168
	global_load_lds_dwordx4 v[154:155], off
	v_lshl_add_u64 v[154:155], s[24:25], 0, v[152:153]
	s_add_i32 m0, s23, 0xe000
	s_nop 0
	global_load_lds_dwordx4 v[154:155], off
	s_waitcnt vmcnt(8) lgkmcnt(0)
	s_barrier
	s_setprio 1
	v_mfma_f32_16x16x32_bf16 v[130:133], v[94:97], v[190:193], 0
	v_mfma_f32_16x16x32_bf16 v[126:129], v[158:161], v[190:193], 0
	v_mfma_f32_16x16x32_bf16 v[114:117], v[94:97], v[198:201], 0
	v_mfma_f32_16x16x32_bf16 v[110:113], v[158:161], v[198:201], 0
	v_mfma_f32_16x16x32_bf16 v[98:101], v[94:97], v[206:209], 0
	v_mfma_f32_16x16x32_bf16 v[90:93], v[158:161], v[206:209], 0
	v_mfma_f32_16x16x32_bf16 v[78:81], v[94:97], v[214:217], 0
	v_mfma_f32_16x16x32_bf16 v[74:77], v[158:161], v[214:217], 0
	v_mfma_f32_16x16x32_bf16 v[130:133], v[134:137], v[194:197], v[130:133]
	v_mfma_f32_16x16x32_bf16 v[126:129], v[162:165], v[194:197], v[126:129]
	v_mfma_f32_16x16x32_bf16 v[114:117], v[134:137], v[202:205], v[114:117]
	v_mfma_f32_16x16x32_bf16 v[110:113], v[162:165], v[202:205], v[110:113]
	v_mfma_f32_16x16x32_bf16 v[98:101], v[134:137], v[210:213], v[98:101]
	v_mfma_f32_16x16x32_bf16 v[90:93], v[162:165], v[210:213], v[90:93]
	v_mfma_f32_16x16x32_bf16 v[78:81], v[134:137], v[218:221], v[78:81]
	v_mfma_f32_16x16x32_bf16 v[74:77], v[162:165], v[218:221], v[74:77]
	v_mfma_f32_16x16x32_bf16 v[122:125], v[166:169], v[190:193], 0
	v_mfma_f32_16x16x32_bf16 v[118:121], v[174:177], v[190:193], 0
	v_mfma_f32_16x16x32_bf16 v[106:109], v[166:169], v[198:201], 0
	v_mfma_f32_16x16x32_bf16 v[102:105], v[174:177], v[198:201], 0
	v_mfma_f32_16x16x32_bf16 v[86:89], v[166:169], v[206:209], 0
	v_mfma_f32_16x16x32_bf16 v[82:85], v[174:177], v[206:209], 0
	v_mfma_f32_16x16x32_bf16 v[70:73], v[166:169], v[214:217], 0
	v_mfma_f32_16x16x32_bf16 v[66:69], v[174:177], v[214:217], 0
	v_mfma_f32_16x16x32_bf16 v[122:125], v[170:173], v[194:197], v[122:125]
	v_mfma_f32_16x16x32_bf16 v[118:121], v[186:189], v[194:197], v[118:121]
	v_mfma_f32_16x16x32_bf16 v[106:109], v[170:173], v[202:205], v[106:109]
	v_mfma_f32_16x16x32_bf16 v[102:105], v[186:189], v[202:205], v[102:105]
	v_mfma_f32_16x16x32_bf16 v[86:89], v[170:173], v[210:213], v[86:89]
	v_mfma_f32_16x16x32_bf16 v[82:85], v[186:189], v[210:213], v[82:85]
	v_mfma_f32_16x16x32_bf16 v[70:73], v[170:173], v[218:221], v[70:73]
	v_mfma_f32_16x16x32_bf16 v[66:69], v[186:189], v[218:221], v[66:69]
	s_setprio 0
	s_barrier
	s_add_i32 s48, s48, s35
	v_lshl_add_u64 v[154:155], s[26:27], 0, v[142:143]
	s_mov_b32 m0, s48
	ds_read_b128 v[190:193], v157 offset:16384
	ds_read_b128 v[194:197], v157 offset:17408
	ds_read_b128 v[198:201], v157 offset:18432
	ds_read_b128 v[202:205], v157 offset:19456
	ds_read_b128 v[206:209], v157 offset:20480
	ds_read_b128 v[210:213], v157 offset:21504
	ds_read_b128 v[214:217], v157 offset:22528
	ds_read_b128 v[218:221], v157 offset:23552
	global_load_lds_dwordx4 v[154:155], off
	s_add_i32 m0, s48, 0x2000
	s_add_u32 s48, s26, 0x40000
	v_lshl_add_u64 v[180:181], s[26:27], 0, v[138:139]
	s_addc_u32 s49, s27, 0
	s_add_i32 s50, s50, s35
	global_load_lds_dwordx4 v[180:181], off
	v_lshl_add_u64 v[182:183], s[48:49], 0, v[142:143]
	s_mov_b32 m0, s50
	v_lshl_add_u64 v[222:223], s[28:29], 0, v[140:141]
	global_load_lds_dwordx4 v[182:183], off
	v_lshl_add_u64 v[182:183], s[48:49], 0, v[138:139]
	s_add_i32 m0, s50, 0x2000
	s_nop 0
	global_load_lds_dwordx4 v[182:183], off
	v_lshl_add_u64 v[182:183], s[28:29], 0, v[144:145]
	s_mov_b32 m0, s23
	s_nop 0
	global_load_lds_dwordx4 v[182:183], off
	s_mov_b32 m0, s37
	s_nop 0
	global_load_lds_dwordx4 v[222:223], off
	s_waitcnt vmcnt(8) lgkmcnt(0)
	s_barrier
; #define PG8_STAGE(bufoff, gbase, voff) do { _Pragma("unroll") for (int _i = 0; _i < 2; ++_i) \
;         __builtin_amdgcn_global_load_lds((const unsigned*)((const char*)(gbase) + (voff)[_i]), (PG8_LAS unsigned*)(lds + (bufoff) + ldsw + _i * 8192), 16, 0, 0); } while (0)
; #define PG8_LDA(dst, b, h) do { _Pragma("unroll") for (int m = 0; m < 4; ++m) _Pragma("unroll") for (int k = 0; k < 2; ++k) dst[m][k] = *(const PG8_LAS bf16x8*)(lds + PG8_SA(b, h) + aoff + m * 2048 + k * 1024); } while (0)
; #define PG8_LDB(dst, b, h) do { _Pragma("unroll") for (int n = 0; n < 2; ++n) _Pragma("unroll") for (int k = 0; k < 2; ++k) dst[n][k] = *(const PG8_LAS bf16x8*)(lds + PG8_SB(b, h) + boff + n * 2048 + k * 1024); } while (0)
; #define PG8_MMA(ai, bj, At, Bt) do { __builtin_amdgcn_s_setprio(1); _Pragma("unroll") for (int m = 0; m < 4; ++m) _Pragma("unroll") for (int n = 0; n < 2; ++n) _Pragma("unroll") for (int k = 0; k < 2; ++k) \
;         acc[ai][bj][m][n] = __builtin_amdgcn_mfma_f32_16x16x32_bf16(Bt[n][k], At[m][k], acc[ai][bj][m][n], 0, 0, 0); __builtin_amdgcn_s_setprio(0); } while (0)
; #define PG8_WAIT_V(n) asm volatile("s_waitcnt vmcnt(" #n ")" ::: "memory")
; #define PG8_WAIT_L(n) asm volatile("s_waitcnt lgkmcnt(" #n ")" ::: "memory")
; #define PG8_BAR __builtin_amdgcn_s_barrier()
; #define PG8_SCHED __builtin_amdgcn_sched_barrier(0)
; template <class Epi, class Sched, bool ALIGN_EPI = false, bool SP2 = false>
; __device__ __forceinline__ void gemm_phase(PG8_LAS unsigned char* lds, const Gemm g, const Sched& S, const Epi& E) {
;     ...
;             PG8_LDB(B0, 0, 0); PG8_LDB(B1, 0, 1); PG8_SCHED; PG8_LDA(At, 0, 0); PG8_STAGE(PG8_SA(1, 1), a1 + hstep, voffA);
;             PG8_WAIT_V(8); PG8_WAIT_L(0); PG8_BAR; PG8_MMA(0, 0, At, B0); PG8_MMA(0, 1, At, B1); PG8_BAR; PG8_SCHED;
;             PG8_LDA(At, 0, 1); PG8_STAGE(PG8_SB(0, 0), b2, voffB); PG8_STAGE(PG8_SB(0, 1), b2 + hstep, voffB); PG8_STAGE(PG8_SA(0, 0), a2, voffA);
;             PG8_WAIT_V(8); PG8_WAIT_L(0); PG8_BAR; PG8_MMA(1, 0, At, B0); PG8_MMA(1, 1, At, B1); PG8_BAR; PG8_SCHED;
;             PG8_LDB(B0, 1, 0); PG8_LDB(B1, 1, 1); PG8_SCHED; PG8_LDA(At, 1, 0); PG8_STAGE(PG8_SA(0, 1), a2 + hstep, voffA);
;             PG8_WAIT_V(8); PG8_WAIT_L(0); PG8_BAR; PG8_MMA(0, 0, At, B0); PG8_MMA(0, 1, At, B1); PG8_BAR; PG8_SCHED;
	s_setprio 1
	v_mfma_f32_16x16x32_bf16 v[62:65], v[94:97], v[190:193], 0
	v_mfma_f32_16x16x32_bf16 v[58:61], v[158:161], v[190:193], 0
	v_mfma_f32_16x16x32_bf16 v[50:53], v[94:97], v[198:201], 0
	v_mfma_f32_16x16x32_bf16 v[42:45], v[158:161], v[198:201], 0
	v_mfma_f32_16x16x32_bf16 v[34:37], v[94:97], v[206:209], 0
	v_mfma_f32_16x16x32_bf16 v[26:29], v[158:161], v[206:209], 0
	v_mfma_f32_16x16x32_bf16 v[18:21], v[94:97], v[214:217], 0
	v_mfma_f32_16x16x32_bf16 v[10:13], v[158:161], v[214:217], 0
	v_mfma_f32_16x16x32_bf16 v[62:65], v[134:137], v[194:197], v[62:65]
	v_mfma_f32_16x16x32_bf16 v[58:61], v[162:165], v[194:197], v[58:61]
	v_mfma_f32_16x16x32_bf16 v[50:53], v[134:137], v[202:205], v[50:53]
	v_mfma_f32_16x16x32_bf16 v[42:45], v[162:165], v[202:205], v[42:45]
	v_mfma_f32_16x16x32_bf16 v[34:37], v[134:137], v[210:213], v[34:37]
	v_mfma_f32_16x16x32_bf16 v[26:29], v[162:165], v[210:213], v[26:29]
	v_mfma_f32_16x16x32_bf16 v[18:21], v[134:137], v[218:221], v[18:21]
	v_mfma_f32_16x16x32_bf16 v[10:13], v[162:165], v[218:221], v[10:13]
	v_mfma_f32_16x16x32_bf16 v[54:57], v[166:169], v[190:193], 0
	v_mfma_f32_16x16x32_bf16 v[46:49], v[174:177], v[190:193], 0
	v_mfma_f32_16x16x32_bf16 v[38:41], v[166:169], v[198:201], 0
	v_mfma_f32_16x16x32_bf16 v[30:33], v[174:177], v[198:201], 0
	v_mfma_f32_16x16x32_bf16 v[22:25], v[166:169], v[206:209], 0
	v_mfma_f32_16x16x32_bf16 v[14:17], v[174:177], v[206:209], 0
	v_mfma_f32_16x16x32_bf16 v[6:9], v[166:169], v[214:217], 0
	v_mfma_f32_16x16x32_bf16 v[2:5], v[174:177], v[214:217], 0
	v_mfma_f32_16x16x32_bf16 v[54:57], v[170:173], v[194:197], v[54:57]
	v_mfma_f32_16x16x32_bf16 v[46:49], v[186:189], v[194:197], v[46:49]
	v_mfma_f32_16x16x32_bf16 v[38:41], v[170:173], v[202:205], v[38:41]
	v_mfma_f32_16x16x32_bf16 v[30:33], v[186:189], v[202:205], v[30:33]
	v_mfma_f32_16x16x32_bf16 v[22:25], v[170:173], v[210:213], v[22:25]
	v_mfma_f32_16x16x32_bf16 v[14:17], v[186:189], v[210:213], v[14:17]
	v_mfma_f32_16x16x32_bf16 v[6:9], v[170:173], v[218:221], v[6:9]
	v_mfma_f32_16x16x32_bf16 v[2:5], v[186:189], v[218:221], v[2:5]
	s_setprio 0
	s_barrier
	s_add_i32 s48, 0, 0x18000
	s_add_i32 s49, 0, 0x1c000
	v_add_u32_e32 v162, s48, v156
	v_add_u32_e32 v179, s49, v156
	ds_read_b128 v[94:97], v162
	ds_read_b128 v[134:137], v162 offset:1024
	ds_read_b128 v[158:161], v162 offset:2048
	ds_read_b128 v[162:165], v162 offset:3072
	ds_read_b128 v[166:169], v179
	ds_read_b128 v[170:173], v179 offset:1024
	ds_read_b128 v[174:177], v179 offset:2048
	ds_read_b128 v[186:189], v179 offset:3072
	s_add_u32 s28, s28, 0x40000
	s_addc_u32 s29, s29, 0
	s_mov_b32 m0, s38
	v_lshl_add_u64 v[240:241], s[28:29], 0, v[144:145]
	ds_read_b128 v[190:193], v157 offset:32768
	ds_read_b128 v[194:197], v157 offset:33792
	ds_read_b128 v[198:201], v157 offset:34816
	ds_read_b128 v[202:205], v157 offset:35840
	ds_read_b128 v[206:209], v157 offset:36864
	ds_read_b128 v[210:213], v157 offset:37888
	ds_read_b128 v[214:217], v157 offset:38912
	ds_read_b128 v[218:221], v157 offset:39936
	global_load_lds_dwordx4 v[240:241], off
	v_lshl_add_u64 v[240:241], s[28:29], 0, v[140:141]
	s_mov_b32 m0, s39
	s_nop 0
	global_load_lds_dwordx4 v[240:241], off
	s_waitcnt vmcnt(8) lgkmcnt(0)
	s_barrier
	s_setprio 1
	v_mfma_f32_16x16x32_bf16 v[130:133], v[94:97], v[190:193], v[130:133]
	v_mfma_f32_16x16x32_bf16 v[126:129], v[158:161], v[190:193], v[126:129]
	v_mfma_f32_16x16x32_bf16 v[114:117], v[94:97], v[198:201], v[114:117]
	v_mfma_f32_16x16x32_bf16 v[110:113], v[158:161], v[198:201], v[110:113]
	v_mfma_f32_16x16x32_bf16 v[98:101], v[94:97], v[206:209], v[98:101]
	v_mfma_f32_16x16x32_bf16 v[90:93], v[158:161], v[206:209], v[90:93]
	v_mfma_f32_16x16x32_bf16 v[78:81], v[94:97], v[214:217], v[78:81]
	v_mfma_f32_16x16x32_bf16 v[74:77], v[158:161], v[214:217], v[74:77]
	v_mfma_f32_16x16x32_bf16 v[130:133], v[134:137], v[194:197], v[130:133]
	v_mfma_f32_16x16x32_bf16 v[126:129], v[162:165], v[194:197], v[126:129]
	v_mfma_f32_16x16x32_bf16 v[114:117], v[134:137], v[202:205], v[114:117]
	v_mfma_f32_16x16x32_bf16 v[110:113], v[162:165], v[202:205], v[110:113]
	v_mfma_f32_16x16x32_bf16 v[98:101], v[134:137], v[210:213], v[98:101]
	v_mfma_f32_16x16x32_bf16 v[90:93], v[162:165], v[210:213], v[90:93]
	v_mfma_f32_16x16x32_bf16 v[78:81], v[134:137], v[218:221], v[78:81]
	v_mfma_f32_16x16x32_bf16 v[74:77], v[162:165], v[218:221], v[74:77]
	v_mfma_f32_16x16x32_bf16 v[122:125], v[166:169], v[190:193], v[122:125]
	v_mfma_f32_16x16x32_bf16 v[118:121], v[174:177], v[190:193], v[118:121]
	v_mfma_f32_16x16x32_bf16 v[106:109], v[166:169], v[198:201], v[106:109]
	v_mfma_f32_16x16x32_bf16 v[102:105], v[174:177], v[198:201], v[102:105]
	v_mfma_f32_16x16x32_bf16 v[86:89], v[166:169], v[206:209], v[86:89]
	v_mfma_f32_16x16x32_bf16 v[82:85], v[174:177], v[206:209], v[82:85]
	v_mfma_f32_16x16x32_bf16 v[70:73], v[166:169], v[214:217], v[70:73]
	v_mfma_f32_16x16x32_bf16 v[66:69], v[174:177], v[214:217], v[66:69]
	v_mfma_f32_16x16x32_bf16 v[122:125], v[170:173], v[194:197], v[122:125]
	v_mfma_f32_16x16x32_bf16 v[118:121], v[186:189], v[194:197], v[118:121]
	v_mfma_f32_16x16x32_bf16 v[106:109], v[170:173], v[202:205], v[106:109]
	v_mfma_f32_16x16x32_bf16 v[102:105], v[186:189], v[202:205], v[102:105]
	v_mfma_f32_16x16x32_bf16 v[86:89], v[170:173], v[210:213], v[86:89]
	v_mfma_f32_16x16x32_bf16 v[82:85], v[186:189], v[210:213], v[82:85]
	v_mfma_f32_16x16x32_bf16 v[70:73], v[170:173], v[218:221], v[70:73]
	v_mfma_f32_16x16x32_bf16 v[66:69], v[186:189], v[218:221], v[66:69]
	s_setprio 0
	s_barrier
; #define PG8_STAGE(bufoff, gbase, voff) do { _Pragma("unroll") for (int _i = 0; _i < 2; ++_i) \
;         __builtin_amdgcn_global_load_lds((const unsigned*)((const char*)(gbase) + (voff)[_i]), (PG8_LAS unsigned*)(lds + (bufoff) + ldsw + _i * 8192), 16, 0, 0); } while (0)
; #define PG8_LDA(dst, b, h) do { _Pragma("unroll") for (int m = 0; m < 4; ++m) _Pragma("unroll") for (int k = 0; k < 2; ++k) dst[m][k] = *(const PG8_LAS bf16x8*)(lds + PG8_SA(b, h) + aoff + m * 2048 + k * 1024); } while (0)
; #define PG8_LDB(dst, b, h) do { _Pragma("unroll") for (int n = 0; n < 2; ++n) _Pragma("unroll") for (int k = 0; k < 2; ++k) dst[n][k] = *(const PG8_LAS bf16x8*)(lds + PG8_SB(b, h) + boff + n * 2048 + k * 1024); } while (0)
; template <class Epi, class Sched, bool ALIGN_EPI = false, bool SP2 = false>
; __device__ __forceinline__ void gemm_phase(PG8_LAS unsigned char* lds, const Gemm g, const Sched& S, const Epi& E) {
;     ...
;         for (int t = 0; t < nt; t += 2) {
;             const bool last = (t == nt - 2);
;             const char* a1 = cA + (size_t)(t + 1) * kstep;
;             const char* a2 = last ? nA : cA + (size_t)(t + 2) * kstep; const char* b2 = last ? nB : cB + (size_t)(t + 2) * kstep;
;             const char* a3 = a2 + kstep; const char* b3 = b2 + kstep;
;             if (last && has_next) S.a_ready(nxt);
;             if constexpr (SP2) {
;             PG8_LDB(B0, 0, 0); PG8_LDB(B1, 0, 1); PG8_SCHED; PG8_LDA(At, 0, 0); PG8_STAGE(PG8_SA(1, 1), a1 + hstep, voffA);
;             PG8_WAIT_V(8); PG8_WAIT_L(0); PG8_BAR; PG8_MMA(0, 0, At, B0); PG8_MMA(0, 1, At, B1); PG8_BAR; PG8_SCHED;
;             PG8_LDA(At, 0, 1); PG8_STAGE(PG8_SB(0, 0), b2, voffB); PG8_STAGE(PG8_SB(0, 1), b2 + hstep, voffB); PG8_STAGE(PG8_SA(0, 0), a2, voffA);
;             PG8_WAIT_V(8); PG8_WAIT_L(0); PG8_BAR; PG8_MMA(1, 0, At, B0); PG8_MMA(1, 1, At, B1); PG8_BAR; PG8_SCHED;
;             PG8_LDB(B0, 1, 0); PG8_LDB(B1, 1, 1); PG8_SCHED; PG8_LDA(At, 1, 0); PG8_STAGE(PG8_SA(0, 1), a2 + hstep, voffA);
;             PG8_WAIT_V(8); PG8_WAIT_L(0); PG8_BAR; PG8_MMA(0, 0, At, B0); PG8_MMA(0, 1, At, B1); PG8_BAR; PG8_SCHED;
;             PG8_LDA(At, 1, 1); PG8_STAGE(PG8_SB(1, 0), b3, voffB); PG8_STAGE(PG8_SB(1, 1), b3 + hstep, voffB); PG8_STAGE(PG8_SA(1, 0), a3, voffA);
;             PG8_WAIT_V(8); PG8_WAIT_L(0); PG8_BAR; PG8_MMA(1, 0, At, B0); PG8_MMA(1, 1, At, B1); PG8_BAR; PG8_SCHED;
	s_add_i32 s28, s48, s35
	v_lshl_add_u64 v[154:155], v[154:155], 0, s[80:81]
	s_mov_b32 m0, s28
	ds_read_b128 v[190:193], v157 offset:49152
	ds_read_b128 v[194:197], v157 offset:50176
	ds_read_b128 v[198:201], v157 offset:51200
	ds_read_b128 v[202:205], v157 offset:52224
	ds_read_b128 v[206:209], v157 offset:53248
	ds_read_b128 v[210:213], v157 offset:54272
	ds_read_b128 v[214:217], v157 offset:55296
	ds_read_b128 v[218:221], v157 offset:56320
	global_load_lds_dwordx4 v[154:155], off
	s_add_i32 m0, s28, 0x2000
	s_add_u32 s26, s26, 0x40080
	v_lshl_add_u64 v[154:155], v[180:181], 0, s[80:81]
	s_addc_u32 s27, s27, 0
	s_add_i32 s28, s49, s35
	global_load_lds_dwordx4 v[154:155], off
	v_lshl_add_u64 v[154:155], s[26:27], 0, v[142:143]
	s_mov_b32 m0, s28
	s_nop 0
	global_load_lds_dwordx4 v[154:155], off
	v_lshl_add_u64 v[154:155], s[26:27], 0, v[138:139]
	s_add_i32 m0, s28, 0x2000
	s_nop 0
	global_load_lds_dwordx4 v[154:155], off
	v_lshl_add_u64 v[154:155], v[182:183], 0, s[80:81]
	s_mov_b32 m0, s40
	s_nop 0
	global_load_lds_dwordx4 v[154:155], off
	v_lshl_add_u64 v[154:155], v[222:223], 0, s[80:81]
	s_mov_b32 m0, s41
	s_nop 0
	global_load_lds_dwordx4 v[154:155], off
	s_waitcnt vmcnt(8) lgkmcnt(0)
	s_barrier
	s_setprio 1
	v_mfma_f32_16x16x32_bf16 v[62:65], v[94:97], v[190:193], v[62:65]
	v_mfma_f32_16x16x32_bf16 v[58:61], v[158:161], v[190:193], v[58:61]
	v_mfma_f32_16x16x32_bf16 v[50:53], v[94:97], v[198:201], v[50:53]
	v_mfma_f32_16x16x32_bf16 v[42:45], v[158:161], v[198:201], v[42:45]
	v_mfma_f32_16x16x32_bf16 v[34:37], v[94:97], v[206:209], v[34:37]
	v_mfma_f32_16x16x32_bf16 v[26:29], v[158:161], v[206:209], v[26:29]
	v_mfma_f32_16x16x32_bf16 v[18:21], v[94:97], v[214:217], v[18:21]
	v_mfma_f32_16x16x32_bf16 v[10:13], v[158:161], v[214:217], v[10:13]
	v_mfma_f32_16x16x32_bf16 v[62:65], v[134:137], v[194:197], v[62:65]
	v_mfma_f32_16x16x32_bf16 v[58:61], v[162:165], v[194:197], v[58:61]
	v_mfma_f32_16x16x32_bf16 v[50:53], v[134:137], v[202:205], v[50:53]
	v_mfma_f32_16x16x32_bf16 v[42:45], v[162:165], v[202:205], v[42:45]
	v_mfma_f32_16x16x32_bf16 v[34:37], v[134:137], v[210:213], v[34:37]
	v_mfma_f32_16x16x32_bf16 v[26:29], v[162:165], v[210:213], v[26:29]
	v_mfma_f32_16x16x32_bf16 v[18:21], v[134:137], v[218:221], v[18:21]
	v_mfma_f32_16x16x32_bf16 v[10:13], v[162:165], v[218:221], v[10:13]
	v_mfma_f32_16x16x32_bf16 v[54:57], v[166:169], v[190:193], v[54:57]
	v_mfma_f32_16x16x32_bf16 v[46:49], v[174:177], v[190:193], v[46:49]
	v_mfma_f32_16x16x32_bf16 v[38:41], v[166:169], v[198:201], v[38:41]
	v_mfma_f32_16x16x32_bf16 v[30:33], v[174:177], v[198:201], v[30:33]
	v_mfma_f32_16x16x32_bf16 v[22:25], v[166:169], v[206:209], v[22:25]
	v_mfma_f32_16x16x32_bf16 v[14:17], v[174:177], v[206:209], v[14:17]
	v_mfma_f32_16x16x32_bf16 v[6:9], v[166:169], v[214:217], v[6:9]
	v_mfma_f32_16x16x32_bf16 v[2:5], v[174:177], v[214:217], v[2:5]
	v_mfma_f32_16x16x32_bf16 v[54:57], v[170:173], v[194:197], v[54:57]
	v_mfma_f32_16x16x32_bf16 v[46:49], v[186:189], v[194:197], v[46:49]
	v_mfma_f32_16x16x32_bf16 v[38:41], v[170:173], v[202:205], v[38:41]
	v_mfma_f32_16x16x32_bf16 v[30:33], v[186:189], v[202:205], v[30:33]
	v_mfma_f32_16x16x32_bf16 v[22:25], v[170:173], v[210:213], v[22:25]
	v_mfma_f32_16x16x32_bf16 v[14:17], v[186:189], v[210:213], v[14:17]
	v_mfma_f32_16x16x32_bf16 v[6:9], v[170:173], v[218:221], v[6:9]
	v_mfma_f32_16x16x32_bf16 v[2:5], v[186:189], v[218:221], v[2:5]
	s_setprio 0
	s_barrier
	s_add_i32 s47, s47, 2
	s_add_u32 s24, s24, 0x100
	s_addc_u32 s25, s25, 0
	s_add_u32 s45, s45, 0x100
	s_addc_u32 s46, s46, 0
	s_cmp_gt_u32 s47, 13
	s_branch .LBB0_301
.LBB0_301:
	s_add_u32 s26, s24, 0xfffc0080
	s_addc_u32 s27, s25, -1
	s_add_i32 s48, 0, 0x10000
	s_cmp_eq_u32 s47, 12
	s_cselect_b32 s29, s13, s27
	s_cselect_b32 s28, s21, s26
	v_add_u32_e32 v154, s48, v156
	s_cselect_b32 s27, s11, s46
	s_cselect_b32 s26, s44, s45
	s_add_i32 s50, 0, 0x14000
	ds_read_b128 v[94:97], v154
	ds_read_b128 v[134:137], v154 offset:1024
	ds_read_b128 v[158:161], v154 offset:2048
	ds_read_b128 v[162:165], v154 offset:3072
	v_add_u32_e32 v154, s50, v156
	ds_read_b128 v[166:169], v154
	ds_read_b128 v[170:173], v154 offset:1024
	ds_read_b128 v[174:177], v154 offset:2048
	ds_read_b128 v[186:189], v154 offset:3072
	v_lshl_add_u64 v[154:155], s[24:25], 0, v[150:151]
	s_add_i32 m0, s23, 0xc000
	ds_read_b128 v[190:193], v157
	ds_read_b128 v[194:197], v157 offset:1024
	ds_read_b128 v[198:201], v157 offset:2048
	ds_read_b128 v[202:205], v157 offset:3072
	ds_read_b128 v[206:209], v157 offset:4096
	ds_read_b128 v[210:213], v157 offset:5120
	ds_read_b128 v[214:217], v157 offset:6144
	ds_read_b128 v[218:221], v157 offset:7168
	global_load_lds_dwordx4 v[154:155], off
	v_lshl_add_u64 v[154:155], s[24:25], 0, v[152:153]
	s_add_i32 m0, s23, 0xe000
	s_nop 0
	global_load_lds_dwordx4 v[154:155], off
	s_waitcnt vmcnt(8) lgkmcnt(0)
	s_barrier
; #define PG8_STAGE(bufoff, gbase, voff) do { _Pragma("unroll") for (int _i = 0; _i < 2; ++_i) \
;         __builtin_amdgcn_global_load_lds((const unsigned*)((const char*)(gbase) + (voff)[_i]), (PG8_LAS unsigned*)(lds + (bufoff) + ldsw + _i * 8192), 16, 0, 0); } while (0)
; #define PG8_LDA(dst, b, h) do { _Pragma("unroll") for (int m = 0; m < 4; ++m) _Pragma("unroll") for (int k = 0; k < 2; ++k) dst[m][k] = *(const PG8_LAS bf16x8*)(lds + PG8_SA(b, h) + aoff + m * 2048 + k * 1024); } while (0)
; #define PG8_LDB(dst, b, h) do { _Pragma("unroll") for (int n = 0; n < 2; ++n) _Pragma("unroll") for (int k = 0; k < 2; ++k) dst[n][k] = *(const PG8_LAS bf16x8*)(lds + PG8_SB(b, h) + boff + n * 2048 + k * 1024); } while (0)
; #define PG8_MMA(ai, bj, At, Bt) do { __builtin_amdgcn_s_setprio(1); _Pragma("unroll") for (int m = 0; m < 4; ++m) _Pragma("unroll") for (int n = 0; n < 2; ++n) _Pragma("unroll") for (int k = 0; k < 2; ++k) \
;         acc[ai][bj][m][n] = __builtin_amdgcn_mfma_f32_16x16x32_bf16(Bt[n][k], At[m][k], acc[ai][bj][m][n], 0, 0, 0); __builtin_amdgcn_s_setprio(0); } while (0)
; #define PG8_BAR __builtin_amdgcn_s_barrier()
; template <class Epi, class Sched, bool ALIGN_EPI = false, bool SP2 = false>
; __device__ __forceinline__ void gemm_phase(PG8_LAS unsigned char* lds, const Gemm g, const Sched& S, const Epi& E) {
;     ...
;             if constexpr (SP2) {
;             PG8_LDB(B0, 0, 0); PG8_LDB(B1, 0, 1); PG8_SCHED; PG8_LDA(At, 0, 0); PG8_STAGE(PG8_SA(1, 1), a1 + hstep, voffA);
;             PG8_WAIT_V(8); PG8_WAIT_L(0); PG8_BAR; PG8_MMA(0, 0, At, B0); PG8_MMA(0, 1, At, B1); PG8_BAR; PG8_SCHED;
;             PG8_LDA(At, 0, 1); PG8_STAGE(PG8_SB(0, 0), b2, voffB); PG8_STAGE(PG8_SB(0, 1), b2 + hstep, voffB); PG8_STAGE(PG8_SA(0, 0), a2, voffA);
;             PG8_WAIT_V(8); PG8_WAIT_L(0); PG8_BAR; PG8_MMA(1, 0, At, B0); PG8_MMA(1, 1, At, B1); PG8_BAR; PG8_SCHED;
;             PG8_LDB(B0, 1, 0); PG8_LDB(B1, 1, 1); PG8_SCHED; PG8_LDA(At, 1, 0); PG8_STAGE(PG8_SA(0, 1), a2 + hstep, voffA);
;             PG8_WAIT_V(8); PG8_WAIT_L(0); PG8_BAR; PG8_MMA(0, 0, At, B0); PG8_MMA(0, 1, At, B1); PG8_BAR; PG8_SCHED;
;             PG8_LDA(At, 1, 1); PG8_STAGE(PG8_SB(1, 0), b3, voffB); PG8_STAGE(PG8_SB(1, 1), b3 + hstep, voffB); PG8_STAGE(PG8_SA(1, 0), a3, voffA);
;             PG8_WAIT_V(8); PG8_WAIT_L(0); PG8_BAR; PG8_MMA(1, 0, At, B0); PG8_MMA(1, 1, At, B1); PG8_BAR; PG8_SCHED;
	s_setprio 1
	v_mfma_f32_16x16x32_bf16 v[130:133], v[94:97], v[190:193], v[130:133]
	v_mfma_f32_16x16x32_bf16 v[126:129], v[158:161], v[190:193], v[126:129]
	v_mfma_f32_16x16x32_bf16 v[114:117], v[94:97], v[198:201], v[114:117]
	v_mfma_f32_16x16x32_bf16 v[110:113], v[158:161], v[198:201], v[110:113]
	v_mfma_f32_16x16x32_bf16 v[98:101], v[94:97], v[206:209], v[98:101]
	v_mfma_f32_16x16x32_bf16 v[90:93], v[158:161], v[206:209], v[90:93]
	v_mfma_f32_16x16x32_bf16 v[78:81], v[94:97], v[214:217], v[78:81]
	v_mfma_f32_16x16x32_bf16 v[74:77], v[158:161], v[214:217], v[74:77]
	v_mfma_f32_16x16x32_bf16 v[130:133], v[134:137], v[194:197], v[130:133]
	v_mfma_f32_16x16x32_bf16 v[126:129], v[162:165], v[194:197], v[126:129]
	v_mfma_f32_16x16x32_bf16 v[114:117], v[134:137], v[202:205], v[114:117]
	v_mfma_f32_16x16x32_bf16 v[110:113], v[162:165], v[202:205], v[110:113]
	v_mfma_f32_16x16x32_bf16 v[98:101], v[134:137], v[210:213], v[98:101]
	v_mfma_f32_16x16x32_bf16 v[90:93], v[162:165], v[210:213], v[90:93]
	v_mfma_f32_16x16x32_bf16 v[78:81], v[134:137], v[218:221], v[78:81]
	v_mfma_f32_16x16x32_bf16 v[74:77], v[162:165], v[218:221], v[74:77]
	v_mfma_f32_16x16x32_bf16 v[122:125], v[166:169], v[190:193], v[122:125]
	v_mfma_f32_16x16x32_bf16 v[118:121], v[174:177], v[190:193], v[118:121]
	v_mfma_f32_16x16x32_bf16 v[106:109], v[166:169], v[198:201], v[106:109]
	v_mfma_f32_16x16x32_bf16 v[102:105], v[174:177], v[198:201], v[102:105]
	v_mfma_f32_16x16x32_bf16 v[86:89], v[166:169], v[206:209], v[86:89]
	v_mfma_f32_16x16x32_bf16 v[82:85], v[174:177], v[206:209], v[82:85]
	v_mfma_f32_16x16x32_bf16 v[70:73], v[166:169], v[214:217], v[70:73]
	v_mfma_f32_16x16x32_bf16 v[66:69], v[174:177], v[214:217], v[66:69]
	v_mfma_f32_16x16x32_bf16 v[122:125], v[170:173], v[194:197], v[122:125]
	v_mfma_f32_16x16x32_bf16 v[118:121], v[186:189], v[194:197], v[118:121]
	v_mfma_f32_16x16x32_bf16 v[106:109], v[170:173], v[202:205], v[106:109]
	v_mfma_f32_16x16x32_bf16 v[102:105], v[186:189], v[202:205], v[102:105]
	v_mfma_f32_16x16x32_bf16 v[86:89], v[170:173], v[210:213], v[86:89]
	v_mfma_f32_16x16x32_bf16 v[82:85], v[186:189], v[210:213], v[82:85]
	v_mfma_f32_16x16x32_bf16 v[70:73], v[170:173], v[218:221], v[70:73]
	v_mfma_f32_16x16x32_bf16 v[66:69], v[186:189], v[218:221], v[66:69]
	s_setprio 0
	s_barrier
	s_add_i32 s48, s48, s35
	v_lshl_add_u64 v[154:155], s[26:27], 0, v[142:143]
	s_mov_b32 m0, s48
	ds_read_b128 v[190:193], v157 offset:16384
	ds_read_b128 v[194:197], v157 offset:17408
	ds_read_b128 v[198:201], v157 offset:18432
	ds_read_b128 v[202:205], v157 offset:19456
	ds_read_b128 v[206:209], v157 offset:20480
	ds_read_b128 v[210:213], v157 offset:21504
	ds_read_b128 v[214:217], v157 offset:22528
	ds_read_b128 v[218:221], v157 offset:23552
	global_load_lds_dwordx4 v[154:155], off
	s_add_i32 m0, s48, 0x2000
	s_add_u32 s48, s26, 0x40000
	v_lshl_add_u64 v[180:181], s[26:27], 0, v[138:139]
	s_addc_u32 s49, s27, 0
	s_add_i32 s50, s50, s35
	global_load_lds_dwordx4 v[180:181], off
	v_lshl_add_u64 v[182:183], s[48:49], 0, v[142:143]
	s_mov_b32 m0, s50
	v_lshl_add_u64 v[222:223], s[28:29], 0, v[140:141]
	global_load_lds_dwordx4 v[182:183], off
	v_lshl_add_u64 v[182:183], s[48:49], 0, v[138:139]
	s_add_i32 m0, s50, 0x2000
	s_nop 0
	global_load_lds_dwordx4 v[182:183], off
	v_lshl_add_u64 v[182:183], s[28:29], 0, v[144:145]
	s_mov_b32 m0, s23
	s_nop 0
	global_load_lds_dwordx4 v[182:183], off
	s_mov_b32 m0, s37
	s_nop 0
	global_load_lds_dwordx4 v[222:223], off
	s_waitcnt vmcnt(8) lgkmcnt(0)
	s_barrier
	s_setprio 1
	v_mfma_f32_16x16x32_bf16 v[62:65], v[94:97], v[190:193], v[62:65]
	v_mfma_f32_16x16x32_bf16 v[58:61], v[158:161], v[190:193], v[58:61]
	v_mfma_f32_16x16x32_bf16 v[50:53], v[94:97], v[198:201], v[50:53]
	v_mfma_f32_16x16x32_bf16 v[42:45], v[158:161], v[198:201], v[42:45]
	v_mfma_f32_16x16x32_bf16 v[34:37], v[94:97], v[206:209], v[34:37]
	v_mfma_f32_16x16x32_bf16 v[26:29], v[158:161], v[206:209], v[26:29]
	v_mfma_f32_16x16x32_bf16 v[18:21], v[94:97], v[214:217], v[18:21]
	v_mfma_f32_16x16x32_bf16 v[10:13], v[158:161], v[214:217], v[10:13]
	v_mfma_f32_16x16x32_bf16 v[62:65], v[134:137], v[194:197], v[62:65]
	v_mfma_f32_16x16x32_bf16 v[58:61], v[162:165], v[194:197], v[58:61]
	v_mfma_f32_16x16x32_bf16 v[50:53], v[134:137], v[202:205], v[50:53]
	v_mfma_f32_16x16x32_bf16 v[42:45], v[162:165], v[202:205], v[42:45]
	v_mfma_f32_16x16x32_bf16 v[34:37], v[134:137], v[210:213], v[34:37]
	v_mfma_f32_16x16x32_bf16 v[26:29], v[162:165], v[210:213], v[26:29]
	v_mfma_f32_16x16x32_bf16 v[18:21], v[134:137], v[218:221], v[18:21]
	v_mfma_f32_16x16x32_bf16 v[10:13], v[162:165], v[218:221], v[10:13]
	v_mfma_f32_16x16x32_bf16 v[54:57], v[166:169], v[190:193], v[54:57]
	v_mfma_f32_16x16x32_bf16 v[46:49], v[174:177], v[190:193], v[46:49]
	v_mfma_f32_16x16x32_bf16 v[38:41], v[166:169], v[198:201], v[38:41]
	v_mfma_f32_16x16x32_bf16 v[30:33], v[174:177], v[198:201], v[30:33]
	v_mfma_f32_16x16x32_bf16 v[22:25], v[166:169], v[206:209], v[22:25]
	v_mfma_f32_16x16x32_bf16 v[14:17], v[174:177], v[206:209], v[14:17]
	v_mfma_f32_16x16x32_bf16 v[6:9], v[166:169], v[214:217], v[6:9]
	v_mfma_f32_16x16x32_bf16 v[2:5], v[174:177], v[214:217], v[2:5]
	v_mfma_f32_16x16x32_bf16 v[54:57], v[170:173], v[194:197], v[54:57]
	v_mfma_f32_16x16x32_bf16 v[46:49], v[186:189], v[194:197], v[46:49]
	v_mfma_f32_16x16x32_bf16 v[38:41], v[170:173], v[202:205], v[38:41]
	v_mfma_f32_16x16x32_bf16 v[30:33], v[186:189], v[202:205], v[30:33]
	v_mfma_f32_16x16x32_bf16 v[22:25], v[170:173], v[210:213], v[22:25]
	v_mfma_f32_16x16x32_bf16 v[14:17], v[186:189], v[210:213], v[14:17]
	v_mfma_f32_16x16x32_bf16 v[6:9], v[170:173], v[218:221], v[6:9]
	v_mfma_f32_16x16x32_bf16 v[2:5], v[186:189], v[218:221], v[2:5]
	s_setprio 0
	s_barrier
; #define PG8_STAGE(bufoff, gbase, voff) do { _Pragma("unroll") for (int _i = 0; _i < 2; ++_i) \
;         __builtin_amdgcn_global_load_lds((const unsigned*)((const char*)(gbase) + (voff)[_i]), (PG8_LAS unsigned*)(lds + (bufoff) + ldsw + _i * 8192), 16, 0, 0); } while (0)
; #define PG8_LDA(dst, b, h) do { _Pragma("unroll") for (int m = 0; m < 4; ++m) _Pragma("unroll") for (int k = 0; k < 2; ++k) dst[m][k] = *(const PG8_LAS bf16x8*)(lds + PG8_SA(b, h) + aoff + m * 2048 + k * 1024); } while (0)
; #define PG8_LDB(dst, b, h) do { _Pragma("unroll") for (int n = 0; n < 2; ++n) _Pragma("unroll") for (int k = 0; k < 2; ++k) dst[n][k] = *(const PG8_LAS bf16x8*)(lds + PG8_SB(b, h) + boff + n * 2048 + k * 1024); } while (0)
; #define PG8_MMA(ai, bj, At, Bt) do { __builtin_amdgcn_s_setprio(1); _Pragma("unroll") for (int m = 0; m < 4; ++m) _Pragma("unroll") for (int n = 0; n < 2; ++n) _Pragma("unroll") for (int k = 0; k < 2; ++k) \
;         acc[ai][bj][m][n] = __builtin_amdgcn_mfma_f32_16x16x32_bf16(Bt[n][k], At[m][k], acc[ai][bj][m][n], 0, 0, 0); __builtin_amdgcn_s_setprio(0); } while (0)
; #define PG8_WAIT_V(n) asm volatile("s_waitcnt vmcnt(" #n ")" ::: "memory")
; #define PG8_WAIT_L(n) asm volatile("s_waitcnt lgkmcnt(" #n ")" ::: "memory")
; #define PG8_BAR __builtin_amdgcn_s_barrier()
; #define PG8_SCHED __builtin_amdgcn_sched_barrier(0)
; template <class Epi, class Sched, bool ALIGN_EPI = false, bool SP2 = false>
; __device__ __forceinline__ void gemm_phase(PG8_LAS unsigned char* lds, const Gemm g, const Sched& S, const Epi& E) {
;     ...
;             PG8_LDB(B0, 1, 0); PG8_LDB(B1, 1, 1); PG8_SCHED; PG8_LDA(At, 1, 0); PG8_STAGE(PG8_SA(0, 1), a2 + hstep, voffA);
;             PG8_WAIT_V(8); PG8_WAIT_L(0); PG8_BAR; PG8_MMA(0, 0, At, B0); PG8_MMA(0, 1, At, B1); PG8_BAR; PG8_SCHED;
	s_add_i32 s48, 0, 0x18000
	s_add_i32 s49, 0, 0x1c000
	v_add_u32_e32 v162, s48, v156
	v_add_u32_e32 v179, s49, v156
	ds_read_b128 v[94:97], v162
	ds_read_b128 v[134:137], v162 offset:1024
	ds_read_b128 v[158:161], v162 offset:2048
	ds_read_b128 v[162:165], v162 offset:3072
	ds_read_b128 v[166:169], v179
	ds_read_b128 v[170:173], v179 offset:1024
	ds_read_b128 v[174:177], v179 offset:2048
	ds_read_b128 v[186:189], v179 offset:3072
	s_add_u32 s28, s28, 0x40000
	s_addc_u32 s29, s29, 0
	s_mov_b32 m0, s38
	v_lshl_add_u64 v[240:241], s[28:29], 0, v[144:145]
	ds_read_b128 v[190:193], v157 offset:32768
	ds_read_b128 v[194:197], v157 offset:33792
	ds_read_b128 v[198:201], v157 offset:34816
	ds_read_b128 v[202:205], v157 offset:35840
	ds_read_b128 v[206:209], v157 offset:36864
	ds_read_b128 v[210:213], v157 offset:37888
	ds_read_b128 v[214:217], v157 offset:38912
	ds_read_b128 v[218:221], v157 offset:39936
	global_load_lds_dwordx4 v[240:241], off
	v_lshl_add_u64 v[240:241], s[28:29], 0, v[140:141]
	s_mov_b32 m0, s39
	s_nop 0
	global_load_lds_dwordx4 v[240:241], off
	s_waitcnt vmcnt(8) lgkmcnt(0)
	s_barrier
	s_setprio 1
	v_mfma_f32_16x16x32_bf16 v[130:133], v[94:97], v[190:193], v[130:133]
	v_mfma_f32_16x16x32_bf16 v[126:129], v[158:161], v[190:193], v[126:129]
	v_mfma_f32_16x16x32_bf16 v[114:117], v[94:97], v[198:201], v[114:117]
	v_mfma_f32_16x16x32_bf16 v[110:113], v[158:161], v[198:201], v[110:113]
	v_mfma_f32_16x16x32_bf16 v[98:101], v[94:97], v[206:209], v[98:101]
	v_mfma_f32_16x16x32_bf16 v[90:93], v[158:161], v[206:209], v[90:93]
	v_mfma_f32_16x16x32_bf16 v[78:81], v[94:97], v[214:217], v[78:81]
	v_mfma_f32_16x16x32_bf16 v[74:77], v[158:161], v[214:217], v[74:77]
	v_mfma_f32_16x16x32_bf16 v[130:133], v[134:137], v[194:197], v[130:133]
	v_mfma_f32_16x16x32_bf16 v[126:129], v[162:165], v[194:197], v[126:129]
	v_mfma_f32_16x16x32_bf16 v[114:117], v[134:137], v[202:205], v[114:117]
	v_mfma_f32_16x16x32_bf16 v[110:113], v[162:165], v[202:205], v[110:113]
	v_mfma_f32_16x16x32_bf16 v[98:101], v[134:137], v[210:213], v[98:101]
	v_mfma_f32_16x16x32_bf16 v[90:93], v[162:165], v[210:213], v[90:93]
	v_mfma_f32_16x16x32_bf16 v[78:81], v[134:137], v[218:221], v[78:81]
	v_mfma_f32_16x16x32_bf16 v[74:77], v[162:165], v[218:221], v[74:77]
	v_mfma_f32_16x16x32_bf16 v[122:125], v[166:169], v[190:193], v[122:125]
	v_mfma_f32_16x16x32_bf16 v[118:121], v[174:177], v[190:193], v[118:121]
	v_mfma_f32_16x16x32_bf16 v[106:109], v[166:169], v[198:201], v[106:109]
	v_mfma_f32_16x16x32_bf16 v[102:105], v[174:177], v[198:201], v[102:105]
	v_mfma_f32_16x16x32_bf16 v[86:89], v[166:169], v[206:209], v[86:89]
	v_mfma_f32_16x16x32_bf16 v[82:85], v[174:177], v[206:209], v[82:85]
	v_mfma_f32_16x16x32_bf16 v[70:73], v[166:169], v[214:217], v[70:73]
	v_mfma_f32_16x16x32_bf16 v[66:69], v[174:177], v[214:217], v[66:69]
	v_mfma_f32_16x16x32_bf16 v[122:125], v[170:173], v[194:197], v[122:125]
	v_mfma_f32_16x16x32_bf16 v[118:121], v[186:189], v[194:197], v[118:121]
	v_mfma_f32_16x16x32_bf16 v[106:109], v[170:173], v[202:205], v[106:109]
	v_mfma_f32_16x16x32_bf16 v[102:105], v[186:189], v[202:205], v[102:105]
	v_mfma_f32_16x16x32_bf16 v[86:89], v[170:173], v[210:213], v[86:89]
	v_mfma_f32_16x16x32_bf16 v[82:85], v[186:189], v[210:213], v[82:85]
	v_mfma_f32_16x16x32_bf16 v[70:73], v[170:173], v[218:221], v[70:73]
	v_mfma_f32_16x16x32_bf16 v[66:69], v[186:189], v[218:221], v[66:69]
	s_setprio 0
	s_barrier
; #define PG8_STAGE(bufoff, gbase, voff) do { _Pragma("unroll") for (int _i = 0; _i < 2; ++_i) \
;         __builtin_amdgcn_global_load_lds((const unsigned*)((const char*)(gbase) + (voff)[_i]), (PG8_LAS unsigned*)(lds + (bufoff) + ldsw + _i * 8192), 16, 0, 0); } while (0)
; #define PG8_LDA(dst, b, h) do { _Pragma("unroll") for (int m = 0; m < 4; ++m) _Pragma("unroll") for (int k = 0; k < 2; ++k) dst[m][k] = *(const PG8_LAS bf16x8*)(lds + PG8_SA(b, h) + aoff + m * 2048 + k * 1024); } while (0)
; #define PG8_WAIT_V(n) asm volatile("s_waitcnt vmcnt(" #n ")" ::: "memory")
; #define PG8_WAIT_L(n) asm volatile("s_waitcnt lgkmcnt(" #n ")" ::: "memory")
; template <class Epi, class Sched, bool ALIGN_EPI = false, bool SP2 = false>
; __device__ __forceinline__ void gemm_phase(PG8_LAS unsigned char* lds, const Gemm g, const Sched& S, const Epi& E) {
;     ...
;         for (int t = 0; t < nt; t += 2) {
;             const bool last = (t == nt - 2);
;             const char* a1 = cA + (size_t)(t + 1) * kstep;
;             const char* a2 = last ? nA : cA + (size_t)(t + 2) * kstep; const char* b2 = last ? nB : cB + (size_t)(t + 2) * kstep;
;             const char* a3 = a2 + kstep; const char* b3 = b2 + kstep;
;             if (last && has_next) S.a_ready(nxt);
;             if constexpr (SP2) {
;             PG8_LDB(B0, 0, 0); PG8_LDB(B1, 0, 1); PG8_SCHED; PG8_LDA(At, 0, 0); PG8_STAGE(PG8_SA(1, 1), a1 + hstep, voffA);
;             PG8_WAIT_V(8); PG8_WAIT_L(0); PG8_BAR; PG8_MMA(0, 0, At, B0); PG8_MMA(0, 1, At, B1); PG8_BAR; PG8_SCHED;
;             PG8_LDA(At, 0, 1); PG8_STAGE(PG8_SB(0, 0), b2, voffB); PG8_STAGE(PG8_SB(0, 1), b2 + hstep, voffB); PG8_STAGE(PG8_SA(0, 0), a2, voffA);
;             PG8_WAIT_V(8); PG8_WAIT_L(0); PG8_BAR; PG8_MMA(1, 0, At, B0); PG8_MMA(1, 1, At, B1); PG8_BAR; PG8_SCHED;
;             PG8_LDB(B0, 1, 0); PG8_LDB(B1, 1, 1); PG8_SCHED; PG8_LDA(At, 1, 0); PG8_STAGE(PG8_SA(0, 1), a2 + hstep, voffA);
;             PG8_WAIT_V(8); PG8_WAIT_L(0); PG8_BAR; PG8_MMA(0, 0, At, B0); PG8_MMA(0, 1, At, B1); PG8_BAR; PG8_SCHED;
;             PG8_LDA(At, 1, 1); PG8_STAGE(PG8_SB(1, 0), b3, voffB); PG8_STAGE(PG8_SB(1, 1), b3 + hstep, voffB); PG8_STAGE(PG8_SA(1, 0), a3, voffA);
;             PG8_WAIT_V(8); PG8_WAIT_L(0); PG8_BAR; PG8_MMA(1, 0, At, B0); PG8_MMA(1, 1, At, B1); PG8_BAR; PG8_SCHED;
;     ...
;         if constexpr (ALIGN_EPI) { if (wr == 0) PG8_BAR; }
	s_add_i32 s28, s48, s35
	v_lshl_add_u64 v[154:155], v[154:155], 0, s[80:81]
	s_mov_b32 m0, s28
	ds_read_b128 v[190:193], v157 offset:49152
	ds_read_b128 v[194:197], v157 offset:50176
	ds_read_b128 v[198:201], v157 offset:51200
	ds_read_b128 v[202:205], v157 offset:52224
	ds_read_b128 v[206:209], v157 offset:53248
	ds_read_b128 v[210:213], v157 offset:54272
	ds_read_b128 v[214:217], v157 offset:55296
	ds_read_b128 v[218:221], v157 offset:56320
	global_load_lds_dwordx4 v[154:155], off
	s_add_i32 m0, s28, 0x2000
	s_add_u32 s26, s26, 0x40080
	v_lshl_add_u64 v[154:155], v[180:181], 0, s[80:81]
	s_addc_u32 s27, s27, 0
	s_add_i32 s28, s49, s35
	global_load_lds_dwordx4 v[154:155], off
	v_lshl_add_u64 v[154:155], s[26:27], 0, v[142:143]
	s_mov_b32 m0, s28
	s_nop 0
	global_load_lds_dwordx4 v[154:155], off
	v_lshl_add_u64 v[154:155], s[26:27], 0, v[138:139]
	s_add_i32 m0, s28, 0x2000
	s_nop 0
	global_load_lds_dwordx4 v[154:155], off
	v_lshl_add_u64 v[154:155], v[182:183], 0, s[80:81]
	s_mov_b32 m0, s40
	s_nop 0
	global_load_lds_dwordx4 v[154:155], off
	v_lshl_add_u64 v[154:155], v[222:223], 0, s[80:81]
	s_mov_b32 m0, s41
	s_nop 0
	global_load_lds_dwordx4 v[154:155], off
	s_waitcnt vmcnt(8) lgkmcnt(0)
	s_barrier
	s_setprio 1
	v_mfma_f32_16x16x32_bf16 v[62:65], v[94:97], v[190:193], v[62:65]
	v_mfma_f32_16x16x32_bf16 v[58:61], v[158:161], v[190:193], v[58:61]
	v_mfma_f32_16x16x32_bf16 v[50:53], v[94:97], v[198:201], v[50:53]
	v_mfma_f32_16x16x32_bf16 v[42:45], v[158:161], v[198:201], v[42:45]
	v_mfma_f32_16x16x32_bf16 v[34:37], v[94:97], v[206:209], v[34:37]
	v_mfma_f32_16x16x32_bf16 v[26:29], v[158:161], v[206:209], v[26:29]
	v_mfma_f32_16x16x32_bf16 v[18:21], v[94:97], v[214:217], v[18:21]
	v_mfma_f32_16x16x32_bf16 v[10:13], v[158:161], v[214:217], v[10:13]
	v_mfma_f32_16x16x32_bf16 v[62:65], v[134:137], v[194:197], v[62:65]
	v_mfma_f32_16x16x32_bf16 v[58:61], v[162:165], v[194:197], v[58:61]
	v_mfma_f32_16x16x32_bf16 v[50:53], v[134:137], v[202:205], v[50:53]
	v_mfma_f32_16x16x32_bf16 v[42:45], v[162:165], v[202:205], v[42:45]
	v_mfma_f32_16x16x32_bf16 v[34:37], v[134:137], v[210:213], v[34:37]
	v_mfma_f32_16x16x32_bf16 v[26:29], v[162:165], v[210:213], v[26:29]
	v_mfma_f32_16x16x32_bf16 v[18:21], v[134:137], v[218:221], v[18:21]
	v_mfma_f32_16x16x32_bf16 v[10:13], v[162:165], v[218:221], v[10:13]
	v_mfma_f32_16x16x32_bf16 v[54:57], v[166:169], v[190:193], v[54:57]
	v_mfma_f32_16x16x32_bf16 v[46:49], v[174:177], v[190:193], v[46:49]
	v_mfma_f32_16x16x32_bf16 v[38:41], v[166:169], v[198:201], v[38:41]
	v_mfma_f32_16x16x32_bf16 v[30:33], v[174:177], v[198:201], v[30:33]
	v_mfma_f32_16x16x32_bf16 v[22:25], v[166:169], v[206:209], v[22:25]
	v_mfma_f32_16x16x32_bf16 v[14:17], v[174:177], v[206:209], v[14:17]
	v_mfma_f32_16x16x32_bf16 v[6:9], v[166:169], v[214:217], v[6:9]
	v_mfma_f32_16x16x32_bf16 v[2:5], v[174:177], v[214:217], v[2:5]
	v_mfma_f32_16x16x32_bf16 v[54:57], v[170:173], v[194:197], v[54:57]
	v_mfma_f32_16x16x32_bf16 v[46:49], v[186:189], v[194:197], v[46:49]
	v_mfma_f32_16x16x32_bf16 v[38:41], v[170:173], v[202:205], v[38:41]
	v_mfma_f32_16x16x32_bf16 v[30:33], v[186:189], v[202:205], v[30:33]
	v_mfma_f32_16x16x32_bf16 v[22:25], v[170:173], v[210:213], v[22:25]
	v_mfma_f32_16x16x32_bf16 v[14:17], v[186:189], v[210:213], v[14:17]
	v_mfma_f32_16x16x32_bf16 v[6:9], v[170:173], v[218:221], v[6:9]
	v_mfma_f32_16x16x32_bf16 v[2:5], v[186:189], v[218:221], v[2:5]
	s_setprio 0
	s_barrier
	s_add_i32 s47, s47, 2
	s_add_u32 s24, s24, 0x100
	s_addc_u32 s25, s25, 0
	s_add_u32 s45, s45, 0x100
	s_addc_u32 s46, s46, 0
	s_cmp_gt_u32 s47, 13
	s_cbranch_scc0 .LBB0_301
	s_and_b64 vcc, exec, s[8:9]
	s_cbranch_vccz .LBB0_304
	s_barrier

; #define PG8_STAGE(bufoff, gbase, voff) do { _Pragma("unroll") for (int _i = 0; _i < 2; ++_i) \
;         __builtin_amdgcn_global_load_lds((const unsigned*)((const char*)(gbase) + (voff)[_i]), (PG8_LAS unsigned*)(lds + (bufoff) + ldsw + _i * 8192), 16, 0, 0); } while (0)
; #define PG8_LDA(dst, b, h) do { _Pragma("unroll") for (int m = 0; m < 4; ++m) _Pragma("unroll") for (int k = 0; k < 2; ++k) dst[m][k] = *(const PG8_LAS bf16x8*)(lds + PG8_SA(b, h) + aoff + m * 2048 + k * 1024); } while (0)
; template <class Epi, class Sched, bool ALIGN_EPI = false, bool SP2 = false>
; __device__ __forceinline__ void gemm_phase(PG8_LAS unsigned char* lds, const Gemm g, const Sched& S, const Epi& E) {
;     ...
;         const bool has_next = S.next(ui + 1, nxt);
;         const char* nA = has_next ? (const char*)g.A + (size_t)nxt.pm * tstep : cA; const char* nB = has_next ? (const char*)g.Bt + (size_t)nxt.pn * tstep : cB;
;         for (int t = 0; t < nt; t += 2) {
;             const bool last = (t == nt - 2);
;             const char* a1 = cA + (size_t)(t + 1) * kstep;
;             const char* a2 = last ? nA : cA + (size_t)(t + 2) * kstep; const char* b2 = last ? nB : cB + (size_t)(t + 2) * kstep;
;             const char* a3 = a2 + kstep; const char* b3 = b2 + kstep;
;             if (last && has_next) S.a_ready(nxt);
;             if constexpr (SP2) {
;             PG8_LDB(B0, 0, 0); PG8_LDB(B1, 0, 1); PG8_SCHED; PG8_LDA(At, 0, 0); PG8_STAGE(PG8_SA(1, 1), a1 + hstep, voffA);
;             PG8_WAIT_V(8); PG8_WAIT_L(0); PG8_BAR; PG8_MMA(0, 0, At, B0); PG8_MMA(0, 1, At, B1); PG8_BAR; PG8_SCHED;
;             PG8_LDA(At, 0, 1); PG8_STAGE(PG8_SB(0, 0), b2, voffB); PG8_STAGE(PG8_SB(0, 1), b2 + hstep, voffB); PG8_STAGE(PG8_SA(0, 0), a2, voffA);
;             PG8_WAIT_V(8); PG8_WAIT_L(0); PG8_BAR; PG8_MMA(1, 0, At, B0); PG8_MMA(1, 1, At, B1); PG8_BAR; PG8_SCHED;
;             PG8_LDB(B0, 1, 0); PG8_LDB(B1, 1, 1); PG8_SCHED; PG8_LDA(At, 1, 0); PG8_STAGE(PG8_SA(0, 1), a2 + hstep, voffA);
;             PG8_WAIT_V(8); PG8_WAIT_L(0); PG8_BAR; PG8_MMA(0, 0, At, B0); PG8_MMA(0, 1, At, B1); PG8_BAR; PG8_SCHED;
;             PG8_LDA(At, 1, 1); PG8_STAGE(PG8_SB(1, 0), b3, voffB); PG8_STAGE(PG8_SB(1, 1), b3 + hstep, voffB); PG8_STAGE(PG8_SA(1, 0), a3, voffA);
;             PG8_WAIT_V(8); PG8_WAIT_L(0); PG8_BAR; PG8_MMA(1, 0, At, B0); PG8_MMA(1, 1, At, B1); PG8_BAR; PG8_SCHED;
.LBB0_317:
	s_ashr_i32 s13, s12, 31
	s_lshl_b64 s[16:17], s[12:13], 19
	s_add_u32 s16, s8, s16
	s_addc_u32 s17, s9, s17
	s_and_b64 s[18:19], s[4:5], exec
	s_cselect_b32 s13, s17, s25
	s_cselect_b32 s21, s16, s24
	s_ashr_i32 s11, s10, 31
	s_lshl_b64 s[18:19], s[10:11], 19
	s_add_u32 s18, s33, s18
	s_addc_u32 s19, s34, s19
	s_and_b64 s[28:29], s[4:5], exec
	s_cselect_b32 s11, s19, s27
	s_cselect_b32 s44, s18, s26
	s_add_u32 s24, s24, 0x40080
	s_addc_u32 s25, s25, 0
	s_add_u32 s45, s26, 0x100
	s_addc_u32 s46, s27, 0
	s_mov_b32 s47, -2
	s_add_u32 s26, s24, 0xfffc0080
	s_addc_u32 s27, s25, -1
	s_add_i32 s48, 0, 0x10000
	s_cmp_eq_u32 s47, 12
	s_cselect_b32 s29, s13, s27
	s_cselect_b32 s28, s21, s26
	v_add_u32_e32 v154, s48, v156
	s_cselect_b32 s27, s11, s46
	s_cselect_b32 s26, s44, s45
	s_add_i32 s50, 0, 0x14000
	ds_read_b128 v[94:97], v154
	ds_read_b128 v[134:137], v154 offset:1024
	ds_read_b128 v[158:161], v154 offset:2048
	ds_read_b128 v[162:165], v154 offset:3072
	v_add_u32_e32 v154, s50, v156
	ds_read_b128 v[166:169], v154
	ds_read_b128 v[170:173], v154 offset:1024
	ds_read_b128 v[174:177], v154 offset:2048
	ds_read_b128 v[186:189], v154 offset:3072
	v_lshl_add_u64 v[154:155], s[24:25], 0, v[150:151]
	s_add_i32 m0, s23, 0xc000
	ds_read_b128 v[190:193], v157
	ds_read_b128 v[194:197], v157 offset:1024
	ds_read_b128 v[198:201], v157 offset:2048
	ds_read_b128 v[202:205], v157 offset:3072
	ds_read_b128 v[206:209], v157 offset:4096
	ds_read_b128 v[210:213], v157 offset:5120
	ds_read_b128 v[214:217], v157 offset:6144
	ds_read_b128 v[218:221], v157 offset:7168
	global_load_lds_dwordx4 v[154:155], off
	v_lshl_add_u64 v[154:155], s[24:25], 0, v[152:153]
	s_add_i32 m0, s23, 0xe000
	s_nop 0
	global_load_lds_dwordx4 v[154:155], off
	s_waitcnt vmcnt(8) lgkmcnt(0)
	s_barrier
	s_setprio 1
	v_mfma_f32_16x16x32_bf16 v[130:133], v[94:97], v[190:193], 0
	v_mfma_f32_16x16x32_bf16 v[126:129], v[158:161], v[190:193], 0
	v_mfma_f32_16x16x32_bf16 v[114:117], v[94:97], v[198:201], 0
	v_mfma_f32_16x16x32_bf16 v[110:113], v[158:161], v[198:201], 0
	v_mfma_f32_16x16x32_bf16 v[98:101], v[94:97], v[206:209], 0
	v_mfma_f32_16x16x32_bf16 v[90:93], v[158:161], v[206:209], 0
	v_mfma_f32_16x16x32_bf16 v[78:81], v[94:97], v[214:217], 0
	v_mfma_f32_16x16x32_bf16 v[74:77], v[158:161], v[214:217], 0
	v_mfma_f32_16x16x32_bf16 v[130:133], v[134:137], v[194:197], v[130:133]
	v_mfma_f32_16x16x32_bf16 v[126:129], v[162:165], v[194:197], v[126:129]
	v_mfma_f32_16x16x32_bf16 v[114:117], v[134:137], v[202:205], v[114:117]
	v_mfma_f32_16x16x32_bf16 v[110:113], v[162:165], v[202:205], v[110:113]
	v_mfma_f32_16x16x32_bf16 v[98:101], v[134:137], v[210:213], v[98:101]
	v_mfma_f32_16x16x32_bf16 v[90:93], v[162:165], v[210:213], v[90:93]
	v_mfma_f32_16x16x32_bf16 v[78:81], v[134:137], v[218:221], v[78:81]
	v_mfma_f32_16x16x32_bf16 v[74:77], v[162:165], v[218:221], v[74:77]
	v_mfma_f32_16x16x32_bf16 v[122:125], v[166:169], v[190:193], 0
	v_mfma_f32_16x16x32_bf16 v[118:121], v[174:177], v[190:193], 0
	v_mfma_f32_16x16x32_bf16 v[106:109], v[166:169], v[198:201], 0
	v_mfma_f32_16x16x32_bf16 v[102:105], v[174:177], v[198:201], 0
	v_mfma_f32_16x16x32_bf16 v[86:89], v[166:169], v[206:209], 0
	v_mfma_f32_16x16x32_bf16 v[82:85], v[174:177], v[206:209], 0
	v_mfma_f32_16x16x32_bf16 v[70:73], v[166:169], v[214:217], 0
	v_mfma_f32_16x16x32_bf16 v[66:69], v[174:177], v[214:217], 0
	v_mfma_f32_16x16x32_bf16 v[122:125], v[170:173], v[194:197], v[122:125]
	v_mfma_f32_16x16x32_bf16 v[118:121], v[186:189], v[194:197], v[118:121]
	v_mfma_f32_16x16x32_bf16 v[106:109], v[170:173], v[202:205], v[106:109]
	v_mfma_f32_16x16x32_bf16 v[102:105], v[186:189], v[202:205], v[102:105]
	v_mfma_f32_16x16x32_bf16 v[86:89], v[170:173], v[210:213], v[86:89]
	v_mfma_f32_16x16x32_bf16 v[82:85], v[186:189], v[210:213], v[82:85]
	v_mfma_f32_16x16x32_bf16 v[70:73], v[170:173], v[218:221], v[70:73]
	v_mfma_f32_16x16x32_bf16 v[66:69], v[186:189], v[218:221], v[66:69]
	s_setprio 0
	s_barrier
	s_add_i32 s48, s48, s35
	v_lshl_add_u64 v[154:155], s[26:27], 0, v[142:143]
	s_mov_b32 m0, s48
	ds_read_b128 v[190:193], v157 offset:16384
	ds_read_b128 v[194:197], v157 offset:17408
	ds_read_b128 v[198:201], v157 offset:18432
	ds_read_b128 v[202:205], v157 offset:19456
	ds_read_b128 v[206:209], v157 offset:20480
	ds_read_b128 v[210:213], v157 offset:21504
	ds_read_b128 v[214:217], v157 offset:22528
	ds_read_b128 v[218:221], v157 offset:23552
	global_load_lds_dwordx4 v[154:155], off
	s_add_i32 m0, s48, 0x2000
	s_add_u32 s48, s26, 0x40000
	v_lshl_add_u64 v[180:181], s[26:27], 0, v[138:139]
	s_addc_u32 s49, s27, 0
	s_add_i32 s50, s50, s35
	global_load_lds_dwordx4 v[180:181], off
	v_lshl_add_u64 v[182:183], s[48:49], 0, v[142:143]
	s_mov_b32 m0, s50
	v_lshl_add_u64 v[222:223], s[28:29], 0, v[140:141]
	global_load_lds_dwordx4 v[182:183], off
	v_lshl_add_u64 v[182:183], s[48:49], 0, v[138:139]
	s_add_i32 m0, s50, 0x2000
	s_nop 0
	global_load_lds_dwordx4 v[182:183], off
	v_lshl_add_u64 v[182:183], s[28:29], 0, v[144:145]
	s_mov_b32 m0, s23
	s_nop 0
	global_load_lds_dwordx4 v[182:183], off
	s_mov_b32 m0, s37
	s_nop 0
	global_load_lds_dwordx4 v[222:223], off
	s_waitcnt vmcnt(8) lgkmcnt(0)
	s_barrier
; #define PG8_STAGE(bufoff, gbase, voff) do { _Pragma("unroll") for (int _i = 0; _i < 2; ++_i) \
;         __builtin_amdgcn_global_load_lds((const unsigned*)((const char*)(gbase) + (voff)[_i]), (PG8_LAS unsigned*)(lds + (bufoff) + ldsw + _i * 8192), 16, 0, 0); } while (0)
; #define PG8_LDA(dst, b, h) do { _Pragma("unroll") for (int m = 0; m < 4; ++m) _Pragma("unroll") for (int k = 0; k < 2; ++k) dst[m][k] = *(const PG8_LAS bf16x8*)(lds + PG8_SA(b, h) + aoff + m * 2048 + k * 1024); } while (0)
; #define PG8_LDB(dst, b, h) do { _Pragma("unroll") for (int n = 0; n < 2; ++n) _Pragma("unroll") for (int k = 0; k < 2; ++k) dst[n][k] = *(const PG8_LAS bf16x8*)(lds + PG8_SB(b, h) + boff + n * 2048 + k * 1024); } while (0)
; #define PG8_MMA(ai, bj, At, Bt) do { __builtin_amdgcn_s_setprio(1); _Pragma("unroll") for (int m = 0; m < 4; ++m) _Pragma("unroll") for (int n = 0; n < 2; ++n) _Pragma("unroll") for (int k = 0; k < 2; ++k) \
;         acc[ai][bj][m][n] = __builtin_amdgcn_mfma_f32_16x16x32_bf16(Bt[n][k], At[m][k], acc[ai][bj][m][n], 0, 0, 0); __builtin_amdgcn_s_setprio(0); } while (0)
; #define PG8_WAIT_V(n) asm volatile("s_waitcnt vmcnt(" #n ")" ::: "memory")
; #define PG8_WAIT_L(n) asm volatile("s_waitcnt lgkmcnt(" #n ")" ::: "memory")
; #define PG8_BAR __builtin_amdgcn_s_barrier()
; #define PG8_SCHED __builtin_amdgcn_sched_barrier(0)
; template <class Epi, class Sched, bool ALIGN_EPI = false, bool SP2 = false>
; __device__ __forceinline__ void gemm_phase(PG8_LAS unsigned char* lds, const Gemm g, const Sched& S, const Epi& E) {
;     ...
;             PG8_LDB(B0, 0, 0); PG8_LDB(B1, 0, 1); PG8_SCHED; PG8_LDA(At, 0, 0); PG8_STAGE(PG8_SA(1, 1), a1 + hstep, voffA);
;             PG8_WAIT_V(8); PG8_WAIT_L(0); PG8_BAR; PG8_MMA(0, 0, At, B0); PG8_MMA(0, 1, At, B1); PG8_BAR; PG8_SCHED;
;             PG8_LDA(At, 0, 1); PG8_STAGE(PG8_SB(0, 0), b2, voffB); PG8_STAGE(PG8_SB(0, 1), b2 + hstep, voffB); PG8_STAGE(PG8_SA(0, 0), a2, voffA);
;             PG8_WAIT_V(8); PG8_WAIT_L(0); PG8_BAR; PG8_MMA(1, 0, At, B0); PG8_MMA(1, 1, At, B1); PG8_BAR; PG8_SCHED;
;             PG8_LDB(B0, 1, 0); PG8_LDB(B1, 1, 1); PG8_SCHED; PG8_LDA(At, 1, 0); PG8_STAGE(PG8_SA(0, 1), a2 + hstep, voffA);
;             PG8_WAIT_V(8); PG8_WAIT_L(0); PG8_BAR; PG8_MMA(0, 0, At, B0); PG8_MMA(0, 1, At, B1); PG8_BAR; PG8_SCHED;
	s_setprio 1
	v_mfma_f32_16x16x32_bf16 v[62:65], v[94:97], v[190:193], 0
	v_mfma_f32_16x16x32_bf16 v[58:61], v[158:161], v[190:193], 0
	v_mfma_f32_16x16x32_bf16 v[50:53], v[94:97], v[198:201], 0
	v_mfma_f32_16x16x32_bf16 v[42:45], v[158:161], v[198:201], 0
	v_mfma_f32_16x16x32_bf16 v[34:37], v[94:97], v[206:209], 0
	v_mfma_f32_16x16x32_bf16 v[26:29], v[158:161], v[206:209], 0
	v_mfma_f32_16x16x32_bf16 v[18:21], v[94:97], v[214:217], 0
	v_mfma_f32_16x16x32_bf16 v[10:13], v[158:161], v[214:217], 0
	v_mfma_f32_16x16x32_bf16 v[62:65], v[134:137], v[194:197], v[62:65]
	v_mfma_f32_16x16x32_bf16 v[58:61], v[162:165], v[194:197], v[58:61]
	v_mfma_f32_16x16x32_bf16 v[50:53], v[134:137], v[202:205], v[50:53]
	v_mfma_f32_16x16x32_bf16 v[42:45], v[162:165], v[202:205], v[42:45]
	v_mfma_f32_16x16x32_bf16 v[34:37], v[134:137], v[210:213], v[34:37]
	v_mfma_f32_16x16x32_bf16 v[26:29], v[162:165], v[210:213], v[26:29]
	v_mfma_f32_16x16x32_bf16 v[18:21], v[134:137], v[218:221], v[18:21]
	v_mfma_f32_16x16x32_bf16 v[10:13], v[162:165], v[218:221], v[10:13]
	v_mfma_f32_16x16x32_bf16 v[54:57], v[166:169], v[190:193], 0
	v_mfma_f32_16x16x32_bf16 v[46:49], v[174:177], v[190:193], 0
	v_mfma_f32_16x16x32_bf16 v[38:41], v[166:169], v[198:201], 0
	v_mfma_f32_16x16x32_bf16 v[30:33], v[174:177], v[198:201], 0
	v_mfma_f32_16x16x32_bf16 v[22:25], v[166:169], v[206:209], 0
	v_mfma_f32_16x16x32_bf16 v[14:17], v[174:177], v[206:209], 0
	v_mfma_f32_16x16x32_bf16 v[6:9], v[166:169], v[214:217], 0
	v_mfma_f32_16x16x32_bf16 v[2:5], v[174:177], v[214:217], 0
	v_mfma_f32_16x16x32_bf16 v[54:57], v[170:173], v[194:197], v[54:57]
	v_mfma_f32_16x16x32_bf16 v[46:49], v[186:189], v[194:197], v[46:49]
	v_mfma_f32_16x16x32_bf16 v[38:41], v[170:173], v[202:205], v[38:41]
	v_mfma_f32_16x16x32_bf16 v[30:33], v[186:189], v[202:205], v[30:33]
	v_mfma_f32_16x16x32_bf16 v[22:25], v[170:173], v[210:213], v[22:25]
	v_mfma_f32_16x16x32_bf16 v[14:17], v[186:189], v[210:213], v[14:17]
	v_mfma_f32_16x16x32_bf16 v[6:9], v[170:173], v[218:221], v[6:9]
	v_mfma_f32_16x16x32_bf16 v[2:5], v[186:189], v[218:221], v[2:5]
	s_setprio 0
	s_barrier
	s_add_i32 s48, 0, 0x18000
	s_add_i32 s49, 0, 0x1c000
	v_add_u32_e32 v162, s48, v156
	v_add_u32_e32 v179, s49, v156
	ds_read_b128 v[94:97], v162
	ds_read_b128 v[134:137], v162 offset:1024
	ds_read_b128 v[158:161], v162 offset:2048
	ds_read_b128 v[162:165], v162 offset:3072
	ds_read_b128 v[166:169], v179
	ds_read_b128 v[170:173], v179 offset:1024
	ds_read_b128 v[174:177], v179 offset:2048
	ds_read_b128 v[186:189], v179 offset:3072
	s_add_u32 s28, s28, 0x40000
	s_addc_u32 s29, s29, 0
	s_mov_b32 m0, s38
	v_lshl_add_u64 v[240:241], s[28:29], 0, v[144:145]
	ds_read_b128 v[190:193], v157 offset:32768
	ds_read_b128 v[194:197], v157 offset:33792
	ds_read_b128 v[198:201], v157 offset:34816
	ds_read_b128 v[202:205], v157 offset:35840
	ds_read_b128 v[206:209], v157 offset:36864
	ds_read_b128 v[210:213], v157 offset:37888
	ds_read_b128 v[214:217], v157 offset:38912
	ds_read_b128 v[218:221], v157 offset:39936
	global_load_lds_dwordx4 v[240:241], off
	v_lshl_add_u64 v[240:241], s[28:29], 0, v[140:141]
	s_mov_b32 m0, s39
	s_nop 0
	global_load_lds_dwordx4 v[240:241], off
	s_waitcnt vmcnt(8) lgkmcnt(0)
	s_barrier
	s_setprio 1
	v_mfma_f32_16x16x32_bf16 v[130:133], v[94:97], v[190:193], v[130:133]
	v_mfma_f32_16x16x32_bf16 v[126:129], v[158:161], v[190:193], v[126:129]
	v_mfma_f32_16x16x32_bf16 v[114:117], v[94:97], v[198:201], v[114:117]
	v_mfma_f32_16x16x32_bf16 v[110:113], v[158:161], v[198:201], v[110:113]
	v_mfma_f32_16x16x32_bf16 v[98:101], v[94:97], v[206:209], v[98:101]
	v_mfma_f32_16x16x32_bf16 v[90:93], v[158:161], v[206:209], v[90:93]
	v_mfma_f32_16x16x32_bf16 v[78:81], v[94:97], v[214:217], v[78:81]
	v_mfma_f32_16x16x32_bf16 v[74:77], v[158:161], v[214:217], v[74:77]
	v_mfma_f32_16x16x32_bf16 v[130:133], v[134:137], v[194:197], v[130:133]
	v_mfma_f32_16x16x32_bf16 v[126:129], v[162:165], v[194:197], v[126:129]
	v_mfma_f32_16x16x32_bf16 v[114:117], v[134:137], v[202:205], v[114:117]
	v_mfma_f32_16x16x32_bf16 v[110:113], v[162:165], v[202:205], v[110:113]
	v_mfma_f32_16x16x32_bf16 v[98:101], v[134:137], v[210:213], v[98:101]
	v_mfma_f32_16x16x32_bf16 v[90:93], v[162:165], v[210:213], v[90:93]
	v_mfma_f32_16x16x32_bf16 v[78:81], v[134:137], v[218:221], v[78:81]
	v_mfma_f32_16x16x32_bf16 v[74:77], v[162:165], v[218:221], v[74:77]
	v_mfma_f32_16x16x32_bf16 v[122:125], v[166:169], v[190:193], v[122:125]
	v_mfma_f32_16x16x32_bf16 v[118:121], v[174:177], v[190:193], v[118:121]
	v_mfma_f32_16x16x32_bf16 v[106:109], v[166:169], v[198:201], v[106:109]
	v_mfma_f32_16x16x32_bf16 v[102:105], v[174:177], v[198:201], v[102:105]
	v_mfma_f32_16x16x32_bf16 v[86:89], v[166:169], v[206:209], v[86:89]
	v_mfma_f32_16x16x32_bf16 v[82:85], v[174:177], v[206:209], v[82:85]
	v_mfma_f32_16x16x32_bf16 v[70:73], v[166:169], v[214:217], v[70:73]
	v_mfma_f32_16x16x32_bf16 v[66:69], v[174:177], v[214:217], v[66:69]
	v_mfma_f32_16x16x32_bf16 v[122:125], v[170:173], v[194:197], v[122:125]
	v_mfma_f32_16x16x32_bf16 v[118:121], v[186:189], v[194:197], v[118:121]
	v_mfma_f32_16x16x32_bf16 v[106:109], v[170:173], v[202:205], v[106:109]
	v_mfma_f32_16x16x32_bf16 v[102:105], v[186:189], v[202:205], v[102:105]
	v_mfma_f32_16x16x32_bf16 v[86:89], v[170:173], v[210:213], v[86:89]
	v_mfma_f32_16x16x32_bf16 v[82:85], v[186:189], v[210:213], v[82:85]
	v_mfma_f32_16x16x32_bf16 v[70:73], v[170:173], v[218:221], v[70:73]
	v_mfma_f32_16x16x32_bf16 v[66:69], v[186:189], v[218:221], v[66:69]
	s_setprio 0
	s_barrier
; #define PG8_STAGE(bufoff, gbase, voff) do { _Pragma("unroll") for (int _i = 0; _i < 2; ++_i) \
;         __builtin_amdgcn_global_load_lds((const unsigned*)((const char*)(gbase) + (voff)[_i]), (PG8_LAS unsigned*)(lds + (bufoff) + ldsw + _i * 8192), 16, 0, 0); } while (0)
; #define PG8_LDA(dst, b, h) do { _Pragma("unroll") for (int m = 0; m < 4; ++m) _Pragma("unroll") for (int k = 0; k < 2; ++k) dst[m][k] = *(const PG8_LAS bf16x8*)(lds + PG8_SA(b, h) + aoff + m * 2048 + k * 1024); } while (0)
; #define PG8_LDB(dst, b, h) do { _Pragma("unroll") for (int n = 0; n < 2; ++n) _Pragma("unroll") for (int k = 0; k < 2; ++k) dst[n][k] = *(const PG8_LAS bf16x8*)(lds + PG8_SB(b, h) + boff + n * 2048 + k * 1024); } while (0)
; template <class Epi, class Sched, bool ALIGN_EPI = false, bool SP2 = false>
; __device__ __forceinline__ void gemm_phase(PG8_LAS unsigned char* lds, const Gemm g, const Sched& S, const Epi& E) {
;     ...
;         for (int t = 0; t < nt; t += 2) {
;             const bool last = (t == nt - 2);
;             const char* a1 = cA + (size_t)(t + 1) * kstep;
;             const char* a2 = last ? nA : cA + (size_t)(t + 2) * kstep; const char* b2 = last ? nB : cB + (size_t)(t + 2) * kstep;
;             const char* a3 = a2 + kstep; const char* b3 = b2 + kstep;
;             if (last && has_next) S.a_ready(nxt);
;             if constexpr (SP2) {
;             PG8_LDB(B0, 0, 0); PG8_LDB(B1, 0, 1); PG8_SCHED; PG8_LDA(At, 0, 0); PG8_STAGE(PG8_SA(1, 1), a1 + hstep, voffA);
;             PG8_WAIT_V(8); PG8_WAIT_L(0); PG8_BAR; PG8_MMA(0, 0, At, B0); PG8_MMA(0, 1, At, B1); PG8_BAR; PG8_SCHED;
;             PG8_LDA(At, 0, 1); PG8_STAGE(PG8_SB(0, 0), b2, voffB); PG8_STAGE(PG8_SB(0, 1), b2 + hstep, voffB); PG8_STAGE(PG8_SA(0, 0), a2, voffA);
;             PG8_WAIT_V(8); PG8_WAIT_L(0); PG8_BAR; PG8_MMA(1, 0, At, B0); PG8_MMA(1, 1, At, B1); PG8_BAR; PG8_SCHED;
;             PG8_LDB(B0, 1, 0); PG8_LDB(B1, 1, 1); PG8_SCHED; PG8_LDA(At, 1, 0); PG8_STAGE(PG8_SA(0, 1), a2 + hstep, voffA);
;             PG8_WAIT_V(8); PG8_WAIT_L(0); PG8_BAR; PG8_MMA(0, 0, At, B0); PG8_MMA(0, 1, At, B1); PG8_BAR; PG8_SCHED;
;             PG8_LDA(At, 1, 1); PG8_STAGE(PG8_SB(1, 0), b3, voffB); PG8_STAGE(PG8_SB(1, 1), b3 + hstep, voffB); PG8_STAGE(PG8_SA(1, 0), a3, voffA);
;             PG8_WAIT_V(8); PG8_WAIT_L(0); PG8_BAR; PG8_MMA(1, 0, At, B0); PG8_MMA(1, 1, At, B1); PG8_BAR; PG8_SCHED;
	s_add_i32 s28, s48, s35
	v_lshl_add_u64 v[154:155], v[154:155], 0, s[80:81]
	s_mov_b32 m0, s28
	ds_read_b128 v[190:193], v157 offset:49152
	ds_read_b128 v[194:197], v157 offset:50176
	ds_read_b128 v[198:201], v157 offset:51200
	ds_read_b128 v[202:205], v157 offset:52224
	ds_read_b128 v[206:209], v157 offset:53248
	ds_read_b128 v[210:213], v157 offset:54272
	ds_read_b128 v[214:217], v157 offset:55296
	ds_read_b128 v[218:221], v157 offset:56320
	global_load_lds_dwordx4 v[154:155], off
	s_add_i32 m0, s28, 0x2000
	s_add_u32 s26, s26, 0x40080
	v_lshl_add_u64 v[154:155], v[180:181], 0, s[80:81]
	s_addc_u32 s27, s27, 0
	s_add_i32 s28, s49, s35
	global_load_lds_dwordx4 v[154:155], off
	v_lshl_add_u64 v[154:155], s[26:27], 0, v[142:143]
	s_mov_b32 m0, s28
	s_nop 0
	global_load_lds_dwordx4 v[154:155], off
	v_lshl_add_u64 v[154:155], s[26:27], 0, v[138:139]
	s_add_i32 m0, s28, 0x2000
	s_nop 0
	global_load_lds_dwordx4 v[154:155], off
	v_lshl_add_u64 v[154:155], v[182:183], 0, s[80:81]
	s_mov_b32 m0, s40
	s_nop 0
	global_load_lds_dwordx4 v[154:155], off
	v_lshl_add_u64 v[154:155], v[222:223], 0, s[80:81]
	s_mov_b32 m0, s41
	s_nop 0
	global_load_lds_dwordx4 v[154:155], off
	s_waitcnt vmcnt(8) lgkmcnt(0)
	s_barrier
	s_setprio 1
	v_mfma_f32_16x16x32_bf16 v[62:65], v[94:97], v[190:193], v[62:65]
	v_mfma_f32_16x16x32_bf16 v[58:61], v[158:161], v[190:193], v[58:61]
	v_mfma_f32_16x16x32_bf16 v[50:53], v[94:97], v[198:201], v[50:53]
	v_mfma_f32_16x16x32_bf16 v[42:45], v[158:161], v[198:201], v[42:45]
	v_mfma_f32_16x16x32_bf16 v[34:37], v[94:97], v[206:209], v[34:37]
	v_mfma_f32_16x16x32_bf16 v[26:29], v[158:161], v[206:209], v[26:29]
	v_mfma_f32_16x16x32_bf16 v[18:21], v[94:97], v[214:217], v[18:21]
	v_mfma_f32_16x16x32_bf16 v[10:13], v[158:161], v[214:217], v[10:13]
	v_mfma_f32_16x16x32_bf16 v[62:65], v[134:137], v[194:197], v[62:65]
	v_mfma_f32_16x16x32_bf16 v[58:61], v[162:165], v[194:197], v[58:61]
	v_mfma_f32_16x16x32_bf16 v[50:53], v[134:137], v[202:205], v[50:53]
	v_mfma_f32_16x16x32_bf16 v[42:45], v[162:165], v[202:205], v[42:45]
	v_mfma_f32_16x16x32_bf16 v[34:37], v[134:137], v[210:213], v[34:37]
	v_mfma_f32_16x16x32_bf16 v[26:29], v[162:165], v[210:213], v[26:29]
	v_mfma_f32_16x16x32_bf16 v[18:21], v[134:137], v[218:221], v[18:21]
	v_mfma_f32_16x16x32_bf16 v[10:13], v[162:165], v[218:221], v[10:13]
	v_mfma_f32_16x16x32_bf16 v[54:57], v[166:169], v[190:193], v[54:57]
	v_mfma_f32_16x16x32_bf16 v[46:49], v[174:177], v[190:193], v[46:49]
	v_mfma_f32_16x16x32_bf16 v[38:41], v[166:169], v[198:201], v[38:41]
	v_mfma_f32_16x16x32_bf16 v[30:33], v[174:177], v[198:201], v[30:33]
	v_mfma_f32_16x16x32_bf16 v[22:25], v[166:169], v[206:209], v[22:25]
	v_mfma_f32_16x16x32_bf16 v[14:17], v[174:177], v[206:209], v[14:17]
	v_mfma_f32_16x16x32_bf16 v[6:9], v[166:169], v[214:217], v[6:9]
	v_mfma_f32_16x16x32_bf16 v[2:5], v[174:177], v[214:217], v[2:5]
	v_mfma_f32_16x16x32_bf16 v[54:57], v[170:173], v[194:197], v[54:57]
	v_mfma_f32_16x16x32_bf16 v[46:49], v[186:189], v[194:197], v[46:49]
	v_mfma_f32_16x16x32_bf16 v[38:41], v[170:173], v[202:205], v[38:41]
	v_mfma_f32_16x16x32_bf16 v[30:33], v[186:189], v[202:205], v[30:33]
	v_mfma_f32_16x16x32_bf16 v[22:25], v[170:173], v[210:213], v[22:25]
	v_mfma_f32_16x16x32_bf16 v[14:17], v[186:189], v[210:213], v[14:17]
	v_mfma_f32_16x16x32_bf16 v[6:9], v[170:173], v[218:221], v[6:9]
	v_mfma_f32_16x16x32_bf16 v[2:5], v[186:189], v[218:221], v[2:5]
	s_setprio 0
	s_barrier
	s_add_i32 s47, s47, 2
	s_add_u32 s24, s24, 0x100
	s_addc_u32 s25, s25, 0
	s_add_u32 s45, s45, 0x100
	s_addc_u32 s46, s46, 0
	s_cmp_gt_u32 s47, 13
	s_branch .LBB0_318
.LBB0_318:
	s_add_u32 s26, s24, 0xfffc0080
	s_addc_u32 s27, s25, -1
	s_add_i32 s48, 0, 0x10000
	s_cmp_eq_u32 s47, 12
	s_cselect_b32 s29, s13, s27
	s_cselect_b32 s28, s21, s26
	v_add_u32_e32 v154, s48, v156
	s_cselect_b32 s27, s11, s46
	s_cselect_b32 s26, s44, s45
	s_add_i32 s50, 0, 0x14000
	ds_read_b128 v[94:97], v154
	ds_read_b128 v[134:137], v154 offset:1024
	ds_read_b128 v[158:161], v154 offset:2048
	ds_read_b128 v[162:165], v154 offset:3072
	v_add_u32_e32 v154, s50, v156
	ds_read_b128 v[166:169], v154
	ds_read_b128 v[170:173], v154 offset:1024
	ds_read_b128 v[174:177], v154 offset:2048
	ds_read_b128 v[186:189], v154 offset:3072
	v_lshl_add_u64 v[154:155], s[24:25], 0, v[150:151]
	s_add_i32 m0, s23, 0xc000
	ds_read_b128 v[190:193], v157
	ds_read_b128 v[194:197], v157 offset:1024
	ds_read_b128 v[198:201], v157 offset:2048
	ds_read_b128 v[202:205], v157 offset:3072
	ds_read_b128 v[206:209], v157 offset:4096
	ds_read_b128 v[210:213], v157 offset:5120
	ds_read_b128 v[214:217], v157 offset:6144
	ds_read_b128 v[218:221], v157 offset:7168
	global_load_lds_dwordx4 v[154:155], off
	v_lshl_add_u64 v[154:155], s[24:25], 0, v[152:153]
	s_add_i32 m0, s23, 0xe000
	s_nop 0
	global_load_lds_dwordx4 v[154:155], off
	s_waitcnt vmcnt(8) lgkmcnt(0)
	s_barrier
; #define PG8_STAGE(bufoff, gbase, voff) do { _Pragma("unroll") for (int _i = 0; _i < 2; ++_i) \
;         __builtin_amdgcn_global_load_lds((const unsigned*)((const char*)(gbase) + (voff)[_i]), (PG8_LAS unsigned*)(lds + (bufoff) + ldsw + _i * 8192), 16, 0, 0); } while (0)
; #define PG8_LDA(dst, b, h) do { _Pragma("unroll") for (int m = 0; m < 4; ++m) _Pragma("unroll") for (int k = 0; k < 2; ++k) dst[m][k] = *(const PG8_LAS bf16x8*)(lds + PG8_SA(b, h) + aoff + m * 2048 + k * 1024); } while (0)
; #define PG8_LDB(dst, b, h) do { _Pragma("unroll") for (int n = 0; n < 2; ++n) _Pragma("unroll") for (int k = 0; k < 2; ++k) dst[n][k] = *(const PG8_LAS bf16x8*)(lds + PG8_SB(b, h) + boff + n * 2048 + k * 1024); } while (0)
; #define PG8_MMA(ai, bj, At, Bt) do { __builtin_amdgcn_s_setprio(1); _Pragma("unroll") for (int m = 0; m < 4; ++m) _Pragma("unroll") for (int n = 0; n < 2; ++n) _Pragma("unroll") for (int k = 0; k < 2; ++k) \
;         acc[ai][bj][m][n] = __builtin_amdgcn_mfma_f32_16x16x32_bf16(Bt[n][k], At[m][k], acc[ai][bj][m][n], 0, 0, 0); __builtin_amdgcn_s_setprio(0); } while (0)
; #define PG8_WAIT_V(n) asm volatile("s_waitcnt vmcnt(" #n ")" ::: "memory")
; #define PG8_WAIT_L(n) asm volatile("s_waitcnt lgkmcnt(" #n ")" ::: "memory")
; #define PG8_BAR __builtin_amdgcn_s_barrier()
; #define PG8_SCHED __builtin_amdgcn_sched_barrier(0)
; template <class Epi, class Sched, bool ALIGN_EPI = false, bool SP2 = false>
; __device__ __forceinline__ void gemm_phase(PG8_LAS unsigned char* lds, const Gemm g, const Sched& S, const Epi& E) {
;     ...
;             PG8_LDB(B0, 0, 0); PG8_LDB(B1, 0, 1); PG8_SCHED; PG8_LDA(At, 0, 0); PG8_STAGE(PG8_SA(1, 1), a1 + hstep, voffA);
;             PG8_WAIT_V(8); PG8_WAIT_L(0); PG8_BAR; PG8_MMA(0, 0, At, B0); PG8_MMA(0, 1, At, B1); PG8_BAR; PG8_SCHED;
;             PG8_LDA(At, 0, 1); PG8_STAGE(PG8_SB(0, 0), b2, voffB); PG8_STAGE(PG8_SB(0, 1), b2 + hstep, voffB); PG8_STAGE(PG8_SA(0, 0), a2, voffA);
;             PG8_WAIT_V(8); PG8_WAIT_L(0); PG8_BAR; PG8_MMA(1, 0, At, B0); PG8_MMA(1, 1, At, B1); PG8_BAR; PG8_SCHED;
	s_setprio 1
	v_mfma_f32_16x16x32_bf16 v[130:133], v[94:97], v[190:193], v[130:133]
	v_mfma_f32_16x16x32_bf16 v[126:129], v[158:161], v[190:193], v[126:129]
	v_mfma_f32_16x16x32_bf16 v[114:117], v[94:97], v[198:201], v[114:117]
	v_mfma_f32_16x16x32_bf16 v[110:113], v[158:161], v[198:201], v[110:113]
	v_mfma_f32_16x16x32_bf16 v[98:101], v[94:97], v[206:209], v[98:101]
	v_mfma_f32_16x16x32_bf16 v[90:93], v[158:161], v[206:209], v[90:93]
	v_mfma_f32_16x16x32_bf16 v[78:81], v[94:97], v[214:217], v[78:81]
	v_mfma_f32_16x16x32_bf16 v[74:77], v[158:161], v[214:217], v[74:77]
	v_mfma_f32_16x16x32_bf16 v[130:133], v[134:137], v[194:197], v[130:133]
	v_mfma_f32_16x16x32_bf16 v[126:129], v[162:165], v[194:197], v[126:129]
	v_mfma_f32_16x16x32_bf16 v[114:117], v[134:137], v[202:205], v[114:117]
	v_mfma_f32_16x16x32_bf16 v[110:113], v[162:165], v[202:205], v[110:113]
	v_mfma_f32_16x16x32_bf16 v[98:101], v[134:137], v[210:213], v[98:101]
	v_mfma_f32_16x16x32_bf16 v[90:93], v[162:165], v[210:213], v[90:93]
	v_mfma_f32_16x16x32_bf16 v[78:81], v[134:137], v[218:221], v[78:81]
	v_mfma_f32_16x16x32_bf16 v[74:77], v[162:165], v[218:221], v[74:77]
	v_mfma_f32_16x16x32_bf16 v[122:125], v[166:169], v[190:193], v[122:125]
	v_mfma_f32_16x16x32_bf16 v[118:121], v[174:177], v[190:193], v[118:121]
	v_mfma_f32_16x16x32_bf16 v[106:109], v[166:169], v[198:201], v[106:109]
	v_mfma_f32_16x16x32_bf16 v[102:105], v[174:177], v[198:201], v[102:105]
	v_mfma_f32_16x16x32_bf16 v[86:89], v[166:169], v[206:209], v[86:89]
	v_mfma_f32_16x16x32_bf16 v[82:85], v[174:177], v[206:209], v[82:85]
	v_mfma_f32_16x16x32_bf16 v[70:73], v[166:169], v[214:217], v[70:73]
	v_mfma_f32_16x16x32_bf16 v[66:69], v[174:177], v[214:217], v[66:69]
	v_mfma_f32_16x16x32_bf16 v[122:125], v[170:173], v[194:197], v[122:125]
	v_mfma_f32_16x16x32_bf16 v[118:121], v[186:189], v[194:197], v[118:121]
	v_mfma_f32_16x16x32_bf16 v[106:109], v[170:173], v[202:205], v[106:109]
	v_mfma_f32_16x16x32_bf16 v[102:105], v[186:189], v[202:205], v[102:105]
	v_mfma_f32_16x16x32_bf16 v[86:89], v[170:173], v[210:213], v[86:89]
	v_mfma_f32_16x16x32_bf16 v[82:85], v[186:189], v[210:213], v[82:85]
	v_mfma_f32_16x16x32_bf16 v[70:73], v[170:173], v[218:221], v[70:73]
	v_mfma_f32_16x16x32_bf16 v[66:69], v[186:189], v[218:221], v[66:69]
	s_setprio 0
	s_barrier
	s_add_i32 s48, s48, s35
	v_lshl_add_u64 v[154:155], s[26:27], 0, v[142:143]
	s_mov_b32 m0, s48
	ds_read_b128 v[190:193], v157 offset:16384
	ds_read_b128 v[194:197], v157 offset:17408
	ds_read_b128 v[198:201], v157 offset:18432
	ds_read_b128 v[202:205], v157 offset:19456
	ds_read_b128 v[206:209], v157 offset:20480
	ds_read_b128 v[210:213], v157 offset:21504
	ds_read_b128 v[214:217], v157 offset:22528
	ds_read_b128 v[218:221], v157 offset:23552
	global_load_lds_dwordx4 v[154:155], off
	s_add_i32 m0, s48, 0x2000
	s_add_u32 s48, s26, 0x40000
	v_lshl_add_u64 v[180:181], s[26:27], 0, v[138:139]
	s_addc_u32 s49, s27, 0
	s_add_i32 s50, s50, s35
	global_load_lds_dwordx4 v[180:181], off
	v_lshl_add_u64 v[182:183], s[48:49], 0, v[142:143]
	s_mov_b32 m0, s50
	v_lshl_add_u64 v[222:223], s[28:29], 0, v[140:141]
	global_load_lds_dwordx4 v[182:183], off
	v_lshl_add_u64 v[182:183], s[48:49], 0, v[138:139]
	s_add_i32 m0, s50, 0x2000
	s_nop 0
	global_load_lds_dwordx4 v[182:183], off
	v_lshl_add_u64 v[182:183], s[28:29], 0, v[144:145]
	s_mov_b32 m0, s23
	s_nop 0
	global_load_lds_dwordx4 v[182:183], off
	s_mov_b32 m0, s37
	s_nop 0
	global_load_lds_dwordx4 v[222:223], off
	s_waitcnt vmcnt(8) lgkmcnt(0)
	s_barrier
	s_setprio 1
	v_mfma_f32_16x16x32_bf16 v[62:65], v[94:97], v[190:193], v[62:65]
	v_mfma_f32_16x16x32_bf16 v[58:61], v[158:161], v[190:193], v[58:61]
	v_mfma_f32_16x16x32_bf16 v[50:53], v[94:97], v[198:201], v[50:53]
	v_mfma_f32_16x16x32_bf16 v[42:45], v[158:161], v[198:201], v[42:45]
	v_mfma_f32_16x16x32_bf16 v[34:37], v[94:97], v[206:209], v[34:37]
	v_mfma_f32_16x16x32_bf16 v[26:29], v[158:161], v[206:209], v[26:29]
	v_mfma_f32_16x16x32_bf16 v[18:21], v[94:97], v[214:217], v[18:21]
	v_mfma_f32_16x16x32_bf16 v[10:13], v[158:161], v[214:217], v[10:13]
	v_mfma_f32_16x16x32_bf16 v[62:65], v[134:137], v[194:197], v[62:65]
	v_mfma_f32_16x16x32_bf16 v[58:61], v[162:165], v[194:197], v[58:61]
	v_mfma_f32_16x16x32_bf16 v[50:53], v[134:137], v[202:205], v[50:53]
	v_mfma_f32_16x16x32_bf16 v[42:45], v[162:165], v[202:205], v[42:45]
	v_mfma_f32_16x16x32_bf16 v[34:37], v[134:137], v[210:213], v[34:37]
	v_mfma_f32_16x16x32_bf16 v[26:29], v[162:165], v[210:213], v[26:29]
	v_mfma_f32_16x16x32_bf16 v[18:21], v[134:137], v[218:221], v[18:21]
	v_mfma_f32_16x16x32_bf16 v[10:13], v[162:165], v[218:221], v[10:13]
	v_mfma_f32_16x16x32_bf16 v[54:57], v[166:169], v[190:193], v[54:57]
	v_mfma_f32_16x16x32_bf16 v[46:49], v[174:177], v[190:193], v[46:49]
	v_mfma_f32_16x16x32_bf16 v[38:41], v[166:169], v[198:201], v[38:41]
	v_mfma_f32_16x16x32_bf16 v[30:33], v[174:177], v[198:201], v[30:33]
	v_mfma_f32_16x16x32_bf16 v[22:25], v[166:169], v[206:209], v[22:25]
	v_mfma_f32_16x16x32_bf16 v[14:17], v[174:177], v[206:209], v[14:17]
	v_mfma_f32_16x16x32_bf16 v[6:9], v[166:169], v[214:217], v[6:9]
	v_mfma_f32_16x16x32_bf16 v[2:5], v[174:177], v[214:217], v[2:5]
	v_mfma_f32_16x16x32_bf16 v[54:57], v[170:173], v[194:197], v[54:57]
	v_mfma_f32_16x16x32_bf16 v[46:49], v[186:189], v[194:197], v[46:49]
	v_mfma_f32_16x16x32_bf16 v[38:41], v[170:173], v[202:205], v[38:41]
	v_mfma_f32_16x16x32_bf16 v[30:33], v[186:189], v[202:205], v[30:33]
	v_mfma_f32_16x16x32_bf16 v[22:25], v[170:173], v[210:213], v[22:25]
	v_mfma_f32_16x16x32_bf16 v[14:17], v[186:189], v[210:213], v[14:17]
	v_mfma_f32_16x16x32_bf16 v[6:9], v[170:173], v[218:221], v[6:9]
	v_mfma_f32_16x16x32_bf16 v[2:5], v[186:189], v[218:221], v[2:5]
	s_setprio 0
	s_barrier
; #define PG8_STAGE(bufoff, gbase, voff) do { _Pragma("unroll") for (int _i = 0; _i < 2; ++_i) \
;         __builtin_amdgcn_global_load_lds((const unsigned*)((const char*)(gbase) + (voff)[_i]), (PG8_LAS unsigned*)(lds + (bufoff) + ldsw + _i * 8192), 16, 0, 0); } while (0)
; #define PG8_LDA(dst, b, h) do { _Pragma("unroll") for (int m = 0; m < 4; ++m) _Pragma("unroll") for (int k = 0; k < 2; ++k) dst[m][k] = *(const PG8_LAS bf16x8*)(lds + PG8_SA(b, h) + aoff + m * 2048 + k * 1024); } while (0)
; #define PG8_LDB(dst, b, h) do { _Pragma("unroll") for (int n = 0; n < 2; ++n) _Pragma("unroll") for (int k = 0; k < 2; ++k) dst[n][k] = *(const PG8_LAS bf16x8*)(lds + PG8_SB(b, h) + boff + n * 2048 + k * 1024); } while (0)
; #define PG8_MMA(ai, bj, At, Bt) do { __builtin_amdgcn_s_setprio(1); _Pragma("unroll") for (int m = 0; m < 4; ++m) _Pragma("unroll") for (int n = 0; n < 2; ++n) _Pragma("unroll") for (int k = 0; k < 2; ++k) \
;         acc[ai][bj][m][n] = __builtin_amdgcn_mfma_f32_16x16x32_bf16(Bt[n][k], At[m][k], acc[ai][bj][m][n], 0, 0, 0); __builtin_amdgcn_s_setprio(0); } while (0)
; #define PG8_WAIT_V(n) asm volatile("s_waitcnt vmcnt(" #n ")" ::: "memory")
; #define PG8_WAIT_L(n) asm volatile("s_waitcnt lgkmcnt(" #n ")" ::: "memory")
; #define PG8_BAR __builtin_amdgcn_s_barrier()
; #define PG8_SCHED __builtin_amdgcn_sched_barrier(0)
; template <class Epi, class Sched, bool ALIGN_EPI = false, bool SP2 = false>
; __device__ __forceinline__ void gemm_phase(PG8_LAS unsigned char* lds, const Gemm g, const Sched& S, const Epi& E) {
;     ...
;             PG8_LDB(B0, 1, 0); PG8_LDB(B1, 1, 1); PG8_SCHED; PG8_LDA(At, 1, 0); PG8_STAGE(PG8_SA(0, 1), a2 + hstep, voffA);
;             PG8_WAIT_V(8); PG8_WAIT_L(0); PG8_BAR; PG8_MMA(0, 0, At, B0); PG8_MMA(0, 1, At, B1); PG8_BAR; PG8_SCHED;
	s_add_i32 s48, 0, 0x18000
	s_add_i32 s49, 0, 0x1c000
	v_add_u32_e32 v162, s48, v156
	v_add_u32_e32 v179, s49, v156
	ds_read_b128 v[94:97], v162
	ds_read_b128 v[134:137], v162 offset:1024
	ds_read_b128 v[158:161], v162 offset:2048
	ds_read_b128 v[162:165], v162 offset:3072
	ds_read_b128 v[166:169], v179
	ds_read_b128 v[170:173], v179 offset:1024
	ds_read_b128 v[174:177], v179 offset:2048
	ds_read_b128 v[186:189], v179 offset:3072
	s_add_u32 s28, s28, 0x40000
	s_addc_u32 s29, s29, 0
	s_mov_b32 m0, s38
	v_lshl_add_u64 v[240:241], s[28:29], 0, v[144:145]
	ds_read_b128 v[190:193], v157 offset:32768
	ds_read_b128 v[194:197], v157 offset:33792
	ds_read_b128 v[198:201], v157 offset:34816
	ds_read_b128 v[202:205], v157 offset:35840
	ds_read_b128 v[206:209], v157 offset:36864
	ds_read_b128 v[210:213], v157 offset:37888
	ds_read_b128 v[214:217], v157 offset:38912
	ds_read_b128 v[218:221], v157 offset:39936
	global_load_lds_dwordx4 v[240:241], off
	v_lshl_add_u64 v[240:241], s[28:29], 0, v[140:141]
	s_mov_b32 m0, s39
	s_nop 0
	global_load_lds_dwordx4 v[240:241], off
	s_waitcnt vmcnt(8) lgkmcnt(0)
	s_barrier
	s_setprio 1
	v_mfma_f32_16x16x32_bf16 v[130:133], v[94:97], v[190:193], v[130:133]
	v_mfma_f32_16x16x32_bf16 v[126:129], v[158:161], v[190:193], v[126:129]
	v_mfma_f32_16x16x32_bf16 v[114:117], v[94:97], v[198:201], v[114:117]
	v_mfma_f32_16x16x32_bf16 v[110:113], v[158:161], v[198:201], v[110:113]
	v_mfma_f32_16x16x32_bf16 v[98:101], v[94:97], v[206:209], v[98:101]
	v_mfma_f32_16x16x32_bf16 v[90:93], v[158:161], v[206:209], v[90:93]
	v_mfma_f32_16x16x32_bf16 v[78:81], v[94:97], v[214:217], v[78:81]
	v_mfma_f32_16x16x32_bf16 v[74:77], v[158:161], v[214:217], v[74:77]
	v_mfma_f32_16x16x32_bf16 v[130:133], v[134:137], v[194:197], v[130:133]
	v_mfma_f32_16x16x32_bf16 v[126:129], v[162:165], v[194:197], v[126:129]
	v_mfma_f32_16x16x32_bf16 v[114:117], v[134:137], v[202:205], v[114:117]
	v_mfma_f32_16x16x32_bf16 v[110:113], v[162:165], v[202:205], v[110:113]
	v_mfma_f32_16x16x32_bf16 v[98:101], v[134:137], v[210:213], v[98:101]
	v_mfma_f32_16x16x32_bf16 v[90:93], v[162:165], v[210:213], v[90:93]
	v_mfma_f32_16x16x32_bf16 v[78:81], v[134:137], v[218:221], v[78:81]
	v_mfma_f32_16x16x32_bf16 v[74:77], v[162:165], v[218:221], v[74:77]
	v_mfma_f32_16x16x32_bf16 v[122:125], v[166:169], v[190:193], v[122:125]
	v_mfma_f32_16x16x32_bf16 v[118:121], v[174:177], v[190:193], v[118:121]
	v_mfma_f32_16x16x32_bf16 v[106:109], v[166:169], v[198:201], v[106:109]
	v_mfma_f32_16x16x32_bf16 v[102:105], v[174:177], v[198:201], v[102:105]
	v_mfma_f32_16x16x32_bf16 v[86:89], v[166:169], v[206:209], v[86:89]
	v_mfma_f32_16x16x32_bf16 v[82:85], v[174:177], v[206:209], v[82:85]
	v_mfma_f32_16x16x32_bf16 v[70:73], v[166:169], v[214:217], v[70:73]
	v_mfma_f32_16x16x32_bf16 v[66:69], v[174:177], v[214:217], v[66:69]
	v_mfma_f32_16x16x32_bf16 v[122:125], v[170:173], v[194:197], v[122:125]
	v_mfma_f32_16x16x32_bf16 v[118:121], v[186:189], v[194:197], v[118:121]
	v_mfma_f32_16x16x32_bf16 v[106:109], v[170:173], v[202:205], v[106:109]
	v_mfma_f32_16x16x32_bf16 v[102:105], v[186:189], v[202:205], v[102:105]
	v_mfma_f32_16x16x32_bf16 v[86:89], v[170:173], v[210:213], v[86:89]
	v_mfma_f32_16x16x32_bf16 v[82:85], v[186:189], v[210:213], v[82:85]
	v_mfma_f32_16x16x32_bf16 v[70:73], v[170:173], v[218:221], v[70:73]
	v_mfma_f32_16x16x32_bf16 v[66:69], v[186:189], v[218:221], v[66:69]
	s_setprio 0
	s_barrier
; #define PG8_STAGE(bufoff, gbase, voff) do { _Pragma("unroll") for (int _i = 0; _i < 2; ++_i) \
;         __builtin_amdgcn_global_load_lds((const unsigned*)((const char*)(gbase) + (voff)[_i]), (PG8_LAS unsigned*)(lds + (bufoff) + ldsw + _i * 8192), 16, 0, 0); } while (0)
; #define PG8_LDA(dst, b, h) do { _Pragma("unroll") for (int m = 0; m < 4; ++m) _Pragma("unroll") for (int k = 0; k < 2; ++k) dst[m][k] = *(const PG8_LAS bf16x8*)(lds + PG8_SA(b, h) + aoff + m * 2048 + k * 1024); } while (0)
; #define PG8_MMA(ai, bj, At, Bt) do { __builtin_amdgcn_s_setprio(1); _Pragma("unroll") for (int m = 0; m < 4; ++m) _Pragma("unroll") for (int n = 0; n < 2; ++n) _Pragma("unroll") for (int k = 0; k < 2; ++k) \
;         acc[ai][bj][m][n] = __builtin_amdgcn_mfma_f32_16x16x32_bf16(Bt[n][k], At[m][k], acc[ai][bj][m][n], 0, 0, 0); __builtin_amdgcn_s_setprio(0); } while (0)
; #define PG8_WAIT_V(n) asm volatile("s_waitcnt vmcnt(" #n ")" ::: "memory")
; #define PG8_WAIT_L(n) asm volatile("s_waitcnt lgkmcnt(" #n ")" ::: "memory")
; #define PG8_BAR __builtin_amdgcn_s_barrier()
; #define PG8_SCHED __builtin_amdgcn_sched_barrier(0)
; template <class Epi, class Sched, bool ALIGN_EPI = false, bool SP2 = false>
; __device__ __forceinline__ void gemm_phase(PG8_LAS unsigned char* lds, const Gemm g, const Sched& S, const Epi& E) {
;     ...
;             PG8_LDA(At, 1, 1); PG8_STAGE(PG8_SB(1, 0), b3, voffB); PG8_STAGE(PG8_SB(1, 1), b3 + hstep, voffB); PG8_STAGE(PG8_SA(1, 0), a3, voffA);
;             PG8_WAIT_V(8); PG8_WAIT_L(0); PG8_BAR; PG8_MMA(1, 0, At, B0); PG8_MMA(1, 1, At, B1); PG8_BAR; PG8_SCHED;
	s_add_i32 s28, s48, s35
	v_lshl_add_u64 v[154:155], v[154:155], 0, s[80:81]
	s_mov_b32 m0, s28
	ds_read_b128 v[190:193], v157 offset:49152
	ds_read_b128 v[194:197], v157 offset:50176
	ds_read_b128 v[198:201], v157 offset:51200
	ds_read_b128 v[202:205], v157 offset:52224
	ds_read_b128 v[206:209], v157 offset:53248
	ds_read_b128 v[210:213], v157 offset:54272
	ds_read_b128 v[214:217], v157 offset:55296
	ds_read_b128 v[218:221], v157 offset:56320
	global_load_lds_dwordx4 v[154:155], off
	s_add_i32 m0, s28, 0x2000
	s_add_u32 s26, s26, 0x40080
	v_lshl_add_u64 v[154:155], v[180:181], 0, s[80:81]
	s_addc_u32 s27, s27, 0
	s_add_i32 s28, s49, s35
	global_load_lds_dwordx4 v[154:155], off
	v_lshl_add_u64 v[154:155], s[26:27], 0, v[142:143]
	s_mov_b32 m0, s28
	s_nop 0
	global_load_lds_dwordx4 v[154:155], off
	v_lshl_add_u64 v[154:155], s[26:27], 0, v[138:139]
	s_add_i32 m0, s28, 0x2000
	s_nop 0
	global_load_lds_dwordx4 v[154:155], off
	v_lshl_add_u64 v[154:155], v[182:183], 0, s[80:81]
	s_mov_b32 m0, s40
	s_nop 0
	global_load_lds_dwordx4 v[154:155], off
	v_lshl_add_u64 v[154:155], v[222:223], 0, s[80:81]
	s_mov_b32 m0, s41
	s_nop 0
	global_load_lds_dwordx4 v[154:155], off
	s_waitcnt vmcnt(8) lgkmcnt(0)
	s_barrier
	s_setprio 1
	v_mfma_f32_16x16x32_bf16 v[62:65], v[94:97], v[190:193], v[62:65]
	v_mfma_f32_16x16x32_bf16 v[58:61], v[158:161], v[190:193], v[58:61]
	v_mfma_f32_16x16x32_bf16 v[50:53], v[94:97], v[198:201], v[50:53]
	v_mfma_f32_16x16x32_bf16 v[42:45], v[158:161], v[198:201], v[42:45]
	v_mfma_f32_16x16x32_bf16 v[34:37], v[94:97], v[206:209], v[34:37]
	v_mfma_f32_16x16x32_bf16 v[26:29], v[158:161], v[206:209], v[26:29]
	v_mfma_f32_16x16x32_bf16 v[18:21], v[94:97], v[214:217], v[18:21]
	v_mfma_f32_16x16x32_bf16 v[10:13], v[158:161], v[214:217], v[10:13]
	v_mfma_f32_16x16x32_bf16 v[62:65], v[134:137], v[194:197], v[62:65]
	v_mfma_f32_16x16x32_bf16 v[58:61], v[162:165], v[194:197], v[58:61]
	v_mfma_f32_16x16x32_bf16 v[50:53], v[134:137], v[202:205], v[50:53]
	v_mfma_f32_16x16x32_bf16 v[42:45], v[162:165], v[202:205], v[42:45]
	v_mfma_f32_16x16x32_bf16 v[34:37], v[134:137], v[210:213], v[34:37]
	v_mfma_f32_16x16x32_bf16 v[26:29], v[162:165], v[210:213], v[26:29]
	v_mfma_f32_16x16x32_bf16 v[18:21], v[134:137], v[218:221], v[18:21]
	v_mfma_f32_16x16x32_bf16 v[10:13], v[162:165], v[218:221], v[10:13]
	v_mfma_f32_16x16x32_bf16 v[54:57], v[166:169], v[190:193], v[54:57]
	v_mfma_f32_16x16x32_bf16 v[46:49], v[174:177], v[190:193], v[46:49]
	v_mfma_f32_16x16x32_bf16 v[38:41], v[166:169], v[198:201], v[38:41]
	v_mfma_f32_16x16x32_bf16 v[30:33], v[174:177], v[198:201], v[30:33]
	v_mfma_f32_16x16x32_bf16 v[22:25], v[166:169], v[206:209], v[22:25]
	v_mfma_f32_16x16x32_bf16 v[14:17], v[174:177], v[206:209], v[14:17]
	v_mfma_f32_16x16x32_bf16 v[6:9], v[166:169], v[214:217], v[6:9]
	v_mfma_f32_16x16x32_bf16 v[2:5], v[174:177], v[214:217], v[2:5]
	v_mfma_f32_16x16x32_bf16 v[54:57], v[170:173], v[194:197], v[54:57]
	v_mfma_f32_16x16x32_bf16 v[46:49], v[186:189], v[194:197], v[46:49]
	v_mfma_f32_16x16x32_bf16 v[38:41], v[170:173], v[202:205], v[38:41]
	v_mfma_f32_16x16x32_bf16 v[30:33], v[186:189], v[202:205], v[30:33]
	v_mfma_f32_16x16x32_bf16 v[22:25], v[170:173], v[210:213], v[22:25]
	v_mfma_f32_16x16x32_bf16 v[14:17], v[186:189], v[210:213], v[14:17]
	v_mfma_f32_16x16x32_bf16 v[6:9], v[170:173], v[218:221], v[6:9]
	v_mfma_f32_16x16x32_bf16 v[2:5], v[186:189], v[218:221], v[2:5]
	s_setprio 0
	s_barrier
	s_add_i32 s47, s47, 2
	s_add_u32 s24, s24, 0x100
	s_addc_u32 s25, s25, 0
	s_add_u32 s45, s45, 0x100
	s_addc_u32 s46, s46, 0
	s_cmp_gt_u32 s47, 13
	s_cbranch_scc0 .LBB0_318
	s_and_b64 vcc, exec, s[6:7]
	s_cbranch_vccz .LBB0_321
	s_barrier

; #define PG8_STAGE(bufoff, gbase, voff) do { _Pragma("unroll") for (int _i = 0; _i < 2; ++_i) \
;         __builtin_amdgcn_global_load_lds((const unsigned*)((const char*)(gbase) + (voff)[_i]), (PG8_LAS unsigned*)(lds + (bufoff) + ldsw + _i * 8192), 16, 0, 0); } while (0)
; #define PG8_LDA(dst, b, h) do { _Pragma("unroll") for (int m = 0; m < 4; ++m) _Pragma("unroll") for (int k = 0; k < 2; ++k) dst[m][k] = *(const PG8_LAS bf16x8*)(lds + PG8_SA(b, h) + aoff + m * 2048 + k * 1024); } while (0)
; #define PG8_LDB(dst, b, h) do { _Pragma("unroll") for (int n = 0; n < 2; ++n) _Pragma("unroll") for (int k = 0; k < 2; ++k) dst[n][k] = *(const PG8_LAS bf16x8*)(lds + PG8_SB(b, h) + boff + n * 2048 + k * 1024); } while (0)
; #define PG8_WAIT_V(n) asm volatile("s_waitcnt vmcnt(" #n ")" ::: "memory")
; #define PG8_WAIT_L(n) asm volatile("s_waitcnt lgkmcnt(" #n ")" ::: "memory")
; #define PG8_BAR __builtin_amdgcn_s_barrier()
; #define PG8_SCHED __builtin_amdgcn_sched_barrier(0)
; template <class Epi, class Sched, bool ALIGN_EPI = false, bool SP2 = false>
; __device__ __forceinline__ void gemm_phase(PG8_LAS unsigned char* lds, const Gemm g, const Sched& S, const Epi& E) {
;     ...
;         const bool has_next = S.next(ui + 1, nxt);
;         const char* nA = has_next ? (const char*)g.A + (size_t)nxt.pm * tstep : cA; const char* nB = has_next ? (const char*)g.Bt + (size_t)nxt.pn * tstep : cB;
;         for (int t = 0; t < nt; t += 2) {
;             const bool last = (t == nt - 2);
;             const char* a1 = cA + (size_t)(t + 1) * kstep;
;             const char* a2 = last ? nA : cA + (size_t)(t + 2) * kstep; const char* b2 = last ? nB : cB + (size_t)(t + 2) * kstep;
;             const char* a3 = a2 + kstep; const char* b3 = b2 + kstep;
;             if (last && has_next) S.a_ready(nxt);
;             if constexpr (SP2) {
;             PG8_LDB(B0, 0, 0); PG8_LDB(B1, 0, 1); PG8_SCHED; PG8_LDA(At, 0, 0); PG8_STAGE(PG8_SA(1, 1), a1 + hstep, voffA);
;             PG8_WAIT_V(8); PG8_WAIT_L(0); PG8_BAR; PG8_MMA(0, 0, At, B0); PG8_MMA(0, 1, At, B1); PG8_BAR; PG8_SCHED;
;             PG8_LDA(At, 0, 1); PG8_STAGE(PG8_SB(0, 0), b2, voffB); PG8_STAGE(PG8_SB(0, 1), b2 + hstep, voffB); PG8_STAGE(PG8_SA(0, 0), a2, voffA);
;             PG8_WAIT_V(8); PG8_WAIT_L(0); PG8_BAR; PG8_MMA(1, 0, At, B0); PG8_MMA(1, 1, At, B1); PG8_BAR; PG8_SCHED;
.LBB0_1061:
	s_ashr_i32 s23, s22, 31
	s_lshl_b64 s[24:25], s[22:23], 19
	s_add_u32 s24, s42, s24
	s_addc_u32 s25, s43, s25
	s_and_b64 s[26:27], s[6:7], exec
	s_cselect_b32 s23, s25, s35
	s_cselect_b32 s29, s24, s34
	s_ashr_i32 s21, s20, 31
	s_lshl_b64 s[26:27], s[20:21], 19
	s_add_u32 s26, s40, s26
	s_addc_u32 s27, s41, s27
	s_and_b64 s[38:39], s[6:7], exec
	s_cselect_b32 s21, s27, s37
	s_cselect_b32 s31, s26, s36
	s_add_u32 s34, s34, 0x40080
	s_addc_u32 s35, s35, 0
	s_add_u32 s56, s36, 0x100
	s_addc_u32 s57, s37, 0
	s_mov_b32 s58, -2
	s_waitcnt lgkmcnt(0)
	s_add_u32 s36, s34, 0xfffc0080
	s_addc_u32 s37, s35, -1
	s_add_i32 s59, 0, 0x10000
	s_cmp_eq_u32 s58, 12
	s_cselect_b32 s39, s23, s37
	s_cselect_b32 s38, s29, s36
	s_cselect_b32 s37, s21, s57
	s_cselect_b32 s36, s31, s56
	s_add_i32 s62, 0, 0x14000
	v_add_u32_e32 v142, s59, v179
	v_add_u32_e32 v170, s62, v179
	ds_read_b128 v[130:133], v142
	ds_read_b128 v[134:137], v142 offset:1024
	ds_read_b128 v[138:141], v142 offset:2048
	ds_read_b128 v[142:145], v142 offset:3072
	ds_read_b128 v[146:149], v170
	ds_read_b128 v[150:153], v170 offset:1024
	ds_read_b128 v[166:169], v170 offset:2048
	ds_read_b128 v[170:173], v170 offset:3072
	v_lshl_add_u64 v[212:213], s[34:35], 0, v[162:163]
	s_add_i32 m0, s46, 0xc000
	ds_read_b128 v[174:177], v187
	ds_read_b128 v[180:183], v187 offset:1024
	ds_read_b128 v[188:191], v187 offset:2048
	ds_read_b128 v[192:195], v187 offset:3072
	ds_read_b128 v[196:199], v187 offset:4096
	ds_read_b128 v[200:203], v187 offset:5120
	ds_read_b128 v[204:207], v187 offset:6144
	ds_read_b128 v[208:211], v187 offset:7168
	global_load_lds_dwordx4 v[212:213], off
	v_lshl_add_u64 v[212:213], s[34:35], 0, v[164:165]
	s_add_i32 m0, s46, 0xe000
	s_nop 0
	global_load_lds_dwordx4 v[212:213], off
	s_waitcnt vmcnt(8) lgkmcnt(0)
	s_barrier
	s_setprio 1
	v_mfma_f32_16x16x32_bf16 v[126:129], v[130:133], v[174:177], 0
	v_mfma_f32_16x16x32_bf16 v[122:125], v[138:141], v[174:177], 0
	v_mfma_f32_16x16x32_bf16 v[110:113], v[130:133], v[188:191], 0
	v_mfma_f32_16x16x32_bf16 v[106:109], v[138:141], v[188:191], 0
	v_mfma_f32_16x16x32_bf16 v[94:97], v[130:133], v[196:199], 0
	v_mfma_f32_16x16x32_bf16 v[90:93], v[138:141], v[196:199], 0
	v_mfma_f32_16x16x32_bf16 v[78:81], v[130:133], v[204:207], 0
	v_mfma_f32_16x16x32_bf16 v[74:77], v[138:141], v[204:207], 0
	v_mfma_f32_16x16x32_bf16 v[126:129], v[134:137], v[180:183], v[126:129]
	v_mfma_f32_16x16x32_bf16 v[122:125], v[142:145], v[180:183], v[122:125]
	v_mfma_f32_16x16x32_bf16 v[110:113], v[134:137], v[192:195], v[110:113]
	v_mfma_f32_16x16x32_bf16 v[106:109], v[142:145], v[192:195], v[106:109]
	v_mfma_f32_16x16x32_bf16 v[94:97], v[134:137], v[200:203], v[94:97]
	v_mfma_f32_16x16x32_bf16 v[90:93], v[142:145], v[200:203], v[90:93]
	v_mfma_f32_16x16x32_bf16 v[78:81], v[134:137], v[208:211], v[78:81]
	v_mfma_f32_16x16x32_bf16 v[74:77], v[142:145], v[208:211], v[74:77]
	v_mfma_f32_16x16x32_bf16 v[118:121], v[146:149], v[174:177], 0
	v_mfma_f32_16x16x32_bf16 v[114:117], v[166:169], v[174:177], 0
	v_mfma_f32_16x16x32_bf16 v[102:105], v[146:149], v[188:191], 0
	v_mfma_f32_16x16x32_bf16 v[98:101], v[166:169], v[188:191], 0
	v_mfma_f32_16x16x32_bf16 v[86:89], v[146:149], v[196:199], 0
	v_mfma_f32_16x16x32_bf16 v[82:85], v[166:169], v[196:199], 0
	v_mfma_f32_16x16x32_bf16 v[70:73], v[146:149], v[204:207], 0
	v_mfma_f32_16x16x32_bf16 v[66:69], v[166:169], v[204:207], 0
	v_mfma_f32_16x16x32_bf16 v[118:121], v[150:153], v[180:183], v[118:121]
	v_mfma_f32_16x16x32_bf16 v[114:117], v[170:173], v[180:183], v[114:117]
	v_mfma_f32_16x16x32_bf16 v[102:105], v[150:153], v[192:195], v[102:105]
	v_mfma_f32_16x16x32_bf16 v[98:101], v[170:173], v[192:195], v[98:101]
	v_mfma_f32_16x16x32_bf16 v[86:89], v[150:153], v[200:203], v[86:89]
	v_mfma_f32_16x16x32_bf16 v[82:85], v[170:173], v[200:203], v[82:85]
	v_mfma_f32_16x16x32_bf16 v[70:73], v[150:153], v[208:211], v[70:73]
	v_mfma_f32_16x16x32_bf16 v[66:69], v[170:173], v[208:211], v[66:69]
	s_setprio 0
	s_barrier
	s_add_i32 s59, s59, s33
	v_lshl_add_u64 v[212:213], s[36:37], 0, v[156:157]
	s_mov_b32 m0, s59
	ds_read_b128 v[174:177], v187 offset:16384
	ds_read_b128 v[180:183], v187 offset:17408
	ds_read_b128 v[188:191], v187 offset:18432
	ds_read_b128 v[192:195], v187 offset:19456
	ds_read_b128 v[196:199], v187 offset:20480
	ds_read_b128 v[200:203], v187 offset:21504
	ds_read_b128 v[204:207], v187 offset:22528
	ds_read_b128 v[208:211], v187 offset:23552
	global_load_lds_dwordx4 v[212:213], off
	s_add_i32 m0, s59, 0x2000
	s_add_u32 s60, s36, 0x40000
	v_lshl_add_u64 v[214:215], s[36:37], 0, v[160:161]
	s_addc_u32 s61, s37, 0
	s_add_i32 s59, s62, s33
	global_load_lds_dwordx4 v[214:215], off
	v_lshl_add_u64 v[216:217], s[60:61], 0, v[156:157]
	s_mov_b32 m0, s59
	v_lshl_add_u64 v[218:219], s[38:39], 0, v[158:159]
	global_load_lds_dwordx4 v[216:217], off
	v_lshl_add_u64 v[216:217], s[60:61], 0, v[160:161]
	s_add_i32 m0, s59, 0x2000
	s_nop 0
	global_load_lds_dwordx4 v[216:217], off
	v_lshl_add_u64 v[216:217], s[38:39], 0, v[154:155]
	s_mov_b32 m0, s46
	s_nop 0
	global_load_lds_dwordx4 v[216:217], off
	s_mov_b32 m0, s47
	s_nop 0
	global_load_lds_dwordx4 v[218:219], off
	s_waitcnt vmcnt(8) lgkmcnt(0)
	s_barrier
; #define PG8_STAGE(bufoff, gbase, voff) do { _Pragma("unroll") for (int _i = 0; _i < 2; ++_i) \
;         __builtin_amdgcn_global_load_lds((const unsigned*)((const char*)(gbase) + (voff)[_i]), (PG8_LAS unsigned*)(lds + (bufoff) + ldsw + _i * 8192), 16, 0, 0); } while (0)
; #define PG8_LDA(dst, b, h) do { _Pragma("unroll") for (int m = 0; m < 4; ++m) _Pragma("unroll") for (int k = 0; k < 2; ++k) dst[m][k] = *(const PG8_LAS bf16x8*)(lds + PG8_SA(b, h) + aoff + m * 2048 + k * 1024); } while (0)
; #define PG8_LDB(dst, b, h) do { _Pragma("unroll") for (int n = 0; n < 2; ++n) _Pragma("unroll") for (int k = 0; k < 2; ++k) dst[n][k] = *(const PG8_LAS bf16x8*)(lds + PG8_SB(b, h) + boff + n * 2048 + k * 1024); } while (0)
; #define PG8_MMA(ai, bj, At, Bt) do { __builtin_amdgcn_s_setprio(1); _Pragma("unroll") for (int m = 0; m < 4; ++m) _Pragma("unroll") for (int n = 0; n < 2; ++n) _Pragma("unroll") for (int k = 0; k < 2; ++k) \
;         acc[ai][bj][m][n] = __builtin_amdgcn_mfma_f32_16x16x32_bf16(Bt[n][k], At[m][k], acc[ai][bj][m][n], 0, 0, 0); __builtin_amdgcn_s_setprio(0); } while (0)
; #define PG8_WAIT_V(n) asm volatile("s_waitcnt vmcnt(" #n ")" ::: "memory")
; #define PG8_WAIT_L(n) asm volatile("s_waitcnt lgkmcnt(" #n ")" ::: "memory")
; #define PG8_BAR __builtin_amdgcn_s_barrier()
; #define PG8_SCHED __builtin_amdgcn_sched_barrier(0)
; template <class Epi, class Sched, bool ALIGN_EPI = false, bool SP2 = false>
; __device__ __forceinline__ void gemm_phase(PG8_LAS unsigned char* lds, const Gemm g, const Sched& S, const Epi& E) {
;     ...
;             PG8_WAIT_V(8); PG8_WAIT_L(0); PG8_BAR; PG8_MMA(1, 0, At, B0); PG8_MMA(1, 1, At, B1); PG8_BAR; PG8_SCHED;
;             PG8_LDB(B0, 1, 0); PG8_LDB(B1, 1, 1); PG8_SCHED; PG8_LDA(At, 1, 0); PG8_STAGE(PG8_SA(0, 1), a2 + hstep, voffA);
;             PG8_WAIT_V(8); PG8_WAIT_L(0); PG8_BAR; PG8_MMA(0, 0, At, B0); PG8_MMA(0, 1, At, B1); PG8_BAR; PG8_SCHED;
	s_setprio 1
	v_mfma_f32_16x16x32_bf16 v[62:65], v[130:133], v[174:177], 0
	v_mfma_f32_16x16x32_bf16 v[58:61], v[138:141], v[174:177], 0
	v_mfma_f32_16x16x32_bf16 v[46:49], v[130:133], v[188:191], 0
	v_mfma_f32_16x16x32_bf16 v[42:45], v[138:141], v[188:191], 0
	v_mfma_f32_16x16x32_bf16 v[30:33], v[130:133], v[196:199], 0
	v_mfma_f32_16x16x32_bf16 v[26:29], v[138:141], v[196:199], 0
	v_mfma_f32_16x16x32_bf16 v[14:17], v[130:133], v[204:207], 0
	v_mfma_f32_16x16x32_bf16 v[10:13], v[138:141], v[204:207], 0
	v_mfma_f32_16x16x32_bf16 v[62:65], v[134:137], v[180:183], v[62:65]
	v_mfma_f32_16x16x32_bf16 v[58:61], v[142:145], v[180:183], v[58:61]
	v_mfma_f32_16x16x32_bf16 v[46:49], v[134:137], v[192:195], v[46:49]
	v_mfma_f32_16x16x32_bf16 v[42:45], v[142:145], v[192:195], v[42:45]
	v_mfma_f32_16x16x32_bf16 v[30:33], v[134:137], v[200:203], v[30:33]
	v_mfma_f32_16x16x32_bf16 v[26:29], v[142:145], v[200:203], v[26:29]
	v_mfma_f32_16x16x32_bf16 v[14:17], v[134:137], v[208:211], v[14:17]
	v_mfma_f32_16x16x32_bf16 v[10:13], v[142:145], v[208:211], v[10:13]
	v_mfma_f32_16x16x32_bf16 v[54:57], v[146:149], v[174:177], 0
	v_mfma_f32_16x16x32_bf16 v[50:53], v[166:169], v[174:177], 0
	v_mfma_f32_16x16x32_bf16 v[38:41], v[146:149], v[188:191], 0
	v_mfma_f32_16x16x32_bf16 v[34:37], v[166:169], v[188:191], 0
	v_mfma_f32_16x16x32_bf16 v[22:25], v[146:149], v[196:199], 0
	v_mfma_f32_16x16x32_bf16 v[18:21], v[166:169], v[196:199], 0
	v_mfma_f32_16x16x32_bf16 v[6:9], v[146:149], v[204:207], 0
	v_mfma_f32_16x16x32_bf16 v[2:5], v[166:169], v[204:207], 0
	v_mfma_f32_16x16x32_bf16 v[54:57], v[150:153], v[180:183], v[54:57]
	v_mfma_f32_16x16x32_bf16 v[50:53], v[170:173], v[180:183], v[50:53]
	v_mfma_f32_16x16x32_bf16 v[38:41], v[150:153], v[192:195], v[38:41]
	v_mfma_f32_16x16x32_bf16 v[34:37], v[170:173], v[192:195], v[34:37]
	v_mfma_f32_16x16x32_bf16 v[22:25], v[150:153], v[200:203], v[22:25]
	v_mfma_f32_16x16x32_bf16 v[18:21], v[170:173], v[200:203], v[18:21]
	v_mfma_f32_16x16x32_bf16 v[6:9], v[150:153], v[208:211], v[6:9]
	v_mfma_f32_16x16x32_bf16 v[2:5], v[170:173], v[208:211], v[2:5]
	s_setprio 0
	s_barrier
	s_add_i32 s59, 0, 0x18000
	s_add_i32 s60, 0, 0x1c000
	v_add_u32_e32 v142, s59, v179
	v_add_u32_e32 v170, s60, v179
	ds_read_b128 v[130:133], v142
	ds_read_b128 v[134:137], v142 offset:1024
	ds_read_b128 v[138:141], v142 offset:2048
	ds_read_b128 v[142:145], v142 offset:3072
	ds_read_b128 v[146:149], v170
	ds_read_b128 v[150:153], v170 offset:1024
	ds_read_b128 v[166:169], v170 offset:2048
	ds_read_b128 v[170:173], v170 offset:3072
	s_add_u32 s38, s38, 0x40000
	s_addc_u32 s39, s39, 0
	s_mov_b32 m0, s48
	v_lshl_add_u64 v[220:221], s[38:39], 0, v[154:155]
	ds_read_b128 v[174:177], v187 offset:32768
	ds_read_b128 v[180:183], v187 offset:33792
	ds_read_b128 v[188:191], v187 offset:34816
	ds_read_b128 v[192:195], v187 offset:35840
	ds_read_b128 v[196:199], v187 offset:36864
	ds_read_b128 v[200:203], v187 offset:37888
	ds_read_b128 v[204:207], v187 offset:38912
	ds_read_b128 v[208:211], v187 offset:39936
	global_load_lds_dwordx4 v[220:221], off
	v_lshl_add_u64 v[220:221], s[38:39], 0, v[158:159]
	s_mov_b32 m0, s49
	s_nop 0
	global_load_lds_dwordx4 v[220:221], off
	s_waitcnt vmcnt(8) lgkmcnt(0)
	s_barrier
	s_setprio 1
	v_mfma_f32_16x16x32_bf16 v[126:129], v[130:133], v[174:177], v[126:129]
	v_mfma_f32_16x16x32_bf16 v[122:125], v[138:141], v[174:177], v[122:125]
	v_mfma_f32_16x16x32_bf16 v[110:113], v[130:133], v[188:191], v[110:113]
	v_mfma_f32_16x16x32_bf16 v[106:109], v[138:141], v[188:191], v[106:109]
	v_mfma_f32_16x16x32_bf16 v[94:97], v[130:133], v[196:199], v[94:97]
	v_mfma_f32_16x16x32_bf16 v[90:93], v[138:141], v[196:199], v[90:93]
	v_mfma_f32_16x16x32_bf16 v[78:81], v[130:133], v[204:207], v[78:81]
	v_mfma_f32_16x16x32_bf16 v[74:77], v[138:141], v[204:207], v[74:77]
	v_mfma_f32_16x16x32_bf16 v[126:129], v[134:137], v[180:183], v[126:129]
	v_mfma_f32_16x16x32_bf16 v[122:125], v[142:145], v[180:183], v[122:125]
	v_mfma_f32_16x16x32_bf16 v[110:113], v[134:137], v[192:195], v[110:113]
	v_mfma_f32_16x16x32_bf16 v[106:109], v[142:145], v[192:195], v[106:109]
	v_mfma_f32_16x16x32_bf16 v[94:97], v[134:137], v[200:203], v[94:97]
	v_mfma_f32_16x16x32_bf16 v[90:93], v[142:145], v[200:203], v[90:93]
	v_mfma_f32_16x16x32_bf16 v[78:81], v[134:137], v[208:211], v[78:81]
	v_mfma_f32_16x16x32_bf16 v[74:77], v[142:145], v[208:211], v[74:77]
	v_mfma_f32_16x16x32_bf16 v[118:121], v[146:149], v[174:177], v[118:121]
	v_mfma_f32_16x16x32_bf16 v[114:117], v[166:169], v[174:177], v[114:117]
	v_mfma_f32_16x16x32_bf16 v[102:105], v[146:149], v[188:191], v[102:105]
	v_mfma_f32_16x16x32_bf16 v[98:101], v[166:169], v[188:191], v[98:101]
	v_mfma_f32_16x16x32_bf16 v[86:89], v[146:149], v[196:199], v[86:89]
	v_mfma_f32_16x16x32_bf16 v[82:85], v[166:169], v[196:199], v[82:85]
	v_mfma_f32_16x16x32_bf16 v[70:73], v[146:149], v[204:207], v[70:73]
	v_mfma_f32_16x16x32_bf16 v[66:69], v[166:169], v[204:207], v[66:69]
	v_mfma_f32_16x16x32_bf16 v[118:121], v[150:153], v[180:183], v[118:121]
	v_mfma_f32_16x16x32_bf16 v[114:117], v[170:173], v[180:183], v[114:117]
	v_mfma_f32_16x16x32_bf16 v[102:105], v[150:153], v[192:195], v[102:105]
	v_mfma_f32_16x16x32_bf16 v[98:101], v[170:173], v[192:195], v[98:101]
	v_mfma_f32_16x16x32_bf16 v[86:89], v[150:153], v[200:203], v[86:89]
	v_mfma_f32_16x16x32_bf16 v[82:85], v[170:173], v[200:203], v[82:85]
	v_mfma_f32_16x16x32_bf16 v[70:73], v[150:153], v[208:211], v[70:73]
	v_mfma_f32_16x16x32_bf16 v[66:69], v[170:173], v[208:211], v[66:69]
	s_setprio 0
	s_barrier
; #define PG8_STAGE(bufoff, gbase, voff) do { _Pragma("unroll") for (int _i = 0; _i < 2; ++_i) \
;         __builtin_amdgcn_global_load_lds((const unsigned*)((const char*)(gbase) + (voff)[_i]), (PG8_LAS unsigned*)(lds + (bufoff) + ldsw + _i * 8192), 16, 0, 0); } while (0)
; #define PG8_LDA(dst, b, h) do { _Pragma("unroll") for (int m = 0; m < 4; ++m) _Pragma("unroll") for (int k = 0; k < 2; ++k) dst[m][k] = *(const PG8_LAS bf16x8*)(lds + PG8_SA(b, h) + aoff + m * 2048 + k * 1024); } while (0)
; #define PG8_LDB(dst, b, h) do { _Pragma("unroll") for (int n = 0; n < 2; ++n) _Pragma("unroll") for (int k = 0; k < 2; ++k) dst[n][k] = *(const PG8_LAS bf16x8*)(lds + PG8_SB(b, h) + boff + n * 2048 + k * 1024); } while (0)
; #define PG8_MMA(ai, bj, At, Bt) do { __builtin_amdgcn_s_setprio(1); _Pragma("unroll") for (int m = 0; m < 4; ++m) _Pragma("unroll") for (int n = 0; n < 2; ++n) _Pragma("unroll") for (int k = 0; k < 2; ++k) \
;         acc[ai][bj][m][n] = __builtin_amdgcn_mfma_f32_16x16x32_bf16(Bt[n][k], At[m][k], acc[ai][bj][m][n], 0, 0, 0); __builtin_amdgcn_s_setprio(0); } while (0)
; #define PG8_WAIT_V(n) asm volatile("s_waitcnt vmcnt(" #n ")" ::: "memory")
; #define PG8_WAIT_L(n) asm volatile("s_waitcnt lgkmcnt(" #n ")" ::: "memory")
; #define PG8_BAR __builtin_amdgcn_s_barrier()
; #define PG8_SCHED __builtin_amdgcn_sched_barrier(0)
; template <class Epi, class Sched, bool ALIGN_EPI = false, bool SP2 = false>
; __device__ __forceinline__ void gemm_phase(PG8_LAS unsigned char* lds, const Gemm g, const Sched& S, const Epi& E) {
;     ...
;             PG8_LDB(B0, 0, 0); PG8_LDB(B1, 0, 1); PG8_SCHED; PG8_LDA(At, 0, 0); PG8_STAGE(PG8_SA(1, 1), a1 + hstep, voffA);
;             PG8_WAIT_V(8); PG8_WAIT_L(0); PG8_BAR; PG8_MMA(0, 0, At, B0); PG8_MMA(0, 1, At, B1); PG8_BAR; PG8_SCHED;
;     ...
;             PG8_LDA(At, 1, 1); PG8_STAGE(PG8_SB(1, 0), b3, voffB); PG8_STAGE(PG8_SB(1, 1), b3 + hstep, voffB); PG8_STAGE(PG8_SA(1, 0), a3, voffA);
;             PG8_WAIT_V(8); PG8_WAIT_L(0); PG8_BAR; PG8_MMA(1, 0, At, B0); PG8_MMA(1, 1, At, B1); PG8_BAR; PG8_SCHED;
	s_add_i32 s38, s59, s33
	v_lshl_add_u64 v[212:213], v[212:213], 0, s[80:81]
	s_mov_b32 m0, s38
	ds_read_b128 v[174:177], v187 offset:49152
	ds_read_b128 v[180:183], v187 offset:50176
	ds_read_b128 v[188:191], v187 offset:51200
	ds_read_b128 v[192:195], v187 offset:52224
	ds_read_b128 v[196:199], v187 offset:53248
	ds_read_b128 v[200:203], v187 offset:54272
	ds_read_b128 v[204:207], v187 offset:55296
	ds_read_b128 v[208:211], v187 offset:56320
	global_load_lds_dwordx4 v[212:213], off
	s_add_i32 m0, s38, 0x2000
	s_add_u32 s36, s36, 0x40080
	v_lshl_add_u64 v[212:213], v[214:215], 0, s[80:81]
	s_addc_u32 s37, s37, 0
	s_add_i32 s38, s60, s33
	global_load_lds_dwordx4 v[212:213], off
	v_lshl_add_u64 v[212:213], s[36:37], 0, v[156:157]
	s_mov_b32 m0, s38
	s_nop 0
	global_load_lds_dwordx4 v[212:213], off
	v_lshl_add_u64 v[212:213], s[36:37], 0, v[160:161]
	s_add_i32 m0, s38, 0x2000
	s_nop 0
	global_load_lds_dwordx4 v[212:213], off
	v_lshl_add_u64 v[212:213], v[216:217], 0, s[80:81]
	s_mov_b32 m0, s51
	s_nop 0
	global_load_lds_dwordx4 v[212:213], off
	v_lshl_add_u64 v[212:213], v[218:219], 0, s[80:81]
	s_mov_b32 m0, s52
	s_nop 0
	global_load_lds_dwordx4 v[212:213], off
	s_waitcnt vmcnt(8) lgkmcnt(0)
	s_barrier
	s_setprio 1
	v_mfma_f32_16x16x32_bf16 v[62:65], v[130:133], v[174:177], v[62:65]
	v_mfma_f32_16x16x32_bf16 v[58:61], v[138:141], v[174:177], v[58:61]
	v_mfma_f32_16x16x32_bf16 v[46:49], v[130:133], v[188:191], v[46:49]
	v_mfma_f32_16x16x32_bf16 v[42:45], v[138:141], v[188:191], v[42:45]
	v_mfma_f32_16x16x32_bf16 v[30:33], v[130:133], v[196:199], v[30:33]
	v_mfma_f32_16x16x32_bf16 v[26:29], v[138:141], v[196:199], v[26:29]
	v_mfma_f32_16x16x32_bf16 v[14:17], v[130:133], v[204:207], v[14:17]
	v_mfma_f32_16x16x32_bf16 v[10:13], v[138:141], v[204:207], v[10:13]
	v_mfma_f32_16x16x32_bf16 v[62:65], v[134:137], v[180:183], v[62:65]
	v_mfma_f32_16x16x32_bf16 v[58:61], v[142:145], v[180:183], v[58:61]
	v_mfma_f32_16x16x32_bf16 v[46:49], v[134:137], v[192:195], v[46:49]
	v_mfma_f32_16x16x32_bf16 v[42:45], v[142:145], v[192:195], v[42:45]
	v_mfma_f32_16x16x32_bf16 v[30:33], v[134:137], v[200:203], v[30:33]
	v_mfma_f32_16x16x32_bf16 v[26:29], v[142:145], v[200:203], v[26:29]
	v_mfma_f32_16x16x32_bf16 v[14:17], v[134:137], v[208:211], v[14:17]
	v_mfma_f32_16x16x32_bf16 v[10:13], v[142:145], v[208:211], v[10:13]
	v_mfma_f32_16x16x32_bf16 v[54:57], v[146:149], v[174:177], v[54:57]
	v_mfma_f32_16x16x32_bf16 v[50:53], v[166:169], v[174:177], v[50:53]
	v_mfma_f32_16x16x32_bf16 v[38:41], v[146:149], v[188:191], v[38:41]
	v_mfma_f32_16x16x32_bf16 v[34:37], v[166:169], v[188:191], v[34:37]
	v_mfma_f32_16x16x32_bf16 v[22:25], v[146:149], v[196:199], v[22:25]
	v_mfma_f32_16x16x32_bf16 v[18:21], v[166:169], v[196:199], v[18:21]
	v_mfma_f32_16x16x32_bf16 v[6:9], v[146:149], v[204:207], v[6:9]
	v_mfma_f32_16x16x32_bf16 v[2:5], v[166:169], v[204:207], v[2:5]
	v_mfma_f32_16x16x32_bf16 v[54:57], v[150:153], v[180:183], v[54:57]
	v_mfma_f32_16x16x32_bf16 v[50:53], v[170:173], v[180:183], v[50:53]
	v_mfma_f32_16x16x32_bf16 v[38:41], v[150:153], v[192:195], v[38:41]
	v_mfma_f32_16x16x32_bf16 v[34:37], v[170:173], v[192:195], v[34:37]
	v_mfma_f32_16x16x32_bf16 v[22:25], v[150:153], v[200:203], v[22:25]
	v_mfma_f32_16x16x32_bf16 v[18:21], v[170:173], v[200:203], v[18:21]
	v_mfma_f32_16x16x32_bf16 v[6:9], v[150:153], v[208:211], v[6:9]
	v_mfma_f32_16x16x32_bf16 v[2:5], v[170:173], v[208:211], v[2:5]
	s_setprio 0
	s_barrier
	s_add_i32 s58, s58, 2
	s_add_u32 s34, s34, 0x100
	s_addc_u32 s35, s35, 0
	s_add_u32 s56, s56, 0x100
	s_addc_u32 s57, s57, 0
	s_cmp_gt_u32 s58, 13
	s_branch .LBB0_1062
.LBB0_1062:
	s_add_u32 s36, s34, 0xfffc0080
	s_addc_u32 s37, s35, -1
	s_add_i32 s59, 0, 0x10000
	s_cmp_eq_u32 s58, 12
	s_cselect_b32 s39, s23, s37
	s_cselect_b32 s38, s29, s36
	s_cselect_b32 s37, s21, s57
	s_cselect_b32 s36, s31, s56
	s_add_i32 s62, 0, 0x14000
	v_add_u32_e32 v142, s59, v179
	v_add_u32_e32 v170, s62, v179
	ds_read_b128 v[130:133], v142
	ds_read_b128 v[134:137], v142 offset:1024
	ds_read_b128 v[138:141], v142 offset:2048
	ds_read_b128 v[142:145], v142 offset:3072
	ds_read_b128 v[146:149], v170
	ds_read_b128 v[150:153], v170 offset:1024
	ds_read_b128 v[166:169], v170 offset:2048
	ds_read_b128 v[170:173], v170 offset:3072
	v_lshl_add_u64 v[212:213], s[34:35], 0, v[162:163]
	s_add_i32 m0, s46, 0xc000
	ds_read_b128 v[174:177], v187
	ds_read_b128 v[180:183], v187 offset:1024
	ds_read_b128 v[188:191], v187 offset:2048
	ds_read_b128 v[192:195], v187 offset:3072
	ds_read_b128 v[196:199], v187 offset:4096
	ds_read_b128 v[200:203], v187 offset:5120
	ds_read_b128 v[204:207], v187 offset:6144
	ds_read_b128 v[208:211], v187 offset:7168
	global_load_lds_dwordx4 v[212:213], off
	v_lshl_add_u64 v[212:213], s[34:35], 0, v[164:165]
	s_add_i32 m0, s46, 0xe000
	s_nop 0
	global_load_lds_dwordx4 v[212:213], off
	s_waitcnt vmcnt(8) lgkmcnt(0)
	s_barrier
; #define PG8_STAGE(bufoff, gbase, voff) do { _Pragma("unroll") for (int _i = 0; _i < 2; ++_i) \
;         __builtin_amdgcn_global_load_lds((const unsigned*)((const char*)(gbase) + (voff)[_i]), (PG8_LAS unsigned*)(lds + (bufoff) + ldsw + _i * 8192), 16, 0, 0); } while (0)
; #define PG8_LDA(dst, b, h) do { _Pragma("unroll") for (int m = 0; m < 4; ++m) _Pragma("unroll") for (int k = 0; k < 2; ++k) dst[m][k] = *(const PG8_LAS bf16x8*)(lds + PG8_SA(b, h) + aoff + m * 2048 + k * 1024); } while (0)
; #define PG8_MMA(ai, bj, At, Bt) do { __builtin_amdgcn_s_setprio(1); _Pragma("unroll") for (int m = 0; m < 4; ++m) _Pragma("unroll") for (int n = 0; n < 2; ++n) _Pragma("unroll") for (int k = 0; k < 2; ++k) \
;         acc[ai][bj][m][n] = __builtin_amdgcn_mfma_f32_16x16x32_bf16(Bt[n][k], At[m][k], acc[ai][bj][m][n], 0, 0, 0); __builtin_amdgcn_s_setprio(0); } while (0)
; #define PG8_WAIT_V(n) asm volatile("s_waitcnt vmcnt(" #n ")" ::: "memory")
; #define PG8_WAIT_L(n) asm volatile("s_waitcnt lgkmcnt(" #n ")" ::: "memory")
; #define PG8_BAR __builtin_amdgcn_s_barrier()
; #define PG8_SCHED __builtin_amdgcn_sched_barrier(0)
; template <class Epi, class Sched, bool ALIGN_EPI = false, bool SP2 = false>
; __device__ __forceinline__ void gemm_phase(PG8_LAS unsigned char* lds, const Gemm g, const Sched& S, const Epi& E) {
;     ...
;             PG8_WAIT_V(8); PG8_WAIT_L(0); PG8_BAR; PG8_MMA(0, 0, At, B0); PG8_MMA(0, 1, At, B1); PG8_BAR; PG8_SCHED;
;             PG8_LDA(At, 0, 1); PG8_STAGE(PG8_SB(0, 0), b2, voffB); PG8_STAGE(PG8_SB(0, 1), b2 + hstep, voffB); PG8_STAGE(PG8_SA(0, 0), a2, voffA);
;             PG8_WAIT_V(8); PG8_WAIT_L(0); PG8_BAR; PG8_MMA(1, 0, At, B0); PG8_MMA(1, 1, At, B1); PG8_BAR; PG8_SCHED;
	s_setprio 1
	v_mfma_f32_16x16x32_bf16 v[126:129], v[130:133], v[174:177], v[126:129]
	v_mfma_f32_16x16x32_bf16 v[122:125], v[138:141], v[174:177], v[122:125]
	v_mfma_f32_16x16x32_bf16 v[110:113], v[130:133], v[188:191], v[110:113]
	v_mfma_f32_16x16x32_bf16 v[106:109], v[138:141], v[188:191], v[106:109]
	v_mfma_f32_16x16x32_bf16 v[94:97], v[130:133], v[196:199], v[94:97]
	v_mfma_f32_16x16x32_bf16 v[90:93], v[138:141], v[196:199], v[90:93]
	v_mfma_f32_16x16x32_bf16 v[78:81], v[130:133], v[204:207], v[78:81]
	v_mfma_f32_16x16x32_bf16 v[74:77], v[138:141], v[204:207], v[74:77]
	v_mfma_f32_16x16x32_bf16 v[126:129], v[134:137], v[180:183], v[126:129]
	v_mfma_f32_16x16x32_bf16 v[122:125], v[142:145], v[180:183], v[122:125]
	v_mfma_f32_16x16x32_bf16 v[110:113], v[134:137], v[192:195], v[110:113]
	v_mfma_f32_16x16x32_bf16 v[106:109], v[142:145], v[192:195], v[106:109]
	v_mfma_f32_16x16x32_bf16 v[94:97], v[134:137], v[200:203], v[94:97]
	v_mfma_f32_16x16x32_bf16 v[90:93], v[142:145], v[200:203], v[90:93]
	v_mfma_f32_16x16x32_bf16 v[78:81], v[134:137], v[208:211], v[78:81]
	v_mfma_f32_16x16x32_bf16 v[74:77], v[142:145], v[208:211], v[74:77]
	v_mfma_f32_16x16x32_bf16 v[118:121], v[146:149], v[174:177], v[118:121]
	v_mfma_f32_16x16x32_bf16 v[114:117], v[166:169], v[174:177], v[114:117]
	v_mfma_f32_16x16x32_bf16 v[102:105], v[146:149], v[188:191], v[102:105]
	v_mfma_f32_16x16x32_bf16 v[98:101], v[166:169], v[188:191], v[98:101]
	v_mfma_f32_16x16x32_bf16 v[86:89], v[146:149], v[196:199], v[86:89]
	v_mfma_f32_16x16x32_bf16 v[82:85], v[166:169], v[196:199], v[82:85]
	v_mfma_f32_16x16x32_bf16 v[70:73], v[146:149], v[204:207], v[70:73]
	v_mfma_f32_16x16x32_bf16 v[66:69], v[166:169], v[204:207], v[66:69]
	v_mfma_f32_16x16x32_bf16 v[118:121], v[150:153], v[180:183], v[118:121]
	v_mfma_f32_16x16x32_bf16 v[114:117], v[170:173], v[180:183], v[114:117]
	v_mfma_f32_16x16x32_bf16 v[102:105], v[150:153], v[192:195], v[102:105]
	v_mfma_f32_16x16x32_bf16 v[98:101], v[170:173], v[192:195], v[98:101]
	v_mfma_f32_16x16x32_bf16 v[86:89], v[150:153], v[200:203], v[86:89]
	v_mfma_f32_16x16x32_bf16 v[82:85], v[170:173], v[200:203], v[82:85]
	v_mfma_f32_16x16x32_bf16 v[70:73], v[150:153], v[208:211], v[70:73]
	v_mfma_f32_16x16x32_bf16 v[66:69], v[170:173], v[208:211], v[66:69]
	s_setprio 0
	s_barrier
	s_add_i32 s59, s59, s33
	v_lshl_add_u64 v[212:213], s[36:37], 0, v[156:157]
	s_mov_b32 m0, s59
	ds_read_b128 v[174:177], v187 offset:16384
	ds_read_b128 v[180:183], v187 offset:17408
	ds_read_b128 v[188:191], v187 offset:18432
	ds_read_b128 v[192:195], v187 offset:19456
	ds_read_b128 v[196:199], v187 offset:20480
	ds_read_b128 v[200:203], v187 offset:21504
	ds_read_b128 v[204:207], v187 offset:22528
	ds_read_b128 v[208:211], v187 offset:23552
	global_load_lds_dwordx4 v[212:213], off
	s_add_i32 m0, s59, 0x2000
	s_add_u32 s60, s36, 0x40000
	v_lshl_add_u64 v[214:215], s[36:37], 0, v[160:161]
	s_addc_u32 s61, s37, 0
	s_add_i32 s59, s62, s33
	global_load_lds_dwordx4 v[214:215], off
	v_lshl_add_u64 v[216:217], s[60:61], 0, v[156:157]
	s_mov_b32 m0, s59
	v_lshl_add_u64 v[218:219], s[38:39], 0, v[158:159]
	global_load_lds_dwordx4 v[216:217], off
	v_lshl_add_u64 v[216:217], s[60:61], 0, v[160:161]
	s_add_i32 m0, s59, 0x2000
	s_nop 0
	global_load_lds_dwordx4 v[216:217], off
	v_lshl_add_u64 v[216:217], s[38:39], 0, v[154:155]
	s_mov_b32 m0, s46
	s_nop 0
	global_load_lds_dwordx4 v[216:217], off
	s_mov_b32 m0, s47
	s_nop 0
	global_load_lds_dwordx4 v[218:219], off
	s_waitcnt vmcnt(8) lgkmcnt(0)
	s_barrier
	s_setprio 1
	v_mfma_f32_16x16x32_bf16 v[62:65], v[130:133], v[174:177], v[62:65]
	v_mfma_f32_16x16x32_bf16 v[58:61], v[138:141], v[174:177], v[58:61]
	v_mfma_f32_16x16x32_bf16 v[46:49], v[130:133], v[188:191], v[46:49]
	v_mfma_f32_16x16x32_bf16 v[42:45], v[138:141], v[188:191], v[42:45]
	v_mfma_f32_16x16x32_bf16 v[30:33], v[130:133], v[196:199], v[30:33]
	v_mfma_f32_16x16x32_bf16 v[26:29], v[138:141], v[196:199], v[26:29]
	v_mfma_f32_16x16x32_bf16 v[14:17], v[130:133], v[204:207], v[14:17]
	v_mfma_f32_16x16x32_bf16 v[10:13], v[138:141], v[204:207], v[10:13]
	v_mfma_f32_16x16x32_bf16 v[62:65], v[134:137], v[180:183], v[62:65]
	v_mfma_f32_16x16x32_bf16 v[58:61], v[142:145], v[180:183], v[58:61]
	v_mfma_f32_16x16x32_bf16 v[46:49], v[134:137], v[192:195], v[46:49]
	v_mfma_f32_16x16x32_bf16 v[42:45], v[142:145], v[192:195], v[42:45]
	v_mfma_f32_16x16x32_bf16 v[30:33], v[134:137], v[200:203], v[30:33]
	v_mfma_f32_16x16x32_bf16 v[26:29], v[142:145], v[200:203], v[26:29]
	v_mfma_f32_16x16x32_bf16 v[14:17], v[134:137], v[208:211], v[14:17]
	v_mfma_f32_16x16x32_bf16 v[10:13], v[142:145], v[208:211], v[10:13]
	v_mfma_f32_16x16x32_bf16 v[54:57], v[146:149], v[174:177], v[54:57]
	v_mfma_f32_16x16x32_bf16 v[50:53], v[166:169], v[174:177], v[50:53]
	v_mfma_f32_16x16x32_bf16 v[38:41], v[146:149], v[188:191], v[38:41]
	v_mfma_f32_16x16x32_bf16 v[34:37], v[166:169], v[188:191], v[34:37]
	v_mfma_f32_16x16x32_bf16 v[22:25], v[146:149], v[196:199], v[22:25]
	v_mfma_f32_16x16x32_bf16 v[18:21], v[166:169], v[196:199], v[18:21]
	v_mfma_f32_16x16x32_bf16 v[6:9], v[146:149], v[204:207], v[6:9]
	v_mfma_f32_16x16x32_bf16 v[2:5], v[166:169], v[204:207], v[2:5]
	v_mfma_f32_16x16x32_bf16 v[54:57], v[150:153], v[180:183], v[54:57]
	v_mfma_f32_16x16x32_bf16 v[50:53], v[170:173], v[180:183], v[50:53]
	v_mfma_f32_16x16x32_bf16 v[38:41], v[150:153], v[192:195], v[38:41]
	v_mfma_f32_16x16x32_bf16 v[34:37], v[170:173], v[192:195], v[34:37]
	v_mfma_f32_16x16x32_bf16 v[22:25], v[150:153], v[200:203], v[22:25]
	v_mfma_f32_16x16x32_bf16 v[18:21], v[170:173], v[200:203], v[18:21]
	v_mfma_f32_16x16x32_bf16 v[6:9], v[150:153], v[208:211], v[6:9]
	v_mfma_f32_16x16x32_bf16 v[2:5], v[170:173], v[208:211], v[2:5]
	s_setprio 0
	s_barrier
; #define PG8_STAGE(bufoff, gbase, voff) do { _Pragma("unroll") for (int _i = 0; _i < 2; ++_i) \
;         __builtin_amdgcn_global_load_lds((const unsigned*)((const char*)(gbase) + (voff)[_i]), (PG8_LAS unsigned*)(lds + (bufoff) + ldsw + _i * 8192), 16, 0, 0); } while (0)
; #define PG8_LDA(dst, b, h) do { _Pragma("unroll") for (int m = 0; m < 4; ++m) _Pragma("unroll") for (int k = 0; k < 2; ++k) dst[m][k] = *(const PG8_LAS bf16x8*)(lds + PG8_SA(b, h) + aoff + m * 2048 + k * 1024); } while (0)
; #define PG8_LDB(dst, b, h) do { _Pragma("unroll") for (int n = 0; n < 2; ++n) _Pragma("unroll") for (int k = 0; k < 2; ++k) dst[n][k] = *(const PG8_LAS bf16x8*)(lds + PG8_SB(b, h) + boff + n * 2048 + k * 1024); } while (0)
; #define PG8_MMA(ai, bj, At, Bt) do { __builtin_amdgcn_s_setprio(1); _Pragma("unroll") for (int m = 0; m < 4; ++m) _Pragma("unroll") for (int n = 0; n < 2; ++n) _Pragma("unroll") for (int k = 0; k < 2; ++k) \
;         acc[ai][bj][m][n] = __builtin_amdgcn_mfma_f32_16x16x32_bf16(Bt[n][k], At[m][k], acc[ai][bj][m][n], 0, 0, 0); __builtin_amdgcn_s_setprio(0); } while (0)
; #define PG8_WAIT_V(n) asm volatile("s_waitcnt vmcnt(" #n ")" ::: "memory")
; #define PG8_WAIT_L(n) asm volatile("s_waitcnt lgkmcnt(" #n ")" ::: "memory")
; #define PG8_BAR __builtin_amdgcn_s_barrier()
; #define PG8_SCHED __builtin_amdgcn_sched_barrier(0)
; template <class Epi, class Sched, bool ALIGN_EPI = false, bool SP2 = false>
; __device__ __forceinline__ void gemm_phase(PG8_LAS unsigned char* lds, const Gemm g, const Sched& S, const Epi& E) {
;     ...
;             PG8_LDB(B0, 1, 0); PG8_LDB(B1, 1, 1); PG8_SCHED; PG8_LDA(At, 1, 0); PG8_STAGE(PG8_SA(0, 1), a2 + hstep, voffA);
;             PG8_WAIT_V(8); PG8_WAIT_L(0); PG8_BAR; PG8_MMA(0, 0, At, B0); PG8_MMA(0, 1, At, B1); PG8_BAR; PG8_SCHED;
	s_add_i32 s59, 0, 0x18000
	s_add_i32 s60, 0, 0x1c000
	v_add_u32_e32 v142, s59, v179
	v_add_u32_e32 v170, s60, v179
	ds_read_b128 v[130:133], v142
	ds_read_b128 v[134:137], v142 offset:1024
	ds_read_b128 v[138:141], v142 offset:2048
	ds_read_b128 v[142:145], v142 offset:3072
	ds_read_b128 v[146:149], v170
	ds_read_b128 v[150:153], v170 offset:1024
	ds_read_b128 v[166:169], v170 offset:2048
	ds_read_b128 v[170:173], v170 offset:3072
	s_add_u32 s38, s38, 0x40000
	s_addc_u32 s39, s39, 0
	s_mov_b32 m0, s48
	v_lshl_add_u64 v[220:221], s[38:39], 0, v[154:155]
	ds_read_b128 v[174:177], v187 offset:32768
	ds_read_b128 v[180:183], v187 offset:33792
	ds_read_b128 v[188:191], v187 offset:34816
	ds_read_b128 v[192:195], v187 offset:35840
	ds_read_b128 v[196:199], v187 offset:36864
	ds_read_b128 v[200:203], v187 offset:37888
	ds_read_b128 v[204:207], v187 offset:38912
	ds_read_b128 v[208:211], v187 offset:39936
	global_load_lds_dwordx4 v[220:221], off
	v_lshl_add_u64 v[220:221], s[38:39], 0, v[158:159]
	s_mov_b32 m0, s49
	s_nop 0
	global_load_lds_dwordx4 v[220:221], off
	s_waitcnt vmcnt(8) lgkmcnt(0)
	s_barrier
	s_setprio 1
	v_mfma_f32_16x16x32_bf16 v[126:129], v[130:133], v[174:177], v[126:129]
	v_mfma_f32_16x16x32_bf16 v[122:125], v[138:141], v[174:177], v[122:125]
	v_mfma_f32_16x16x32_bf16 v[110:113], v[130:133], v[188:191], v[110:113]
	v_mfma_f32_16x16x32_bf16 v[106:109], v[138:141], v[188:191], v[106:109]
	v_mfma_f32_16x16x32_bf16 v[94:97], v[130:133], v[196:199], v[94:97]
	v_mfma_f32_16x16x32_bf16 v[90:93], v[138:141], v[196:199], v[90:93]
	v_mfma_f32_16x16x32_bf16 v[78:81], v[130:133], v[204:207], v[78:81]
	v_mfma_f32_16x16x32_bf16 v[74:77], v[138:141], v[204:207], v[74:77]
	v_mfma_f32_16x16x32_bf16 v[126:129], v[134:137], v[180:183], v[126:129]
	v_mfma_f32_16x16x32_bf16 v[122:125], v[142:145], v[180:183], v[122:125]
	v_mfma_f32_16x16x32_bf16 v[110:113], v[134:137], v[192:195], v[110:113]
	v_mfma_f32_16x16x32_bf16 v[106:109], v[142:145], v[192:195], v[106:109]
	v_mfma_f32_16x16x32_bf16 v[94:97], v[134:137], v[200:203], v[94:97]
	v_mfma_f32_16x16x32_bf16 v[90:93], v[142:145], v[200:203], v[90:93]
	v_mfma_f32_16x16x32_bf16 v[78:81], v[134:137], v[208:211], v[78:81]
	v_mfma_f32_16x16x32_bf16 v[74:77], v[142:145], v[208:211], v[74:77]
	v_mfma_f32_16x16x32_bf16 v[118:121], v[146:149], v[174:177], v[118:121]
	v_mfma_f32_16x16x32_bf16 v[114:117], v[166:169], v[174:177], v[114:117]
	v_mfma_f32_16x16x32_bf16 v[102:105], v[146:149], v[188:191], v[102:105]
	v_mfma_f32_16x16x32_bf16 v[98:101], v[166:169], v[188:191], v[98:101]
	v_mfma_f32_16x16x32_bf16 v[86:89], v[146:149], v[196:199], v[86:89]
	v_mfma_f32_16x16x32_bf16 v[82:85], v[166:169], v[196:199], v[82:85]
	v_mfma_f32_16x16x32_bf16 v[70:73], v[146:149], v[204:207], v[70:73]
	v_mfma_f32_16x16x32_bf16 v[66:69], v[166:169], v[204:207], v[66:69]
	v_mfma_f32_16x16x32_bf16 v[118:121], v[150:153], v[180:183], v[118:121]
	v_mfma_f32_16x16x32_bf16 v[114:117], v[170:173], v[180:183], v[114:117]
	v_mfma_f32_16x16x32_bf16 v[102:105], v[150:153], v[192:195], v[102:105]
	v_mfma_f32_16x16x32_bf16 v[98:101], v[170:173], v[192:195], v[98:101]
	v_mfma_f32_16x16x32_bf16 v[86:89], v[150:153], v[200:203], v[86:89]
	v_mfma_f32_16x16x32_bf16 v[82:85], v[170:173], v[200:203], v[82:85]
	v_mfma_f32_16x16x32_bf16 v[70:73], v[150:153], v[208:211], v[70:73]
	v_mfma_f32_16x16x32_bf16 v[66:69], v[170:173], v[208:211], v[66:69]
	s_setprio 0
	s_barrier
; #define PG8_STAGE(bufoff, gbase, voff) do { _Pragma("unroll") for (int _i = 0; _i < 2; ++_i) \
;         __builtin_amdgcn_global_load_lds((const unsigned*)((const char*)(gbase) + (voff)[_i]), (PG8_LAS unsigned*)(lds + (bufoff) + ldsw + _i * 8192), 16, 0, 0); } while (0)
; #define PG8_LDA(dst, b, h) do { _Pragma("unroll") for (int m = 0; m < 4; ++m) _Pragma("unroll") for (int k = 0; k < 2; ++k) dst[m][k] = *(const PG8_LAS bf16x8*)(lds + PG8_SA(b, h) + aoff + m * 2048 + k * 1024); } while (0)
; #define PG8_MMA(ai, bj, At, Bt) do { __builtin_amdgcn_s_setprio(1); _Pragma("unroll") for (int m = 0; m < 4; ++m) _Pragma("unroll") for (int n = 0; n < 2; ++n) _Pragma("unroll") for (int k = 0; k < 2; ++k) \
;         acc[ai][bj][m][n] = __builtin_amdgcn_mfma_f32_16x16x32_bf16(Bt[n][k], At[m][k], acc[ai][bj][m][n], 0, 0, 0); __builtin_amdgcn_s_setprio(0); } while (0)
; #define PG8_WAIT_V(n) asm volatile("s_waitcnt vmcnt(" #n ")" ::: "memory")
; #define PG8_WAIT_L(n) asm volatile("s_waitcnt lgkmcnt(" #n ")" ::: "memory")
; #define PG8_BAR __builtin_amdgcn_s_barrier()
; #define PG8_SCHED __builtin_amdgcn_sched_barrier(0)
; template <class Epi, class Sched, bool ALIGN_EPI = false, bool SP2 = false>
; __device__ __forceinline__ void gemm_phase(PG8_LAS unsigned char* lds, const Gemm g, const Sched& S, const Epi& E) {
;     ...
;             PG8_LDA(At, 1, 1); PG8_STAGE(PG8_SB(1, 0), b3, voffB); PG8_STAGE(PG8_SB(1, 1), b3 + hstep, voffB); PG8_STAGE(PG8_SA(1, 0), a3, voffA);
;             PG8_WAIT_V(8); PG8_WAIT_L(0); PG8_BAR; PG8_MMA(1, 0, At, B0); PG8_MMA(1, 1, At, B1); PG8_BAR; PG8_SCHED;
;     ...
;         if constexpr (ALIGN_EPI) { if (wr == 0) PG8_BAR; }
	s_add_i32 s38, s59, s33
	v_lshl_add_u64 v[212:213], v[212:213], 0, s[80:81]
	s_mov_b32 m0, s38
	ds_read_b128 v[174:177], v187 offset:49152
	ds_read_b128 v[180:183], v187 offset:50176
	ds_read_b128 v[188:191], v187 offset:51200
	ds_read_b128 v[192:195], v187 offset:52224
	ds_read_b128 v[196:199], v187 offset:53248
	ds_read_b128 v[200:203], v187 offset:54272
	ds_read_b128 v[204:207], v187 offset:55296
	ds_read_b128 v[208:211], v187 offset:56320
	global_load_lds_dwordx4 v[212:213], off
	s_add_i32 m0, s38, 0x2000
	s_add_u32 s36, s36, 0x40080
	v_lshl_add_u64 v[212:213], v[214:215], 0, s[80:81]
	s_addc_u32 s37, s37, 0
	s_add_i32 s38, s60, s33
	global_load_lds_dwordx4 v[212:213], off
	v_lshl_add_u64 v[212:213], s[36:37], 0, v[156:157]
	s_mov_b32 m0, s38
	s_nop 0
	global_load_lds_dwordx4 v[212:213], off
	v_lshl_add_u64 v[212:213], s[36:37], 0, v[160:161]
	s_add_i32 m0, s38, 0x2000
	s_nop 0
	global_load_lds_dwordx4 v[212:213], off
	v_lshl_add_u64 v[212:213], v[216:217], 0, s[80:81]
	s_mov_b32 m0, s51
	s_nop 0
	global_load_lds_dwordx4 v[212:213], off
	v_lshl_add_u64 v[212:213], v[218:219], 0, s[80:81]
	s_mov_b32 m0, s52
	s_nop 0
	global_load_lds_dwordx4 v[212:213], off
	s_waitcnt vmcnt(8) lgkmcnt(0)
	s_barrier
	s_setprio 1
	v_mfma_f32_16x16x32_bf16 v[62:65], v[130:133], v[174:177], v[62:65]
	v_mfma_f32_16x16x32_bf16 v[58:61], v[138:141], v[174:177], v[58:61]
	v_mfma_f32_16x16x32_bf16 v[46:49], v[130:133], v[188:191], v[46:49]
	v_mfma_f32_16x16x32_bf16 v[42:45], v[138:141], v[188:191], v[42:45]
	v_mfma_f32_16x16x32_bf16 v[30:33], v[130:133], v[196:199], v[30:33]
	v_mfma_f32_16x16x32_bf16 v[26:29], v[138:141], v[196:199], v[26:29]
	v_mfma_f32_16x16x32_bf16 v[14:17], v[130:133], v[204:207], v[14:17]
	v_mfma_f32_16x16x32_bf16 v[10:13], v[138:141], v[204:207], v[10:13]
	v_mfma_f32_16x16x32_bf16 v[62:65], v[134:137], v[180:183], v[62:65]
	v_mfma_f32_16x16x32_bf16 v[58:61], v[142:145], v[180:183], v[58:61]
	v_mfma_f32_16x16x32_bf16 v[46:49], v[134:137], v[192:195], v[46:49]
	v_mfma_f32_16x16x32_bf16 v[42:45], v[142:145], v[192:195], v[42:45]
	v_mfma_f32_16x16x32_bf16 v[30:33], v[134:137], v[200:203], v[30:33]
	v_mfma_f32_16x16x32_bf16 v[26:29], v[142:145], v[200:203], v[26:29]
	v_mfma_f32_16x16x32_bf16 v[14:17], v[134:137], v[208:211], v[14:17]
	v_mfma_f32_16x16x32_bf16 v[10:13], v[142:145], v[208:211], v[10:13]
	v_mfma_f32_16x16x32_bf16 v[54:57], v[146:149], v[174:177], v[54:57]
	v_mfma_f32_16x16x32_bf16 v[50:53], v[166:169], v[174:177], v[50:53]
	v_mfma_f32_16x16x32_bf16 v[38:41], v[146:149], v[188:191], v[38:41]
	v_mfma_f32_16x16x32_bf16 v[34:37], v[166:169], v[188:191], v[34:37]
	v_mfma_f32_16x16x32_bf16 v[22:25], v[146:149], v[196:199], v[22:25]
	v_mfma_f32_16x16x32_bf16 v[18:21], v[166:169], v[196:199], v[18:21]
	v_mfma_f32_16x16x32_bf16 v[6:9], v[146:149], v[204:207], v[6:9]
	v_mfma_f32_16x16x32_bf16 v[2:5], v[166:169], v[204:207], v[2:5]
	v_mfma_f32_16x16x32_bf16 v[54:57], v[150:153], v[180:183], v[54:57]
	v_mfma_f32_16x16x32_bf16 v[50:53], v[170:173], v[180:183], v[50:53]
	v_mfma_f32_16x16x32_bf16 v[38:41], v[150:153], v[192:195], v[38:41]
	v_mfma_f32_16x16x32_bf16 v[34:37], v[170:173], v[192:195], v[34:37]
	v_mfma_f32_16x16x32_bf16 v[22:25], v[150:153], v[200:203], v[22:25]
	v_mfma_f32_16x16x32_bf16 v[18:21], v[170:173], v[200:203], v[18:21]
	v_mfma_f32_16x16x32_bf16 v[6:9], v[150:153], v[208:211], v[6:9]
	v_mfma_f32_16x16x32_bf16 v[2:5], v[170:173], v[208:211], v[2:5]
	s_setprio 0
	s_barrier
	s_add_i32 s58, s58, 2
	s_add_u32 s34, s34, 0x100
	s_addc_u32 s35, s35, 0
	s_add_u32 s56, s56, 0x100
	s_addc_u32 s57, s57, 0
	s_cmp_gt_u32 s58, 13
	s_cbranch_scc0 .LBB0_1062
	s_and_b64 vcc, exec, s[18:19]
	s_cbranch_vccz .LBB0_1065
	s_barrier

; #define PG8_STAGE(bufoff, gbase, voff) do { _Pragma("unroll") for (int _i = 0; _i < 2; ++_i) \
;         __builtin_amdgcn_global_load_lds((const unsigned*)((const char*)(gbase) + (voff)[_i]), (PG8_LAS unsigned*)(lds + (bufoff) + ldsw + _i * 8192), 16, 0, 0); } while (0)
; #define PG8_LDA(dst, b, h) do { _Pragma("unroll") for (int m = 0; m < 4; ++m) _Pragma("unroll") for (int k = 0; k < 2; ++k) dst[m][k] = *(const PG8_LAS bf16x8*)(lds + PG8_SA(b, h) + aoff + m * 2048 + k * 1024); } while (0)
; #define PG8_LDB(dst, b, h) do { _Pragma("unroll") for (int n = 0; n < 2; ++n) _Pragma("unroll") for (int k = 0; k < 2; ++k) dst[n][k] = *(const PG8_LAS bf16x8*)(lds + PG8_SB(b, h) + boff + n * 2048 + k * 1024); } while (0)
; #define PG8_WAIT_V(n) asm volatile("s_waitcnt vmcnt(" #n ")" ::: "memory")
; #define PG8_WAIT_L(n) asm volatile("s_waitcnt lgkmcnt(" #n ")" ::: "memory")
; #define PG8_BAR __builtin_amdgcn_s_barrier()
; #define PG8_SCHED __builtin_amdgcn_sched_barrier(0)
; template <class Epi, class Sched, bool ALIGN_EPI = false, bool SP2 = false>
; __device__ __forceinline__ void gemm_phase(PG8_LAS unsigned char* lds, const Gemm g, const Sched& S, const Epi& E) {
;     ...
;         const bool has_next = S.next(ui + 1, nxt);
;         const char* nA = has_next ? (const char*)g.A + (size_t)nxt.pm * tstep : cA; const char* nB = has_next ? (const char*)g.Bt + (size_t)nxt.pn * tstep : cB;
;         for (int t = 0; t < nt; t += 2) {
;             const bool last = (t == nt - 2);
;             const char* a1 = cA + (size_t)(t + 1) * kstep;
;             const char* a2 = last ? nA : cA + (size_t)(t + 2) * kstep; const char* b2 = last ? nB : cB + (size_t)(t + 2) * kstep;
;             const char* a3 = a2 + kstep; const char* b3 = b2 + kstep;
;             if (last && has_next) S.a_ready(nxt);
;             if constexpr (SP2) {
;             PG8_LDB(B0, 0, 0); PG8_LDB(B1, 0, 1); PG8_SCHED; PG8_LDA(At, 0, 0); PG8_STAGE(PG8_SA(1, 1), a1 + hstep, voffA);
;             PG8_WAIT_V(8); PG8_WAIT_L(0); PG8_BAR; PG8_MMA(0, 0, At, B0); PG8_MMA(0, 1, At, B1); PG8_BAR; PG8_SCHED;
;             PG8_LDA(At, 0, 1); PG8_STAGE(PG8_SB(0, 0), b2, voffB); PG8_STAGE(PG8_SB(0, 1), b2 + hstep, voffB); PG8_STAGE(PG8_SA(0, 0), a2, voffA);
;             PG8_WAIT_V(8); PG8_WAIT_L(0); PG8_BAR; PG8_MMA(1, 0, At, B0); PG8_MMA(1, 1, At, B1); PG8_BAR; PG8_SCHED;
.LBB0_1105:
	s_ashr_i32 s19, s18, 31
	s_lshl_b64 s[20:21], s[18:19], 19
	s_add_u32 s20, s42, s20
	s_addc_u32 s21, s43, s21
	s_and_b64 s[22:23], s[6:7], exec
	s_cselect_b32 s19, s21, s29
	s_cselect_b32 s25, s20, s28
	s_ashr_i32 s17, s16, 31
	s_lshl_b64 s[22:23], s[16:17], 19
	s_add_u32 s22, s40, s22
	s_addc_u32 s23, s41, s23
	s_and_b64 s[34:35], s[6:7], exec
	s_cselect_b32 s17, s23, s31
	s_cselect_b32 s27, s22, s30
	s_add_u32 s28, s28, 0x40080
	s_addc_u32 s29, s29, 0
	s_add_u32 s52, s30, 0x100
	s_addc_u32 s53, s31, 0
	s_mov_b32 s54, -2
	s_waitcnt lgkmcnt(0)
	s_add_u32 s30, s28, 0xfffc0080
	s_addc_u32 s31, s29, -1
	s_add_i32 s55, 0, 0x10000
	s_cmp_eq_u32 s54, 12
	s_cselect_b32 s35, s19, s31
	s_cselect_b32 s34, s25, s30
	s_cselect_b32 s31, s17, s53
	s_cselect_b32 s30, s27, s52
	s_add_i32 s58, 0, 0x14000
	v_add_u32_e32 v142, s55, v179
	v_add_u32_e32 v158, s58, v179
	ds_read_b128 v[130:133], v142
	ds_read_b128 v[134:137], v142 offset:1024
	ds_read_b128 v[138:141], v142 offset:2048
	ds_read_b128 v[142:145], v142 offset:3072
	ds_read_b128 v[146:149], v158
	ds_read_b128 v[150:153], v158 offset:1024
	ds_read_b128 v[154:157], v158 offset:2048
	ds_read_b128 v[158:161], v158 offset:3072
	v_lshl_add_u64 v[212:213], s[28:29], 0, v[194:195]
	s_add_i32 m0, s36, 0xc000
	ds_read_b128 v[162:165], v211
	ds_read_b128 v[166:169], v211 offset:1024
	ds_read_b128 v[170:173], v211 offset:2048
	ds_read_b128 v[174:177], v211 offset:3072
	ds_read_b128 v[180:183], v211 offset:4096
	ds_read_b128 v[198:201], v211 offset:5120
	ds_read_b128 v[202:205], v211 offset:6144
	ds_read_b128 v[206:209], v211 offset:7168
	global_load_lds_dwordx4 v[212:213], off
	v_lshl_add_u64 v[212:213], s[28:29], 0, v[196:197]
	s_add_i32 m0, s36, 0xe000
	s_nop 0
	global_load_lds_dwordx4 v[212:213], off
	s_waitcnt vmcnt(8) lgkmcnt(0)
	s_barrier
	s_setprio 1
	v_mfma_f32_16x16x32_bf16 v[126:129], v[130:133], v[162:165], 0
	v_mfma_f32_16x16x32_bf16 v[122:125], v[138:141], v[162:165], 0
	v_mfma_f32_16x16x32_bf16 v[110:113], v[130:133], v[170:173], 0
	v_mfma_f32_16x16x32_bf16 v[106:109], v[138:141], v[170:173], 0
	v_mfma_f32_16x16x32_bf16 v[94:97], v[130:133], v[180:183], 0
	v_mfma_f32_16x16x32_bf16 v[90:93], v[138:141], v[180:183], 0
	v_mfma_f32_16x16x32_bf16 v[78:81], v[130:133], v[202:205], 0
	v_mfma_f32_16x16x32_bf16 v[74:77], v[138:141], v[202:205], 0
	v_mfma_f32_16x16x32_bf16 v[126:129], v[134:137], v[166:169], v[126:129]
	v_mfma_f32_16x16x32_bf16 v[122:125], v[142:145], v[166:169], v[122:125]
	v_mfma_f32_16x16x32_bf16 v[110:113], v[134:137], v[174:177], v[110:113]
	v_mfma_f32_16x16x32_bf16 v[106:109], v[142:145], v[174:177], v[106:109]
	v_mfma_f32_16x16x32_bf16 v[94:97], v[134:137], v[198:201], v[94:97]
	v_mfma_f32_16x16x32_bf16 v[90:93], v[142:145], v[198:201], v[90:93]
	v_mfma_f32_16x16x32_bf16 v[78:81], v[134:137], v[206:209], v[78:81]
	v_mfma_f32_16x16x32_bf16 v[74:77], v[142:145], v[206:209], v[74:77]
	v_mfma_f32_16x16x32_bf16 v[118:121], v[146:149], v[162:165], 0
	v_mfma_f32_16x16x32_bf16 v[114:117], v[154:157], v[162:165], 0
	v_mfma_f32_16x16x32_bf16 v[102:105], v[146:149], v[170:173], 0
	v_mfma_f32_16x16x32_bf16 v[98:101], v[154:157], v[170:173], 0
	v_mfma_f32_16x16x32_bf16 v[86:89], v[146:149], v[180:183], 0
	v_mfma_f32_16x16x32_bf16 v[82:85], v[154:157], v[180:183], 0
	v_mfma_f32_16x16x32_bf16 v[70:73], v[146:149], v[202:205], 0
	v_mfma_f32_16x16x32_bf16 v[66:69], v[154:157], v[202:205], 0
	v_mfma_f32_16x16x32_bf16 v[118:121], v[150:153], v[166:169], v[118:121]
	v_mfma_f32_16x16x32_bf16 v[114:117], v[158:161], v[166:169], v[114:117]
	v_mfma_f32_16x16x32_bf16 v[102:105], v[150:153], v[174:177], v[102:105]
	v_mfma_f32_16x16x32_bf16 v[98:101], v[158:161], v[174:177], v[98:101]
	v_mfma_f32_16x16x32_bf16 v[86:89], v[150:153], v[198:201], v[86:89]
	v_mfma_f32_16x16x32_bf16 v[82:85], v[158:161], v[198:201], v[82:85]
	v_mfma_f32_16x16x32_bf16 v[70:73], v[150:153], v[206:209], v[70:73]
	v_mfma_f32_16x16x32_bf16 v[66:69], v[158:161], v[206:209], v[66:69]
	s_setprio 0
	s_barrier
	s_add_i32 s55, s55, s33
	v_lshl_add_u64 v[212:213], s[30:31], 0, v[188:189]
	s_mov_b32 m0, s55
	ds_read_b128 v[162:165], v211 offset:16384
	ds_read_b128 v[166:169], v211 offset:17408
	ds_read_b128 v[170:173], v211 offset:18432
	ds_read_b128 v[174:177], v211 offset:19456
	ds_read_b128 v[180:183], v211 offset:20480
	ds_read_b128 v[198:201], v211 offset:21504
	ds_read_b128 v[202:205], v211 offset:22528
	ds_read_b128 v[206:209], v211 offset:23552
	global_load_lds_dwordx4 v[212:213], off
	s_add_i32 m0, s55, 0x2000
	s_add_u32 s56, s30, 0x40000
	v_lshl_add_u64 v[214:215], s[30:31], 0, v[192:193]
	s_addc_u32 s57, s31, 0
	s_add_i32 s55, s58, s33
	global_load_lds_dwordx4 v[214:215], off
	v_lshl_add_u64 v[216:217], s[56:57], 0, v[188:189]
	s_mov_b32 m0, s55
	v_lshl_add_u64 v[218:219], s[34:35], 0, v[190:191]
	global_load_lds_dwordx4 v[216:217], off
	v_lshl_add_u64 v[216:217], s[56:57], 0, v[192:193]
	s_add_i32 m0, s55, 0x2000
	s_nop 0
	global_load_lds_dwordx4 v[216:217], off
	v_lshl_add_u64 v[216:217], s[34:35], 0, v[186:187]
	s_mov_b32 m0, s36
	s_nop 0
	global_load_lds_dwordx4 v[216:217], off
	s_mov_b32 m0, s37
	s_nop 0
	global_load_lds_dwordx4 v[218:219], off
	s_waitcnt vmcnt(8) lgkmcnt(0)
	s_barrier
; #define PG8_STAGE(bufoff, gbase, voff) do { _Pragma("unroll") for (int _i = 0; _i < 2; ++_i) \
;         __builtin_amdgcn_global_load_lds((const unsigned*)((const char*)(gbase) + (voff)[_i]), (PG8_LAS unsigned*)(lds + (bufoff) + ldsw + _i * 8192), 16, 0, 0); } while (0)
; #define PG8_LDA(dst, b, h) do { _Pragma("unroll") for (int m = 0; m < 4; ++m) _Pragma("unroll") for (int k = 0; k < 2; ++k) dst[m][k] = *(const PG8_LAS bf16x8*)(lds + PG8_SA(b, h) + aoff + m * 2048 + k * 1024); } while (0)
; #define PG8_LDB(dst, b, h) do { _Pragma("unroll") for (int n = 0; n < 2; ++n) _Pragma("unroll") for (int k = 0; k < 2; ++k) dst[n][k] = *(const PG8_LAS bf16x8*)(lds + PG8_SB(b, h) + boff + n * 2048 + k * 1024); } while (0)
; #define PG8_MMA(ai, bj, At, Bt) do { __builtin_amdgcn_s_setprio(1); _Pragma("unroll") for (int m = 0; m < 4; ++m) _Pragma("unroll") for (int n = 0; n < 2; ++n) _Pragma("unroll") for (int k = 0; k < 2; ++k) \
;         acc[ai][bj][m][n] = __builtin_amdgcn_mfma_f32_16x16x32_bf16(Bt[n][k], At[m][k], acc[ai][bj][m][n], 0, 0, 0); __builtin_amdgcn_s_setprio(0); } while (0)
; #define PG8_WAIT_V(n) asm volatile("s_waitcnt vmcnt(" #n ")" ::: "memory")
; #define PG8_WAIT_L(n) asm volatile("s_waitcnt lgkmcnt(" #n ")" ::: "memory")
; #define PG8_BAR __builtin_amdgcn_s_barrier()
; #define PG8_SCHED __builtin_amdgcn_sched_barrier(0)
; template <class Epi, class Sched, bool ALIGN_EPI = false, bool SP2 = false>
; __device__ __forceinline__ void gemm_phase(PG8_LAS unsigned char* lds, const Gemm g, const Sched& S, const Epi& E) {
;     ...
;             PG8_WAIT_V(8); PG8_WAIT_L(0); PG8_BAR; PG8_MMA(1, 0, At, B0); PG8_MMA(1, 1, At, B1); PG8_BAR; PG8_SCHED;
;             PG8_LDB(B0, 1, 0); PG8_LDB(B1, 1, 1); PG8_SCHED; PG8_LDA(At, 1, 0); PG8_STAGE(PG8_SA(0, 1), a2 + hstep, voffA);
;             PG8_WAIT_V(8); PG8_WAIT_L(0); PG8_BAR; PG8_MMA(0, 0, At, B0); PG8_MMA(0, 1, At, B1); PG8_BAR; PG8_SCHED;
	s_setprio 1
	v_mfma_f32_16x16x32_bf16 v[62:65], v[130:133], v[162:165], 0
	v_mfma_f32_16x16x32_bf16 v[58:61], v[138:141], v[162:165], 0
	v_mfma_f32_16x16x32_bf16 v[46:49], v[130:133], v[170:173], 0
	v_mfma_f32_16x16x32_bf16 v[42:45], v[138:141], v[170:173], 0
	v_mfma_f32_16x16x32_bf16 v[30:33], v[130:133], v[180:183], 0
	v_mfma_f32_16x16x32_bf16 v[26:29], v[138:141], v[180:183], 0
	v_mfma_f32_16x16x32_bf16 v[14:17], v[130:133], v[202:205], 0
	v_mfma_f32_16x16x32_bf16 v[10:13], v[138:141], v[202:205], 0
	v_mfma_f32_16x16x32_bf16 v[62:65], v[134:137], v[166:169], v[62:65]
	v_mfma_f32_16x16x32_bf16 v[58:61], v[142:145], v[166:169], v[58:61]
	v_mfma_f32_16x16x32_bf16 v[46:49], v[134:137], v[174:177], v[46:49]
	v_mfma_f32_16x16x32_bf16 v[42:45], v[142:145], v[174:177], v[42:45]
	v_mfma_f32_16x16x32_bf16 v[30:33], v[134:137], v[198:201], v[30:33]
	v_mfma_f32_16x16x32_bf16 v[26:29], v[142:145], v[198:201], v[26:29]
	v_mfma_f32_16x16x32_bf16 v[14:17], v[134:137], v[206:209], v[14:17]
	v_mfma_f32_16x16x32_bf16 v[10:13], v[142:145], v[206:209], v[10:13]
	v_mfma_f32_16x16x32_bf16 v[54:57], v[146:149], v[162:165], 0
	v_mfma_f32_16x16x32_bf16 v[50:53], v[154:157], v[162:165], 0
	v_mfma_f32_16x16x32_bf16 v[38:41], v[146:149], v[170:173], 0
	v_mfma_f32_16x16x32_bf16 v[34:37], v[154:157], v[170:173], 0
	v_mfma_f32_16x16x32_bf16 v[22:25], v[146:149], v[180:183], 0
	v_mfma_f32_16x16x32_bf16 v[18:21], v[154:157], v[180:183], 0
	v_mfma_f32_16x16x32_bf16 v[6:9], v[146:149], v[202:205], 0
	v_mfma_f32_16x16x32_bf16 v[2:5], v[154:157], v[202:205], 0
	v_mfma_f32_16x16x32_bf16 v[54:57], v[150:153], v[166:169], v[54:57]
	v_mfma_f32_16x16x32_bf16 v[50:53], v[158:161], v[166:169], v[50:53]
	v_mfma_f32_16x16x32_bf16 v[38:41], v[150:153], v[174:177], v[38:41]
	v_mfma_f32_16x16x32_bf16 v[34:37], v[158:161], v[174:177], v[34:37]
	v_mfma_f32_16x16x32_bf16 v[22:25], v[150:153], v[198:201], v[22:25]
	v_mfma_f32_16x16x32_bf16 v[18:21], v[158:161], v[198:201], v[18:21]
	v_mfma_f32_16x16x32_bf16 v[6:9], v[150:153], v[206:209], v[6:9]
	v_mfma_f32_16x16x32_bf16 v[2:5], v[158:161], v[206:209], v[2:5]
	s_setprio 0
	s_barrier
	s_add_i32 s55, 0, 0x18000
	s_add_i32 s56, 0, 0x1c000
	v_add_u32_e32 v142, s55, v179
	v_add_u32_e32 v158, s56, v179
	ds_read_b128 v[130:133], v142
	ds_read_b128 v[134:137], v142 offset:1024
	ds_read_b128 v[138:141], v142 offset:2048
	ds_read_b128 v[142:145], v142 offset:3072
	ds_read_b128 v[146:149], v158
	ds_read_b128 v[150:153], v158 offset:1024
	ds_read_b128 v[154:157], v158 offset:2048
	ds_read_b128 v[158:161], v158 offset:3072
	s_add_u32 s34, s34, 0x40000
	s_addc_u32 s35, s35, 0
	s_mov_b32 m0, s38
	v_lshl_add_u64 v[220:221], s[34:35], 0, v[186:187]
	ds_read_b128 v[162:165], v211 offset:32768
	ds_read_b128 v[166:169], v211 offset:33792
	ds_read_b128 v[170:173], v211 offset:34816
	ds_read_b128 v[174:177], v211 offset:35840
	ds_read_b128 v[180:183], v211 offset:36864
	ds_read_b128 v[198:201], v211 offset:37888
	ds_read_b128 v[202:205], v211 offset:38912
	ds_read_b128 v[206:209], v211 offset:39936
	global_load_lds_dwordx4 v[220:221], off
	v_lshl_add_u64 v[220:221], s[34:35], 0, v[190:191]
	s_mov_b32 m0, s39
	s_nop 0
	global_load_lds_dwordx4 v[220:221], off
	s_waitcnt vmcnt(8) lgkmcnt(0)
	s_barrier
	s_setprio 1
	v_mfma_f32_16x16x32_bf16 v[126:129], v[130:133], v[162:165], v[126:129]
	v_mfma_f32_16x16x32_bf16 v[122:125], v[138:141], v[162:165], v[122:125]
	v_mfma_f32_16x16x32_bf16 v[110:113], v[130:133], v[170:173], v[110:113]
	v_mfma_f32_16x16x32_bf16 v[106:109], v[138:141], v[170:173], v[106:109]
	v_mfma_f32_16x16x32_bf16 v[94:97], v[130:133], v[180:183], v[94:97]
	v_mfma_f32_16x16x32_bf16 v[90:93], v[138:141], v[180:183], v[90:93]
	v_mfma_f32_16x16x32_bf16 v[78:81], v[130:133], v[202:205], v[78:81]
	v_mfma_f32_16x16x32_bf16 v[74:77], v[138:141], v[202:205], v[74:77]
	v_mfma_f32_16x16x32_bf16 v[126:129], v[134:137], v[166:169], v[126:129]
	v_mfma_f32_16x16x32_bf16 v[122:125], v[142:145], v[166:169], v[122:125]
	v_mfma_f32_16x16x32_bf16 v[110:113], v[134:137], v[174:177], v[110:113]
	v_mfma_f32_16x16x32_bf16 v[106:109], v[142:145], v[174:177], v[106:109]
	v_mfma_f32_16x16x32_bf16 v[94:97], v[134:137], v[198:201], v[94:97]
	v_mfma_f32_16x16x32_bf16 v[90:93], v[142:145], v[198:201], v[90:93]
	v_mfma_f32_16x16x32_bf16 v[78:81], v[134:137], v[206:209], v[78:81]
	v_mfma_f32_16x16x32_bf16 v[74:77], v[142:145], v[206:209], v[74:77]
	v_mfma_f32_16x16x32_bf16 v[118:121], v[146:149], v[162:165], v[118:121]
	v_mfma_f32_16x16x32_bf16 v[114:117], v[154:157], v[162:165], v[114:117]
	v_mfma_f32_16x16x32_bf16 v[102:105], v[146:149], v[170:173], v[102:105]
	v_mfma_f32_16x16x32_bf16 v[98:101], v[154:157], v[170:173], v[98:101]
	v_mfma_f32_16x16x32_bf16 v[86:89], v[146:149], v[180:183], v[86:89]
	v_mfma_f32_16x16x32_bf16 v[82:85], v[154:157], v[180:183], v[82:85]
	v_mfma_f32_16x16x32_bf16 v[70:73], v[146:149], v[202:205], v[70:73]
	v_mfma_f32_16x16x32_bf16 v[66:69], v[154:157], v[202:205], v[66:69]
	v_mfma_f32_16x16x32_bf16 v[118:121], v[150:153], v[166:169], v[118:121]
	v_mfma_f32_16x16x32_bf16 v[114:117], v[158:161], v[166:169], v[114:117]
	v_mfma_f32_16x16x32_bf16 v[102:105], v[150:153], v[174:177], v[102:105]
	v_mfma_f32_16x16x32_bf16 v[98:101], v[158:161], v[174:177], v[98:101]
	v_mfma_f32_16x16x32_bf16 v[86:89], v[150:153], v[198:201], v[86:89]
	v_mfma_f32_16x16x32_bf16 v[82:85], v[158:161], v[198:201], v[82:85]
	v_mfma_f32_16x16x32_bf16 v[70:73], v[150:153], v[206:209], v[70:73]
	v_mfma_f32_16x16x32_bf16 v[66:69], v[158:161], v[206:209], v[66:69]
	s_setprio 0
	s_barrier
; #define PG8_STAGE(bufoff, gbase, voff) do { _Pragma("unroll") for (int _i = 0; _i < 2; ++_i) \
;         __builtin_amdgcn_global_load_lds((const unsigned*)((const char*)(gbase) + (voff)[_i]), (PG8_LAS unsigned*)(lds + (bufoff) + ldsw + _i * 8192), 16, 0, 0); } while (0)
; #define PG8_LDA(dst, b, h) do { _Pragma("unroll") for (int m = 0; m < 4; ++m) _Pragma("unroll") for (int k = 0; k < 2; ++k) dst[m][k] = *(const PG8_LAS bf16x8*)(lds + PG8_SA(b, h) + aoff + m * 2048 + k * 1024); } while (0)
; #define PG8_LDB(dst, b, h) do { _Pragma("unroll") for (int n = 0; n < 2; ++n) _Pragma("unroll") for (int k = 0; k < 2; ++k) dst[n][k] = *(const PG8_LAS bf16x8*)(lds + PG8_SB(b, h) + boff + n * 2048 + k * 1024); } while (0)
; #define PG8_MMA(ai, bj, At, Bt) do { __builtin_amdgcn_s_setprio(1); _Pragma("unroll") for (int m = 0; m < 4; ++m) _Pragma("unroll") for (int n = 0; n < 2; ++n) _Pragma("unroll") for (int k = 0; k < 2; ++k) \
;         acc[ai][bj][m][n] = __builtin_amdgcn_mfma_f32_16x16x32_bf16(Bt[n][k], At[m][k], acc[ai][bj][m][n], 0, 0, 0); __builtin_amdgcn_s_setprio(0); } while (0)
; #define PG8_WAIT_V(n) asm volatile("s_waitcnt vmcnt(" #n ")" ::: "memory")
; #define PG8_WAIT_L(n) asm volatile("s_waitcnt lgkmcnt(" #n ")" ::: "memory")
; #define PG8_BAR __builtin_amdgcn_s_barrier()
; #define PG8_SCHED __builtin_amdgcn_sched_barrier(0)
; template <class Epi, class Sched, bool ALIGN_EPI = false, bool SP2 = false>
; __device__ __forceinline__ void gemm_phase(PG8_LAS unsigned char* lds, const Gemm g, const Sched& S, const Epi& E) {
;     ...
;             PG8_LDB(B0, 0, 0); PG8_LDB(B1, 0, 1); PG8_SCHED; PG8_LDA(At, 0, 0); PG8_STAGE(PG8_SA(1, 1), a1 + hstep, voffA);
;             PG8_WAIT_V(8); PG8_WAIT_L(0); PG8_BAR; PG8_MMA(0, 0, At, B0); PG8_MMA(0, 1, At, B1); PG8_BAR; PG8_SCHED;
;     ...
;             PG8_LDA(At, 1, 1); PG8_STAGE(PG8_SB(1, 0), b3, voffB); PG8_STAGE(PG8_SB(1, 1), b3 + hstep, voffB); PG8_STAGE(PG8_SA(1, 0), a3, voffA);
;             PG8_WAIT_V(8); PG8_WAIT_L(0); PG8_BAR; PG8_MMA(1, 0, At, B0); PG8_MMA(1, 1, At, B1); PG8_BAR; PG8_SCHED;
	s_add_i32 s34, s55, s33
	v_lshl_add_u64 v[212:213], v[212:213], 0, s[80:81]
	s_mov_b32 m0, s34
	ds_read_b128 v[162:165], v211 offset:49152
	ds_read_b128 v[166:169], v211 offset:50176
	ds_read_b128 v[170:173], v211 offset:51200
	ds_read_b128 v[174:177], v211 offset:52224
	ds_read_b128 v[180:183], v211 offset:53248
	ds_read_b128 v[198:201], v211 offset:54272
	ds_read_b128 v[202:205], v211 offset:55296
	ds_read_b128 v[206:209], v211 offset:56320
	global_load_lds_dwordx4 v[212:213], off
	s_add_i32 m0, s34, 0x2000
	s_add_u32 s30, s30, 0x40080
	v_lshl_add_u64 v[212:213], v[214:215], 0, s[80:81]
	s_addc_u32 s31, s31, 0
	s_add_i32 s34, s56, s33
	global_load_lds_dwordx4 v[212:213], off
	v_lshl_add_u64 v[212:213], s[30:31], 0, v[188:189]
	s_mov_b32 m0, s34
	s_nop 0
	global_load_lds_dwordx4 v[212:213], off
	v_lshl_add_u64 v[212:213], s[30:31], 0, v[192:193]
	s_add_i32 m0, s34, 0x2000
	s_nop 0
	global_load_lds_dwordx4 v[212:213], off
	v_lshl_add_u64 v[212:213], v[216:217], 0, s[80:81]
	s_mov_b32 m0, s47
	s_nop 0
	global_load_lds_dwordx4 v[212:213], off
	v_lshl_add_u64 v[212:213], v[218:219], 0, s[80:81]
	s_mov_b32 m0, s48
	s_nop 0
	global_load_lds_dwordx4 v[212:213], off
	s_waitcnt vmcnt(8) lgkmcnt(0)
	s_barrier
	s_setprio 1
	v_mfma_f32_16x16x32_bf16 v[62:65], v[130:133], v[162:165], v[62:65]
	v_mfma_f32_16x16x32_bf16 v[58:61], v[138:141], v[162:165], v[58:61]
	v_mfma_f32_16x16x32_bf16 v[46:49], v[130:133], v[170:173], v[46:49]
	v_mfma_f32_16x16x32_bf16 v[42:45], v[138:141], v[170:173], v[42:45]
	v_mfma_f32_16x16x32_bf16 v[30:33], v[130:133], v[180:183], v[30:33]
	v_mfma_f32_16x16x32_bf16 v[26:29], v[138:141], v[180:183], v[26:29]
	v_mfma_f32_16x16x32_bf16 v[14:17], v[130:133], v[202:205], v[14:17]
	v_mfma_f32_16x16x32_bf16 v[10:13], v[138:141], v[202:205], v[10:13]
	v_mfma_f32_16x16x32_bf16 v[62:65], v[134:137], v[166:169], v[62:65]
	v_mfma_f32_16x16x32_bf16 v[58:61], v[142:145], v[166:169], v[58:61]
	v_mfma_f32_16x16x32_bf16 v[46:49], v[134:137], v[174:177], v[46:49]
	v_mfma_f32_16x16x32_bf16 v[42:45], v[142:145], v[174:177], v[42:45]
	v_mfma_f32_16x16x32_bf16 v[30:33], v[134:137], v[198:201], v[30:33]
	v_mfma_f32_16x16x32_bf16 v[26:29], v[142:145], v[198:201], v[26:29]
	v_mfma_f32_16x16x32_bf16 v[14:17], v[134:137], v[206:209], v[14:17]
	v_mfma_f32_16x16x32_bf16 v[10:13], v[142:145], v[206:209], v[10:13]
	v_mfma_f32_16x16x32_bf16 v[54:57], v[146:149], v[162:165], v[54:57]
	v_mfma_f32_16x16x32_bf16 v[50:53], v[154:157], v[162:165], v[50:53]
	v_mfma_f32_16x16x32_bf16 v[38:41], v[146:149], v[170:173], v[38:41]
	v_mfma_f32_16x16x32_bf16 v[34:37], v[154:157], v[170:173], v[34:37]
	v_mfma_f32_16x16x32_bf16 v[22:25], v[146:149], v[180:183], v[22:25]
	v_mfma_f32_16x16x32_bf16 v[18:21], v[154:157], v[180:183], v[18:21]
	v_mfma_f32_16x16x32_bf16 v[6:9], v[146:149], v[202:205], v[6:9]
	v_mfma_f32_16x16x32_bf16 v[2:5], v[154:157], v[202:205], v[2:5]
	v_mfma_f32_16x16x32_bf16 v[54:57], v[150:153], v[166:169], v[54:57]
	v_mfma_f32_16x16x32_bf16 v[50:53], v[158:161], v[166:169], v[50:53]
	v_mfma_f32_16x16x32_bf16 v[38:41], v[150:153], v[174:177], v[38:41]
	v_mfma_f32_16x16x32_bf16 v[34:37], v[158:161], v[174:177], v[34:37]
	v_mfma_f32_16x16x32_bf16 v[22:25], v[150:153], v[198:201], v[22:25]
	v_mfma_f32_16x16x32_bf16 v[18:21], v[158:161], v[198:201], v[18:21]
	v_mfma_f32_16x16x32_bf16 v[6:9], v[150:153], v[206:209], v[6:9]
	v_mfma_f32_16x16x32_bf16 v[2:5], v[158:161], v[206:209], v[2:5]
	s_setprio 0
	s_barrier
	s_add_i32 s54, s54, 2
	s_add_u32 s28, s28, 0x100
	s_addc_u32 s29, s29, 0
	s_add_u32 s52, s52, 0x100
	s_addc_u32 s53, s53, 0
	s_cmp_gt_u32 s54, 13
	s_branch .LBB0_1106
.LBB0_1106:
	s_add_u32 s30, s28, 0xfffc0080
	s_addc_u32 s31, s29, -1
	s_add_i32 s55, 0, 0x10000
	s_cmp_eq_u32 s54, 12
	s_cselect_b32 s35, s19, s31
	s_cselect_b32 s34, s25, s30
	s_cselect_b32 s31, s17, s53
	s_cselect_b32 s30, s27, s52
	s_add_i32 s58, 0, 0x14000
	v_add_u32_e32 v142, s55, v179
	v_add_u32_e32 v158, s58, v179
	ds_read_b128 v[130:133], v142
	ds_read_b128 v[134:137], v142 offset:1024
	ds_read_b128 v[138:141], v142 offset:2048
	ds_read_b128 v[142:145], v142 offset:3072
	ds_read_b128 v[146:149], v158
	ds_read_b128 v[150:153], v158 offset:1024
	ds_read_b128 v[154:157], v158 offset:2048
	ds_read_b128 v[158:161], v158 offset:3072
	v_lshl_add_u64 v[212:213], s[28:29], 0, v[194:195]
	s_add_i32 m0, s36, 0xc000
	ds_read_b128 v[162:165], v211
	ds_read_b128 v[166:169], v211 offset:1024
	ds_read_b128 v[170:173], v211 offset:2048
	ds_read_b128 v[174:177], v211 offset:3072
	ds_read_b128 v[180:183], v211 offset:4096
	ds_read_b128 v[198:201], v211 offset:5120
	ds_read_b128 v[202:205], v211 offset:6144
	ds_read_b128 v[206:209], v211 offset:7168
	global_load_lds_dwordx4 v[212:213], off
	v_lshl_add_u64 v[212:213], s[28:29], 0, v[196:197]
	s_add_i32 m0, s36, 0xe000
	s_nop 0
	global_load_lds_dwordx4 v[212:213], off
	s_waitcnt vmcnt(8) lgkmcnt(0)
	s_barrier
; #define PG8_STAGE(bufoff, gbase, voff) do { _Pragma("unroll") for (int _i = 0; _i < 2; ++_i) \
;         __builtin_amdgcn_global_load_lds((const unsigned*)((const char*)(gbase) + (voff)[_i]), (PG8_LAS unsigned*)(lds + (bufoff) + ldsw + _i * 8192), 16, 0, 0); } while (0)
; #define PG8_LDA(dst, b, h) do { _Pragma("unroll") for (int m = 0; m < 4; ++m) _Pragma("unroll") for (int k = 0; k < 2; ++k) dst[m][k] = *(const PG8_LAS bf16x8*)(lds + PG8_SA(b, h) + aoff + m * 2048 + k * 1024); } while (0)
; #define PG8_MMA(ai, bj, At, Bt) do { __builtin_amdgcn_s_setprio(1); _Pragma("unroll") for (int m = 0; m < 4; ++m) _Pragma("unroll") for (int n = 0; n < 2; ++n) _Pragma("unroll") for (int k = 0; k < 2; ++k) \
;         acc[ai][bj][m][n] = __builtin_amdgcn_mfma_f32_16x16x32_bf16(Bt[n][k], At[m][k], acc[ai][bj][m][n], 0, 0, 0); __builtin_amdgcn_s_setprio(0); } while (0)
; #define PG8_WAIT_V(n) asm volatile("s_waitcnt vmcnt(" #n ")" ::: "memory")
; #define PG8_WAIT_L(n) asm volatile("s_waitcnt lgkmcnt(" #n ")" ::: "memory")
; #define PG8_BAR __builtin_amdgcn_s_barrier()
; #define PG8_SCHED __builtin_amdgcn_sched_barrier(0)
; template <class Epi, class Sched, bool ALIGN_EPI = false, bool SP2 = false>
; __device__ __forceinline__ void gemm_phase(PG8_LAS unsigned char* lds, const Gemm g, const Sched& S, const Epi& E) {
;     ...
;             PG8_WAIT_V(8); PG8_WAIT_L(0); PG8_BAR; PG8_MMA(0, 0, At, B0); PG8_MMA(0, 1, At, B1); PG8_BAR; PG8_SCHED;
;             PG8_LDA(At, 0, 1); PG8_STAGE(PG8_SB(0, 0), b2, voffB); PG8_STAGE(PG8_SB(0, 1), b2 + hstep, voffB); PG8_STAGE(PG8_SA(0, 0), a2, voffA);
;             PG8_WAIT_V(8); PG8_WAIT_L(0); PG8_BAR; PG8_MMA(1, 0, At, B0); PG8_MMA(1, 1, At, B1); PG8_BAR; PG8_SCHED;
	s_setprio 1
	v_mfma_f32_16x16x32_bf16 v[126:129], v[130:133], v[162:165], v[126:129]
	v_mfma_f32_16x16x32_bf16 v[122:125], v[138:141], v[162:165], v[122:125]
	v_mfma_f32_16x16x32_bf16 v[110:113], v[130:133], v[170:173], v[110:113]
	v_mfma_f32_16x16x32_bf16 v[106:109], v[138:141], v[170:173], v[106:109]
	v_mfma_f32_16x16x32_bf16 v[94:97], v[130:133], v[180:183], v[94:97]
	v_mfma_f32_16x16x32_bf16 v[90:93], v[138:141], v[180:183], v[90:93]
	v_mfma_f32_16x16x32_bf16 v[78:81], v[130:133], v[202:205], v[78:81]
	v_mfma_f32_16x16x32_bf16 v[74:77], v[138:141], v[202:205], v[74:77]
	v_mfma_f32_16x16x32_bf16 v[126:129], v[134:137], v[166:169], v[126:129]
	v_mfma_f32_16x16x32_bf16 v[122:125], v[142:145], v[166:169], v[122:125]
	v_mfma_f32_16x16x32_bf16 v[110:113], v[134:137], v[174:177], v[110:113]
	v_mfma_f32_16x16x32_bf16 v[106:109], v[142:145], v[174:177], v[106:109]
	v_mfma_f32_16x16x32_bf16 v[94:97], v[134:137], v[198:201], v[94:97]
	v_mfma_f32_16x16x32_bf16 v[90:93], v[142:145], v[198:201], v[90:93]
	v_mfma_f32_16x16x32_bf16 v[78:81], v[134:137], v[206:209], v[78:81]
	v_mfma_f32_16x16x32_bf16 v[74:77], v[142:145], v[206:209], v[74:77]
	v_mfma_f32_16x16x32_bf16 v[118:121], v[146:149], v[162:165], v[118:121]
	v_mfma_f32_16x16x32_bf16 v[114:117], v[154:157], v[162:165], v[114:117]
	v_mfma_f32_16x16x32_bf16 v[102:105], v[146:149], v[170:173], v[102:105]
	v_mfma_f32_16x16x32_bf16 v[98:101], v[154:157], v[170:173], v[98:101]
	v_mfma_f32_16x16x32_bf16 v[86:89], v[146:149], v[180:183], v[86:89]
	v_mfma_f32_16x16x32_bf16 v[82:85], v[154:157], v[180:183], v[82:85]
	v_mfma_f32_16x16x32_bf16 v[70:73], v[146:149], v[202:205], v[70:73]
	v_mfma_f32_16x16x32_bf16 v[66:69], v[154:157], v[202:205], v[66:69]
	v_mfma_f32_16x16x32_bf16 v[118:121], v[150:153], v[166:169], v[118:121]
	v_mfma_f32_16x16x32_bf16 v[114:117], v[158:161], v[166:169], v[114:117]
	v_mfma_f32_16x16x32_bf16 v[102:105], v[150:153], v[174:177], v[102:105]
	v_mfma_f32_16x16x32_bf16 v[98:101], v[158:161], v[174:177], v[98:101]
	v_mfma_f32_16x16x32_bf16 v[86:89], v[150:153], v[198:201], v[86:89]
	v_mfma_f32_16x16x32_bf16 v[82:85], v[158:161], v[198:201], v[82:85]
	v_mfma_f32_16x16x32_bf16 v[70:73], v[150:153], v[206:209], v[70:73]
	v_mfma_f32_16x16x32_bf16 v[66:69], v[158:161], v[206:209], v[66:69]
	s_setprio 0
	s_barrier
	s_add_i32 s55, s55, s33
	v_lshl_add_u64 v[212:213], s[30:31], 0, v[188:189]
	s_mov_b32 m0, s55
	ds_read_b128 v[162:165], v211 offset:16384
	ds_read_b128 v[166:169], v211 offset:17408
	ds_read_b128 v[170:173], v211 offset:18432
	ds_read_b128 v[174:177], v211 offset:19456
	ds_read_b128 v[180:183], v211 offset:20480
	ds_read_b128 v[198:201], v211 offset:21504
	ds_read_b128 v[202:205], v211 offset:22528
	ds_read_b128 v[206:209], v211 offset:23552
	global_load_lds_dwordx4 v[212:213], off
	s_add_i32 m0, s55, 0x2000
	s_add_u32 s56, s30, 0x40000
	v_lshl_add_u64 v[214:215], s[30:31], 0, v[192:193]
	s_addc_u32 s57, s31, 0
	s_add_i32 s55, s58, s33
	global_load_lds_dwordx4 v[214:215], off
	v_lshl_add_u64 v[216:217], s[56:57], 0, v[188:189]
	s_mov_b32 m0, s55
	v_lshl_add_u64 v[218:219], s[34:35], 0, v[190:191]
	global_load_lds_dwordx4 v[216:217], off
	v_lshl_add_u64 v[216:217], s[56:57], 0, v[192:193]
	s_add_i32 m0, s55, 0x2000
	s_nop 0
	global_load_lds_dwordx4 v[216:217], off
	v_lshl_add_u64 v[216:217], s[34:35], 0, v[186:187]
	s_mov_b32 m0, s36
	s_nop 0
	global_load_lds_dwordx4 v[216:217], off
	s_mov_b32 m0, s37
	s_nop 0
	global_load_lds_dwordx4 v[218:219], off
	s_waitcnt vmcnt(8) lgkmcnt(0)
	s_barrier
	s_setprio 1
	v_mfma_f32_16x16x32_bf16 v[62:65], v[130:133], v[162:165], v[62:65]
	v_mfma_f32_16x16x32_bf16 v[58:61], v[138:141], v[162:165], v[58:61]
	v_mfma_f32_16x16x32_bf16 v[46:49], v[130:133], v[170:173], v[46:49]
	v_mfma_f32_16x16x32_bf16 v[42:45], v[138:141], v[170:173], v[42:45]
	v_mfma_f32_16x16x32_bf16 v[30:33], v[130:133], v[180:183], v[30:33]
	v_mfma_f32_16x16x32_bf16 v[26:29], v[138:141], v[180:183], v[26:29]
	v_mfma_f32_16x16x32_bf16 v[14:17], v[130:133], v[202:205], v[14:17]
	v_mfma_f32_16x16x32_bf16 v[10:13], v[138:141], v[202:205], v[10:13]
	v_mfma_f32_16x16x32_bf16 v[62:65], v[134:137], v[166:169], v[62:65]
	v_mfma_f32_16x16x32_bf16 v[58:61], v[142:145], v[166:169], v[58:61]
	v_mfma_f32_16x16x32_bf16 v[46:49], v[134:137], v[174:177], v[46:49]
	v_mfma_f32_16x16x32_bf16 v[42:45], v[142:145], v[174:177], v[42:45]
	v_mfma_f32_16x16x32_bf16 v[30:33], v[134:137], v[198:201], v[30:33]
	v_mfma_f32_16x16x32_bf16 v[26:29], v[142:145], v[198:201], v[26:29]
	v_mfma_f32_16x16x32_bf16 v[14:17], v[134:137], v[206:209], v[14:17]
	v_mfma_f32_16x16x32_bf16 v[10:13], v[142:145], v[206:209], v[10:13]
	v_mfma_f32_16x16x32_bf16 v[54:57], v[146:149], v[162:165], v[54:57]
	v_mfma_f32_16x16x32_bf16 v[50:53], v[154:157], v[162:165], v[50:53]
	v_mfma_f32_16x16x32_bf16 v[38:41], v[146:149], v[170:173], v[38:41]
	v_mfma_f32_16x16x32_bf16 v[34:37], v[154:157], v[170:173], v[34:37]
	v_mfma_f32_16x16x32_bf16 v[22:25], v[146:149], v[180:183], v[22:25]
	v_mfma_f32_16x16x32_bf16 v[18:21], v[154:157], v[180:183], v[18:21]
	v_mfma_f32_16x16x32_bf16 v[6:9], v[146:149], v[202:205], v[6:9]
	v_mfma_f32_16x16x32_bf16 v[2:5], v[154:157], v[202:205], v[2:5]
	v_mfma_f32_16x16x32_bf16 v[54:57], v[150:153], v[166:169], v[54:57]
	v_mfma_f32_16x16x32_bf16 v[50:53], v[158:161], v[166:169], v[50:53]
	v_mfma_f32_16x16x32_bf16 v[38:41], v[150:153], v[174:177], v[38:41]
	v_mfma_f32_16x16x32_bf16 v[34:37], v[158:161], v[174:177], v[34:37]
	v_mfma_f32_16x16x32_bf16 v[22:25], v[150:153], v[198:201], v[22:25]
	v_mfma_f32_16x16x32_bf16 v[18:21], v[158:161], v[198:201], v[18:21]
	v_mfma_f32_16x16x32_bf16 v[6:9], v[150:153], v[206:209], v[6:9]
	v_mfma_f32_16x16x32_bf16 v[2:5], v[158:161], v[206:209], v[2:5]
	s_setprio 0
	s_barrier
; #define PG8_STAGE(bufoff, gbase, voff) do { _Pragma("unroll") for (int _i = 0; _i < 2; ++_i) \
;         __builtin_amdgcn_global_load_lds((const unsigned*)((const char*)(gbase) + (voff)[_i]), (PG8_LAS unsigned*)(lds + (bufoff) + ldsw + _i * 8192), 16, 0, 0); } while (0)
; #define PG8_LDA(dst, b, h) do { _Pragma("unroll") for (int m = 0; m < 4; ++m) _Pragma("unroll") for (int k = 0; k < 2; ++k) dst[m][k] = *(const PG8_LAS bf16x8*)(lds + PG8_SA(b, h) + aoff + m * 2048 + k * 1024); } while (0)
; #define PG8_LDB(dst, b, h) do { _Pragma("unroll") for (int n = 0; n < 2; ++n) _Pragma("unroll") for (int k = 0; k < 2; ++k) dst[n][k] = *(const PG8_LAS bf16x8*)(lds + PG8_SB(b, h) + boff + n * 2048 + k * 1024); } while (0)
; #define PG8_MMA(ai, bj, At, Bt) do { __builtin_amdgcn_s_setprio(1); _Pragma("unroll") for (int m = 0; m < 4; ++m) _Pragma("unroll") for (int n = 0; n < 2; ++n) _Pragma("unroll") for (int k = 0; k < 2; ++k) \
;         acc[ai][bj][m][n] = __builtin_amdgcn_mfma_f32_16x16x32_bf16(Bt[n][k], At[m][k], acc[ai][bj][m][n], 0, 0, 0); __builtin_amdgcn_s_setprio(0); } while (0)
; #define PG8_WAIT_V(n) asm volatile("s_waitcnt vmcnt(" #n ")" ::: "memory")
; #define PG8_WAIT_L(n) asm volatile("s_waitcnt lgkmcnt(" #n ")" ::: "memory")
; #define PG8_BAR __builtin_amdgcn_s_barrier()
; #define PG8_SCHED __builtin_amdgcn_sched_barrier(0)
; template <class Epi, class Sched, bool ALIGN_EPI = false, bool SP2 = false>
; __device__ __forceinline__ void gemm_phase(PG8_LAS unsigned char* lds, const Gemm g, const Sched& S, const Epi& E) {
;     ...
;             PG8_LDB(B0, 1, 0); PG8_LDB(B1, 1, 1); PG8_SCHED; PG8_LDA(At, 1, 0); PG8_STAGE(PG8_SA(0, 1), a2 + hstep, voffA);
;             PG8_WAIT_V(8); PG8_WAIT_L(0); PG8_BAR; PG8_MMA(0, 0, At, B0); PG8_MMA(0, 1, At, B1); PG8_BAR; PG8_SCHED;
	s_add_i32 s55, 0, 0x18000
	s_add_i32 s56, 0, 0x1c000
	v_add_u32_e32 v142, s55, v179
	v_add_u32_e32 v158, s56, v179
	ds_read_b128 v[130:133], v142
	ds_read_b128 v[134:137], v142 offset:1024
	ds_read_b128 v[138:141], v142 offset:2048
	ds_read_b128 v[142:145], v142 offset:3072
	ds_read_b128 v[146:149], v158
	ds_read_b128 v[150:153], v158 offset:1024
	ds_read_b128 v[154:157], v158 offset:2048
	ds_read_b128 v[158:161], v158 offset:3072
	s_add_u32 s34, s34, 0x40000
	s_addc_u32 s35, s35, 0
	s_mov_b32 m0, s38
	v_lshl_add_u64 v[220:221], s[34:35], 0, v[186:187]
	ds_read_b128 v[162:165], v211 offset:32768
	ds_read_b128 v[166:169], v211 offset:33792
	ds_read_b128 v[170:173], v211 offset:34816
	ds_read_b128 v[174:177], v211 offset:35840
	ds_read_b128 v[180:183], v211 offset:36864
	ds_read_b128 v[198:201], v211 offset:37888
	ds_read_b128 v[202:205], v211 offset:38912
	ds_read_b128 v[206:209], v211 offset:39936
	global_load_lds_dwordx4 v[220:221], off
	v_lshl_add_u64 v[220:221], s[34:35], 0, v[190:191]
	s_mov_b32 m0, s39
	s_nop 0
	global_load_lds_dwordx4 v[220:221], off
	s_waitcnt vmcnt(8) lgkmcnt(0)
	s_barrier
	s_setprio 1
	v_mfma_f32_16x16x32_bf16 v[126:129], v[130:133], v[162:165], v[126:129]
	v_mfma_f32_16x16x32_bf16 v[122:125], v[138:141], v[162:165], v[122:125]
	v_mfma_f32_16x16x32_bf16 v[110:113], v[130:133], v[170:173], v[110:113]
	v_mfma_f32_16x16x32_bf16 v[106:109], v[138:141], v[170:173], v[106:109]
	v_mfma_f32_16x16x32_bf16 v[94:97], v[130:133], v[180:183], v[94:97]
	v_mfma_f32_16x16x32_bf16 v[90:93], v[138:141], v[180:183], v[90:93]
	v_mfma_f32_16x16x32_bf16 v[78:81], v[130:133], v[202:205], v[78:81]
	v_mfma_f32_16x16x32_bf16 v[74:77], v[138:141], v[202:205], v[74:77]
	v_mfma_f32_16x16x32_bf16 v[126:129], v[134:137], v[166:169], v[126:129]
	v_mfma_f32_16x16x32_bf16 v[122:125], v[142:145], v[166:169], v[122:125]
	v_mfma_f32_16x16x32_bf16 v[110:113], v[134:137], v[174:177], v[110:113]
	v_mfma_f32_16x16x32_bf16 v[106:109], v[142:145], v[174:177], v[106:109]
	v_mfma_f32_16x16x32_bf16 v[94:97], v[134:137], v[198:201], v[94:97]
	v_mfma_f32_16x16x32_bf16 v[90:93], v[142:145], v[198:201], v[90:93]
	v_mfma_f32_16x16x32_bf16 v[78:81], v[134:137], v[206:209], v[78:81]
	v_mfma_f32_16x16x32_bf16 v[74:77], v[142:145], v[206:209], v[74:77]
	v_mfma_f32_16x16x32_bf16 v[118:121], v[146:149], v[162:165], v[118:121]
	v_mfma_f32_16x16x32_bf16 v[114:117], v[154:157], v[162:165], v[114:117]
	v_mfma_f32_16x16x32_bf16 v[102:105], v[146:149], v[170:173], v[102:105]
	v_mfma_f32_16x16x32_bf16 v[98:101], v[154:157], v[170:173], v[98:101]
	v_mfma_f32_16x16x32_bf16 v[86:89], v[146:149], v[180:183], v[86:89]
	v_mfma_f32_16x16x32_bf16 v[82:85], v[154:157], v[180:183], v[82:85]
	v_mfma_f32_16x16x32_bf16 v[70:73], v[146:149], v[202:205], v[70:73]
	v_mfma_f32_16x16x32_bf16 v[66:69], v[154:157], v[202:205], v[66:69]
	v_mfma_f32_16x16x32_bf16 v[118:121], v[150:153], v[166:169], v[118:121]
	v_mfma_f32_16x16x32_bf16 v[114:117], v[158:161], v[166:169], v[114:117]
	v_mfma_f32_16x16x32_bf16 v[102:105], v[150:153], v[174:177], v[102:105]
	v_mfma_f32_16x16x32_bf16 v[98:101], v[158:161], v[174:177], v[98:101]
	v_mfma_f32_16x16x32_bf16 v[86:89], v[150:153], v[198:201], v[86:89]
	v_mfma_f32_16x16x32_bf16 v[82:85], v[158:161], v[198:201], v[82:85]
	v_mfma_f32_16x16x32_bf16 v[70:73], v[150:153], v[206:209], v[70:73]
	v_mfma_f32_16x16x32_bf16 v[66:69], v[158:161], v[206:209], v[66:69]
	s_setprio 0
	s_barrier
; #define PG8_STAGE(bufoff, gbase, voff) do { _Pragma("unroll") for (int _i = 0; _i < 2; ++_i) \
;         __builtin_amdgcn_global_load_lds((const unsigned*)((const char*)(gbase) + (voff)[_i]), (PG8_LAS unsigned*)(lds + (bufoff) + ldsw + _i * 8192), 16, 0, 0); } while (0)
; #define PG8_LDA(dst, b, h) do { _Pragma("unroll") for (int m = 0; m < 4; ++m) _Pragma("unroll") for (int k = 0; k < 2; ++k) dst[m][k] = *(const PG8_LAS bf16x8*)(lds + PG8_SA(b, h) + aoff + m * 2048 + k * 1024); } while (0)
; #define PG8_MMA(ai, bj, At, Bt) do { __builtin_amdgcn_s_setprio(1); _Pragma("unroll") for (int m = 0; m < 4; ++m) _Pragma("unroll") for (int n = 0; n < 2; ++n) _Pragma("unroll") for (int k = 0; k < 2; ++k) \
;         acc[ai][bj][m][n] = __builtin_amdgcn_mfma_f32_16x16x32_bf16(Bt[n][k], At[m][k], acc[ai][bj][m][n], 0, 0, 0); __builtin_amdgcn_s_setprio(0); } while (0)
; #define PG8_WAIT_V(n) asm volatile("s_waitcnt vmcnt(" #n ")" ::: "memory")
; #define PG8_WAIT_L(n) asm volatile("s_waitcnt lgkmcnt(" #n ")" ::: "memory")
; #define PG8_BAR __builtin_amdgcn_s_barrier()
; #define PG8_SCHED __builtin_amdgcn_sched_barrier(0)
; template <class Epi, class Sched, bool ALIGN_EPI = false, bool SP2 = false>
; __device__ __forceinline__ void gemm_phase(PG8_LAS unsigned char* lds, const Gemm g, const Sched& S, const Epi& E) {
;     ...
;             PG8_LDA(At, 1, 1); PG8_STAGE(PG8_SB(1, 0), b3, voffB); PG8_STAGE(PG8_SB(1, 1), b3 + hstep, voffB); PG8_STAGE(PG8_SA(1, 0), a3, voffA);
;             PG8_WAIT_V(8); PG8_WAIT_L(0); PG8_BAR; PG8_MMA(1, 0, At, B0); PG8_MMA(1, 1, At, B1); PG8_BAR; PG8_SCHED;
;     ...
;         if constexpr (ALIGN_EPI) { if (wr == 0) PG8_BAR; }
	s_add_i32 s34, s55, s33
	v_lshl_add_u64 v[212:213], v[212:213], 0, s[80:81]
	s_mov_b32 m0, s34
	ds_read_b128 v[162:165], v211 offset:49152
	ds_read_b128 v[166:169], v211 offset:50176
	ds_read_b128 v[170:173], v211 offset:51200
	ds_read_b128 v[174:177], v211 offset:52224
	ds_read_b128 v[180:183], v211 offset:53248
	ds_read_b128 v[198:201], v211 offset:54272
	ds_read_b128 v[202:205], v211 offset:55296
	ds_read_b128 v[206:209], v211 offset:56320
	global_load_lds_dwordx4 v[212:213], off
	s_add_i32 m0, s34, 0x2000
	s_add_u32 s30, s30, 0x40080
	v_lshl_add_u64 v[212:213], v[214:215], 0, s[80:81]
	s_addc_u32 s31, s31, 0
	s_add_i32 s34, s56, s33
	global_load_lds_dwordx4 v[212:213], off
	v_lshl_add_u64 v[212:213], s[30:31], 0, v[188:189]
	s_mov_b32 m0, s34
	s_nop 0
	global_load_lds_dwordx4 v[212:213], off
	v_lshl_add_u64 v[212:213], s[30:31], 0, v[192:193]
	s_add_i32 m0, s34, 0x2000
	s_nop 0
	global_load_lds_dwordx4 v[212:213], off
	v_lshl_add_u64 v[212:213], v[216:217], 0, s[80:81]
	s_mov_b32 m0, s47
	s_nop 0
	global_load_lds_dwordx4 v[212:213], off
	v_lshl_add_u64 v[212:213], v[218:219], 0, s[80:81]
	s_mov_b32 m0, s48
	s_nop 0
	global_load_lds_dwordx4 v[212:213], off
	s_waitcnt vmcnt(8) lgkmcnt(0)
	s_barrier
	s_setprio 1
	v_mfma_f32_16x16x32_bf16 v[62:65], v[130:133], v[162:165], v[62:65]
	v_mfma_f32_16x16x32_bf16 v[58:61], v[138:141], v[162:165], v[58:61]
	v_mfma_f32_16x16x32_bf16 v[46:49], v[130:133], v[170:173], v[46:49]
	v_mfma_f32_16x16x32_bf16 v[42:45], v[138:141], v[170:173], v[42:45]
	v_mfma_f32_16x16x32_bf16 v[30:33], v[130:133], v[180:183], v[30:33]
	v_mfma_f32_16x16x32_bf16 v[26:29], v[138:141], v[180:183], v[26:29]
	v_mfma_f32_16x16x32_bf16 v[14:17], v[130:133], v[202:205], v[14:17]
	v_mfma_f32_16x16x32_bf16 v[10:13], v[138:141], v[202:205], v[10:13]
	v_mfma_f32_16x16x32_bf16 v[62:65], v[134:137], v[166:169], v[62:65]
	v_mfma_f32_16x16x32_bf16 v[58:61], v[142:145], v[166:169], v[58:61]
	v_mfma_f32_16x16x32_bf16 v[46:49], v[134:137], v[174:177], v[46:49]
	v_mfma_f32_16x16x32_bf16 v[42:45], v[142:145], v[174:177], v[42:45]
	v_mfma_f32_16x16x32_bf16 v[30:33], v[134:137], v[198:201], v[30:33]
	v_mfma_f32_16x16x32_bf16 v[26:29], v[142:145], v[198:201], v[26:29]
	v_mfma_f32_16x16x32_bf16 v[14:17], v[134:137], v[206:209], v[14:17]
	v_mfma_f32_16x16x32_bf16 v[10:13], v[142:145], v[206:209], v[10:13]
	v_mfma_f32_16x16x32_bf16 v[54:57], v[146:149], v[162:165], v[54:57]
	v_mfma_f32_16x16x32_bf16 v[50:53], v[154:157], v[162:165], v[50:53]
	v_mfma_f32_16x16x32_bf16 v[38:41], v[146:149], v[170:173], v[38:41]
	v_mfma_f32_16x16x32_bf16 v[34:37], v[154:157], v[170:173], v[34:37]
	v_mfma_f32_16x16x32_bf16 v[22:25], v[146:149], v[180:183], v[22:25]
	v_mfma_f32_16x16x32_bf16 v[18:21], v[154:157], v[180:183], v[18:21]
	v_mfma_f32_16x16x32_bf16 v[6:9], v[146:149], v[202:205], v[6:9]
	v_mfma_f32_16x16x32_bf16 v[2:5], v[154:157], v[202:205], v[2:5]
	v_mfma_f32_16x16x32_bf16 v[54:57], v[150:153], v[166:169], v[54:57]
	v_mfma_f32_16x16x32_bf16 v[50:53], v[158:161], v[166:169], v[50:53]
	v_mfma_f32_16x16x32_bf16 v[38:41], v[150:153], v[174:177], v[38:41]
	v_mfma_f32_16x16x32_bf16 v[34:37], v[158:161], v[174:177], v[34:37]
	v_mfma_f32_16x16x32_bf16 v[22:25], v[150:153], v[198:201], v[22:25]
	v_mfma_f32_16x16x32_bf16 v[18:21], v[158:161], v[198:201], v[18:21]
	v_mfma_f32_16x16x32_bf16 v[6:9], v[150:153], v[206:209], v[6:9]
	v_mfma_f32_16x16x32_bf16 v[2:5], v[158:161], v[206:209], v[2:5]
	s_setprio 0
	s_barrier
	s_add_i32 s54, s54, 2
	s_add_u32 s28, s28, 0x100
	s_addc_u32 s29, s29, 0
	s_add_u32 s52, s52, 0x100
	s_addc_u32 s53, s53, 0
	s_cmp_gt_u32 s54, 13
	s_cbranch_scc0 .LBB0_1106
	s_and_b64 vcc, exec, s[14:15]
	s_cbranch_vccz .LBB0_1109
	s_barrier

; #define PG8_STAGE(bufoff, gbase, voff) do { _Pragma("unroll") for (int _i = 0; _i < 2; ++_i) \
;         __builtin_amdgcn_global_load_lds((const unsigned*)((const char*)(gbase) + (voff)[_i]), (PG8_LAS unsigned*)(lds + (bufoff) + ldsw + _i * 8192), 16, 0, 0); } while (0)
; #define PG8_LDA(dst, b, h) do { _Pragma("unroll") for (int m = 0; m < 4; ++m) _Pragma("unroll") for (int k = 0; k < 2; ++k) dst[m][k] = *(const PG8_LAS bf16x8*)(lds + PG8_SA(b, h) + aoff + m * 2048 + k * 1024); } while (0)
; #define PG8_LDB(dst, b, h) do { _Pragma("unroll") for (int n = 0; n < 2; ++n) _Pragma("unroll") for (int k = 0; k < 2; ++k) dst[n][k] = *(const PG8_LAS bf16x8*)(lds + PG8_SB(b, h) + boff + n * 2048 + k * 1024); } while (0)
; #define PG8_WAIT_V(n) asm volatile("s_waitcnt vmcnt(" #n ")" ::: "memory")
; #define PG8_WAIT_L(n) asm volatile("s_waitcnt lgkmcnt(" #n ")" ::: "memory")
; #define PG8_BAR __builtin_amdgcn_s_barrier()
; #define PG8_SCHED __builtin_amdgcn_sched_barrier(0)
; template <class Epi, class Sched, bool ALIGN_EPI = false, bool SP2 = false>
; __device__ __forceinline__ void gemm_phase(PG8_LAS unsigned char* lds, const Gemm g, const Sched& S, const Epi& E) {
;     ...
;         const bool has_next = S.next(ui + 1, nxt);
;         const char* nA = has_next ? (const char*)g.A + (size_t)nxt.pm * tstep : cA; const char* nB = has_next ? (const char*)g.Bt + (size_t)nxt.pn * tstep : cB;
;         for (int t = 0; t < nt; t += 2) {
;             const bool last = (t == nt - 2);
;             const char* a1 = cA + (size_t)(t + 1) * kstep;
;             const char* a2 = last ? nA : cA + (size_t)(t + 2) * kstep; const char* b2 = last ? nB : cB + (size_t)(t + 2) * kstep;
;             const char* a3 = a2 + kstep; const char* b3 = b2 + kstep;
;             if (last && has_next) S.a_ready(nxt);
;             if constexpr (SP2) {
;             PG8_LDB(B0, 0, 0); PG8_LDB(B1, 0, 1); PG8_SCHED; PG8_LDA(At, 0, 0); PG8_STAGE(PG8_SA(1, 1), a1 + hstep, voffA);
;             PG8_WAIT_V(8); PG8_WAIT_L(0); PG8_BAR; PG8_MMA(0, 0, At, B0); PG8_MMA(0, 1, At, B1); PG8_BAR; PG8_SCHED;
;             PG8_LDA(At, 0, 1); PG8_STAGE(PG8_SB(0, 0), b2, voffB); PG8_STAGE(PG8_SB(0, 1), b2 + hstep, voffB); PG8_STAGE(PG8_SA(0, 0), a2, voffA);
;             PG8_WAIT_V(8); PG8_WAIT_L(0); PG8_BAR; PG8_MMA(1, 0, At, B0); PG8_MMA(1, 1, At, B1); PG8_BAR; PG8_SCHED;
.LBB0_1248:
	s_ashr_i32 s17, s16, 31
	s_lshl_b64 s[18:19], s[16:17], 19
	s_add_u32 s18, s0, s18
	s_addc_u32 s19, s1, s19
	s_and_b64 s[20:21], s[4:5], exec
	s_cselect_b32 s17, s19, s25
	s_cselect_b32 s45, s18, s24
	s_ashr_i32 s15, s14, 31
	s_lshl_b64 s[20:21], s[14:15], 19
	s_add_u32 s20, s34, s20
	s_addc_u32 s21, s35, s21
	s_and_b64 s[28:29], s[4:5], exec
	s_cselect_b32 s15, s21, s27
	s_cselect_b32 s46, s20, s26
	s_add_u32 s24, s24, 0x40080
	s_addc_u32 s25, s25, 0
	s_add_u32 s47, s26, 0x100
	s_addc_u32 s48, s27, 0
	s_mov_b32 s49, -2
	s_add_u32 s26, s24, 0xfffc0080
	s_addc_u32 s27, s25, -1
	s_add_i32 s50, 0, 0x10000
	s_cmp_eq_u32 s49, 12
	s_cselect_b32 s29, s17, s27
	s_cselect_b32 s28, s45, s26
	v_add_u32_e32 v156, s50, v158
	s_cselect_b32 s27, s15, s48
	s_cselect_b32 s26, s46, s47
	s_add_i32 s52, 0, 0x14000
	ds_read_b128 v[66:69], v156
	ds_read_b128 v[118:121], v156 offset:1024
	ds_read_b128 v[152:155], v156 offset:2048
	ds_read_b128 v[162:165], v156 offset:3072
	v_add_u32_e32 v156, s52, v158
	ds_read_b128 v[166:169], v156
	ds_read_b128 v[170:173], v156 offset:1024
	ds_read_b128 v[174:177], v156 offset:2048
	ds_read_b128 v[180:183], v156 offset:3072
	v_lshl_add_u64 v[156:157], s[24:25], 0, v[148:149]
	s_add_i32 m0, s33, 0xc000
	ds_read_b128 v[186:189], v160
	ds_read_b128 v[190:193], v160 offset:1024
	ds_read_b128 v[194:197], v160 offset:2048
	ds_read_b128 v[198:201], v160 offset:3072
	ds_read_b128 v[202:205], v160 offset:4096
	ds_read_b128 v[206:209], v160 offset:5120
	ds_read_b128 v[210:213], v160 offset:6144
	ds_read_b128 v[214:217], v160 offset:7168
	global_load_lds_dwordx4 v[156:157], off
	v_lshl_add_u64 v[156:157], s[24:25], 0, v[150:151]
	s_add_i32 m0, s33, 0xe000
	s_nop 0
	global_load_lds_dwordx4 v[156:157], off
	s_waitcnt vmcnt(8) lgkmcnt(0)
	s_barrier
	s_setprio 1
	v_mfma_f32_16x16x32_bf16 v[134:137], v[66:69], v[186:189], 0
	v_mfma_f32_16x16x32_bf16 v[126:129], v[152:155], v[186:189], 0
	v_mfma_f32_16x16x32_bf16 v[114:117], v[66:69], v[194:197], 0
	v_mfma_f32_16x16x32_bf16 v[110:113], v[152:155], v[194:197], 0
	v_mfma_f32_16x16x32_bf16 v[98:101], v[66:69], v[202:205], 0
	v_mfma_f32_16x16x32_bf16 v[94:97], v[152:155], v[202:205], 0
	v_mfma_f32_16x16x32_bf16 v[82:85], v[66:69], v[210:213], 0
	v_mfma_f32_16x16x32_bf16 v[78:81], v[152:155], v[210:213], 0
	v_mfma_f32_16x16x32_bf16 v[134:137], v[118:121], v[190:193], v[134:137]
	v_mfma_f32_16x16x32_bf16 v[126:129], v[162:165], v[190:193], v[126:129]
	v_mfma_f32_16x16x32_bf16 v[114:117], v[118:121], v[198:201], v[114:117]
	v_mfma_f32_16x16x32_bf16 v[110:113], v[162:165], v[198:201], v[110:113]
	v_mfma_f32_16x16x32_bf16 v[98:101], v[118:121], v[206:209], v[98:101]
	v_mfma_f32_16x16x32_bf16 v[94:97], v[162:165], v[206:209], v[94:97]
	v_mfma_f32_16x16x32_bf16 v[82:85], v[118:121], v[214:217], v[82:85]
	v_mfma_f32_16x16x32_bf16 v[78:81], v[162:165], v[214:217], v[78:81]
	v_mfma_f32_16x16x32_bf16 v[130:133], v[166:169], v[186:189], 0
	v_mfma_f32_16x16x32_bf16 v[122:125], v[174:177], v[186:189], 0
	v_mfma_f32_16x16x32_bf16 v[106:109], v[166:169], v[194:197], 0
	v_mfma_f32_16x16x32_bf16 v[102:105], v[174:177], v[194:197], 0
	v_mfma_f32_16x16x32_bf16 v[90:93], v[166:169], v[202:205], 0
	v_mfma_f32_16x16x32_bf16 v[86:89], v[174:177], v[202:205], 0
	v_mfma_f32_16x16x32_bf16 v[74:77], v[166:169], v[210:213], 0
	v_mfma_f32_16x16x32_bf16 v[70:73], v[174:177], v[210:213], 0
	v_mfma_f32_16x16x32_bf16 v[130:133], v[170:173], v[190:193], v[130:133]
	v_mfma_f32_16x16x32_bf16 v[122:125], v[180:183], v[190:193], v[122:125]
	v_mfma_f32_16x16x32_bf16 v[106:109], v[170:173], v[198:201], v[106:109]
	v_mfma_f32_16x16x32_bf16 v[102:105], v[180:183], v[198:201], v[102:105]
	v_mfma_f32_16x16x32_bf16 v[90:93], v[170:173], v[206:209], v[90:93]
	v_mfma_f32_16x16x32_bf16 v[86:89], v[180:183], v[206:209], v[86:89]
	v_mfma_f32_16x16x32_bf16 v[74:77], v[170:173], v[214:217], v[74:77]
	v_mfma_f32_16x16x32_bf16 v[70:73], v[180:183], v[214:217], v[70:73]
	s_setprio 0
	s_barrier
	s_add_i32 s50, s50, s36
	v_lshl_add_u64 v[156:157], s[26:27], 0, v[142:143]
	s_mov_b32 m0, s50
	ds_read_b128 v[186:189], v160 offset:16384
	ds_read_b128 v[190:193], v160 offset:17408
	ds_read_b128 v[194:197], v160 offset:18432
	ds_read_b128 v[198:201], v160 offset:19456
	ds_read_b128 v[202:205], v160 offset:20480
	ds_read_b128 v[206:209], v160 offset:21504
	ds_read_b128 v[210:213], v160 offset:22528
	ds_read_b128 v[214:217], v160 offset:23552
	global_load_lds_dwordx4 v[156:157], off
	s_add_i32 m0, s50, 0x2000
	s_add_u32 s50, s26, 0x40000
	v_lshl_add_u64 v[218:219], s[26:27], 0, v[138:139]
	s_addc_u32 s51, s27, 0
	s_add_i32 s52, s52, s36
	global_load_lds_dwordx4 v[218:219], off
	v_lshl_add_u64 v[220:221], s[50:51], 0, v[142:143]
	s_mov_b32 m0, s52
	v_lshl_add_u64 v[222:223], s[28:29], 0, v[140:141]
	global_load_lds_dwordx4 v[220:221], off
	v_lshl_add_u64 v[220:221], s[50:51], 0, v[138:139]
	s_add_i32 m0, s52, 0x2000
	s_nop 0
	global_load_lds_dwordx4 v[220:221], off
	v_lshl_add_u64 v[220:221], s[28:29], 0, v[144:145]
	s_mov_b32 m0, s33
	s_nop 0
	global_load_lds_dwordx4 v[220:221], off
	s_mov_b32 m0, s38
	s_nop 0
	global_load_lds_dwordx4 v[222:223], off
	s_waitcnt vmcnt(8) lgkmcnt(0)
	s_barrier
; #define PG8_STAGE(bufoff, gbase, voff) do { _Pragma("unroll") for (int _i = 0; _i < 2; ++_i) \
;         __builtin_amdgcn_global_load_lds((const unsigned*)((const char*)(gbase) + (voff)[_i]), (PG8_LAS unsigned*)(lds + (bufoff) + ldsw + _i * 8192), 16, 0, 0); } while (0)
; #define PG8_LDA(dst, b, h) do { _Pragma("unroll") for (int m = 0; m < 4; ++m) _Pragma("unroll") for (int k = 0; k < 2; ++k) dst[m][k] = *(const PG8_LAS bf16x8*)(lds + PG8_SA(b, h) + aoff + m * 2048 + k * 1024); } while (0)
; #define PG8_LDB(dst, b, h) do { _Pragma("unroll") for (int n = 0; n < 2; ++n) _Pragma("unroll") for (int k = 0; k < 2; ++k) dst[n][k] = *(const PG8_LAS bf16x8*)(lds + PG8_SB(b, h) + boff + n * 2048 + k * 1024); } while (0)
; #define PG8_MMA(ai, bj, At, Bt) do { __builtin_amdgcn_s_setprio(1); _Pragma("unroll") for (int m = 0; m < 4; ++m) _Pragma("unroll") for (int n = 0; n < 2; ++n) _Pragma("unroll") for (int k = 0; k < 2; ++k) \
;         acc[ai][bj][m][n] = __builtin_amdgcn_mfma_f32_16x16x32_bf16(Bt[n][k], At[m][k], acc[ai][bj][m][n], 0, 0, 0); __builtin_amdgcn_s_setprio(0); } while (0)
; #define PG8_WAIT_V(n) asm volatile("s_waitcnt vmcnt(" #n ")" ::: "memory")
; #define PG8_WAIT_L(n) asm volatile("s_waitcnt lgkmcnt(" #n ")" ::: "memory")
; #define PG8_BAR __builtin_amdgcn_s_barrier()
; #define PG8_SCHED __builtin_amdgcn_sched_barrier(0)
; template <class Epi, class Sched, bool ALIGN_EPI = false, bool SP2 = false>
; __device__ __forceinline__ void gemm_phase(PG8_LAS unsigned char* lds, const Gemm g, const Sched& S, const Epi& E) {
;     ...
;             PG8_WAIT_V(8); PG8_WAIT_L(0); PG8_BAR; PG8_MMA(1, 0, At, B0); PG8_MMA(1, 1, At, B1); PG8_BAR; PG8_SCHED;
;             PG8_LDB(B0, 1, 0); PG8_LDB(B1, 1, 1); PG8_SCHED; PG8_LDA(At, 1, 0); PG8_STAGE(PG8_SA(0, 1), a2 + hstep, voffA);
;             PG8_WAIT_V(8); PG8_WAIT_L(0); PG8_BAR; PG8_MMA(0, 0, At, B0); PG8_MMA(0, 1, At, B1); PG8_BAR; PG8_SCHED;
	s_setprio 1
	v_mfma_f32_16x16x32_bf16 v[62:65], v[66:69], v[186:189], 0
	v_mfma_f32_16x16x32_bf16 v[58:61], v[152:155], v[186:189], 0
	v_mfma_f32_16x16x32_bf16 v[46:49], v[66:69], v[194:197], 0
	v_mfma_f32_16x16x32_bf16 v[42:45], v[152:155], v[194:197], 0
	v_mfma_f32_16x16x32_bf16 v[30:33], v[66:69], v[202:205], 0
	v_mfma_f32_16x16x32_bf16 v[26:29], v[152:155], v[202:205], 0
	v_mfma_f32_16x16x32_bf16 v[14:17], v[66:69], v[210:213], 0
	v_mfma_f32_16x16x32_bf16 v[10:13], v[152:155], v[210:213], 0
	v_mfma_f32_16x16x32_bf16 v[62:65], v[118:121], v[190:193], v[62:65]
	v_mfma_f32_16x16x32_bf16 v[58:61], v[162:165], v[190:193], v[58:61]
	v_mfma_f32_16x16x32_bf16 v[46:49], v[118:121], v[198:201], v[46:49]
	v_mfma_f32_16x16x32_bf16 v[42:45], v[162:165], v[198:201], v[42:45]
	v_mfma_f32_16x16x32_bf16 v[30:33], v[118:121], v[206:209], v[30:33]
	v_mfma_f32_16x16x32_bf16 v[26:29], v[162:165], v[206:209], v[26:29]
	v_mfma_f32_16x16x32_bf16 v[14:17], v[118:121], v[214:217], v[14:17]
	v_mfma_f32_16x16x32_bf16 v[10:13], v[162:165], v[214:217], v[10:13]
	v_mfma_f32_16x16x32_bf16 v[54:57], v[166:169], v[186:189], 0
	v_mfma_f32_16x16x32_bf16 v[50:53], v[174:177], v[186:189], 0
	v_mfma_f32_16x16x32_bf16 v[38:41], v[166:169], v[194:197], 0
	v_mfma_f32_16x16x32_bf16 v[34:37], v[174:177], v[194:197], 0
	v_mfma_f32_16x16x32_bf16 v[22:25], v[166:169], v[202:205], 0
	v_mfma_f32_16x16x32_bf16 v[18:21], v[174:177], v[202:205], 0
	v_mfma_f32_16x16x32_bf16 v[6:9], v[166:169], v[210:213], 0
	v_mfma_f32_16x16x32_bf16 v[2:5], v[174:177], v[210:213], 0
	v_mfma_f32_16x16x32_bf16 v[54:57], v[170:173], v[190:193], v[54:57]
	v_mfma_f32_16x16x32_bf16 v[50:53], v[180:183], v[190:193], v[50:53]
	v_mfma_f32_16x16x32_bf16 v[38:41], v[170:173], v[198:201], v[38:41]
	v_mfma_f32_16x16x32_bf16 v[34:37], v[180:183], v[198:201], v[34:37]
	v_mfma_f32_16x16x32_bf16 v[22:25], v[170:173], v[206:209], v[22:25]
	v_mfma_f32_16x16x32_bf16 v[18:21], v[180:183], v[206:209], v[18:21]
	v_mfma_f32_16x16x32_bf16 v[6:9], v[170:173], v[214:217], v[6:9]
	v_mfma_f32_16x16x32_bf16 v[2:5], v[180:183], v[214:217], v[2:5]
	s_setprio 0
	s_barrier
	s_add_i32 s50, 0, 0x18000
	v_add_u32_e32 v161, s50, v158
	s_add_i32 s51, 0, 0x1c000
	ds_read_b128 v[66:69], v161
	ds_read_b128 v[118:121], v161 offset:1024
	ds_read_b128 v[152:155], v161 offset:2048
	ds_read_b128 v[162:165], v161 offset:3072
	v_add_u32_e32 v161, s51, v158
	ds_read_b128 v[166:169], v161
	ds_read_b128 v[170:173], v161 offset:1024
	ds_read_b128 v[174:177], v161 offset:2048
	ds_read_b128 v[180:183], v161 offset:3072
	s_add_u32 s28, s28, 0x40000
	s_addc_u32 s29, s29, 0
	s_mov_b32 m0, s39
	v_lshl_add_u64 v[240:241], s[28:29], 0, v[144:145]
	ds_read_b128 v[186:189], v160 offset:32768
	ds_read_b128 v[190:193], v160 offset:33792
	ds_read_b128 v[194:197], v160 offset:34816
	ds_read_b128 v[198:201], v160 offset:35840
	ds_read_b128 v[202:205], v160 offset:36864
	ds_read_b128 v[206:209], v160 offset:37888
	ds_read_b128 v[210:213], v160 offset:38912
	ds_read_b128 v[214:217], v160 offset:39936
	global_load_lds_dwordx4 v[240:241], off
	v_lshl_add_u64 v[240:241], s[28:29], 0, v[140:141]
	s_mov_b32 m0, s40
	s_nop 0
	global_load_lds_dwordx4 v[240:241], off
	s_waitcnt vmcnt(8) lgkmcnt(0)
	s_barrier
	s_setprio 1
	v_mfma_f32_16x16x32_bf16 v[134:137], v[66:69], v[186:189], v[134:137]
	v_mfma_f32_16x16x32_bf16 v[126:129], v[152:155], v[186:189], v[126:129]
	v_mfma_f32_16x16x32_bf16 v[114:117], v[66:69], v[194:197], v[114:117]
	v_mfma_f32_16x16x32_bf16 v[110:113], v[152:155], v[194:197], v[110:113]
	v_mfma_f32_16x16x32_bf16 v[98:101], v[66:69], v[202:205], v[98:101]
	v_mfma_f32_16x16x32_bf16 v[94:97], v[152:155], v[202:205], v[94:97]
	v_mfma_f32_16x16x32_bf16 v[82:85], v[66:69], v[210:213], v[82:85]
	v_mfma_f32_16x16x32_bf16 v[78:81], v[152:155], v[210:213], v[78:81]
	v_mfma_f32_16x16x32_bf16 v[134:137], v[118:121], v[190:193], v[134:137]
	v_mfma_f32_16x16x32_bf16 v[126:129], v[162:165], v[190:193], v[126:129]
	v_mfma_f32_16x16x32_bf16 v[114:117], v[118:121], v[198:201], v[114:117]
	v_mfma_f32_16x16x32_bf16 v[110:113], v[162:165], v[198:201], v[110:113]
	v_mfma_f32_16x16x32_bf16 v[98:101], v[118:121], v[206:209], v[98:101]
	v_mfma_f32_16x16x32_bf16 v[94:97], v[162:165], v[206:209], v[94:97]
	v_mfma_f32_16x16x32_bf16 v[82:85], v[118:121], v[214:217], v[82:85]
	v_mfma_f32_16x16x32_bf16 v[78:81], v[162:165], v[214:217], v[78:81]
	v_mfma_f32_16x16x32_bf16 v[130:133], v[166:169], v[186:189], v[130:133]
	v_mfma_f32_16x16x32_bf16 v[122:125], v[174:177], v[186:189], v[122:125]
	v_mfma_f32_16x16x32_bf16 v[106:109], v[166:169], v[194:197], v[106:109]
	v_mfma_f32_16x16x32_bf16 v[102:105], v[174:177], v[194:197], v[102:105]
	v_mfma_f32_16x16x32_bf16 v[90:93], v[166:169], v[202:205], v[90:93]
	v_mfma_f32_16x16x32_bf16 v[86:89], v[174:177], v[202:205], v[86:89]
	v_mfma_f32_16x16x32_bf16 v[74:77], v[166:169], v[210:213], v[74:77]
	v_mfma_f32_16x16x32_bf16 v[70:73], v[174:177], v[210:213], v[70:73]
	v_mfma_f32_16x16x32_bf16 v[130:133], v[170:173], v[190:193], v[130:133]
	v_mfma_f32_16x16x32_bf16 v[122:125], v[180:183], v[190:193], v[122:125]
	v_mfma_f32_16x16x32_bf16 v[106:109], v[170:173], v[198:201], v[106:109]
	v_mfma_f32_16x16x32_bf16 v[102:105], v[180:183], v[198:201], v[102:105]
	v_mfma_f32_16x16x32_bf16 v[90:93], v[170:173], v[206:209], v[90:93]
	v_mfma_f32_16x16x32_bf16 v[86:89], v[180:183], v[206:209], v[86:89]
	v_mfma_f32_16x16x32_bf16 v[74:77], v[170:173], v[214:217], v[74:77]
	v_mfma_f32_16x16x32_bf16 v[70:73], v[180:183], v[214:217], v[70:73]
	s_setprio 0
	s_barrier
; #define PG8_STAGE(bufoff, gbase, voff) do { _Pragma("unroll") for (int _i = 0; _i < 2; ++_i) \
;         __builtin_amdgcn_global_load_lds((const unsigned*)((const char*)(gbase) + (voff)[_i]), (PG8_LAS unsigned*)(lds + (bufoff) + ldsw + _i * 8192), 16, 0, 0); } while (0)
; #define PG8_LDA(dst, b, h) do { _Pragma("unroll") for (int m = 0; m < 4; ++m) _Pragma("unroll") for (int k = 0; k < 2; ++k) dst[m][k] = *(const PG8_LAS bf16x8*)(lds + PG8_SA(b, h) + aoff + m * 2048 + k * 1024); } while (0)
; #define PG8_LDB(dst, b, h) do { _Pragma("unroll") for (int n = 0; n < 2; ++n) _Pragma("unroll") for (int k = 0; k < 2; ++k) dst[n][k] = *(const PG8_LAS bf16x8*)(lds + PG8_SB(b, h) + boff + n * 2048 + k * 1024); } while (0)
; #define PG8_MMA(ai, bj, At, Bt) do { __builtin_amdgcn_s_setprio(1); _Pragma("unroll") for (int m = 0; m < 4; ++m) _Pragma("unroll") for (int n = 0; n < 2; ++n) _Pragma("unroll") for (int k = 0; k < 2; ++k) \
;         acc[ai][bj][m][n] = __builtin_amdgcn_mfma_f32_16x16x32_bf16(Bt[n][k], At[m][k], acc[ai][bj][m][n], 0, 0, 0); __builtin_amdgcn_s_setprio(0); } while (0)
; #define PG8_WAIT_V(n) asm volatile("s_waitcnt vmcnt(" #n ")" ::: "memory")
; #define PG8_WAIT_L(n) asm volatile("s_waitcnt lgkmcnt(" #n ")" ::: "memory")
; #define PG8_BAR __builtin_amdgcn_s_barrier()
; #define PG8_SCHED __builtin_amdgcn_sched_barrier(0)
; template <class Epi, class Sched, bool ALIGN_EPI = false, bool SP2 = false>
; __device__ __forceinline__ void gemm_phase(PG8_LAS unsigned char* lds, const Gemm g, const Sched& S, const Epi& E) {
;     ...
;             PG8_LDB(B0, 0, 0); PG8_LDB(B1, 0, 1); PG8_SCHED; PG8_LDA(At, 0, 0); PG8_STAGE(PG8_SA(1, 1), a1 + hstep, voffA);
;             PG8_WAIT_V(8); PG8_WAIT_L(0); PG8_BAR; PG8_MMA(0, 0, At, B0); PG8_MMA(0, 1, At, B1); PG8_BAR; PG8_SCHED;
;     ...
;             PG8_LDA(At, 1, 1); PG8_STAGE(PG8_SB(1, 0), b3, voffB); PG8_STAGE(PG8_SB(1, 1), b3 + hstep, voffB); PG8_STAGE(PG8_SA(1, 0), a3, voffA);
;             PG8_WAIT_V(8); PG8_WAIT_L(0); PG8_BAR; PG8_MMA(1, 0, At, B0); PG8_MMA(1, 1, At, B1); PG8_BAR; PG8_SCHED;
	s_add_i32 s28, s50, s36
	v_lshl_add_u64 v[156:157], v[156:157], 0, s[80:81]
	s_mov_b32 m0, s28
	ds_read_b128 v[186:189], v160 offset:49152
	ds_read_b128 v[190:193], v160 offset:50176
	ds_read_b128 v[194:197], v160 offset:51200
	ds_read_b128 v[198:201], v160 offset:52224
	ds_read_b128 v[202:205], v160 offset:53248
	ds_read_b128 v[206:209], v160 offset:54272
	ds_read_b128 v[210:213], v160 offset:55296
	ds_read_b128 v[214:217], v160 offset:56320
	global_load_lds_dwordx4 v[156:157], off
	s_add_i32 m0, s28, 0x2000
	s_add_u32 s26, s26, 0x40080
	v_lshl_add_u64 v[156:157], v[218:219], 0, s[80:81]
	s_addc_u32 s27, s27, 0
	s_add_i32 s28, s51, s36
	global_load_lds_dwordx4 v[156:157], off
	v_lshl_add_u64 v[156:157], s[26:27], 0, v[142:143]
	s_mov_b32 m0, s28
	s_nop 0
	global_load_lds_dwordx4 v[156:157], off
	v_lshl_add_u64 v[156:157], s[26:27], 0, v[138:139]
	s_add_i32 m0, s28, 0x2000
	s_nop 0
	global_load_lds_dwordx4 v[156:157], off
	v_lshl_add_u64 v[156:157], v[220:221], 0, s[80:81]
	s_mov_b32 m0, s41
	s_nop 0
	global_load_lds_dwordx4 v[156:157], off
	v_lshl_add_u64 v[156:157], v[222:223], 0, s[80:81]
	s_mov_b32 m0, s42
	s_nop 0
	global_load_lds_dwordx4 v[156:157], off
	s_waitcnt vmcnt(8) lgkmcnt(0)
	s_barrier
	s_setprio 1
	v_mfma_f32_16x16x32_bf16 v[62:65], v[66:69], v[186:189], v[62:65]
	v_mfma_f32_16x16x32_bf16 v[58:61], v[152:155], v[186:189], v[58:61]
	v_mfma_f32_16x16x32_bf16 v[46:49], v[66:69], v[194:197], v[46:49]
	v_mfma_f32_16x16x32_bf16 v[42:45], v[152:155], v[194:197], v[42:45]
	v_mfma_f32_16x16x32_bf16 v[30:33], v[66:69], v[202:205], v[30:33]
	v_mfma_f32_16x16x32_bf16 v[26:29], v[152:155], v[202:205], v[26:29]
	v_mfma_f32_16x16x32_bf16 v[14:17], v[66:69], v[210:213], v[14:17]
	v_mfma_f32_16x16x32_bf16 v[10:13], v[152:155], v[210:213], v[10:13]
	v_mfma_f32_16x16x32_bf16 v[62:65], v[118:121], v[190:193], v[62:65]
	v_mfma_f32_16x16x32_bf16 v[58:61], v[162:165], v[190:193], v[58:61]
	v_mfma_f32_16x16x32_bf16 v[46:49], v[118:121], v[198:201], v[46:49]
	v_mfma_f32_16x16x32_bf16 v[42:45], v[162:165], v[198:201], v[42:45]
	v_mfma_f32_16x16x32_bf16 v[30:33], v[118:121], v[206:209], v[30:33]
	v_mfma_f32_16x16x32_bf16 v[26:29], v[162:165], v[206:209], v[26:29]
	v_mfma_f32_16x16x32_bf16 v[14:17], v[118:121], v[214:217], v[14:17]
	v_mfma_f32_16x16x32_bf16 v[10:13], v[162:165], v[214:217], v[10:13]
	v_mfma_f32_16x16x32_bf16 v[54:57], v[166:169], v[186:189], v[54:57]
	v_mfma_f32_16x16x32_bf16 v[50:53], v[174:177], v[186:189], v[50:53]
	v_mfma_f32_16x16x32_bf16 v[38:41], v[166:169], v[194:197], v[38:41]
	v_mfma_f32_16x16x32_bf16 v[34:37], v[174:177], v[194:197], v[34:37]
	v_mfma_f32_16x16x32_bf16 v[22:25], v[166:169], v[202:205], v[22:25]
	v_mfma_f32_16x16x32_bf16 v[18:21], v[174:177], v[202:205], v[18:21]
	v_mfma_f32_16x16x32_bf16 v[6:9], v[166:169], v[210:213], v[6:9]
	v_mfma_f32_16x16x32_bf16 v[2:5], v[174:177], v[210:213], v[2:5]
	v_mfma_f32_16x16x32_bf16 v[54:57], v[170:173], v[190:193], v[54:57]
	v_mfma_f32_16x16x32_bf16 v[50:53], v[180:183], v[190:193], v[50:53]
	v_mfma_f32_16x16x32_bf16 v[38:41], v[170:173], v[198:201], v[38:41]
	v_mfma_f32_16x16x32_bf16 v[34:37], v[180:183], v[198:201], v[34:37]
	v_mfma_f32_16x16x32_bf16 v[22:25], v[170:173], v[206:209], v[22:25]
	v_mfma_f32_16x16x32_bf16 v[18:21], v[180:183], v[206:209], v[18:21]
	v_mfma_f32_16x16x32_bf16 v[6:9], v[170:173], v[214:217], v[6:9]
	v_mfma_f32_16x16x32_bf16 v[2:5], v[180:183], v[214:217], v[2:5]
	s_setprio 0
	s_barrier
	s_add_i32 s49, s49, 2
	s_add_u32 s24, s24, 0x100
	s_addc_u32 s25, s25, 0
	s_add_u32 s47, s47, 0x100
	s_addc_u32 s48, s48, 0
	s_cmp_gt_u32 s49, 13
	s_branch .LBB0_1249
.LBB0_1249:
	s_add_u32 s26, s24, 0xfffc0080
	s_addc_u32 s27, s25, -1
	s_add_i32 s50, 0, 0x10000
	s_cmp_eq_u32 s49, 12
	s_cselect_b32 s29, s17, s27
	s_cselect_b32 s28, s45, s26
	v_add_u32_e32 v156, s50, v158
	s_cselect_b32 s27, s15, s48
	s_cselect_b32 s26, s46, s47
	s_add_i32 s52, 0, 0x14000
	ds_read_b128 v[66:69], v156
	ds_read_b128 v[118:121], v156 offset:1024
	ds_read_b128 v[152:155], v156 offset:2048
	ds_read_b128 v[162:165], v156 offset:3072
	v_add_u32_e32 v156, s52, v158
	ds_read_b128 v[166:169], v156
	ds_read_b128 v[170:173], v156 offset:1024
	ds_read_b128 v[174:177], v156 offset:2048
	ds_read_b128 v[180:183], v156 offset:3072
	v_lshl_add_u64 v[156:157], s[24:25], 0, v[148:149]
	s_add_i32 m0, s33, 0xc000
	ds_read_b128 v[186:189], v160
	ds_read_b128 v[190:193], v160 offset:1024
	ds_read_b128 v[194:197], v160 offset:2048
	ds_read_b128 v[198:201], v160 offset:3072
	ds_read_b128 v[202:205], v160 offset:4096
	ds_read_b128 v[206:209], v160 offset:5120
	ds_read_b128 v[210:213], v160 offset:6144
	ds_read_b128 v[214:217], v160 offset:7168
	global_load_lds_dwordx4 v[156:157], off
	v_lshl_add_u64 v[156:157], s[24:25], 0, v[150:151]
	s_add_i32 m0, s33, 0xe000
	s_nop 0
	global_load_lds_dwordx4 v[156:157], off
	s_waitcnt vmcnt(8) lgkmcnt(0)
	s_barrier
; #define PG8_STAGE(bufoff, gbase, voff) do { _Pragma("unroll") for (int _i = 0; _i < 2; ++_i) \
;         __builtin_amdgcn_global_load_lds((const unsigned*)((const char*)(gbase) + (voff)[_i]), (PG8_LAS unsigned*)(lds + (bufoff) + ldsw + _i * 8192), 16, 0, 0); } while (0)
; #define PG8_LDA(dst, b, h) do { _Pragma("unroll") for (int m = 0; m < 4; ++m) _Pragma("unroll") for (int k = 0; k < 2; ++k) dst[m][k] = *(const PG8_LAS bf16x8*)(lds + PG8_SA(b, h) + aoff + m * 2048 + k * 1024); } while (0)
; #define PG8_MMA(ai, bj, At, Bt) do { __builtin_amdgcn_s_setprio(1); _Pragma("unroll") for (int m = 0; m < 4; ++m) _Pragma("unroll") for (int n = 0; n < 2; ++n) _Pragma("unroll") for (int k = 0; k < 2; ++k) \
;         acc[ai][bj][m][n] = __builtin_amdgcn_mfma_f32_16x16x32_bf16(Bt[n][k], At[m][k], acc[ai][bj][m][n], 0, 0, 0); __builtin_amdgcn_s_setprio(0); } while (0)
; #define PG8_WAIT_V(n) asm volatile("s_waitcnt vmcnt(" #n ")" ::: "memory")
; #define PG8_WAIT_L(n) asm volatile("s_waitcnt lgkmcnt(" #n ")" ::: "memory")
; #define PG8_BAR __builtin_amdgcn_s_barrier()
; #define PG8_SCHED __builtin_amdgcn_sched_barrier(0)
; template <class Epi, class Sched, bool ALIGN_EPI = false, bool SP2 = false>
; __device__ __forceinline__ void gemm_phase(PG8_LAS unsigned char* lds, const Gemm g, const Sched& S, const Epi& E) {
;     ...
;             PG8_WAIT_V(8); PG8_WAIT_L(0); PG8_BAR; PG8_MMA(0, 0, At, B0); PG8_MMA(0, 1, At, B1); PG8_BAR; PG8_SCHED;
;             PG8_LDA(At, 0, 1); PG8_STAGE(PG8_SB(0, 0), b2, voffB); PG8_STAGE(PG8_SB(0, 1), b2 + hstep, voffB); PG8_STAGE(PG8_SA(0, 0), a2, voffA);
;             PG8_WAIT_V(8); PG8_WAIT_L(0); PG8_BAR; PG8_MMA(1, 0, At, B0); PG8_MMA(1, 1, At, B1); PG8_BAR; PG8_SCHED;
	s_setprio 1
	v_mfma_f32_16x16x32_bf16 v[134:137], v[66:69], v[186:189], v[134:137]
	v_mfma_f32_16x16x32_bf16 v[126:129], v[152:155], v[186:189], v[126:129]
	v_mfma_f32_16x16x32_bf16 v[114:117], v[66:69], v[194:197], v[114:117]
	v_mfma_f32_16x16x32_bf16 v[110:113], v[152:155], v[194:197], v[110:113]
	v_mfma_f32_16x16x32_bf16 v[98:101], v[66:69], v[202:205], v[98:101]
	v_mfma_f32_16x16x32_bf16 v[94:97], v[152:155], v[202:205], v[94:97]
	v_mfma_f32_16x16x32_bf16 v[82:85], v[66:69], v[210:213], v[82:85]
	v_mfma_f32_16x16x32_bf16 v[78:81], v[152:155], v[210:213], v[78:81]
	v_mfma_f32_16x16x32_bf16 v[134:137], v[118:121], v[190:193], v[134:137]
	v_mfma_f32_16x16x32_bf16 v[126:129], v[162:165], v[190:193], v[126:129]
	v_mfma_f32_16x16x32_bf16 v[114:117], v[118:121], v[198:201], v[114:117]
	v_mfma_f32_16x16x32_bf16 v[110:113], v[162:165], v[198:201], v[110:113]
	v_mfma_f32_16x16x32_bf16 v[98:101], v[118:121], v[206:209], v[98:101]
	v_mfma_f32_16x16x32_bf16 v[94:97], v[162:165], v[206:209], v[94:97]
	v_mfma_f32_16x16x32_bf16 v[82:85], v[118:121], v[214:217], v[82:85]
	v_mfma_f32_16x16x32_bf16 v[78:81], v[162:165], v[214:217], v[78:81]
	v_mfma_f32_16x16x32_bf16 v[130:133], v[166:169], v[186:189], v[130:133]
	v_mfma_f32_16x16x32_bf16 v[122:125], v[174:177], v[186:189], v[122:125]
	v_mfma_f32_16x16x32_bf16 v[106:109], v[166:169], v[194:197], v[106:109]
	v_mfma_f32_16x16x32_bf16 v[102:105], v[174:177], v[194:197], v[102:105]
	v_mfma_f32_16x16x32_bf16 v[90:93], v[166:169], v[202:205], v[90:93]
	v_mfma_f32_16x16x32_bf16 v[86:89], v[174:177], v[202:205], v[86:89]
	v_mfma_f32_16x16x32_bf16 v[74:77], v[166:169], v[210:213], v[74:77]
	v_mfma_f32_16x16x32_bf16 v[70:73], v[174:177], v[210:213], v[70:73]
	v_mfma_f32_16x16x32_bf16 v[130:133], v[170:173], v[190:193], v[130:133]
	v_mfma_f32_16x16x32_bf16 v[122:125], v[180:183], v[190:193], v[122:125]
	v_mfma_f32_16x16x32_bf16 v[106:109], v[170:173], v[198:201], v[106:109]
	v_mfma_f32_16x16x32_bf16 v[102:105], v[180:183], v[198:201], v[102:105]
	v_mfma_f32_16x16x32_bf16 v[90:93], v[170:173], v[206:209], v[90:93]
	v_mfma_f32_16x16x32_bf16 v[86:89], v[180:183], v[206:209], v[86:89]
	v_mfma_f32_16x16x32_bf16 v[74:77], v[170:173], v[214:217], v[74:77]
	v_mfma_f32_16x16x32_bf16 v[70:73], v[180:183], v[214:217], v[70:73]
	s_setprio 0
	s_barrier
	s_add_i32 s50, s50, s36
	v_lshl_add_u64 v[156:157], s[26:27], 0, v[142:143]
	s_mov_b32 m0, s50
	ds_read_b128 v[186:189], v160 offset:16384
	ds_read_b128 v[190:193], v160 offset:17408
	ds_read_b128 v[194:197], v160 offset:18432
	ds_read_b128 v[198:201], v160 offset:19456
	ds_read_b128 v[202:205], v160 offset:20480
	ds_read_b128 v[206:209], v160 offset:21504
	ds_read_b128 v[210:213], v160 offset:22528
	ds_read_b128 v[214:217], v160 offset:23552
	global_load_lds_dwordx4 v[156:157], off
	s_add_i32 m0, s50, 0x2000
	s_add_u32 s50, s26, 0x40000
	v_lshl_add_u64 v[218:219], s[26:27], 0, v[138:139]
	s_addc_u32 s51, s27, 0
	s_add_i32 s52, s52, s36
	global_load_lds_dwordx4 v[218:219], off
	v_lshl_add_u64 v[220:221], s[50:51], 0, v[142:143]
	s_mov_b32 m0, s52
	v_lshl_add_u64 v[222:223], s[28:29], 0, v[140:141]
	global_load_lds_dwordx4 v[220:221], off
	v_lshl_add_u64 v[220:221], s[50:51], 0, v[138:139]
	s_add_i32 m0, s52, 0x2000
	s_nop 0
	global_load_lds_dwordx4 v[220:221], off
	v_lshl_add_u64 v[220:221], s[28:29], 0, v[144:145]
	s_mov_b32 m0, s33
	s_nop 0
	global_load_lds_dwordx4 v[220:221], off
	s_mov_b32 m0, s38
	s_nop 0
	global_load_lds_dwordx4 v[222:223], off
	s_waitcnt vmcnt(8) lgkmcnt(0)
	s_barrier
	s_setprio 1
	v_mfma_f32_16x16x32_bf16 v[62:65], v[66:69], v[186:189], v[62:65]
	v_mfma_f32_16x16x32_bf16 v[58:61], v[152:155], v[186:189], v[58:61]
	v_mfma_f32_16x16x32_bf16 v[46:49], v[66:69], v[194:197], v[46:49]
	v_mfma_f32_16x16x32_bf16 v[42:45], v[152:155], v[194:197], v[42:45]
	v_mfma_f32_16x16x32_bf16 v[30:33], v[66:69], v[202:205], v[30:33]
	v_mfma_f32_16x16x32_bf16 v[26:29], v[152:155], v[202:205], v[26:29]
	v_mfma_f32_16x16x32_bf16 v[14:17], v[66:69], v[210:213], v[14:17]
	v_mfma_f32_16x16x32_bf16 v[10:13], v[152:155], v[210:213], v[10:13]
	v_mfma_f32_16x16x32_bf16 v[62:65], v[118:121], v[190:193], v[62:65]
	v_mfma_f32_16x16x32_bf16 v[58:61], v[162:165], v[190:193], v[58:61]
	v_mfma_f32_16x16x32_bf16 v[46:49], v[118:121], v[198:201], v[46:49]
	v_mfma_f32_16x16x32_bf16 v[42:45], v[162:165], v[198:201], v[42:45]
	v_mfma_f32_16x16x32_bf16 v[30:33], v[118:121], v[206:209], v[30:33]
	v_mfma_f32_16x16x32_bf16 v[26:29], v[162:165], v[206:209], v[26:29]
	v_mfma_f32_16x16x32_bf16 v[14:17], v[118:121], v[214:217], v[14:17]
	v_mfma_f32_16x16x32_bf16 v[10:13], v[162:165], v[214:217], v[10:13]
	v_mfma_f32_16x16x32_bf16 v[54:57], v[166:169], v[186:189], v[54:57]
	v_mfma_f32_16x16x32_bf16 v[50:53], v[174:177], v[186:189], v[50:53]
	v_mfma_f32_16x16x32_bf16 v[38:41], v[166:169], v[194:197], v[38:41]
	v_mfma_f32_16x16x32_bf16 v[34:37], v[174:177], v[194:197], v[34:37]
	v_mfma_f32_16x16x32_bf16 v[22:25], v[166:169], v[202:205], v[22:25]
	v_mfma_f32_16x16x32_bf16 v[18:21], v[174:177], v[202:205], v[18:21]
	v_mfma_f32_16x16x32_bf16 v[6:9], v[166:169], v[210:213], v[6:9]
	v_mfma_f32_16x16x32_bf16 v[2:5], v[174:177], v[210:213], v[2:5]
	v_mfma_f32_16x16x32_bf16 v[54:57], v[170:173], v[190:193], v[54:57]
	v_mfma_f32_16x16x32_bf16 v[50:53], v[180:183], v[190:193], v[50:53]
	v_mfma_f32_16x16x32_bf16 v[38:41], v[170:173], v[198:201], v[38:41]
	v_mfma_f32_16x16x32_bf16 v[34:37], v[180:183], v[198:201], v[34:37]
	v_mfma_f32_16x16x32_bf16 v[22:25], v[170:173], v[206:209], v[22:25]
	v_mfma_f32_16x16x32_bf16 v[18:21], v[180:183], v[206:209], v[18:21]
	v_mfma_f32_16x16x32_bf16 v[6:9], v[170:173], v[214:217], v[6:9]
	v_mfma_f32_16x16x32_bf16 v[2:5], v[180:183], v[214:217], v[2:5]
	s_setprio 0
	s_barrier
; #define PG8_STAGE(bufoff, gbase, voff) do { _Pragma("unroll") for (int _i = 0; _i < 2; ++_i) \
;         __builtin_amdgcn_global_load_lds((const unsigned*)((const char*)(gbase) + (voff)[_i]), (PG8_LAS unsigned*)(lds + (bufoff) + ldsw + _i * 8192), 16, 0, 0); } while (0)
; #define PG8_LDA(dst, b, h) do { _Pragma("unroll") for (int m = 0; m < 4; ++m) _Pragma("unroll") for (int k = 0; k < 2; ++k) dst[m][k] = *(const PG8_LAS bf16x8*)(lds + PG8_SA(b, h) + aoff + m * 2048 + k * 1024); } while (0)
; #define PG8_LDB(dst, b, h) do { _Pragma("unroll") for (int n = 0; n < 2; ++n) _Pragma("unroll") for (int k = 0; k < 2; ++k) dst[n][k] = *(const PG8_LAS bf16x8*)(lds + PG8_SB(b, h) + boff + n * 2048 + k * 1024); } while (0)
; #define PG8_MMA(ai, bj, At, Bt) do { __builtin_amdgcn_s_setprio(1); _Pragma("unroll") for (int m = 0; m < 4; ++m) _Pragma("unroll") for (int n = 0; n < 2; ++n) _Pragma("unroll") for (int k = 0; k < 2; ++k) \
;         acc[ai][bj][m][n] = __builtin_amdgcn_mfma_f32_16x16x32_bf16(Bt[n][k], At[m][k], acc[ai][bj][m][n], 0, 0, 0); __builtin_amdgcn_s_setprio(0); } while (0)
; #define PG8_WAIT_V(n) asm volatile("s_waitcnt vmcnt(" #n ")" ::: "memory")
; #define PG8_WAIT_L(n) asm volatile("s_waitcnt lgkmcnt(" #n ")" ::: "memory")
; #define PG8_BAR __builtin_amdgcn_s_barrier()
; #define PG8_SCHED __builtin_amdgcn_sched_barrier(0)
; template <class Epi, class Sched, bool ALIGN_EPI = false, bool SP2 = false>
; __device__ __forceinline__ void gemm_phase(PG8_LAS unsigned char* lds, const Gemm g, const Sched& S, const Epi& E) {
;     ...
;             PG8_LDB(B0, 1, 0); PG8_LDB(B1, 1, 1); PG8_SCHED; PG8_LDA(At, 1, 0); PG8_STAGE(PG8_SA(0, 1), a2 + hstep, voffA);
;             PG8_WAIT_V(8); PG8_WAIT_L(0); PG8_BAR; PG8_MMA(0, 0, At, B0); PG8_MMA(0, 1, At, B1); PG8_BAR; PG8_SCHED;
	s_add_i32 s50, 0, 0x18000
	v_add_u32_e32 v161, s50, v158
	s_add_i32 s51, 0, 0x1c000
	ds_read_b128 v[66:69], v161
	ds_read_b128 v[118:121], v161 offset:1024
	ds_read_b128 v[152:155], v161 offset:2048
	ds_read_b128 v[162:165], v161 offset:3072
	v_add_u32_e32 v161, s51, v158
	ds_read_b128 v[166:169], v161
	ds_read_b128 v[170:173], v161 offset:1024
	ds_read_b128 v[174:177], v161 offset:2048
	ds_read_b128 v[180:183], v161 offset:3072
	s_add_u32 s28, s28, 0x40000
	s_addc_u32 s29, s29, 0
	s_mov_b32 m0, s39
	v_lshl_add_u64 v[240:241], s[28:29], 0, v[144:145]
	ds_read_b128 v[186:189], v160 offset:32768
	ds_read_b128 v[190:193], v160 offset:33792
	ds_read_b128 v[194:197], v160 offset:34816
	ds_read_b128 v[198:201], v160 offset:35840
	ds_read_b128 v[202:205], v160 offset:36864
	ds_read_b128 v[206:209], v160 offset:37888
	ds_read_b128 v[210:213], v160 offset:38912
	ds_read_b128 v[214:217], v160 offset:39936
	global_load_lds_dwordx4 v[240:241], off
	v_lshl_add_u64 v[240:241], s[28:29], 0, v[140:141]
	s_mov_b32 m0, s40
	s_nop 0
	global_load_lds_dwordx4 v[240:241], off
	s_waitcnt vmcnt(8) lgkmcnt(0)
	s_barrier
	s_setprio 1
	v_mfma_f32_16x16x32_bf16 v[134:137], v[66:69], v[186:189], v[134:137]
	v_mfma_f32_16x16x32_bf16 v[126:129], v[152:155], v[186:189], v[126:129]
	v_mfma_f32_16x16x32_bf16 v[114:117], v[66:69], v[194:197], v[114:117]
	v_mfma_f32_16x16x32_bf16 v[110:113], v[152:155], v[194:197], v[110:113]
	v_mfma_f32_16x16x32_bf16 v[98:101], v[66:69], v[202:205], v[98:101]
	v_mfma_f32_16x16x32_bf16 v[94:97], v[152:155], v[202:205], v[94:97]
	v_mfma_f32_16x16x32_bf16 v[82:85], v[66:69], v[210:213], v[82:85]
	v_mfma_f32_16x16x32_bf16 v[78:81], v[152:155], v[210:213], v[78:81]
	v_mfma_f32_16x16x32_bf16 v[134:137], v[118:121], v[190:193], v[134:137]
	v_mfma_f32_16x16x32_bf16 v[126:129], v[162:165], v[190:193], v[126:129]
	v_mfma_f32_16x16x32_bf16 v[114:117], v[118:121], v[198:201], v[114:117]
	v_mfma_f32_16x16x32_bf16 v[110:113], v[162:165], v[198:201], v[110:113]
	v_mfma_f32_16x16x32_bf16 v[98:101], v[118:121], v[206:209], v[98:101]
	v_mfma_f32_16x16x32_bf16 v[94:97], v[162:165], v[206:209], v[94:97]
	v_mfma_f32_16x16x32_bf16 v[82:85], v[118:121], v[214:217], v[82:85]
	v_mfma_f32_16x16x32_bf16 v[78:81], v[162:165], v[214:217], v[78:81]
	v_mfma_f32_16x16x32_bf16 v[130:133], v[166:169], v[186:189], v[130:133]
	v_mfma_f32_16x16x32_bf16 v[122:125], v[174:177], v[186:189], v[122:125]
	v_mfma_f32_16x16x32_bf16 v[106:109], v[166:169], v[194:197], v[106:109]
	v_mfma_f32_16x16x32_bf16 v[102:105], v[174:177], v[194:197], v[102:105]
	v_mfma_f32_16x16x32_bf16 v[90:93], v[166:169], v[202:205], v[90:93]
	v_mfma_f32_16x16x32_bf16 v[86:89], v[174:177], v[202:205], v[86:89]
	v_mfma_f32_16x16x32_bf16 v[74:77], v[166:169], v[210:213], v[74:77]
	v_mfma_f32_16x16x32_bf16 v[70:73], v[174:177], v[210:213], v[70:73]
	v_mfma_f32_16x16x32_bf16 v[130:133], v[170:173], v[190:193], v[130:133]
	v_mfma_f32_16x16x32_bf16 v[122:125], v[180:183], v[190:193], v[122:125]
	v_mfma_f32_16x16x32_bf16 v[106:109], v[170:173], v[198:201], v[106:109]
	v_mfma_f32_16x16x32_bf16 v[102:105], v[180:183], v[198:201], v[102:105]
	v_mfma_f32_16x16x32_bf16 v[90:93], v[170:173], v[206:209], v[90:93]
	v_mfma_f32_16x16x32_bf16 v[86:89], v[180:183], v[206:209], v[86:89]
	v_mfma_f32_16x16x32_bf16 v[74:77], v[170:173], v[214:217], v[74:77]
	v_mfma_f32_16x16x32_bf16 v[70:73], v[180:183], v[214:217], v[70:73]
	s_setprio 0
	s_barrier
; #define PG8_STAGE(bufoff, gbase, voff) do { _Pragma("unroll") for (int _i = 0; _i < 2; ++_i) \
;         __builtin_amdgcn_global_load_lds((const unsigned*)((const char*)(gbase) + (voff)[_i]), (PG8_LAS unsigned*)(lds + (bufoff) + ldsw + _i * 8192), 16, 0, 0); } while (0)
; #define PG8_LDA(dst, b, h) do { _Pragma("unroll") for (int m = 0; m < 4; ++m) _Pragma("unroll") for (int k = 0; k < 2; ++k) dst[m][k] = *(const PG8_LAS bf16x8*)(lds + PG8_SA(b, h) + aoff + m * 2048 + k * 1024); } while (0)
; #define PG8_MMA(ai, bj, At, Bt) do { __builtin_amdgcn_s_setprio(1); _Pragma("unroll") for (int m = 0; m < 4; ++m) _Pragma("unroll") for (int n = 0; n < 2; ++n) _Pragma("unroll") for (int k = 0; k < 2; ++k) \
;         acc[ai][bj][m][n] = __builtin_amdgcn_mfma_f32_16x16x32_bf16(Bt[n][k], At[m][k], acc[ai][bj][m][n], 0, 0, 0); __builtin_amdgcn_s_setprio(0); } while (0)
; #define PG8_WAIT_V(n) asm volatile("s_waitcnt vmcnt(" #n ")" ::: "memory")
; #define PG8_WAIT_L(n) asm volatile("s_waitcnt lgkmcnt(" #n ")" ::: "memory")
; #define PG8_BAR __builtin_amdgcn_s_barrier()
; #define PG8_SCHED __builtin_amdgcn_sched_barrier(0)
; template <class Epi, class Sched, bool ALIGN_EPI = false, bool SP2 = false>
; __device__ __forceinline__ void gemm_phase(PG8_LAS unsigned char* lds, const Gemm g, const Sched& S, const Epi& E) {
;     ...
;             PG8_LDA(At, 1, 1); PG8_STAGE(PG8_SB(1, 0), b3, voffB); PG8_STAGE(PG8_SB(1, 1), b3 + hstep, voffB); PG8_STAGE(PG8_SA(1, 0), a3, voffA);
;             PG8_WAIT_V(8); PG8_WAIT_L(0); PG8_BAR; PG8_MMA(1, 0, At, B0); PG8_MMA(1, 1, At, B1); PG8_BAR; PG8_SCHED;
;     ...
;         if constexpr (ALIGN_EPI) { if (wr == 0) PG8_BAR; }
	s_add_i32 s28, s50, s36
	v_lshl_add_u64 v[156:157], v[156:157], 0, s[80:81]
	s_mov_b32 m0, s28
	ds_read_b128 v[186:189], v160 offset:49152
	ds_read_b128 v[190:193], v160 offset:50176
	ds_read_b128 v[194:197], v160 offset:51200
	ds_read_b128 v[198:201], v160 offset:52224
	ds_read_b128 v[202:205], v160 offset:53248
	ds_read_b128 v[206:209], v160 offset:54272
	ds_read_b128 v[210:213], v160 offset:55296
	ds_read_b128 v[214:217], v160 offset:56320
	global_load_lds_dwordx4 v[156:157], off
	s_add_i32 m0, s28, 0x2000
	s_add_u32 s26, s26, 0x40080
	v_lshl_add_u64 v[156:157], v[218:219], 0, s[80:81]
	s_addc_u32 s27, s27, 0
	s_add_i32 s28, s51, s36
	global_load_lds_dwordx4 v[156:157], off
	v_lshl_add_u64 v[156:157], s[26:27], 0, v[142:143]
	s_mov_b32 m0, s28
	s_nop 0
	global_load_lds_dwordx4 v[156:157], off
	v_lshl_add_u64 v[156:157], s[26:27], 0, v[138:139]
	s_add_i32 m0, s28, 0x2000
	s_nop 0
	global_load_lds_dwordx4 v[156:157], off
	v_lshl_add_u64 v[156:157], v[220:221], 0, s[80:81]
	s_mov_b32 m0, s41
	s_nop 0
	global_load_lds_dwordx4 v[156:157], off
	v_lshl_add_u64 v[156:157], v[222:223], 0, s[80:81]
	s_mov_b32 m0, s42
	s_nop 0
	global_load_lds_dwordx4 v[156:157], off
	s_waitcnt vmcnt(8) lgkmcnt(0)
	s_barrier
	s_setprio 1
	v_mfma_f32_16x16x32_bf16 v[62:65], v[66:69], v[186:189], v[62:65]
	v_mfma_f32_16x16x32_bf16 v[58:61], v[152:155], v[186:189], v[58:61]
	v_mfma_f32_16x16x32_bf16 v[46:49], v[66:69], v[194:197], v[46:49]
	v_mfma_f32_16x16x32_bf16 v[42:45], v[152:155], v[194:197], v[42:45]
	v_mfma_f32_16x16x32_bf16 v[30:33], v[66:69], v[202:205], v[30:33]
	v_mfma_f32_16x16x32_bf16 v[26:29], v[152:155], v[202:205], v[26:29]
	v_mfma_f32_16x16x32_bf16 v[14:17], v[66:69], v[210:213], v[14:17]
	v_mfma_f32_16x16x32_bf16 v[10:13], v[152:155], v[210:213], v[10:13]
	v_mfma_f32_16x16x32_bf16 v[62:65], v[118:121], v[190:193], v[62:65]
	v_mfma_f32_16x16x32_bf16 v[58:61], v[162:165], v[190:193], v[58:61]
	v_mfma_f32_16x16x32_bf16 v[46:49], v[118:121], v[198:201], v[46:49]
	v_mfma_f32_16x16x32_bf16 v[42:45], v[162:165], v[198:201], v[42:45]
	v_mfma_f32_16x16x32_bf16 v[30:33], v[118:121], v[206:209], v[30:33]
	v_mfma_f32_16x16x32_bf16 v[26:29], v[162:165], v[206:209], v[26:29]
	v_mfma_f32_16x16x32_bf16 v[14:17], v[118:121], v[214:217], v[14:17]
	v_mfma_f32_16x16x32_bf16 v[10:13], v[162:165], v[214:217], v[10:13]
	v_mfma_f32_16x16x32_bf16 v[54:57], v[166:169], v[186:189], v[54:57]
	v_mfma_f32_16x16x32_bf16 v[50:53], v[174:177], v[186:189], v[50:53]
	v_mfma_f32_16x16x32_bf16 v[38:41], v[166:169], v[194:197], v[38:41]
	v_mfma_f32_16x16x32_bf16 v[34:37], v[174:177], v[194:197], v[34:37]
	v_mfma_f32_16x16x32_bf16 v[22:25], v[166:169], v[202:205], v[22:25]
	v_mfma_f32_16x16x32_bf16 v[18:21], v[174:177], v[202:205], v[18:21]
	v_mfma_f32_16x16x32_bf16 v[6:9], v[166:169], v[210:213], v[6:9]
	v_mfma_f32_16x16x32_bf16 v[2:5], v[174:177], v[210:213], v[2:5]
	v_mfma_f32_16x16x32_bf16 v[54:57], v[170:173], v[190:193], v[54:57]
	v_mfma_f32_16x16x32_bf16 v[50:53], v[180:183], v[190:193], v[50:53]
	v_mfma_f32_16x16x32_bf16 v[38:41], v[170:173], v[198:201], v[38:41]
	v_mfma_f32_16x16x32_bf16 v[34:37], v[180:183], v[198:201], v[34:37]
	v_mfma_f32_16x16x32_bf16 v[22:25], v[170:173], v[206:209], v[22:25]
	v_mfma_f32_16x16x32_bf16 v[18:21], v[180:183], v[206:209], v[18:21]
	v_mfma_f32_16x16x32_bf16 v[6:9], v[170:173], v[214:217], v[6:9]
	v_mfma_f32_16x16x32_bf16 v[2:5], v[180:183], v[214:217], v[2:5]
	s_setprio 0
	s_barrier
	s_add_i32 s49, s49, 2
	s_add_u32 s24, s24, 0x100
	s_addc_u32 s25, s25, 0
	s_add_u32 s47, s47, 0x100
	s_addc_u32 s48, s48, 0
	s_cmp_gt_u32 s49, 13
	s_cbranch_scc0 .LBB0_1249
	s_and_b64 vcc, exec, s[12:13]
	s_cbranch_vccz .LBB0_1252
	s_barrier

; #define PG8_STAGE(bufoff, gbase, voff) do { _Pragma("unroll") for (int _i = 0; _i < 2; ++_i) \
;         __builtin_amdgcn_global_load_lds((const unsigned*)((const char*)(gbase) + (voff)[_i]), (PG8_LAS unsigned*)(lds + (bufoff) + ldsw + _i * 8192), 16, 0, 0); } while (0)
; #define PG8_LDA(dst, b, h) do { _Pragma("unroll") for (int m = 0; m < 4; ++m) _Pragma("unroll") for (int k = 0; k < 2; ++k) dst[m][k] = *(const PG8_LAS bf16x8*)(lds + PG8_SA(b, h) + aoff + m * 2048 + k * 1024); } while (0)
; #define PG8_LDB(dst, b, h) do { _Pragma("unroll") for (int n = 0; n < 2; ++n) _Pragma("unroll") for (int k = 0; k < 2; ++k) dst[n][k] = *(const PG8_LAS bf16x8*)(lds + PG8_SB(b, h) + boff + n * 2048 + k * 1024); } while (0)
; #define PG8_WAIT_V(n) asm volatile("s_waitcnt vmcnt(" #n ")" ::: "memory")
; #define PG8_WAIT_L(n) asm volatile("s_waitcnt lgkmcnt(" #n ")" ::: "memory")
; #define PG8_BAR __builtin_amdgcn_s_barrier()
; #define PG8_SCHED __builtin_amdgcn_sched_barrier(0)
; template <class Epi, class Sched, bool ALIGN_EPI = false, bool SP2 = false>
; __device__ __forceinline__ void gemm_phase(PG8_LAS unsigned char* lds, const Gemm g, const Sched& S, const Epi& E) {
;     ...
;         const bool has_next = S.next(ui + 1, nxt);
;         const char* nA = has_next ? (const char*)g.A + (size_t)nxt.pm * tstep : cA; const char* nB = has_next ? (const char*)g.Bt + (size_t)nxt.pn * tstep : cB;
;         for (int t = 0; t < nt; t += 2) {
;             const bool last = (t == nt - 2);
;             const char* a1 = cA + (size_t)(t + 1) * kstep;
;             const char* a2 = last ? nA : cA + (size_t)(t + 2) * kstep; const char* b2 = last ? nB : cB + (size_t)(t + 2) * kstep;
;             const char* a3 = a2 + kstep; const char* b3 = b2 + kstep;
;             if (last && has_next) S.a_ready(nxt);
;             if constexpr (SP2) {
;             PG8_LDB(B0, 0, 0); PG8_LDB(B1, 0, 1); PG8_SCHED; PG8_LDA(At, 0, 0); PG8_STAGE(PG8_SA(1, 1), a1 + hstep, voffA);
;             PG8_WAIT_V(8); PG8_WAIT_L(0); PG8_BAR; PG8_MMA(0, 0, At, B0); PG8_MMA(0, 1, At, B1); PG8_BAR; PG8_SCHED;
;             PG8_LDA(At, 0, 1); PG8_STAGE(PG8_SB(0, 0), b2, voffB); PG8_STAGE(PG8_SB(0, 1), b2 + hstep, voffB); PG8_STAGE(PG8_SA(0, 0), a2, voffA);
;             PG8_WAIT_V(8); PG8_WAIT_L(0); PG8_BAR; PG8_MMA(1, 0, At, B0); PG8_MMA(1, 1, At, B1); PG8_BAR; PG8_SCHED;
.LBB0_1329:
	s_add_u32 s49, s22, 0x100
	s_addc_u32 s50, s23, 0
	s_mov_b32 s51, -2
	s_add_u32 s22, s20, 0x100
	s_addc_u32 s23, s21, 0
	s_add_i32 s52, 0, 0x10000
	s_cmp_eq_u32 s51, 40
	s_cselect_b32 s27, s7, s23
	s_cselect_b32 s26, s6, s22
	v_add_u32_e32 v157, s52, v154
	s_cselect_b32 s25, s19, s50
	s_cselect_b32 s24, s18, s49
	s_add_i32 s53, 0, 0x14000
	ds_read_b128 v[142:145], v157
	ds_read_b128 v[146:149], v157 offset:1024
	ds_read_b128 v[150:153], v157 offset:2048
	ds_read_b128 v[158:161], v157 offset:3072
	v_add_u32_e32 v157, s53, v154
	ds_read_b128 v[162:165], v157
	ds_read_b128 v[166:169], v157 offset:1024
	ds_read_b128 v[170:173], v157 offset:2048
	ds_read_b128 v[174:177], v157 offset:3072
	v_lshl_add_u64 v[214:215], s[20:21], 0, v[138:139]
	s_add_i32 m0, s37, 0xc000
	ds_read_b128 v[180:183], v156
	ds_read_b128 v[186:189], v156 offset:1024
	ds_read_b128 v[190:193], v156 offset:2048
	ds_read_b128 v[194:197], v156 offset:3072
	ds_read_b128 v[198:201], v156 offset:4096
	ds_read_b128 v[202:205], v156 offset:5120
	ds_read_b128 v[206:209], v156 offset:6144
	ds_read_b128 v[210:213], v156 offset:7168
	global_load_lds_dwordx4 v[214:215], off
	v_lshl_add_u64 v[214:215], s[20:21], 0, v[140:141]
	s_add_i32 m0, s37, 0xe000
	s_nop 0
	global_load_lds_dwordx4 v[214:215], off
	s_waitcnt vmcnt(8) lgkmcnt(0)
	s_barrier
	s_setprio 1
	v_mfma_f32_16x16x32_bf16 v[126:129], v[142:145], v[180:183], 0
	v_mfma_f32_16x16x32_bf16 v[122:125], v[150:153], v[180:183], 0
	v_mfma_f32_16x16x32_bf16 v[114:117], v[142:145], v[190:193], 0
	v_mfma_f32_16x16x32_bf16 v[106:109], v[150:153], v[190:193], 0
	v_mfma_f32_16x16x32_bf16 v[98:101], v[142:145], v[198:201], 0
	v_mfma_f32_16x16x32_bf16 v[90:93], v[150:153], v[198:201], 0
	v_mfma_f32_16x16x32_bf16 v[82:85], v[142:145], v[206:209], 0
	v_mfma_f32_16x16x32_bf16 v[74:77], v[150:153], v[206:209], 0
	v_mfma_f32_16x16x32_bf16 v[126:129], v[146:149], v[186:189], v[126:129]
	v_mfma_f32_16x16x32_bf16 v[122:125], v[158:161], v[186:189], v[122:125]
	v_mfma_f32_16x16x32_bf16 v[114:117], v[146:149], v[194:197], v[114:117]
	v_mfma_f32_16x16x32_bf16 v[106:109], v[158:161], v[194:197], v[106:109]
	v_mfma_f32_16x16x32_bf16 v[98:101], v[146:149], v[202:205], v[98:101]
	v_mfma_f32_16x16x32_bf16 v[90:93], v[158:161], v[202:205], v[90:93]
	v_mfma_f32_16x16x32_bf16 v[82:85], v[146:149], v[210:213], v[82:85]
	v_mfma_f32_16x16x32_bf16 v[74:77], v[158:161], v[210:213], v[74:77]
	v_mfma_f32_16x16x32_bf16 v[118:121], v[162:165], v[180:183], 0
	v_mfma_f32_16x16x32_bf16 v[110:113], v[170:173], v[180:183], 0
	v_mfma_f32_16x16x32_bf16 v[102:105], v[162:165], v[190:193], 0
	v_mfma_f32_16x16x32_bf16 v[94:97], v[170:173], v[190:193], 0
	v_mfma_f32_16x16x32_bf16 v[86:89], v[162:165], v[198:201], 0
	v_mfma_f32_16x16x32_bf16 v[78:81], v[170:173], v[198:201], 0
	v_mfma_f32_16x16x32_bf16 v[70:73], v[162:165], v[206:209], 0
	v_mfma_f32_16x16x32_bf16 v[66:69], v[170:173], v[206:209], 0
	v_mfma_f32_16x16x32_bf16 v[118:121], v[166:169], v[186:189], v[118:121]
	v_mfma_f32_16x16x32_bf16 v[110:113], v[174:177], v[186:189], v[110:113]
	v_mfma_f32_16x16x32_bf16 v[102:105], v[166:169], v[194:197], v[102:105]
	v_mfma_f32_16x16x32_bf16 v[94:97], v[174:177], v[194:197], v[94:97]
	v_mfma_f32_16x16x32_bf16 v[86:89], v[166:169], v[202:205], v[86:89]
	v_mfma_f32_16x16x32_bf16 v[78:81], v[174:177], v[202:205], v[78:81]
	v_mfma_f32_16x16x32_bf16 v[70:73], v[166:169], v[210:213], v[70:73]
	v_mfma_f32_16x16x32_bf16 v[66:69], v[174:177], v[210:213], v[66:69]
	s_setprio 0
	s_barrier
	s_add_i32 s20, s52, s36
	v_lshl_add_u64 v[214:215], s[24:25], 0, v[132:133]
	s_mov_b32 m0, s20
	ds_read_b128 v[180:183], v156 offset:16384
	ds_read_b128 v[186:189], v156 offset:17408
	ds_read_b128 v[190:193], v156 offset:18432
	ds_read_b128 v[194:197], v156 offset:19456
	ds_read_b128 v[198:201], v156 offset:20480
	ds_read_b128 v[202:205], v156 offset:21504
	ds_read_b128 v[206:209], v156 offset:22528
	ds_read_b128 v[210:213], v156 offset:23552
	global_load_lds_dwordx4 v[214:215], off
	s_add_i32 m0, s20, 0x2000
	s_add_u32 s20, s24, 0xb0000
	v_lshl_add_u64 v[216:217], s[24:25], 0, v[136:137]
	s_addc_u32 s21, s25, 0
	s_add_i32 s52, s53, s36
	global_load_lds_dwordx4 v[216:217], off
	v_lshl_add_u64 v[218:219], s[20:21], 0, v[132:133]
	s_mov_b32 m0, s52
	v_lshl_add_u64 v[220:221], s[26:27], 0, v[134:135]
	global_load_lds_dwordx4 v[218:219], off
	v_lshl_add_u64 v[218:219], s[20:21], 0, v[136:137]
	s_add_i32 m0, s52, 0x2000
	s_nop 0
	global_load_lds_dwordx4 v[218:219], off
	v_lshl_add_u64 v[218:219], s[26:27], 0, v[130:131]
	s_mov_b32 m0, s37
	s_nop 0
	global_load_lds_dwordx4 v[218:219], off
	s_mov_b32 m0, s38
	s_nop 0
	global_load_lds_dwordx4 v[220:221], off
	s_waitcnt vmcnt(8) lgkmcnt(0)
	s_barrier
; #define PG8_STAGE(bufoff, gbase, voff) do { _Pragma("unroll") for (int _i = 0; _i < 2; ++_i) \
;         __builtin_amdgcn_global_load_lds((const unsigned*)((const char*)(gbase) + (voff)[_i]), (PG8_LAS unsigned*)(lds + (bufoff) + ldsw + _i * 8192), 16, 0, 0); } while (0)
; #define PG8_LDA(dst, b, h) do { _Pragma("unroll") for (int m = 0; m < 4; ++m) _Pragma("unroll") for (int k = 0; k < 2; ++k) dst[m][k] = *(const PG8_LAS bf16x8*)(lds + PG8_SA(b, h) + aoff + m * 2048 + k * 1024); } while (0)
; #define PG8_LDB(dst, b, h) do { _Pragma("unroll") for (int n = 0; n < 2; ++n) _Pragma("unroll") for (int k = 0; k < 2; ++k) dst[n][k] = *(const PG8_LAS bf16x8*)(lds + PG8_SB(b, h) + boff + n * 2048 + k * 1024); } while (0)
; #define PG8_MMA(ai, bj, At, Bt) do { __builtin_amdgcn_s_setprio(1); _Pragma("unroll") for (int m = 0; m < 4; ++m) _Pragma("unroll") for (int n = 0; n < 2; ++n) _Pragma("unroll") for (int k = 0; k < 2; ++k) \
;         acc[ai][bj][m][n] = __builtin_amdgcn_mfma_f32_16x16x32_bf16(Bt[n][k], At[m][k], acc[ai][bj][m][n], 0, 0, 0); __builtin_amdgcn_s_setprio(0); } while (0)
; #define PG8_WAIT_V(n) asm volatile("s_waitcnt vmcnt(" #n ")" ::: "memory")
; #define PG8_WAIT_L(n) asm volatile("s_waitcnt lgkmcnt(" #n ")" ::: "memory")
; #define PG8_BAR __builtin_amdgcn_s_barrier()
; #define PG8_SCHED __builtin_amdgcn_sched_barrier(0)
; template <class Epi, class Sched, bool ALIGN_EPI = false, bool SP2 = false>
; __device__ __forceinline__ void gemm_phase(PG8_LAS unsigned char* lds, const Gemm g, const Sched& S, const Epi& E) {
;     ...
;             PG8_WAIT_V(8); PG8_WAIT_L(0); PG8_BAR; PG8_MMA(1, 0, At, B0); PG8_MMA(1, 1, At, B1); PG8_BAR; PG8_SCHED;
;             PG8_LDB(B0, 1, 0); PG8_LDB(B1, 1, 1); PG8_SCHED; PG8_LDA(At, 1, 0); PG8_STAGE(PG8_SA(0, 1), a2 + hstep, voffA);
;             PG8_WAIT_V(8); PG8_WAIT_L(0); PG8_BAR; PG8_MMA(0, 0, At, B0); PG8_MMA(0, 1, At, B1); PG8_BAR; PG8_SCHED;
	s_setprio 1
	v_mfma_f32_16x16x32_bf16 v[62:65], v[142:145], v[180:183], 0
	v_mfma_f32_16x16x32_bf16 v[58:61], v[150:153], v[180:183], 0
	v_mfma_f32_16x16x32_bf16 v[50:53], v[142:145], v[190:193], 0
	v_mfma_f32_16x16x32_bf16 v[42:45], v[150:153], v[190:193], 0
	v_mfma_f32_16x16x32_bf16 v[34:37], v[142:145], v[198:201], 0
	v_mfma_f32_16x16x32_bf16 v[26:29], v[150:153], v[198:201], 0
	v_mfma_f32_16x16x32_bf16 v[18:21], v[142:145], v[206:209], 0
	v_mfma_f32_16x16x32_bf16 v[10:13], v[150:153], v[206:209], 0
	v_mfma_f32_16x16x32_bf16 v[62:65], v[146:149], v[186:189], v[62:65]
	v_mfma_f32_16x16x32_bf16 v[58:61], v[158:161], v[186:189], v[58:61]
	v_mfma_f32_16x16x32_bf16 v[50:53], v[146:149], v[194:197], v[50:53]
	v_mfma_f32_16x16x32_bf16 v[42:45], v[158:161], v[194:197], v[42:45]
	v_mfma_f32_16x16x32_bf16 v[34:37], v[146:149], v[202:205], v[34:37]
	v_mfma_f32_16x16x32_bf16 v[26:29], v[158:161], v[202:205], v[26:29]
	v_mfma_f32_16x16x32_bf16 v[18:21], v[146:149], v[210:213], v[18:21]
	v_mfma_f32_16x16x32_bf16 v[10:13], v[158:161], v[210:213], v[10:13]
	v_mfma_f32_16x16x32_bf16 v[54:57], v[162:165], v[180:183], 0
	v_mfma_f32_16x16x32_bf16 v[46:49], v[170:173], v[180:183], 0
	v_mfma_f32_16x16x32_bf16 v[38:41], v[162:165], v[190:193], 0
	v_mfma_f32_16x16x32_bf16 v[30:33], v[170:173], v[190:193], 0
	v_mfma_f32_16x16x32_bf16 v[22:25], v[162:165], v[198:201], 0
	v_mfma_f32_16x16x32_bf16 v[14:17], v[170:173], v[198:201], 0
	v_mfma_f32_16x16x32_bf16 v[6:9], v[162:165], v[206:209], 0
	v_mfma_f32_16x16x32_bf16 v[2:5], v[170:173], v[206:209], 0
	v_mfma_f32_16x16x32_bf16 v[54:57], v[166:169], v[186:189], v[54:57]
	v_mfma_f32_16x16x32_bf16 v[46:49], v[174:177], v[186:189], v[46:49]
	v_mfma_f32_16x16x32_bf16 v[38:41], v[166:169], v[194:197], v[38:41]
	v_mfma_f32_16x16x32_bf16 v[30:33], v[174:177], v[194:197], v[30:33]
	v_mfma_f32_16x16x32_bf16 v[22:25], v[166:169], v[202:205], v[22:25]
	v_mfma_f32_16x16x32_bf16 v[14:17], v[174:177], v[202:205], v[14:17]
	v_mfma_f32_16x16x32_bf16 v[6:9], v[166:169], v[210:213], v[6:9]
	v_mfma_f32_16x16x32_bf16 v[2:5], v[174:177], v[210:213], v[2:5]
	s_setprio 0
	s_barrier
	s_add_i32 s52, 0, 0x18000
	v_add_u32_e32 v157, s52, v154
	s_add_i32 s53, 0, 0x1c000
	ds_read_b128 v[142:145], v157
	ds_read_b128 v[146:149], v157 offset:1024
	ds_read_b128 v[150:153], v157 offset:2048
	ds_read_b128 v[158:161], v157 offset:3072
	v_add_u32_e32 v157, s53, v154
	ds_read_b128 v[162:165], v157
	ds_read_b128 v[166:169], v157 offset:1024
	ds_read_b128 v[170:173], v157 offset:2048
	ds_read_b128 v[174:177], v157 offset:3072
	s_add_u32 s20, s26, 0xb0000
	s_addc_u32 s21, s27, 0
	s_mov_b32 m0, s39
	v_lshl_add_u64 v[222:223], s[20:21], 0, v[130:131]
	ds_read_b128 v[180:183], v156 offset:32768
	ds_read_b128 v[186:189], v156 offset:33792
	ds_read_b128 v[190:193], v156 offset:34816
	ds_read_b128 v[194:197], v156 offset:35840
	ds_read_b128 v[198:201], v156 offset:36864
	ds_read_b128 v[202:205], v156 offset:37888
	ds_read_b128 v[206:209], v156 offset:38912
	ds_read_b128 v[210:213], v156 offset:39936
	global_load_lds_dwordx4 v[222:223], off
	v_lshl_add_u64 v[222:223], s[20:21], 0, v[134:135]
	s_mov_b32 m0, s40
	s_nop 0
	global_load_lds_dwordx4 v[222:223], off
	s_waitcnt vmcnt(8) lgkmcnt(0)
	s_barrier
	s_setprio 1
	v_mfma_f32_16x16x32_bf16 v[126:129], v[142:145], v[180:183], v[126:129]
	v_mfma_f32_16x16x32_bf16 v[122:125], v[150:153], v[180:183], v[122:125]
	v_mfma_f32_16x16x32_bf16 v[114:117], v[142:145], v[190:193], v[114:117]
	v_mfma_f32_16x16x32_bf16 v[106:109], v[150:153], v[190:193], v[106:109]
	v_mfma_f32_16x16x32_bf16 v[98:101], v[142:145], v[198:201], v[98:101]
	v_mfma_f32_16x16x32_bf16 v[90:93], v[150:153], v[198:201], v[90:93]
	v_mfma_f32_16x16x32_bf16 v[82:85], v[142:145], v[206:209], v[82:85]
	v_mfma_f32_16x16x32_bf16 v[74:77], v[150:153], v[206:209], v[74:77]
	v_mfma_f32_16x16x32_bf16 v[126:129], v[146:149], v[186:189], v[126:129]
	v_mfma_f32_16x16x32_bf16 v[122:125], v[158:161], v[186:189], v[122:125]
	v_mfma_f32_16x16x32_bf16 v[114:117], v[146:149], v[194:197], v[114:117]
	v_mfma_f32_16x16x32_bf16 v[106:109], v[158:161], v[194:197], v[106:109]
	v_mfma_f32_16x16x32_bf16 v[98:101], v[146:149], v[202:205], v[98:101]
	v_mfma_f32_16x16x32_bf16 v[90:93], v[158:161], v[202:205], v[90:93]
	v_mfma_f32_16x16x32_bf16 v[82:85], v[146:149], v[210:213], v[82:85]
	v_mfma_f32_16x16x32_bf16 v[74:77], v[158:161], v[210:213], v[74:77]
	v_mfma_f32_16x16x32_bf16 v[118:121], v[162:165], v[180:183], v[118:121]
	v_mfma_f32_16x16x32_bf16 v[110:113], v[170:173], v[180:183], v[110:113]
	v_mfma_f32_16x16x32_bf16 v[102:105], v[162:165], v[190:193], v[102:105]
	v_mfma_f32_16x16x32_bf16 v[94:97], v[170:173], v[190:193], v[94:97]
	v_mfma_f32_16x16x32_bf16 v[86:89], v[162:165], v[198:201], v[86:89]
	v_mfma_f32_16x16x32_bf16 v[78:81], v[170:173], v[198:201], v[78:81]
	v_mfma_f32_16x16x32_bf16 v[70:73], v[162:165], v[206:209], v[70:73]
	v_mfma_f32_16x16x32_bf16 v[66:69], v[170:173], v[206:209], v[66:69]
	v_mfma_f32_16x16x32_bf16 v[118:121], v[166:169], v[186:189], v[118:121]
	v_mfma_f32_16x16x32_bf16 v[110:113], v[174:177], v[186:189], v[110:113]
	v_mfma_f32_16x16x32_bf16 v[102:105], v[166:169], v[194:197], v[102:105]
	v_mfma_f32_16x16x32_bf16 v[94:97], v[174:177], v[194:197], v[94:97]
	v_mfma_f32_16x16x32_bf16 v[86:89], v[166:169], v[202:205], v[86:89]
	v_mfma_f32_16x16x32_bf16 v[78:81], v[174:177], v[202:205], v[78:81]
	v_mfma_f32_16x16x32_bf16 v[70:73], v[166:169], v[210:213], v[70:73]
	v_mfma_f32_16x16x32_bf16 v[66:69], v[174:177], v[210:213], v[66:69]
	s_setprio 0
	s_barrier
; #define PG8_STAGE(bufoff, gbase, voff) do { _Pragma("unroll") for (int _i = 0; _i < 2; ++_i) \
;         __builtin_amdgcn_global_load_lds((const unsigned*)((const char*)(gbase) + (voff)[_i]), (PG8_LAS unsigned*)(lds + (bufoff) + ldsw + _i * 8192), 16, 0, 0); } while (0)
; #define PG8_LDA(dst, b, h) do { _Pragma("unroll") for (int m = 0; m < 4; ++m) _Pragma("unroll") for (int k = 0; k < 2; ++k) dst[m][k] = *(const PG8_LAS bf16x8*)(lds + PG8_SA(b, h) + aoff + m * 2048 + k * 1024); } while (0)
; #define PG8_LDB(dst, b, h) do { _Pragma("unroll") for (int n = 0; n < 2; ++n) _Pragma("unroll") for (int k = 0; k < 2; ++k) dst[n][k] = *(const PG8_LAS bf16x8*)(lds + PG8_SB(b, h) + boff + n * 2048 + k * 1024); } while (0)
; #define PG8_MMA(ai, bj, At, Bt) do { __builtin_amdgcn_s_setprio(1); _Pragma("unroll") for (int m = 0; m < 4; ++m) _Pragma("unroll") for (int n = 0; n < 2; ++n) _Pragma("unroll") for (int k = 0; k < 2; ++k) \
;         acc[ai][bj][m][n] = __builtin_amdgcn_mfma_f32_16x16x32_bf16(Bt[n][k], At[m][k], acc[ai][bj][m][n], 0, 0, 0); __builtin_amdgcn_s_setprio(0); } while (0)
; #define PG8_WAIT_V(n) asm volatile("s_waitcnt vmcnt(" #n ")" ::: "memory")
; #define PG8_WAIT_L(n) asm volatile("s_waitcnt lgkmcnt(" #n ")" ::: "memory")
; #define PG8_BAR __builtin_amdgcn_s_barrier()
; #define PG8_SCHED __builtin_amdgcn_sched_barrier(0)
; template <class Epi, class Sched, bool ALIGN_EPI = false, bool SP2 = false>
; __device__ __forceinline__ void gemm_phase(PG8_LAS unsigned char* lds, const Gemm g, const Sched& S, const Epi& E) {
;     ...
;             PG8_LDB(B0, 0, 0); PG8_LDB(B1, 0, 1); PG8_SCHED; PG8_LDA(At, 0, 0); PG8_STAGE(PG8_SA(1, 1), a1 + hstep, voffA);
;             PG8_WAIT_V(8); PG8_WAIT_L(0); PG8_BAR; PG8_MMA(0, 0, At, B0); PG8_MMA(0, 1, At, B1); PG8_BAR; PG8_SCHED;
;     ...
;             PG8_LDA(At, 1, 1); PG8_STAGE(PG8_SB(1, 0), b3, voffB); PG8_STAGE(PG8_SB(1, 1), b3 + hstep, voffB); PG8_STAGE(PG8_SA(1, 0), a3, voffA);
;             PG8_WAIT_V(8); PG8_WAIT_L(0); PG8_BAR; PG8_MMA(1, 0, At, B0); PG8_MMA(1, 1, At, B1); PG8_BAR; PG8_SCHED;
	s_add_i32 s20, s52, s36
	v_lshl_add_u64 v[214:215], v[214:215], 0, s[80:81]
	s_mov_b32 m0, s20
	ds_read_b128 v[180:183], v156 offset:49152
	ds_read_b128 v[186:189], v156 offset:50176
	ds_read_b128 v[190:193], v156 offset:51200
	ds_read_b128 v[194:197], v156 offset:52224
	ds_read_b128 v[198:201], v156 offset:53248
	ds_read_b128 v[202:205], v156 offset:54272
	ds_read_b128 v[206:209], v156 offset:55296
	ds_read_b128 v[210:213], v156 offset:56320
	global_load_lds_dwordx4 v[214:215], off
	s_add_i32 m0, s20, 0x2000
	s_add_u32 s20, s24, 0xb0080
	v_lshl_add_u64 v[214:215], v[216:217], 0, s[80:81]
	s_addc_u32 s21, s25, 0
	s_add_i32 s24, s53, s36
	global_load_lds_dwordx4 v[214:215], off
	v_lshl_add_u64 v[214:215], s[20:21], 0, v[132:133]
	s_mov_b32 m0, s24
	s_nop 0
	global_load_lds_dwordx4 v[214:215], off
	v_lshl_add_u64 v[214:215], s[20:21], 0, v[136:137]
	s_add_i32 m0, s24, 0x2000
	s_nop 0
	global_load_lds_dwordx4 v[214:215], off
	v_lshl_add_u64 v[214:215], v[218:219], 0, s[80:81]
	s_mov_b32 m0, s41
	s_nop 0
	global_load_lds_dwordx4 v[214:215], off
	v_lshl_add_u64 v[214:215], v[220:221], 0, s[80:81]
	s_mov_b32 m0, s42
	s_nop 0
	global_load_lds_dwordx4 v[214:215], off
	s_waitcnt vmcnt(8) lgkmcnt(0)
	s_barrier
	s_setprio 1
	v_mfma_f32_16x16x32_bf16 v[62:65], v[142:145], v[180:183], v[62:65]
	v_mfma_f32_16x16x32_bf16 v[58:61], v[150:153], v[180:183], v[58:61]
	v_mfma_f32_16x16x32_bf16 v[50:53], v[142:145], v[190:193], v[50:53]
	v_mfma_f32_16x16x32_bf16 v[42:45], v[150:153], v[190:193], v[42:45]
	v_mfma_f32_16x16x32_bf16 v[34:37], v[142:145], v[198:201], v[34:37]
	v_mfma_f32_16x16x32_bf16 v[26:29], v[150:153], v[198:201], v[26:29]
	v_mfma_f32_16x16x32_bf16 v[18:21], v[142:145], v[206:209], v[18:21]
	v_mfma_f32_16x16x32_bf16 v[10:13], v[150:153], v[206:209], v[10:13]
	v_mfma_f32_16x16x32_bf16 v[62:65], v[146:149], v[186:189], v[62:65]
	v_mfma_f32_16x16x32_bf16 v[58:61], v[158:161], v[186:189], v[58:61]
	v_mfma_f32_16x16x32_bf16 v[50:53], v[146:149], v[194:197], v[50:53]
	v_mfma_f32_16x16x32_bf16 v[42:45], v[158:161], v[194:197], v[42:45]
	v_mfma_f32_16x16x32_bf16 v[34:37], v[146:149], v[202:205], v[34:37]
	v_mfma_f32_16x16x32_bf16 v[26:29], v[158:161], v[202:205], v[26:29]
	v_mfma_f32_16x16x32_bf16 v[18:21], v[146:149], v[210:213], v[18:21]
	v_mfma_f32_16x16x32_bf16 v[10:13], v[158:161], v[210:213], v[10:13]
	v_mfma_f32_16x16x32_bf16 v[54:57], v[162:165], v[180:183], v[54:57]
	v_mfma_f32_16x16x32_bf16 v[46:49], v[170:173], v[180:183], v[46:49]
	v_mfma_f32_16x16x32_bf16 v[38:41], v[162:165], v[190:193], v[38:41]
	v_mfma_f32_16x16x32_bf16 v[30:33], v[170:173], v[190:193], v[30:33]
	v_mfma_f32_16x16x32_bf16 v[22:25], v[162:165], v[198:201], v[22:25]
	v_mfma_f32_16x16x32_bf16 v[14:17], v[170:173], v[198:201], v[14:17]
	v_mfma_f32_16x16x32_bf16 v[6:9], v[162:165], v[206:209], v[6:9]
	v_mfma_f32_16x16x32_bf16 v[2:5], v[170:173], v[206:209], v[2:5]
	v_mfma_f32_16x16x32_bf16 v[54:57], v[166:169], v[186:189], v[54:57]
	v_mfma_f32_16x16x32_bf16 v[46:49], v[174:177], v[186:189], v[46:49]
	v_mfma_f32_16x16x32_bf16 v[38:41], v[166:169], v[194:197], v[38:41]
	v_mfma_f32_16x16x32_bf16 v[30:33], v[174:177], v[194:197], v[30:33]
	v_mfma_f32_16x16x32_bf16 v[22:25], v[166:169], v[202:205], v[22:25]
	v_mfma_f32_16x16x32_bf16 v[14:17], v[174:177], v[202:205], v[14:17]
	v_mfma_f32_16x16x32_bf16 v[6:9], v[166:169], v[210:213], v[6:9]
	v_mfma_f32_16x16x32_bf16 v[2:5], v[174:177], v[210:213], v[2:5]
	s_setprio 0
	s_barrier
	s_add_i32 s51, s51, 2
	s_add_u32 s49, s49, 0x100
	s_addc_u32 s50, s50, 0
	s_cmp_gt_u32 s51, 41
	s_mov_b64 s[20:21], s[22:23]
	s_branch .LBB0_1330
.LBB0_1330:
	s_add_u32 s22, s20, 0x100
	s_addc_u32 s23, s21, 0
	s_add_i32 s52, 0, 0x10000
	s_cmp_eq_u32 s51, 40
	s_cselect_b32 s27, s7, s23
	s_cselect_b32 s26, s6, s22
	v_add_u32_e32 v157, s52, v154
	s_cselect_b32 s25, s19, s50
	s_cselect_b32 s24, s18, s49
	s_add_i32 s53, 0, 0x14000
	ds_read_b128 v[142:145], v157
	ds_read_b128 v[146:149], v157 offset:1024
	ds_read_b128 v[150:153], v157 offset:2048
	ds_read_b128 v[158:161], v157 offset:3072
	v_add_u32_e32 v157, s53, v154
	ds_read_b128 v[162:165], v157
	ds_read_b128 v[166:169], v157 offset:1024
	ds_read_b128 v[170:173], v157 offset:2048
	ds_read_b128 v[174:177], v157 offset:3072
	v_lshl_add_u64 v[214:215], s[20:21], 0, v[138:139]
	s_add_i32 m0, s37, 0xc000
	ds_read_b128 v[180:183], v156
	ds_read_b128 v[186:189], v156 offset:1024
	ds_read_b128 v[190:193], v156 offset:2048
	ds_read_b128 v[194:197], v156 offset:3072
	ds_read_b128 v[198:201], v156 offset:4096
	ds_read_b128 v[202:205], v156 offset:5120
	ds_read_b128 v[206:209], v156 offset:6144
	ds_read_b128 v[210:213], v156 offset:7168
	global_load_lds_dwordx4 v[214:215], off
	v_lshl_add_u64 v[214:215], s[20:21], 0, v[140:141]
	s_add_i32 m0, s37, 0xe000
	s_nop 0
	global_load_lds_dwordx4 v[214:215], off
	s_waitcnt vmcnt(8) lgkmcnt(0)
	s_barrier
; #define PG8_STAGE(bufoff, gbase, voff) do { _Pragma("unroll") for (int _i = 0; _i < 2; ++_i) \
;         __builtin_amdgcn_global_load_lds((const unsigned*)((const char*)(gbase) + (voff)[_i]), (PG8_LAS unsigned*)(lds + (bufoff) + ldsw + _i * 8192), 16, 0, 0); } while (0)
; #define PG8_LDA(dst, b, h) do { _Pragma("unroll") for (int m = 0; m < 4; ++m) _Pragma("unroll") for (int k = 0; k < 2; ++k) dst[m][k] = *(const PG8_LAS bf16x8*)(lds + PG8_SA(b, h) + aoff + m * 2048 + k * 1024); } while (0)
; #define PG8_MMA(ai, bj, At, Bt) do { __builtin_amdgcn_s_setprio(1); _Pragma("unroll") for (int m = 0; m < 4; ++m) _Pragma("unroll") for (int n = 0; n < 2; ++n) _Pragma("unroll") for (int k = 0; k < 2; ++k) \
;         acc[ai][bj][m][n] = __builtin_amdgcn_mfma_f32_16x16x32_bf16(Bt[n][k], At[m][k], acc[ai][bj][m][n], 0, 0, 0); __builtin_amdgcn_s_setprio(0); } while (0)
; #define PG8_WAIT_V(n) asm volatile("s_waitcnt vmcnt(" #n ")" ::: "memory")
; #define PG8_WAIT_L(n) asm volatile("s_waitcnt lgkmcnt(" #n ")" ::: "memory")
; #define PG8_BAR __builtin_amdgcn_s_barrier()
; #define PG8_SCHED __builtin_amdgcn_sched_barrier(0)
; template <class Epi, class Sched, bool ALIGN_EPI = false, bool SP2 = false>
; __device__ __forceinline__ void gemm_phase(PG8_LAS unsigned char* lds, const Gemm g, const Sched& S, const Epi& E) {
;     ...
;             PG8_WAIT_V(8); PG8_WAIT_L(0); PG8_BAR; PG8_MMA(0, 0, At, B0); PG8_MMA(0, 1, At, B1); PG8_BAR; PG8_SCHED;
;             PG8_LDA(At, 0, 1); PG8_STAGE(PG8_SB(0, 0), b2, voffB); PG8_STAGE(PG8_SB(0, 1), b2 + hstep, voffB); PG8_STAGE(PG8_SA(0, 0), a2, voffA);
;             PG8_WAIT_V(8); PG8_WAIT_L(0); PG8_BAR; PG8_MMA(1, 0, At, B0); PG8_MMA(1, 1, At, B1); PG8_BAR; PG8_SCHED;
	s_setprio 1
	v_mfma_f32_16x16x32_bf16 v[126:129], v[142:145], v[180:183], v[126:129]
	v_mfma_f32_16x16x32_bf16 v[122:125], v[150:153], v[180:183], v[122:125]
	v_mfma_f32_16x16x32_bf16 v[114:117], v[142:145], v[190:193], v[114:117]
	v_mfma_f32_16x16x32_bf16 v[106:109], v[150:153], v[190:193], v[106:109]
	v_mfma_f32_16x16x32_bf16 v[98:101], v[142:145], v[198:201], v[98:101]
	v_mfma_f32_16x16x32_bf16 v[90:93], v[150:153], v[198:201], v[90:93]
	v_mfma_f32_16x16x32_bf16 v[82:85], v[142:145], v[206:209], v[82:85]
	v_mfma_f32_16x16x32_bf16 v[74:77], v[150:153], v[206:209], v[74:77]
	v_mfma_f32_16x16x32_bf16 v[126:129], v[146:149], v[186:189], v[126:129]
	v_mfma_f32_16x16x32_bf16 v[122:125], v[158:161], v[186:189], v[122:125]
	v_mfma_f32_16x16x32_bf16 v[114:117], v[146:149], v[194:197], v[114:117]
	v_mfma_f32_16x16x32_bf16 v[106:109], v[158:161], v[194:197], v[106:109]
	v_mfma_f32_16x16x32_bf16 v[98:101], v[146:149], v[202:205], v[98:101]
	v_mfma_f32_16x16x32_bf16 v[90:93], v[158:161], v[202:205], v[90:93]
	v_mfma_f32_16x16x32_bf16 v[82:85], v[146:149], v[210:213], v[82:85]
	v_mfma_f32_16x16x32_bf16 v[74:77], v[158:161], v[210:213], v[74:77]
	v_mfma_f32_16x16x32_bf16 v[118:121], v[162:165], v[180:183], v[118:121]
	v_mfma_f32_16x16x32_bf16 v[110:113], v[170:173], v[180:183], v[110:113]
	v_mfma_f32_16x16x32_bf16 v[102:105], v[162:165], v[190:193], v[102:105]
	v_mfma_f32_16x16x32_bf16 v[94:97], v[170:173], v[190:193], v[94:97]
	v_mfma_f32_16x16x32_bf16 v[86:89], v[162:165], v[198:201], v[86:89]
	v_mfma_f32_16x16x32_bf16 v[78:81], v[170:173], v[198:201], v[78:81]
	v_mfma_f32_16x16x32_bf16 v[70:73], v[162:165], v[206:209], v[70:73]
	v_mfma_f32_16x16x32_bf16 v[66:69], v[170:173], v[206:209], v[66:69]
	v_mfma_f32_16x16x32_bf16 v[118:121], v[166:169], v[186:189], v[118:121]
	v_mfma_f32_16x16x32_bf16 v[110:113], v[174:177], v[186:189], v[110:113]
	v_mfma_f32_16x16x32_bf16 v[102:105], v[166:169], v[194:197], v[102:105]
	v_mfma_f32_16x16x32_bf16 v[94:97], v[174:177], v[194:197], v[94:97]
	v_mfma_f32_16x16x32_bf16 v[86:89], v[166:169], v[202:205], v[86:89]
	v_mfma_f32_16x16x32_bf16 v[78:81], v[174:177], v[202:205], v[78:81]
	v_mfma_f32_16x16x32_bf16 v[70:73], v[166:169], v[210:213], v[70:73]
	v_mfma_f32_16x16x32_bf16 v[66:69], v[174:177], v[210:213], v[66:69]
	s_setprio 0
	s_barrier
	s_add_i32 s20, s52, s36
	v_lshl_add_u64 v[214:215], s[24:25], 0, v[132:133]
	s_mov_b32 m0, s20
	ds_read_b128 v[180:183], v156 offset:16384
	ds_read_b128 v[186:189], v156 offset:17408
	ds_read_b128 v[190:193], v156 offset:18432
	ds_read_b128 v[194:197], v156 offset:19456
	ds_read_b128 v[198:201], v156 offset:20480
	ds_read_b128 v[202:205], v156 offset:21504
	ds_read_b128 v[206:209], v156 offset:22528
	ds_read_b128 v[210:213], v156 offset:23552
	global_load_lds_dwordx4 v[214:215], off
	s_add_i32 m0, s20, 0x2000
	s_add_u32 s20, s24, 0xb0000
	v_lshl_add_u64 v[216:217], s[24:25], 0, v[136:137]
	s_addc_u32 s21, s25, 0
	s_add_i32 s52, s53, s36
	global_load_lds_dwordx4 v[216:217], off
	v_lshl_add_u64 v[218:219], s[20:21], 0, v[132:133]
	s_mov_b32 m0, s52
	v_lshl_add_u64 v[220:221], s[26:27], 0, v[134:135]
	global_load_lds_dwordx4 v[218:219], off
	v_lshl_add_u64 v[218:219], s[20:21], 0, v[136:137]
	s_add_i32 m0, s52, 0x2000
	s_nop 0
	global_load_lds_dwordx4 v[218:219], off
	v_lshl_add_u64 v[218:219], s[26:27], 0, v[130:131]
	s_mov_b32 m0, s37
	s_nop 0
	global_load_lds_dwordx4 v[218:219], off
	s_mov_b32 m0, s38
	s_nop 0
	global_load_lds_dwordx4 v[220:221], off
	s_waitcnt vmcnt(8) lgkmcnt(0)
	s_barrier
	s_setprio 1
	v_mfma_f32_16x16x32_bf16 v[62:65], v[142:145], v[180:183], v[62:65]
	v_mfma_f32_16x16x32_bf16 v[58:61], v[150:153], v[180:183], v[58:61]
	v_mfma_f32_16x16x32_bf16 v[50:53], v[142:145], v[190:193], v[50:53]
	v_mfma_f32_16x16x32_bf16 v[42:45], v[150:153], v[190:193], v[42:45]
	v_mfma_f32_16x16x32_bf16 v[34:37], v[142:145], v[198:201], v[34:37]
	v_mfma_f32_16x16x32_bf16 v[26:29], v[150:153], v[198:201], v[26:29]
	v_mfma_f32_16x16x32_bf16 v[18:21], v[142:145], v[206:209], v[18:21]
	v_mfma_f32_16x16x32_bf16 v[10:13], v[150:153], v[206:209], v[10:13]
	v_mfma_f32_16x16x32_bf16 v[62:65], v[146:149], v[186:189], v[62:65]
	v_mfma_f32_16x16x32_bf16 v[58:61], v[158:161], v[186:189], v[58:61]
	v_mfma_f32_16x16x32_bf16 v[50:53], v[146:149], v[194:197], v[50:53]
	v_mfma_f32_16x16x32_bf16 v[42:45], v[158:161], v[194:197], v[42:45]
	v_mfma_f32_16x16x32_bf16 v[34:37], v[146:149], v[202:205], v[34:37]
	v_mfma_f32_16x16x32_bf16 v[26:29], v[158:161], v[202:205], v[26:29]
	v_mfma_f32_16x16x32_bf16 v[18:21], v[146:149], v[210:213], v[18:21]
	v_mfma_f32_16x16x32_bf16 v[10:13], v[158:161], v[210:213], v[10:13]
	v_mfma_f32_16x16x32_bf16 v[54:57], v[162:165], v[180:183], v[54:57]
	v_mfma_f32_16x16x32_bf16 v[46:49], v[170:173], v[180:183], v[46:49]
	v_mfma_f32_16x16x32_bf16 v[38:41], v[162:165], v[190:193], v[38:41]
	v_mfma_f32_16x16x32_bf16 v[30:33], v[170:173], v[190:193], v[30:33]
	v_mfma_f32_16x16x32_bf16 v[22:25], v[162:165], v[198:201], v[22:25]
	v_mfma_f32_16x16x32_bf16 v[14:17], v[170:173], v[198:201], v[14:17]
	v_mfma_f32_16x16x32_bf16 v[6:9], v[162:165], v[206:209], v[6:9]
	v_mfma_f32_16x16x32_bf16 v[2:5], v[170:173], v[206:209], v[2:5]
	v_mfma_f32_16x16x32_bf16 v[54:57], v[166:169], v[186:189], v[54:57]
	v_mfma_f32_16x16x32_bf16 v[46:49], v[174:177], v[186:189], v[46:49]
	v_mfma_f32_16x16x32_bf16 v[38:41], v[166:169], v[194:197], v[38:41]
	v_mfma_f32_16x16x32_bf16 v[30:33], v[174:177], v[194:197], v[30:33]
	v_mfma_f32_16x16x32_bf16 v[22:25], v[166:169], v[202:205], v[22:25]
	v_mfma_f32_16x16x32_bf16 v[14:17], v[174:177], v[202:205], v[14:17]
	v_mfma_f32_16x16x32_bf16 v[6:9], v[166:169], v[210:213], v[6:9]
	v_mfma_f32_16x16x32_bf16 v[2:5], v[174:177], v[210:213], v[2:5]
	s_setprio 0
	s_barrier
; #define PG8_STAGE(bufoff, gbase, voff) do { _Pragma("unroll") for (int _i = 0; _i < 2; ++_i) \
;         __builtin_amdgcn_global_load_lds((const unsigned*)((const char*)(gbase) + (voff)[_i]), (PG8_LAS unsigned*)(lds + (bufoff) + ldsw + _i * 8192), 16, 0, 0); } while (0)
; #define PG8_LDA(dst, b, h) do { _Pragma("unroll") for (int m = 0; m < 4; ++m) _Pragma("unroll") for (int k = 0; k < 2; ++k) dst[m][k] = *(const PG8_LAS bf16x8*)(lds + PG8_SA(b, h) + aoff + m * 2048 + k * 1024); } while (0)
; #define PG8_LDB(dst, b, h) do { _Pragma("unroll") for (int n = 0; n < 2; ++n) _Pragma("unroll") for (int k = 0; k < 2; ++k) dst[n][k] = *(const PG8_LAS bf16x8*)(lds + PG8_SB(b, h) + boff + n * 2048 + k * 1024); } while (0)
; #define PG8_MMA(ai, bj, At, Bt) do { __builtin_amdgcn_s_setprio(1); _Pragma("unroll") for (int m = 0; m < 4; ++m) _Pragma("unroll") for (int n = 0; n < 2; ++n) _Pragma("unroll") for (int k = 0; k < 2; ++k) \
;         acc[ai][bj][m][n] = __builtin_amdgcn_mfma_f32_16x16x32_bf16(Bt[n][k], At[m][k], acc[ai][bj][m][n], 0, 0, 0); __builtin_amdgcn_s_setprio(0); } while (0)
; #define PG8_WAIT_V(n) asm volatile("s_waitcnt vmcnt(" #n ")" ::: "memory")
; #define PG8_WAIT_L(n) asm volatile("s_waitcnt lgkmcnt(" #n ")" ::: "memory")
; #define PG8_BAR __builtin_amdgcn_s_barrier()
; #define PG8_SCHED __builtin_amdgcn_sched_barrier(0)
; template <class Epi, class Sched, bool ALIGN_EPI = false, bool SP2 = false>
; __device__ __forceinline__ void gemm_phase(PG8_LAS unsigned char* lds, const Gemm g, const Sched& S, const Epi& E) {
;     ...
;             PG8_LDB(B0, 1, 0); PG8_LDB(B1, 1, 1); PG8_SCHED; PG8_LDA(At, 1, 0); PG8_STAGE(PG8_SA(0, 1), a2 + hstep, voffA);
;             PG8_WAIT_V(8); PG8_WAIT_L(0); PG8_BAR; PG8_MMA(0, 0, At, B0); PG8_MMA(0, 1, At, B1); PG8_BAR; PG8_SCHED;
	s_add_i32 s52, 0, 0x18000
	v_add_u32_e32 v157, s52, v154
	s_add_i32 s53, 0, 0x1c000
	ds_read_b128 v[142:145], v157
	ds_read_b128 v[146:149], v157 offset:1024
	ds_read_b128 v[150:153], v157 offset:2048
	ds_read_b128 v[158:161], v157 offset:3072
	v_add_u32_e32 v157, s53, v154
	ds_read_b128 v[162:165], v157
	ds_read_b128 v[166:169], v157 offset:1024
	ds_read_b128 v[170:173], v157 offset:2048
	ds_read_b128 v[174:177], v157 offset:3072
	s_add_u32 s20, s26, 0xb0000
	s_addc_u32 s21, s27, 0
	s_mov_b32 m0, s39
	v_lshl_add_u64 v[222:223], s[20:21], 0, v[130:131]
	ds_read_b128 v[180:183], v156 offset:32768
	ds_read_b128 v[186:189], v156 offset:33792
	ds_read_b128 v[190:193], v156 offset:34816
	ds_read_b128 v[194:197], v156 offset:35840
	ds_read_b128 v[198:201], v156 offset:36864
	ds_read_b128 v[202:205], v156 offset:37888
	ds_read_b128 v[206:209], v156 offset:38912
	ds_read_b128 v[210:213], v156 offset:39936
	global_load_lds_dwordx4 v[222:223], off
	v_lshl_add_u64 v[222:223], s[20:21], 0, v[134:135]
	s_mov_b32 m0, s40
	s_nop 0
	global_load_lds_dwordx4 v[222:223], off
	s_waitcnt vmcnt(8) lgkmcnt(0)
	s_barrier
	s_setprio 1
	v_mfma_f32_16x16x32_bf16 v[126:129], v[142:145], v[180:183], v[126:129]
	v_mfma_f32_16x16x32_bf16 v[122:125], v[150:153], v[180:183], v[122:125]
	v_mfma_f32_16x16x32_bf16 v[114:117], v[142:145], v[190:193], v[114:117]
	v_mfma_f32_16x16x32_bf16 v[106:109], v[150:153], v[190:193], v[106:109]
	v_mfma_f32_16x16x32_bf16 v[98:101], v[142:145], v[198:201], v[98:101]
	v_mfma_f32_16x16x32_bf16 v[90:93], v[150:153], v[198:201], v[90:93]
	v_mfma_f32_16x16x32_bf16 v[82:85], v[142:145], v[206:209], v[82:85]
	v_mfma_f32_16x16x32_bf16 v[74:77], v[150:153], v[206:209], v[74:77]
	v_mfma_f32_16x16x32_bf16 v[126:129], v[146:149], v[186:189], v[126:129]
	v_mfma_f32_16x16x32_bf16 v[122:125], v[158:161], v[186:189], v[122:125]
	v_mfma_f32_16x16x32_bf16 v[114:117], v[146:149], v[194:197], v[114:117]
	v_mfma_f32_16x16x32_bf16 v[106:109], v[158:161], v[194:197], v[106:109]
	v_mfma_f32_16x16x32_bf16 v[98:101], v[146:149], v[202:205], v[98:101]
	v_mfma_f32_16x16x32_bf16 v[90:93], v[158:161], v[202:205], v[90:93]
	v_mfma_f32_16x16x32_bf16 v[82:85], v[146:149], v[210:213], v[82:85]
	v_mfma_f32_16x16x32_bf16 v[74:77], v[158:161], v[210:213], v[74:77]
	v_mfma_f32_16x16x32_bf16 v[118:121], v[162:165], v[180:183], v[118:121]
	v_mfma_f32_16x16x32_bf16 v[110:113], v[170:173], v[180:183], v[110:113]
	v_mfma_f32_16x16x32_bf16 v[102:105], v[162:165], v[190:193], v[102:105]
	v_mfma_f32_16x16x32_bf16 v[94:97], v[170:173], v[190:193], v[94:97]
	v_mfma_f32_16x16x32_bf16 v[86:89], v[162:165], v[198:201], v[86:89]
	v_mfma_f32_16x16x32_bf16 v[78:81], v[170:173], v[198:201], v[78:81]
	v_mfma_f32_16x16x32_bf16 v[70:73], v[162:165], v[206:209], v[70:73]
	v_mfma_f32_16x16x32_bf16 v[66:69], v[170:173], v[206:209], v[66:69]
	v_mfma_f32_16x16x32_bf16 v[118:121], v[166:169], v[186:189], v[118:121]
	v_mfma_f32_16x16x32_bf16 v[110:113], v[174:177], v[186:189], v[110:113]
	v_mfma_f32_16x16x32_bf16 v[102:105], v[166:169], v[194:197], v[102:105]
	v_mfma_f32_16x16x32_bf16 v[94:97], v[174:177], v[194:197], v[94:97]
	v_mfma_f32_16x16x32_bf16 v[86:89], v[166:169], v[202:205], v[86:89]
	v_mfma_f32_16x16x32_bf16 v[78:81], v[174:177], v[202:205], v[78:81]
	v_mfma_f32_16x16x32_bf16 v[70:73], v[166:169], v[210:213], v[70:73]
	v_mfma_f32_16x16x32_bf16 v[66:69], v[174:177], v[210:213], v[66:69]
	s_setprio 0
	s_barrier
; #define PG8_STAGE(bufoff, gbase, voff) do { _Pragma("unroll") for (int _i = 0; _i < 2; ++_i) \
;         __builtin_amdgcn_global_load_lds((const unsigned*)((const char*)(gbase) + (voff)[_i]), (PG8_LAS unsigned*)(lds + (bufoff) + ldsw + _i * 8192), 16, 0, 0); } while (0)
; #define PG8_LDA(dst, b, h) do { _Pragma("unroll") for (int m = 0; m < 4; ++m) _Pragma("unroll") for (int k = 0; k < 2; ++k) dst[m][k] = *(const PG8_LAS bf16x8*)(lds + PG8_SA(b, h) + aoff + m * 2048 + k * 1024); } while (0)
; #define PG8_MMA(ai, bj, At, Bt) do { __builtin_amdgcn_s_setprio(1); _Pragma("unroll") for (int m = 0; m < 4; ++m) _Pragma("unroll") for (int n = 0; n < 2; ++n) _Pragma("unroll") for (int k = 0; k < 2; ++k) \
;         acc[ai][bj][m][n] = __builtin_amdgcn_mfma_f32_16x16x32_bf16(Bt[n][k], At[m][k], acc[ai][bj][m][n], 0, 0, 0); __builtin_amdgcn_s_setprio(0); } while (0)
; #define PG8_WAIT_V(n) asm volatile("s_waitcnt vmcnt(" #n ")" ::: "memory")
; #define PG8_WAIT_L(n) asm volatile("s_waitcnt lgkmcnt(" #n ")" ::: "memory")
; #define PG8_BAR __builtin_amdgcn_s_barrier()
; #define PG8_SCHED __builtin_amdgcn_sched_barrier(0)
; template <class Epi, class Sched, bool ALIGN_EPI = false, bool SP2 = false>
; __device__ __forceinline__ void gemm_phase(PG8_LAS unsigned char* lds, const Gemm g, const Sched& S, const Epi& E) {
;     ...
;             PG8_LDA(At, 1, 1); PG8_STAGE(PG8_SB(1, 0), b3, voffB); PG8_STAGE(PG8_SB(1, 1), b3 + hstep, voffB); PG8_STAGE(PG8_SA(1, 0), a3, voffA);
;             PG8_WAIT_V(8); PG8_WAIT_L(0); PG8_BAR; PG8_MMA(1, 0, At, B0); PG8_MMA(1, 1, At, B1); PG8_BAR; PG8_SCHED;
;     ...
;         if constexpr (ALIGN_EPI) { if (wr == 0) PG8_BAR; }
	s_add_i32 s20, s52, s36
	v_lshl_add_u64 v[214:215], v[214:215], 0, s[80:81]
	s_mov_b32 m0, s20
	ds_read_b128 v[180:183], v156 offset:49152
	ds_read_b128 v[186:189], v156 offset:50176
	ds_read_b128 v[190:193], v156 offset:51200
	ds_read_b128 v[194:197], v156 offset:52224
	ds_read_b128 v[198:201], v156 offset:53248
	ds_read_b128 v[202:205], v156 offset:54272
	ds_read_b128 v[206:209], v156 offset:55296
	ds_read_b128 v[210:213], v156 offset:56320
	global_load_lds_dwordx4 v[214:215], off
	s_add_i32 m0, s20, 0x2000
	s_add_u32 s20, s24, 0xb0080
	v_lshl_add_u64 v[214:215], v[216:217], 0, s[80:81]
	s_addc_u32 s21, s25, 0
	s_add_i32 s24, s53, s36
	global_load_lds_dwordx4 v[214:215], off
	v_lshl_add_u64 v[214:215], s[20:21], 0, v[132:133]
	s_mov_b32 m0, s24
	s_nop 0
	global_load_lds_dwordx4 v[214:215], off
	v_lshl_add_u64 v[214:215], s[20:21], 0, v[136:137]
	s_add_i32 m0, s24, 0x2000
	s_nop 0
	global_load_lds_dwordx4 v[214:215], off
	v_lshl_add_u64 v[214:215], v[218:219], 0, s[80:81]
	s_mov_b32 m0, s41
	s_nop 0
	global_load_lds_dwordx4 v[214:215], off
	v_lshl_add_u64 v[214:215], v[220:221], 0, s[80:81]
	s_mov_b32 m0, s42
	s_nop 0
	global_load_lds_dwordx4 v[214:215], off
	s_waitcnt vmcnt(8) lgkmcnt(0)
	s_barrier
	s_setprio 1
	v_mfma_f32_16x16x32_bf16 v[62:65], v[142:145], v[180:183], v[62:65]
	v_mfma_f32_16x16x32_bf16 v[58:61], v[150:153], v[180:183], v[58:61]
	v_mfma_f32_16x16x32_bf16 v[50:53], v[142:145], v[190:193], v[50:53]
	v_mfma_f32_16x16x32_bf16 v[42:45], v[150:153], v[190:193], v[42:45]
	v_mfma_f32_16x16x32_bf16 v[34:37], v[142:145], v[198:201], v[34:37]
	v_mfma_f32_16x16x32_bf16 v[26:29], v[150:153], v[198:201], v[26:29]
	v_mfma_f32_16x16x32_bf16 v[18:21], v[142:145], v[206:209], v[18:21]
	v_mfma_f32_16x16x32_bf16 v[10:13], v[150:153], v[206:209], v[10:13]
	v_mfma_f32_16x16x32_bf16 v[62:65], v[146:149], v[186:189], v[62:65]
	v_mfma_f32_16x16x32_bf16 v[58:61], v[158:161], v[186:189], v[58:61]
	v_mfma_f32_16x16x32_bf16 v[50:53], v[146:149], v[194:197], v[50:53]
	v_mfma_f32_16x16x32_bf16 v[42:45], v[158:161], v[194:197], v[42:45]
	v_mfma_f32_16x16x32_bf16 v[34:37], v[146:149], v[202:205], v[34:37]
	v_mfma_f32_16x16x32_bf16 v[26:29], v[158:161], v[202:205], v[26:29]
	v_mfma_f32_16x16x32_bf16 v[18:21], v[146:149], v[210:213], v[18:21]
	v_mfma_f32_16x16x32_bf16 v[10:13], v[158:161], v[210:213], v[10:13]
	v_mfma_f32_16x16x32_bf16 v[54:57], v[162:165], v[180:183], v[54:57]
	v_mfma_f32_16x16x32_bf16 v[46:49], v[170:173], v[180:183], v[46:49]
	v_mfma_f32_16x16x32_bf16 v[38:41], v[162:165], v[190:193], v[38:41]
	v_mfma_f32_16x16x32_bf16 v[30:33], v[170:173], v[190:193], v[30:33]
	v_mfma_f32_16x16x32_bf16 v[22:25], v[162:165], v[198:201], v[22:25]
	v_mfma_f32_16x16x32_bf16 v[14:17], v[170:173], v[198:201], v[14:17]
	v_mfma_f32_16x16x32_bf16 v[6:9], v[162:165], v[206:209], v[6:9]
	v_mfma_f32_16x16x32_bf16 v[2:5], v[170:173], v[206:209], v[2:5]
	v_mfma_f32_16x16x32_bf16 v[54:57], v[166:169], v[186:189], v[54:57]
	v_mfma_f32_16x16x32_bf16 v[46:49], v[174:177], v[186:189], v[46:49]
	v_mfma_f32_16x16x32_bf16 v[38:41], v[166:169], v[194:197], v[38:41]
	v_mfma_f32_16x16x32_bf16 v[30:33], v[174:177], v[194:197], v[30:33]
	v_mfma_f32_16x16x32_bf16 v[22:25], v[166:169], v[202:205], v[22:25]
	v_mfma_f32_16x16x32_bf16 v[14:17], v[174:177], v[202:205], v[14:17]
	v_mfma_f32_16x16x32_bf16 v[6:9], v[166:169], v[210:213], v[6:9]
	v_mfma_f32_16x16x32_bf16 v[2:5], v[174:177], v[210:213], v[2:5]
	s_setprio 0
	s_barrier
	s_add_i32 s51, s51, 2
	s_add_u32 s49, s49, 0x100
	s_addc_u32 s50, s50, 0
	s_cmp_gt_u32 s51, 41
	s_mov_b64 s[20:21], s[22:23]
	s_cbranch_scc0 .LBB0_1330
	s_and_b64 vcc, exec, s[16:17]
	s_cbranch_vccz .LBB0_1333
	s_barrier

; #define PG8_STAGE(bufoff, gbase, voff) do { _Pragma("unroll") for (int _i = 0; _i < 2; ++_i) \
;         __builtin_amdgcn_global_load_lds((const unsigned*)((const char*)(gbase) + (voff)[_i]), (PG8_LAS unsigned*)(lds + (bufoff) + ldsw + _i * 8192), 16, 0, 0); } while (0)
; #define PG8_LDA(dst, b, h) do { _Pragma("unroll") for (int m = 0; m < 4; ++m) _Pragma("unroll") for (int k = 0; k < 2; ++k) dst[m][k] = *(const PG8_LAS bf16x8*)(lds + PG8_SA(b, h) + aoff + m * 2048 + k * 1024); } while (0)
; #define PG8_LDB(dst, b, h) do { _Pragma("unroll") for (int n = 0; n < 2; ++n) _Pragma("unroll") for (int k = 0; k < 2; ++k) dst[n][k] = *(const PG8_LAS bf16x8*)(lds + PG8_SB(b, h) + boff + n * 2048 + k * 1024); } while (0)
; #define PG8_WAIT_V(n) asm volatile("s_waitcnt vmcnt(" #n ")" ::: "memory")
; #define PG8_WAIT_L(n) asm volatile("s_waitcnt lgkmcnt(" #n ")" ::: "memory")
; #define PG8_BAR __builtin_amdgcn_s_barrier()
; #define PG8_SCHED __builtin_amdgcn_sched_barrier(0)
; template <class Epi, class Sched, bool ALIGN_EPI = false, bool SP2 = false>
; __device__ __forceinline__ void gemm_phase(PG8_LAS unsigned char* lds, const Gemm g, const Sched& S, const Epi& E) {
;     ...
;         const bool has_next = S.next(ui + 1, nxt);
;         const char* nA = has_next ? (const char*)g.A + (size_t)nxt.pm * tstep : cA; const char* nB = has_next ? (const char*)g.Bt + (size_t)nxt.pn * tstep : cB;
;         for (int t = 0; t < nt; t += 2) {
;             const bool last = (t == nt - 2);
;             const char* a1 = cA + (size_t)(t + 1) * kstep;
;             const char* a2 = last ? nA : cA + (size_t)(t + 2) * kstep; const char* b2 = last ? nB : cB + (size_t)(t + 2) * kstep;
;             const char* a3 = a2 + kstep; const char* b3 = b2 + kstep;
;             if (last && has_next) S.a_ready(nxt);
;             if constexpr (SP2) {
;             PG8_LDB(B0, 0, 0); PG8_LDB(B1, 0, 1); PG8_SCHED; PG8_LDA(At, 0, 0); PG8_STAGE(PG8_SA(1, 1), a1 + hstep, voffA);
;             PG8_WAIT_V(8); PG8_WAIT_L(0); PG8_BAR; PG8_MMA(0, 0, At, B0); PG8_MMA(0, 1, At, B1); PG8_BAR; PG8_SCHED;
;             PG8_LDA(At, 0, 1); PG8_STAGE(PG8_SB(0, 0), b2, voffB); PG8_STAGE(PG8_SB(0, 1), b2 + hstep, voffB); PG8_STAGE(PG8_SA(0, 0), a2, voffA);
;             PG8_WAIT_V(8); PG8_WAIT_L(0); PG8_BAR; PG8_MMA(1, 0, At, B0); PG8_MMA(1, 1, At, B1); PG8_BAR; PG8_SCHED;
.LBB0_1359:
	s_add_u32 s47, s20, 0x100
	s_addc_u32 s48, s21, 0
	s_mov_b32 s49, -2
	s_add_u32 s20, s18, 0x100
	s_addc_u32 s21, s19, 0
	s_add_i32 s50, 0, 0x10000
	s_cmp_eq_u32 s49, 40
	s_cselect_b32 s25, s7, s21
	s_cselect_b32 s24, s6, s20
	v_add_u32_e32 v146, s50, v148
	s_cselect_b32 s23, s17, s48
	s_cselect_b32 s22, s16, s47
	s_add_i32 s51, 0, 0x14000
	ds_read_b128 v[142:145], v146
	ds_read_b128 v[152:155], v146 offset:1024
	ds_read_b128 v[156:159], v146 offset:2048
	ds_read_b128 v[160:163], v146 offset:3072
	v_add_u32_e32 v146, s51, v148
	ds_read_b128 v[164:167], v146
	ds_read_b128 v[168:171], v146 offset:1024
	ds_read_b128 v[172:175], v146 offset:2048
	ds_read_b128 v[180:183], v146 offset:3072
	v_lshl_add_u64 v[146:147], s[18:19], 0, v[138:139]
	s_add_i32 m0, s33, 0xc000
	ds_read_b128 v[186:189], v150
	ds_read_b128 v[190:193], v150 offset:1024
	ds_read_b128 v[194:197], v150 offset:2048
	ds_read_b128 v[198:201], v150 offset:3072
	ds_read_b128 v[202:205], v150 offset:4096
	ds_read_b128 v[206:209], v150 offset:5120
	ds_read_b128 v[210:213], v150 offset:6144
	ds_read_b128 v[214:217], v150 offset:7168
	global_load_lds_dwordx4 v[146:147], off
	v_lshl_add_u64 v[146:147], s[18:19], 0, v[140:141]
	s_add_i32 m0, s33, 0xe000
	s_nop 0
	global_load_lds_dwordx4 v[146:147], off
	s_waitcnt vmcnt(8) lgkmcnt(0)
	s_barrier
	s_setprio 1
	v_mfma_f32_16x16x32_bf16 v[126:129], v[142:145], v[186:189], 0
	v_mfma_f32_16x16x32_bf16 v[122:125], v[156:159], v[186:189], 0
	v_mfma_f32_16x16x32_bf16 v[114:117], v[142:145], v[194:197], 0
	v_mfma_f32_16x16x32_bf16 v[106:109], v[156:159], v[194:197], 0
	v_mfma_f32_16x16x32_bf16 v[98:101], v[142:145], v[202:205], 0
	v_mfma_f32_16x16x32_bf16 v[90:93], v[156:159], v[202:205], 0
	v_mfma_f32_16x16x32_bf16 v[82:85], v[142:145], v[210:213], 0
	v_mfma_f32_16x16x32_bf16 v[74:77], v[156:159], v[210:213], 0
	v_mfma_f32_16x16x32_bf16 v[126:129], v[152:155], v[190:193], v[126:129]
	v_mfma_f32_16x16x32_bf16 v[122:125], v[160:163], v[190:193], v[122:125]
	v_mfma_f32_16x16x32_bf16 v[114:117], v[152:155], v[198:201], v[114:117]
	v_mfma_f32_16x16x32_bf16 v[106:109], v[160:163], v[198:201], v[106:109]
	v_mfma_f32_16x16x32_bf16 v[98:101], v[152:155], v[206:209], v[98:101]
	v_mfma_f32_16x16x32_bf16 v[90:93], v[160:163], v[206:209], v[90:93]
	v_mfma_f32_16x16x32_bf16 v[82:85], v[152:155], v[214:217], v[82:85]
	v_mfma_f32_16x16x32_bf16 v[74:77], v[160:163], v[214:217], v[74:77]
	v_mfma_f32_16x16x32_bf16 v[118:121], v[164:167], v[186:189], 0
	v_mfma_f32_16x16x32_bf16 v[110:113], v[172:175], v[186:189], 0
	v_mfma_f32_16x16x32_bf16 v[102:105], v[164:167], v[194:197], 0
	v_mfma_f32_16x16x32_bf16 v[94:97], v[172:175], v[194:197], 0
	v_mfma_f32_16x16x32_bf16 v[86:89], v[164:167], v[202:205], 0
	v_mfma_f32_16x16x32_bf16 v[78:81], v[172:175], v[202:205], 0
	v_mfma_f32_16x16x32_bf16 v[70:73], v[164:167], v[210:213], 0
	v_mfma_f32_16x16x32_bf16 v[66:69], v[172:175], v[210:213], 0
	v_mfma_f32_16x16x32_bf16 v[118:121], v[168:171], v[190:193], v[118:121]
	v_mfma_f32_16x16x32_bf16 v[110:113], v[180:183], v[190:193], v[110:113]
	v_mfma_f32_16x16x32_bf16 v[102:105], v[168:171], v[198:201], v[102:105]
	v_mfma_f32_16x16x32_bf16 v[94:97], v[180:183], v[198:201], v[94:97]
	v_mfma_f32_16x16x32_bf16 v[86:89], v[168:171], v[206:209], v[86:89]
	v_mfma_f32_16x16x32_bf16 v[78:81], v[180:183], v[206:209], v[78:81]
	v_mfma_f32_16x16x32_bf16 v[70:73], v[168:171], v[214:217], v[70:73]
	v_mfma_f32_16x16x32_bf16 v[66:69], v[180:183], v[214:217], v[66:69]
	s_setprio 0
	s_barrier
	s_add_i32 s18, s50, s27
	v_lshl_add_u64 v[146:147], s[22:23], 0, v[132:133]
	s_mov_b32 m0, s18
	ds_read_b128 v[186:189], v150 offset:16384
	ds_read_b128 v[190:193], v150 offset:17408
	ds_read_b128 v[194:197], v150 offset:18432
	ds_read_b128 v[198:201], v150 offset:19456
	ds_read_b128 v[202:205], v150 offset:20480
	ds_read_b128 v[206:209], v150 offset:21504
	ds_read_b128 v[210:213], v150 offset:22528
	ds_read_b128 v[214:217], v150 offset:23552
	global_load_lds_dwordx4 v[146:147], off
	s_add_i32 m0, s18, 0x2000
	s_add_u32 s18, s22, 0xb0000
	v_lshl_add_u64 v[176:177], s[22:23], 0, v[136:137]
	s_addc_u32 s19, s23, 0
	s_add_i32 s50, s51, s27
	global_load_lds_dwordx4 v[176:177], off
	v_lshl_add_u64 v[218:219], s[18:19], 0, v[132:133]
	s_mov_b32 m0, s50
	v_lshl_add_u64 v[220:221], s[24:25], 0, v[134:135]
	global_load_lds_dwordx4 v[218:219], off
	v_lshl_add_u64 v[218:219], s[18:19], 0, v[136:137]
	s_add_i32 m0, s50, 0x2000
	s_nop 0
	global_load_lds_dwordx4 v[218:219], off
	v_lshl_add_u64 v[218:219], s[24:25], 0, v[130:131]
	s_mov_b32 m0, s33
	s_nop 0
	global_load_lds_dwordx4 v[218:219], off
	s_mov_b32 m0, s36
	s_nop 0
	global_load_lds_dwordx4 v[220:221], off
	s_waitcnt vmcnt(8) lgkmcnt(0)
	s_barrier
; #define PG8_STAGE(bufoff, gbase, voff) do { _Pragma("unroll") for (int _i = 0; _i < 2; ++_i) \
;         __builtin_amdgcn_global_load_lds((const unsigned*)((const char*)(gbase) + (voff)[_i]), (PG8_LAS unsigned*)(lds + (bufoff) + ldsw + _i * 8192), 16, 0, 0); } while (0)
; #define PG8_LDA(dst, b, h) do { _Pragma("unroll") for (int m = 0; m < 4; ++m) _Pragma("unroll") for (int k = 0; k < 2; ++k) dst[m][k] = *(const PG8_LAS bf16x8*)(lds + PG8_SA(b, h) + aoff + m * 2048 + k * 1024); } while (0)
; #define PG8_LDB(dst, b, h) do { _Pragma("unroll") for (int n = 0; n < 2; ++n) _Pragma("unroll") for (int k = 0; k < 2; ++k) dst[n][k] = *(const PG8_LAS bf16x8*)(lds + PG8_SB(b, h) + boff + n * 2048 + k * 1024); } while (0)
; #define PG8_MMA(ai, bj, At, Bt) do { __builtin_amdgcn_s_setprio(1); _Pragma("unroll") for (int m = 0; m < 4; ++m) _Pragma("unroll") for (int n = 0; n < 2; ++n) _Pragma("unroll") for (int k = 0; k < 2; ++k) \
;         acc[ai][bj][m][n] = __builtin_amdgcn_mfma_f32_16x16x32_bf16(Bt[n][k], At[m][k], acc[ai][bj][m][n], 0, 0, 0); __builtin_amdgcn_s_setprio(0); } while (0)
; #define PG8_WAIT_V(n) asm volatile("s_waitcnt vmcnt(" #n ")" ::: "memory")
; #define PG8_WAIT_L(n) asm volatile("s_waitcnt lgkmcnt(" #n ")" ::: "memory")
; #define PG8_BAR __builtin_amdgcn_s_barrier()
; #define PG8_SCHED __builtin_amdgcn_sched_barrier(0)
; template <class Epi, class Sched, bool ALIGN_EPI = false, bool SP2 = false>
; __device__ __forceinline__ void gemm_phase(PG8_LAS unsigned char* lds, const Gemm g, const Sched& S, const Epi& E) {
;     ...
;             PG8_LDA(At, 0, 1); PG8_STAGE(PG8_SB(0, 0), b2, voffB); PG8_STAGE(PG8_SB(0, 1), b2 + hstep, voffB); PG8_STAGE(PG8_SA(0, 0), a2, voffA);
;             PG8_WAIT_V(8); PG8_WAIT_L(0); PG8_BAR; PG8_MMA(1, 0, At, B0); PG8_MMA(1, 1, At, B1); PG8_BAR; PG8_SCHED;
;             PG8_LDB(B0, 1, 0); PG8_LDB(B1, 1, 1); PG8_SCHED; PG8_LDA(At, 1, 0); PG8_STAGE(PG8_SA(0, 1), a2 + hstep, voffA);
;             PG8_WAIT_V(8); PG8_WAIT_L(0); PG8_BAR; PG8_MMA(0, 0, At, B0); PG8_MMA(0, 1, At, B1); PG8_BAR; PG8_SCHED;
	s_setprio 1
	v_mfma_f32_16x16x32_bf16 v[62:65], v[142:145], v[186:189], 0
	v_mfma_f32_16x16x32_bf16 v[58:61], v[156:159], v[186:189], 0
	v_mfma_f32_16x16x32_bf16 v[50:53], v[142:145], v[194:197], 0
	v_mfma_f32_16x16x32_bf16 v[42:45], v[156:159], v[194:197], 0
	v_mfma_f32_16x16x32_bf16 v[34:37], v[142:145], v[202:205], 0
	v_mfma_f32_16x16x32_bf16 v[26:29], v[156:159], v[202:205], 0
	v_mfma_f32_16x16x32_bf16 v[18:21], v[142:145], v[210:213], 0
	v_mfma_f32_16x16x32_bf16 v[10:13], v[156:159], v[210:213], 0
	v_mfma_f32_16x16x32_bf16 v[62:65], v[152:155], v[190:193], v[62:65]
	v_mfma_f32_16x16x32_bf16 v[58:61], v[160:163], v[190:193], v[58:61]
	v_mfma_f32_16x16x32_bf16 v[50:53], v[152:155], v[198:201], v[50:53]
	v_mfma_f32_16x16x32_bf16 v[42:45], v[160:163], v[198:201], v[42:45]
	v_mfma_f32_16x16x32_bf16 v[34:37], v[152:155], v[206:209], v[34:37]
	v_mfma_f32_16x16x32_bf16 v[26:29], v[160:163], v[206:209], v[26:29]
	v_mfma_f32_16x16x32_bf16 v[18:21], v[152:155], v[214:217], v[18:21]
	v_mfma_f32_16x16x32_bf16 v[10:13], v[160:163], v[214:217], v[10:13]
	v_mfma_f32_16x16x32_bf16 v[54:57], v[164:167], v[186:189], 0
	v_mfma_f32_16x16x32_bf16 v[46:49], v[172:175], v[186:189], 0
	v_mfma_f32_16x16x32_bf16 v[38:41], v[164:167], v[194:197], 0
	v_mfma_f32_16x16x32_bf16 v[30:33], v[172:175], v[194:197], 0
	v_mfma_f32_16x16x32_bf16 v[22:25], v[164:167], v[202:205], 0
	v_mfma_f32_16x16x32_bf16 v[14:17], v[172:175], v[202:205], 0
	v_mfma_f32_16x16x32_bf16 v[6:9], v[164:167], v[210:213], 0
	v_mfma_f32_16x16x32_bf16 v[2:5], v[172:175], v[210:213], 0
	v_mfma_f32_16x16x32_bf16 v[54:57], v[168:171], v[190:193], v[54:57]
	v_mfma_f32_16x16x32_bf16 v[46:49], v[180:183], v[190:193], v[46:49]
	v_mfma_f32_16x16x32_bf16 v[38:41], v[168:171], v[198:201], v[38:41]
	v_mfma_f32_16x16x32_bf16 v[30:33], v[180:183], v[198:201], v[30:33]
	v_mfma_f32_16x16x32_bf16 v[22:25], v[168:171], v[206:209], v[22:25]
	v_mfma_f32_16x16x32_bf16 v[14:17], v[180:183], v[206:209], v[14:17]
	v_mfma_f32_16x16x32_bf16 v[6:9], v[168:171], v[214:217], v[6:9]
	v_mfma_f32_16x16x32_bf16 v[2:5], v[180:183], v[214:217], v[2:5]
	s_setprio 0
	s_barrier
	s_add_i32 s50, 0, 0x18000
	v_add_u32_e32 v151, s50, v148
	s_add_i32 s51, 0, 0x1c000
	ds_read_b128 v[142:145], v151
	ds_read_b128 v[152:155], v151 offset:1024
	ds_read_b128 v[156:159], v151 offset:2048
	ds_read_b128 v[160:163], v151 offset:3072
	v_add_u32_e32 v151, s51, v148
	ds_read_b128 v[164:167], v151
	ds_read_b128 v[168:171], v151 offset:1024
	ds_read_b128 v[172:175], v151 offset:2048
	ds_read_b128 v[180:183], v151 offset:3072
	s_add_u32 s18, s24, 0xb0000
	s_addc_u32 s19, s25, 0
	s_mov_b32 m0, s37
	v_lshl_add_u64 v[222:223], s[18:19], 0, v[130:131]
	ds_read_b128 v[186:189], v150 offset:32768
	ds_read_b128 v[190:193], v150 offset:33792
	ds_read_b128 v[194:197], v150 offset:34816
	ds_read_b128 v[198:201], v150 offset:35840
	ds_read_b128 v[202:205], v150 offset:36864
	ds_read_b128 v[206:209], v150 offset:37888
	ds_read_b128 v[210:213], v150 offset:38912
	ds_read_b128 v[214:217], v150 offset:39936
	global_load_lds_dwordx4 v[222:223], off
	v_lshl_add_u64 v[222:223], s[18:19], 0, v[134:135]
	s_mov_b32 m0, s38
	s_nop 0
	global_load_lds_dwordx4 v[222:223], off
	s_waitcnt vmcnt(8) lgkmcnt(0)
	s_barrier
	s_setprio 1
	v_mfma_f32_16x16x32_bf16 v[126:129], v[142:145], v[186:189], v[126:129]
	v_mfma_f32_16x16x32_bf16 v[122:125], v[156:159], v[186:189], v[122:125]
	v_mfma_f32_16x16x32_bf16 v[114:117], v[142:145], v[194:197], v[114:117]
	v_mfma_f32_16x16x32_bf16 v[106:109], v[156:159], v[194:197], v[106:109]
	v_mfma_f32_16x16x32_bf16 v[98:101], v[142:145], v[202:205], v[98:101]
	v_mfma_f32_16x16x32_bf16 v[90:93], v[156:159], v[202:205], v[90:93]
	v_mfma_f32_16x16x32_bf16 v[82:85], v[142:145], v[210:213], v[82:85]
	v_mfma_f32_16x16x32_bf16 v[74:77], v[156:159], v[210:213], v[74:77]
	v_mfma_f32_16x16x32_bf16 v[126:129], v[152:155], v[190:193], v[126:129]
	v_mfma_f32_16x16x32_bf16 v[122:125], v[160:163], v[190:193], v[122:125]
	v_mfma_f32_16x16x32_bf16 v[114:117], v[152:155], v[198:201], v[114:117]
	v_mfma_f32_16x16x32_bf16 v[106:109], v[160:163], v[198:201], v[106:109]
	v_mfma_f32_16x16x32_bf16 v[98:101], v[152:155], v[206:209], v[98:101]
	v_mfma_f32_16x16x32_bf16 v[90:93], v[160:163], v[206:209], v[90:93]
	v_mfma_f32_16x16x32_bf16 v[82:85], v[152:155], v[214:217], v[82:85]
	v_mfma_f32_16x16x32_bf16 v[74:77], v[160:163], v[214:217], v[74:77]
	v_mfma_f32_16x16x32_bf16 v[118:121], v[164:167], v[186:189], v[118:121]
	v_mfma_f32_16x16x32_bf16 v[110:113], v[172:175], v[186:189], v[110:113]
	v_mfma_f32_16x16x32_bf16 v[102:105], v[164:167], v[194:197], v[102:105]
	v_mfma_f32_16x16x32_bf16 v[94:97], v[172:175], v[194:197], v[94:97]
	v_mfma_f32_16x16x32_bf16 v[86:89], v[164:167], v[202:205], v[86:89]
	v_mfma_f32_16x16x32_bf16 v[78:81], v[172:175], v[202:205], v[78:81]
	v_mfma_f32_16x16x32_bf16 v[70:73], v[164:167], v[210:213], v[70:73]
	v_mfma_f32_16x16x32_bf16 v[66:69], v[172:175], v[210:213], v[66:69]
	v_mfma_f32_16x16x32_bf16 v[118:121], v[168:171], v[190:193], v[118:121]
	v_mfma_f32_16x16x32_bf16 v[110:113], v[180:183], v[190:193], v[110:113]
	v_mfma_f32_16x16x32_bf16 v[102:105], v[168:171], v[198:201], v[102:105]
	v_mfma_f32_16x16x32_bf16 v[94:97], v[180:183], v[198:201], v[94:97]
	v_mfma_f32_16x16x32_bf16 v[86:89], v[168:171], v[206:209], v[86:89]
	v_mfma_f32_16x16x32_bf16 v[78:81], v[180:183], v[206:209], v[78:81]
	v_mfma_f32_16x16x32_bf16 v[70:73], v[168:171], v[214:217], v[70:73]
	v_mfma_f32_16x16x32_bf16 v[66:69], v[180:183], v[214:217], v[66:69]
	s_setprio 0
	s_barrier
; #define PG8_STAGE(bufoff, gbase, voff) do { _Pragma("unroll") for (int _i = 0; _i < 2; ++_i) \
;         __builtin_amdgcn_global_load_lds((const unsigned*)((const char*)(gbase) + (voff)[_i]), (PG8_LAS unsigned*)(lds + (bufoff) + ldsw + _i * 8192), 16, 0, 0); } while (0)
; #define PG8_LDA(dst, b, h) do { _Pragma("unroll") for (int m = 0; m < 4; ++m) _Pragma("unroll") for (int k = 0; k < 2; ++k) dst[m][k] = *(const PG8_LAS bf16x8*)(lds + PG8_SA(b, h) + aoff + m * 2048 + k * 1024); } while (0)
; #define PG8_LDB(dst, b, h) do { _Pragma("unroll") for (int n = 0; n < 2; ++n) _Pragma("unroll") for (int k = 0; k < 2; ++k) dst[n][k] = *(const PG8_LAS bf16x8*)(lds + PG8_SB(b, h) + boff + n * 2048 + k * 1024); } while (0)
; #define PG8_MMA(ai, bj, At, Bt) do { __builtin_amdgcn_s_setprio(1); _Pragma("unroll") for (int m = 0; m < 4; ++m) _Pragma("unroll") for (int n = 0; n < 2; ++n) _Pragma("unroll") for (int k = 0; k < 2; ++k) \
;         acc[ai][bj][m][n] = __builtin_amdgcn_mfma_f32_16x16x32_bf16(Bt[n][k], At[m][k], acc[ai][bj][m][n], 0, 0, 0); __builtin_amdgcn_s_setprio(0); } while (0)
; #define PG8_WAIT_V(n) asm volatile("s_waitcnt vmcnt(" #n ")" ::: "memory")
; #define PG8_BAR __builtin_amdgcn_s_barrier()
; template <class Epi, class Sched, bool ALIGN_EPI = false, bool SP2 = false>
; __device__ __forceinline__ void gemm_phase(PG8_LAS unsigned char* lds, const Gemm g, const Sched& S, const Epi& E) {
;     ...
;         for (int t = 0; t < nt; t += 2) {
;             const bool last = (t == nt - 2);
;             const char* a1 = cA + (size_t)(t + 1) * kstep;
;             const char* a2 = last ? nA : cA + (size_t)(t + 2) * kstep; const char* b2 = last ? nB : cB + (size_t)(t + 2) * kstep;
;             const char* a3 = a2 + kstep; const char* b3 = b2 + kstep;
;             if (last && has_next) S.a_ready(nxt);
;             if constexpr (SP2) {
;             PG8_LDB(B0, 0, 0); PG8_LDB(B1, 0, 1); PG8_SCHED; PG8_LDA(At, 0, 0); PG8_STAGE(PG8_SA(1, 1), a1 + hstep, voffA);
;             PG8_WAIT_V(8); PG8_WAIT_L(0); PG8_BAR; PG8_MMA(0, 0, At, B0); PG8_MMA(0, 1, At, B1); PG8_BAR; PG8_SCHED;
;     ...
;             PG8_LDA(At, 1, 1); PG8_STAGE(PG8_SB(1, 0), b3, voffB); PG8_STAGE(PG8_SB(1, 1), b3 + hstep, voffB); PG8_STAGE(PG8_SA(1, 0), a3, voffA);
;             PG8_WAIT_V(8); PG8_WAIT_L(0); PG8_BAR; PG8_MMA(1, 0, At, B0); PG8_MMA(1, 1, At, B1); PG8_BAR; PG8_SCHED;
	s_add_i32 s18, s50, s27
	v_lshl_add_u64 v[146:147], v[146:147], 0, s[80:81]
	s_mov_b32 m0, s18
	ds_read_b128 v[186:189], v150 offset:49152
	ds_read_b128 v[190:193], v150 offset:50176
	ds_read_b128 v[194:197], v150 offset:51200
	ds_read_b128 v[198:201], v150 offset:52224
	ds_read_b128 v[202:205], v150 offset:53248
	ds_read_b128 v[206:209], v150 offset:54272
	ds_read_b128 v[210:213], v150 offset:55296
	ds_read_b128 v[214:217], v150 offset:56320
	global_load_lds_dwordx4 v[146:147], off
	s_add_i32 m0, s18, 0x2000
	s_add_u32 s18, s22, 0xb0080
	v_lshl_add_u64 v[146:147], v[176:177], 0, s[80:81]
	s_addc_u32 s19, s23, 0
	s_add_i32 s22, s51, s27
	global_load_lds_dwordx4 v[146:147], off
	v_lshl_add_u64 v[146:147], s[18:19], 0, v[132:133]
	s_mov_b32 m0, s22
	s_nop 0
	global_load_lds_dwordx4 v[146:147], off
	v_lshl_add_u64 v[146:147], s[18:19], 0, v[136:137]
	s_add_i32 m0, s22, 0x2000
	s_nop 0
	global_load_lds_dwordx4 v[146:147], off
	v_lshl_add_u64 v[146:147], v[218:219], 0, s[80:81]
	s_mov_b32 m0, s39
	s_nop 0
	global_load_lds_dwordx4 v[146:147], off
	v_lshl_add_u64 v[146:147], v[220:221], 0, s[80:81]
	s_mov_b32 m0, s40
	s_nop 0
	global_load_lds_dwordx4 v[146:147], off
	s_waitcnt vmcnt(8) lgkmcnt(0)
	s_barrier
	s_setprio 1
	v_mfma_f32_16x16x32_bf16 v[62:65], v[142:145], v[186:189], v[62:65]
	v_mfma_f32_16x16x32_bf16 v[58:61], v[156:159], v[186:189], v[58:61]
	v_mfma_f32_16x16x32_bf16 v[50:53], v[142:145], v[194:197], v[50:53]
	v_mfma_f32_16x16x32_bf16 v[42:45], v[156:159], v[194:197], v[42:45]
	v_mfma_f32_16x16x32_bf16 v[34:37], v[142:145], v[202:205], v[34:37]
	v_mfma_f32_16x16x32_bf16 v[26:29], v[156:159], v[202:205], v[26:29]
	v_mfma_f32_16x16x32_bf16 v[18:21], v[142:145], v[210:213], v[18:21]
	v_mfma_f32_16x16x32_bf16 v[10:13], v[156:159], v[210:213], v[10:13]
	v_mfma_f32_16x16x32_bf16 v[62:65], v[152:155], v[190:193], v[62:65]
	v_mfma_f32_16x16x32_bf16 v[58:61], v[160:163], v[190:193], v[58:61]
	v_mfma_f32_16x16x32_bf16 v[50:53], v[152:155], v[198:201], v[50:53]
	v_mfma_f32_16x16x32_bf16 v[42:45], v[160:163], v[198:201], v[42:45]
	v_mfma_f32_16x16x32_bf16 v[34:37], v[152:155], v[206:209], v[34:37]
	v_mfma_f32_16x16x32_bf16 v[26:29], v[160:163], v[206:209], v[26:29]
	v_mfma_f32_16x16x32_bf16 v[18:21], v[152:155], v[214:217], v[18:21]
	v_mfma_f32_16x16x32_bf16 v[10:13], v[160:163], v[214:217], v[10:13]
	v_mfma_f32_16x16x32_bf16 v[54:57], v[164:167], v[186:189], v[54:57]
	v_mfma_f32_16x16x32_bf16 v[46:49], v[172:175], v[186:189], v[46:49]
	v_mfma_f32_16x16x32_bf16 v[38:41], v[164:167], v[194:197], v[38:41]
	v_mfma_f32_16x16x32_bf16 v[30:33], v[172:175], v[194:197], v[30:33]
	v_mfma_f32_16x16x32_bf16 v[22:25], v[164:167], v[202:205], v[22:25]
	v_mfma_f32_16x16x32_bf16 v[14:17], v[172:175], v[202:205], v[14:17]
	v_mfma_f32_16x16x32_bf16 v[6:9], v[164:167], v[210:213], v[6:9]
	v_mfma_f32_16x16x32_bf16 v[2:5], v[172:175], v[210:213], v[2:5]
	v_mfma_f32_16x16x32_bf16 v[54:57], v[168:171], v[190:193], v[54:57]
	v_mfma_f32_16x16x32_bf16 v[46:49], v[180:183], v[190:193], v[46:49]
	v_mfma_f32_16x16x32_bf16 v[38:41], v[168:171], v[198:201], v[38:41]
	v_mfma_f32_16x16x32_bf16 v[30:33], v[180:183], v[198:201], v[30:33]
	v_mfma_f32_16x16x32_bf16 v[22:25], v[168:171], v[206:209], v[22:25]
	v_mfma_f32_16x16x32_bf16 v[14:17], v[180:183], v[206:209], v[14:17]
	v_mfma_f32_16x16x32_bf16 v[6:9], v[168:171], v[214:217], v[6:9]
	v_mfma_f32_16x16x32_bf16 v[2:5], v[180:183], v[214:217], v[2:5]
	s_setprio 0
	s_barrier
	s_add_i32 s49, s49, 2
	s_add_u32 s47, s47, 0x100
	s_addc_u32 s48, s48, 0
	s_cmp_gt_u32 s49, 41
	s_mov_b64 s[18:19], s[20:21]
	s_branch .LBB0_1360
.LBB0_1360:
	s_add_u32 s20, s18, 0x100
	s_addc_u32 s21, s19, 0
	s_add_i32 s50, 0, 0x10000
	s_cmp_eq_u32 s49, 40
	s_cselect_b32 s25, s7, s21
	s_cselect_b32 s24, s6, s20
	v_add_u32_e32 v146, s50, v148
	s_cselect_b32 s23, s17, s48
	s_cselect_b32 s22, s16, s47
	s_add_i32 s51, 0, 0x14000
	ds_read_b128 v[142:145], v146
	ds_read_b128 v[152:155], v146 offset:1024
	ds_read_b128 v[156:159], v146 offset:2048
	ds_read_b128 v[160:163], v146 offset:3072
	v_add_u32_e32 v146, s51, v148
	ds_read_b128 v[164:167], v146
	ds_read_b128 v[168:171], v146 offset:1024
	ds_read_b128 v[172:175], v146 offset:2048
	ds_read_b128 v[180:183], v146 offset:3072
	v_lshl_add_u64 v[146:147], s[18:19], 0, v[138:139]
	s_add_i32 m0, s33, 0xc000
	ds_read_b128 v[186:189], v150
	ds_read_b128 v[190:193], v150 offset:1024
	ds_read_b128 v[194:197], v150 offset:2048
	ds_read_b128 v[198:201], v150 offset:3072
	ds_read_b128 v[202:205], v150 offset:4096
	ds_read_b128 v[206:209], v150 offset:5120
	ds_read_b128 v[210:213], v150 offset:6144
	ds_read_b128 v[214:217], v150 offset:7168
	global_load_lds_dwordx4 v[146:147], off
	v_lshl_add_u64 v[146:147], s[18:19], 0, v[140:141]
	s_add_i32 m0, s33, 0xe000
	s_nop 0
	global_load_lds_dwordx4 v[146:147], off
	s_waitcnt vmcnt(8) lgkmcnt(0)
	s_barrier
; #define PG8_STAGE(bufoff, gbase, voff) do { _Pragma("unroll") for (int _i = 0; _i < 2; ++_i) \
;         __builtin_amdgcn_global_load_lds((const unsigned*)((const char*)(gbase) + (voff)[_i]), (PG8_LAS unsigned*)(lds + (bufoff) + ldsw + _i * 8192), 16, 0, 0); } while (0)
; #define PG8_LDA(dst, b, h) do { _Pragma("unroll") for (int m = 0; m < 4; ++m) _Pragma("unroll") for (int k = 0; k < 2; ++k) dst[m][k] = *(const PG8_LAS bf16x8*)(lds + PG8_SA(b, h) + aoff + m * 2048 + k * 1024); } while (0)
; #define PG8_LDB(dst, b, h) do { _Pragma("unroll") for (int n = 0; n < 2; ++n) _Pragma("unroll") for (int k = 0; k < 2; ++k) dst[n][k] = *(const PG8_LAS bf16x8*)(lds + PG8_SB(b, h) + boff + n * 2048 + k * 1024); } while (0)
; #define PG8_MMA(ai, bj, At, Bt) do { __builtin_amdgcn_s_setprio(1); _Pragma("unroll") for (int m = 0; m < 4; ++m) _Pragma("unroll") for (int n = 0; n < 2; ++n) _Pragma("unroll") for (int k = 0; k < 2; ++k) \
;         acc[ai][bj][m][n] = __builtin_amdgcn_mfma_f32_16x16x32_bf16(Bt[n][k], At[m][k], acc[ai][bj][m][n], 0, 0, 0); __builtin_amdgcn_s_setprio(0); } while (0)
; #define PG8_WAIT_V(n) asm volatile("s_waitcnt vmcnt(" #n ")" ::: "memory")
; #define PG8_WAIT_L(n) asm volatile("s_waitcnt lgkmcnt(" #n ")" ::: "memory")
; #define PG8_BAR __builtin_amdgcn_s_barrier()
; #define PG8_SCHED __builtin_amdgcn_sched_barrier(0)
; template <class Epi, class Sched, bool ALIGN_EPI = false, bool SP2 = false>
; __device__ __forceinline__ void gemm_phase(PG8_LAS unsigned char* lds, const Gemm g, const Sched& S, const Epi& E) {
;     ...
;             PG8_LDB(B0, 0, 0); PG8_LDB(B1, 0, 1); PG8_SCHED; PG8_LDA(At, 0, 0); PG8_STAGE(PG8_SA(1, 1), a1 + hstep, voffA);
;             PG8_WAIT_V(8); PG8_WAIT_L(0); PG8_BAR; PG8_MMA(0, 0, At, B0); PG8_MMA(0, 1, At, B1); PG8_BAR; PG8_SCHED;
;             PG8_LDA(At, 0, 1); PG8_STAGE(PG8_SB(0, 0), b2, voffB); PG8_STAGE(PG8_SB(0, 1), b2 + hstep, voffB); PG8_STAGE(PG8_SA(0, 0), a2, voffA);
;             PG8_WAIT_V(8); PG8_WAIT_L(0); PG8_BAR; PG8_MMA(1, 0, At, B0); PG8_MMA(1, 1, At, B1); PG8_BAR; PG8_SCHED;
	s_setprio 1
	v_mfma_f32_16x16x32_bf16 v[126:129], v[142:145], v[186:189], v[126:129]
	v_mfma_f32_16x16x32_bf16 v[122:125], v[156:159], v[186:189], v[122:125]
	v_mfma_f32_16x16x32_bf16 v[114:117], v[142:145], v[194:197], v[114:117]
	v_mfma_f32_16x16x32_bf16 v[106:109], v[156:159], v[194:197], v[106:109]
	v_mfma_f32_16x16x32_bf16 v[98:101], v[142:145], v[202:205], v[98:101]
	v_mfma_f32_16x16x32_bf16 v[90:93], v[156:159], v[202:205], v[90:93]
	v_mfma_f32_16x16x32_bf16 v[82:85], v[142:145], v[210:213], v[82:85]
	v_mfma_f32_16x16x32_bf16 v[74:77], v[156:159], v[210:213], v[74:77]
	v_mfma_f32_16x16x32_bf16 v[126:129], v[152:155], v[190:193], v[126:129]
	v_mfma_f32_16x16x32_bf16 v[122:125], v[160:163], v[190:193], v[122:125]
	v_mfma_f32_16x16x32_bf16 v[114:117], v[152:155], v[198:201], v[114:117]
	v_mfma_f32_16x16x32_bf16 v[106:109], v[160:163], v[198:201], v[106:109]
	v_mfma_f32_16x16x32_bf16 v[98:101], v[152:155], v[206:209], v[98:101]
	v_mfma_f32_16x16x32_bf16 v[90:93], v[160:163], v[206:209], v[90:93]
	v_mfma_f32_16x16x32_bf16 v[82:85], v[152:155], v[214:217], v[82:85]
	v_mfma_f32_16x16x32_bf16 v[74:77], v[160:163], v[214:217], v[74:77]
	v_mfma_f32_16x16x32_bf16 v[118:121], v[164:167], v[186:189], v[118:121]
	v_mfma_f32_16x16x32_bf16 v[110:113], v[172:175], v[186:189], v[110:113]
	v_mfma_f32_16x16x32_bf16 v[102:105], v[164:167], v[194:197], v[102:105]
	v_mfma_f32_16x16x32_bf16 v[94:97], v[172:175], v[194:197], v[94:97]
	v_mfma_f32_16x16x32_bf16 v[86:89], v[164:167], v[202:205], v[86:89]
	v_mfma_f32_16x16x32_bf16 v[78:81], v[172:175], v[202:205], v[78:81]
	v_mfma_f32_16x16x32_bf16 v[70:73], v[164:167], v[210:213], v[70:73]
	v_mfma_f32_16x16x32_bf16 v[66:69], v[172:175], v[210:213], v[66:69]
	v_mfma_f32_16x16x32_bf16 v[118:121], v[168:171], v[190:193], v[118:121]
	v_mfma_f32_16x16x32_bf16 v[110:113], v[180:183], v[190:193], v[110:113]
	v_mfma_f32_16x16x32_bf16 v[102:105], v[168:171], v[198:201], v[102:105]
	v_mfma_f32_16x16x32_bf16 v[94:97], v[180:183], v[198:201], v[94:97]
	v_mfma_f32_16x16x32_bf16 v[86:89], v[168:171], v[206:209], v[86:89]
	v_mfma_f32_16x16x32_bf16 v[78:81], v[180:183], v[206:209], v[78:81]
	v_mfma_f32_16x16x32_bf16 v[70:73], v[168:171], v[214:217], v[70:73]
	v_mfma_f32_16x16x32_bf16 v[66:69], v[180:183], v[214:217], v[66:69]
	s_setprio 0
	s_barrier
	s_add_i32 s18, s50, s27
	v_lshl_add_u64 v[146:147], s[22:23], 0, v[132:133]
	s_mov_b32 m0, s18
	ds_read_b128 v[186:189], v150 offset:16384
	ds_read_b128 v[190:193], v150 offset:17408
	ds_read_b128 v[194:197], v150 offset:18432
	ds_read_b128 v[198:201], v150 offset:19456
	ds_read_b128 v[202:205], v150 offset:20480
	ds_read_b128 v[206:209], v150 offset:21504
	ds_read_b128 v[210:213], v150 offset:22528
	ds_read_b128 v[214:217], v150 offset:23552
	global_load_lds_dwordx4 v[146:147], off
	s_add_i32 m0, s18, 0x2000
	s_add_u32 s18, s22, 0xb0000
	v_lshl_add_u64 v[176:177], s[22:23], 0, v[136:137]
	s_addc_u32 s19, s23, 0
	s_add_i32 s50, s51, s27
	global_load_lds_dwordx4 v[176:177], off
	v_lshl_add_u64 v[218:219], s[18:19], 0, v[132:133]
	s_mov_b32 m0, s50
	v_lshl_add_u64 v[220:221], s[24:25], 0, v[134:135]
	global_load_lds_dwordx4 v[218:219], off
	v_lshl_add_u64 v[218:219], s[18:19], 0, v[136:137]
	s_add_i32 m0, s50, 0x2000
	s_nop 0
	global_load_lds_dwordx4 v[218:219], off
	v_lshl_add_u64 v[218:219], s[24:25], 0, v[130:131]
	s_mov_b32 m0, s33
	s_nop 0
	global_load_lds_dwordx4 v[218:219], off
	s_mov_b32 m0, s36
	s_nop 0
	global_load_lds_dwordx4 v[220:221], off
	s_waitcnt vmcnt(8) lgkmcnt(0)
	s_barrier
	s_setprio 1
	v_mfma_f32_16x16x32_bf16 v[62:65], v[142:145], v[186:189], v[62:65]
	v_mfma_f32_16x16x32_bf16 v[58:61], v[156:159], v[186:189], v[58:61]
	v_mfma_f32_16x16x32_bf16 v[50:53], v[142:145], v[194:197], v[50:53]
	v_mfma_f32_16x16x32_bf16 v[42:45], v[156:159], v[194:197], v[42:45]
	v_mfma_f32_16x16x32_bf16 v[34:37], v[142:145], v[202:205], v[34:37]
	v_mfma_f32_16x16x32_bf16 v[26:29], v[156:159], v[202:205], v[26:29]
	v_mfma_f32_16x16x32_bf16 v[18:21], v[142:145], v[210:213], v[18:21]
	v_mfma_f32_16x16x32_bf16 v[10:13], v[156:159], v[210:213], v[10:13]
	v_mfma_f32_16x16x32_bf16 v[62:65], v[152:155], v[190:193], v[62:65]
	v_mfma_f32_16x16x32_bf16 v[58:61], v[160:163], v[190:193], v[58:61]
	v_mfma_f32_16x16x32_bf16 v[50:53], v[152:155], v[198:201], v[50:53]
	v_mfma_f32_16x16x32_bf16 v[42:45], v[160:163], v[198:201], v[42:45]
	v_mfma_f32_16x16x32_bf16 v[34:37], v[152:155], v[206:209], v[34:37]
	v_mfma_f32_16x16x32_bf16 v[26:29], v[160:163], v[206:209], v[26:29]
	v_mfma_f32_16x16x32_bf16 v[18:21], v[152:155], v[214:217], v[18:21]
	v_mfma_f32_16x16x32_bf16 v[10:13], v[160:163], v[214:217], v[10:13]
	v_mfma_f32_16x16x32_bf16 v[54:57], v[164:167], v[186:189], v[54:57]
	v_mfma_f32_16x16x32_bf16 v[46:49], v[172:175], v[186:189], v[46:49]
	v_mfma_f32_16x16x32_bf16 v[38:41], v[164:167], v[194:197], v[38:41]
	v_mfma_f32_16x16x32_bf16 v[30:33], v[172:175], v[194:197], v[30:33]
	v_mfma_f32_16x16x32_bf16 v[22:25], v[164:167], v[202:205], v[22:25]
	v_mfma_f32_16x16x32_bf16 v[14:17], v[172:175], v[202:205], v[14:17]
	v_mfma_f32_16x16x32_bf16 v[6:9], v[164:167], v[210:213], v[6:9]
	v_mfma_f32_16x16x32_bf16 v[2:5], v[172:175], v[210:213], v[2:5]
	v_mfma_f32_16x16x32_bf16 v[54:57], v[168:171], v[190:193], v[54:57]
	v_mfma_f32_16x16x32_bf16 v[46:49], v[180:183], v[190:193], v[46:49]
	v_mfma_f32_16x16x32_bf16 v[38:41], v[168:171], v[198:201], v[38:41]
	v_mfma_f32_16x16x32_bf16 v[30:33], v[180:183], v[198:201], v[30:33]
	v_mfma_f32_16x16x32_bf16 v[22:25], v[168:171], v[206:209], v[22:25]
	v_mfma_f32_16x16x32_bf16 v[14:17], v[180:183], v[206:209], v[14:17]
	v_mfma_f32_16x16x32_bf16 v[6:9], v[168:171], v[214:217], v[6:9]
	v_mfma_f32_16x16x32_bf16 v[2:5], v[180:183], v[214:217], v[2:5]
	s_setprio 0
	s_barrier
; #define PG8_STAGE(bufoff, gbase, voff) do { _Pragma("unroll") for (int _i = 0; _i < 2; ++_i) \
;         __builtin_amdgcn_global_load_lds((const unsigned*)((const char*)(gbase) + (voff)[_i]), (PG8_LAS unsigned*)(lds + (bufoff) + ldsw + _i * 8192), 16, 0, 0); } while (0)
; #define PG8_LDA(dst, b, h) do { _Pragma("unroll") for (int m = 0; m < 4; ++m) _Pragma("unroll") for (int k = 0; k < 2; ++k) dst[m][k] = *(const PG8_LAS bf16x8*)(lds + PG8_SA(b, h) + aoff + m * 2048 + k * 1024); } while (0)
; #define PG8_LDB(dst, b, h) do { _Pragma("unroll") for (int n = 0; n < 2; ++n) _Pragma("unroll") for (int k = 0; k < 2; ++k) dst[n][k] = *(const PG8_LAS bf16x8*)(lds + PG8_SB(b, h) + boff + n * 2048 + k * 1024); } while (0)
; #define PG8_MMA(ai, bj, At, Bt) do { __builtin_amdgcn_s_setprio(1); _Pragma("unroll") for (int m = 0; m < 4; ++m) _Pragma("unroll") for (int n = 0; n < 2; ++n) _Pragma("unroll") for (int k = 0; k < 2; ++k) \
;         acc[ai][bj][m][n] = __builtin_amdgcn_mfma_f32_16x16x32_bf16(Bt[n][k], At[m][k], acc[ai][bj][m][n], 0, 0, 0); __builtin_amdgcn_s_setprio(0); } while (0)
; #define PG8_WAIT_V(n) asm volatile("s_waitcnt vmcnt(" #n ")" ::: "memory")
; #define PG8_WAIT_L(n) asm volatile("s_waitcnt lgkmcnt(" #n ")" ::: "memory")
; #define PG8_BAR __builtin_amdgcn_s_barrier()
; #define PG8_SCHED __builtin_amdgcn_sched_barrier(0)
; template <class Epi, class Sched, bool ALIGN_EPI = false, bool SP2 = false>
; __device__ __forceinline__ void gemm_phase(PG8_LAS unsigned char* lds, const Gemm g, const Sched& S, const Epi& E) {
;     ...
;             PG8_LDB(B0, 1, 0); PG8_LDB(B1, 1, 1); PG8_SCHED; PG8_LDA(At, 1, 0); PG8_STAGE(PG8_SA(0, 1), a2 + hstep, voffA);
;             PG8_WAIT_V(8); PG8_WAIT_L(0); PG8_BAR; PG8_MMA(0, 0, At, B0); PG8_MMA(0, 1, At, B1); PG8_BAR; PG8_SCHED;
	s_add_i32 s50, 0, 0x18000
	v_add_u32_e32 v151, s50, v148
	s_add_i32 s51, 0, 0x1c000
	ds_read_b128 v[142:145], v151
	ds_read_b128 v[152:155], v151 offset:1024
	ds_read_b128 v[156:159], v151 offset:2048
	ds_read_b128 v[160:163], v151 offset:3072
	v_add_u32_e32 v151, s51, v148
	ds_read_b128 v[164:167], v151
	ds_read_b128 v[168:171], v151 offset:1024
	ds_read_b128 v[172:175], v151 offset:2048
	ds_read_b128 v[180:183], v151 offset:3072
	s_add_u32 s18, s24, 0xb0000
	s_addc_u32 s19, s25, 0
	s_mov_b32 m0, s37
	v_lshl_add_u64 v[222:223], s[18:19], 0, v[130:131]
	ds_read_b128 v[186:189], v150 offset:32768
	ds_read_b128 v[190:193], v150 offset:33792
	ds_read_b128 v[194:197], v150 offset:34816
	ds_read_b128 v[198:201], v150 offset:35840
	ds_read_b128 v[202:205], v150 offset:36864
	ds_read_b128 v[206:209], v150 offset:37888
	ds_read_b128 v[210:213], v150 offset:38912
	ds_read_b128 v[214:217], v150 offset:39936
	global_load_lds_dwordx4 v[222:223], off
	v_lshl_add_u64 v[222:223], s[18:19], 0, v[134:135]
	s_mov_b32 m0, s38
	s_nop 0
	global_load_lds_dwordx4 v[222:223], off
	s_waitcnt vmcnt(8) lgkmcnt(0)
	s_barrier
	s_setprio 1
	v_mfma_f32_16x16x32_bf16 v[126:129], v[142:145], v[186:189], v[126:129]
	v_mfma_f32_16x16x32_bf16 v[122:125], v[156:159], v[186:189], v[122:125]
	v_mfma_f32_16x16x32_bf16 v[114:117], v[142:145], v[194:197], v[114:117]
	v_mfma_f32_16x16x32_bf16 v[106:109], v[156:159], v[194:197], v[106:109]
	v_mfma_f32_16x16x32_bf16 v[98:101], v[142:145], v[202:205], v[98:101]
	v_mfma_f32_16x16x32_bf16 v[90:93], v[156:159], v[202:205], v[90:93]
	v_mfma_f32_16x16x32_bf16 v[82:85], v[142:145], v[210:213], v[82:85]
	v_mfma_f32_16x16x32_bf16 v[74:77], v[156:159], v[210:213], v[74:77]
	v_mfma_f32_16x16x32_bf16 v[126:129], v[152:155], v[190:193], v[126:129]
	v_mfma_f32_16x16x32_bf16 v[122:125], v[160:163], v[190:193], v[122:125]
	v_mfma_f32_16x16x32_bf16 v[114:117], v[152:155], v[198:201], v[114:117]
	v_mfma_f32_16x16x32_bf16 v[106:109], v[160:163], v[198:201], v[106:109]
	v_mfma_f32_16x16x32_bf16 v[98:101], v[152:155], v[206:209], v[98:101]
	v_mfma_f32_16x16x32_bf16 v[90:93], v[160:163], v[206:209], v[90:93]
	v_mfma_f32_16x16x32_bf16 v[82:85], v[152:155], v[214:217], v[82:85]
	v_mfma_f32_16x16x32_bf16 v[74:77], v[160:163], v[214:217], v[74:77]
	v_mfma_f32_16x16x32_bf16 v[118:121], v[164:167], v[186:189], v[118:121]
	v_mfma_f32_16x16x32_bf16 v[110:113], v[172:175], v[186:189], v[110:113]
	v_mfma_f32_16x16x32_bf16 v[102:105], v[164:167], v[194:197], v[102:105]
	v_mfma_f32_16x16x32_bf16 v[94:97], v[172:175], v[194:197], v[94:97]
	v_mfma_f32_16x16x32_bf16 v[86:89], v[164:167], v[202:205], v[86:89]
	v_mfma_f32_16x16x32_bf16 v[78:81], v[172:175], v[202:205], v[78:81]
	v_mfma_f32_16x16x32_bf16 v[70:73], v[164:167], v[210:213], v[70:73]
	v_mfma_f32_16x16x32_bf16 v[66:69], v[172:175], v[210:213], v[66:69]
	v_mfma_f32_16x16x32_bf16 v[118:121], v[168:171], v[190:193], v[118:121]
	v_mfma_f32_16x16x32_bf16 v[110:113], v[180:183], v[190:193], v[110:113]
	v_mfma_f32_16x16x32_bf16 v[102:105], v[168:171], v[198:201], v[102:105]
	v_mfma_f32_16x16x32_bf16 v[94:97], v[180:183], v[198:201], v[94:97]
	v_mfma_f32_16x16x32_bf16 v[86:89], v[168:171], v[206:209], v[86:89]
	v_mfma_f32_16x16x32_bf16 v[78:81], v[180:183], v[206:209], v[78:81]
	v_mfma_f32_16x16x32_bf16 v[70:73], v[168:171], v[214:217], v[70:73]
	v_mfma_f32_16x16x32_bf16 v[66:69], v[180:183], v[214:217], v[66:69]
	s_setprio 0
	s_barrier
; #define PG8_STAGE(bufoff, gbase, voff) do { _Pragma("unroll") for (int _i = 0; _i < 2; ++_i) \
;         __builtin_amdgcn_global_load_lds((const unsigned*)((const char*)(gbase) + (voff)[_i]), (PG8_LAS unsigned*)(lds + (bufoff) + ldsw + _i * 8192), 16, 0, 0); } while (0)
; #define PG8_LDA(dst, b, h) do { _Pragma("unroll") for (int m = 0; m < 4; ++m) _Pragma("unroll") for (int k = 0; k < 2; ++k) dst[m][k] = *(const PG8_LAS bf16x8*)(lds + PG8_SA(b, h) + aoff + m * 2048 + k * 1024); } while (0)
; #define PG8_MMA(ai, bj, At, Bt) do { __builtin_amdgcn_s_setprio(1); _Pragma("unroll") for (int m = 0; m < 4; ++m) _Pragma("unroll") for (int n = 0; n < 2; ++n) _Pragma("unroll") for (int k = 0; k < 2; ++k) \
;         acc[ai][bj][m][n] = __builtin_amdgcn_mfma_f32_16x16x32_bf16(Bt[n][k], At[m][k], acc[ai][bj][m][n], 0, 0, 0); __builtin_amdgcn_s_setprio(0); } while (0)
; #define PG8_WAIT_V(n) asm volatile("s_waitcnt vmcnt(" #n ")" ::: "memory")
; #define PG8_WAIT_L(n) asm volatile("s_waitcnt lgkmcnt(" #n ")" ::: "memory")
; #define PG8_BAR __builtin_amdgcn_s_barrier()
; #define PG8_SCHED __builtin_amdgcn_sched_barrier(0)
; template <class Epi, class Sched, bool ALIGN_EPI = false, bool SP2 = false>
; __device__ __forceinline__ void gemm_phase(PG8_LAS unsigned char* lds, const Gemm g, const Sched& S, const Epi& E) {
;     ...
;             PG8_LDA(At, 1, 1); PG8_STAGE(PG8_SB(1, 0), b3, voffB); PG8_STAGE(PG8_SB(1, 1), b3 + hstep, voffB); PG8_STAGE(PG8_SA(1, 0), a3, voffA);
;             PG8_WAIT_V(8); PG8_WAIT_L(0); PG8_BAR; PG8_MMA(1, 0, At, B0); PG8_MMA(1, 1, At, B1); PG8_BAR; PG8_SCHED;
;     ...
;         if constexpr (ALIGN_EPI) { if (wr == 0) PG8_BAR; }
	s_add_i32 s18, s50, s27
	v_lshl_add_u64 v[146:147], v[146:147], 0, s[80:81]
	s_mov_b32 m0, s18
	ds_read_b128 v[186:189], v150 offset:49152
	ds_read_b128 v[190:193], v150 offset:50176
	ds_read_b128 v[194:197], v150 offset:51200
	ds_read_b128 v[198:201], v150 offset:52224
	ds_read_b128 v[202:205], v150 offset:53248
	ds_read_b128 v[206:209], v150 offset:54272
	ds_read_b128 v[210:213], v150 offset:55296
	ds_read_b128 v[214:217], v150 offset:56320
	global_load_lds_dwordx4 v[146:147], off
	s_add_i32 m0, s18, 0x2000
	s_add_u32 s18, s22, 0xb0080
	v_lshl_add_u64 v[146:147], v[176:177], 0, s[80:81]
	s_addc_u32 s19, s23, 0
	s_add_i32 s22, s51, s27
	global_load_lds_dwordx4 v[146:147], off
	v_lshl_add_u64 v[146:147], s[18:19], 0, v[132:133]
	s_mov_b32 m0, s22
	s_nop 0
	global_load_lds_dwordx4 v[146:147], off
	v_lshl_add_u64 v[146:147], s[18:19], 0, v[136:137]
	s_add_i32 m0, s22, 0x2000
	s_nop 0
	global_load_lds_dwordx4 v[146:147], off
	v_lshl_add_u64 v[146:147], v[218:219], 0, s[80:81]
	s_mov_b32 m0, s39
	s_nop 0
	global_load_lds_dwordx4 v[146:147], off
	v_lshl_add_u64 v[146:147], v[220:221], 0, s[80:81]
	s_mov_b32 m0, s40
	s_nop 0
	global_load_lds_dwordx4 v[146:147], off
	s_waitcnt vmcnt(8) lgkmcnt(0)
	s_barrier
	s_setprio 1
	v_mfma_f32_16x16x32_bf16 v[62:65], v[142:145], v[186:189], v[62:65]
	v_mfma_f32_16x16x32_bf16 v[58:61], v[156:159], v[186:189], v[58:61]
	v_mfma_f32_16x16x32_bf16 v[50:53], v[142:145], v[194:197], v[50:53]
	v_mfma_f32_16x16x32_bf16 v[42:45], v[156:159], v[194:197], v[42:45]
	v_mfma_f32_16x16x32_bf16 v[34:37], v[142:145], v[202:205], v[34:37]
	v_mfma_f32_16x16x32_bf16 v[26:29], v[156:159], v[202:205], v[26:29]
	v_mfma_f32_16x16x32_bf16 v[18:21], v[142:145], v[210:213], v[18:21]
	v_mfma_f32_16x16x32_bf16 v[10:13], v[156:159], v[210:213], v[10:13]
	v_mfma_f32_16x16x32_bf16 v[62:65], v[152:155], v[190:193], v[62:65]
	v_mfma_f32_16x16x32_bf16 v[58:61], v[160:163], v[190:193], v[58:61]
	v_mfma_f32_16x16x32_bf16 v[50:53], v[152:155], v[198:201], v[50:53]
	v_mfma_f32_16x16x32_bf16 v[42:45], v[160:163], v[198:201], v[42:45]
	v_mfma_f32_16x16x32_bf16 v[34:37], v[152:155], v[206:209], v[34:37]
	v_mfma_f32_16x16x32_bf16 v[26:29], v[160:163], v[206:209], v[26:29]
	v_mfma_f32_16x16x32_bf16 v[18:21], v[152:155], v[214:217], v[18:21]
	v_mfma_f32_16x16x32_bf16 v[10:13], v[160:163], v[214:217], v[10:13]
	v_mfma_f32_16x16x32_bf16 v[54:57], v[164:167], v[186:189], v[54:57]
	v_mfma_f32_16x16x32_bf16 v[46:49], v[172:175], v[186:189], v[46:49]
	v_mfma_f32_16x16x32_bf16 v[38:41], v[164:167], v[194:197], v[38:41]
	v_mfma_f32_16x16x32_bf16 v[30:33], v[172:175], v[194:197], v[30:33]
	v_mfma_f32_16x16x32_bf16 v[22:25], v[164:167], v[202:205], v[22:25]
	v_mfma_f32_16x16x32_bf16 v[14:17], v[172:175], v[202:205], v[14:17]
	v_mfma_f32_16x16x32_bf16 v[6:9], v[164:167], v[210:213], v[6:9]
	v_mfma_f32_16x16x32_bf16 v[2:5], v[172:175], v[210:213], v[2:5]
	v_mfma_f32_16x16x32_bf16 v[54:57], v[168:171], v[190:193], v[54:57]
	v_mfma_f32_16x16x32_bf16 v[46:49], v[180:183], v[190:193], v[46:49]
	v_mfma_f32_16x16x32_bf16 v[38:41], v[168:171], v[198:201], v[38:41]
	v_mfma_f32_16x16x32_bf16 v[30:33], v[180:183], v[198:201], v[30:33]
	v_mfma_f32_16x16x32_bf16 v[22:25], v[168:171], v[206:209], v[22:25]
	v_mfma_f32_16x16x32_bf16 v[14:17], v[180:183], v[206:209], v[14:17]
	v_mfma_f32_16x16x32_bf16 v[6:9], v[168:171], v[214:217], v[6:9]
	v_mfma_f32_16x16x32_bf16 v[2:5], v[180:183], v[214:217], v[2:5]
	s_setprio 0
	s_barrier
	s_add_i32 s49, s49, 2
	s_add_u32 s47, s47, 0x100
	s_addc_u32 s48, s48, 0
	s_cmp_gt_u32 s49, 41
	s_mov_b64 s[18:19], s[20:21]
	s_cbranch_scc0 .LBB0_1360
	s_and_b64 vcc, exec, s[14:15]
	s_cbranch_vccz .LBB0_1363
	s_barrier
